# v36 + residual-row and row-stat loads fetched as 64B-contiguous segments (lane exchange after the load) in the residual epilogues
# speedup vs baseline: 1.0095x; 1.0095x over previous
; __device__ __forceinline__ float xsum16(float v) { const auto r = __builtin_amdgcn_permlane16_swap(__float_as_uint(v), __float_as_uint(v), false, false); return __uint_as_float(r[0]) + __uint_as_float(r[1]); }
; __device__ __forceinline__ float xsum32(float v) { const auto r = __builtin_amdgcn_permlane32_swap(__float_as_uint(v), __float_as_uint(v), false, false); return __uint_as_float(r[0]) + __uint_as_float(r[1]); }
; __device__ __forceinline__ void row_stats4(const float* st, int rowb, int fq, float (&mu)[4], float (&rs)[4]) {
;     ...
;     for (int m = 0; m < 4; ++m) { const f32x4* p = (const f32x4*)(st + (size_t)(rowb + m * 16) * 32 + fq * 8); a[m] = p[0]; b[m] = p[1]; }
; #pragma unroll
;     for (int m = 0; m < 4; ++m) { float s1 = (a[m][0] + a[m][2]) + (b[m][0] + b[m][2]), s2 = (a[m][1] + a[m][3]) + (b[m][1] + b[m][3]);
;         s1 = xsum32(xsum16(s1)); s2 = xsum32(xsum16(s2));
;         const float mm = s1 * (1.0f / 1024.0f); mu[m] = mm; rs[m] = rsqrtf(fmaxf(s2 * (1.0f / 1024.0f) - mm * mm, 0.f) + LN_EPS_); }
;     __device__ __forceinline__ void operator()(const f32x4 (&acc)[2][2][4][2], const pg8::Unit& u, int wr, int wc, int fr, int fq) const {
;     ...
;         for (int ai = 0; ai < 2; ++ai) { float mu4[4], rs4[4]; row_stats4(stp, row0 + ai * 128, fq, mu4, rs4);
; #pragma unroll
;             for (int m = 0; m < 4; ++m) { const int row = row0 + ai * 128 + m * 16; const float mu = mu4[m], rs = rs4[m];
;                 f32x4 yv[2][2], gq[2][2], bq_[2][2];
; #pragma unroll
;                 for (int bj = 0; bj < 2; ++bj)
; #pragma unroll
;                     for (int n = 0; n < 2; ++n) { yv[bj][n] = *(const f32x4*)(Yin + (size_t)row * D_ + col0 + bj * 128 + 4 * n); gq[bj][n] = *(const f32x4*)(g + col0 + bj * 128 + 4 * n); bq_[bj][n] = *(const f32x4*)(b + col0 + bj * 128 + 4 * n); }
.LBB0_372:
	s_lshl_b32 s3, s3, 8
	s_add_i32 s3, s3, s53
	v_or_b32_e32 v158, s3, v182
	v_ashrrev_i32_e32 v159, 31, v158
	v_lshlrev_b64 v[130:131], 7, v[158:159]
	v_lshl_add_u64 v[136:137], v[146:147], 0, v[130:131]
	v_or_b32_e32 v180, 16, v158
	s_nop 1
	v_bfe_u32 v153, v227, 4, 2
	v_sub_u32_e32 v152, 0, v153
	v_lshlrev_b32_e32 v152, 4, v152
	v_ashrrev_i32_e32 v153, 31, v152
	v_lshl_add_u64 v[152:153], v[136:137], 0, v[152:153]
	global_load_dwordx4 v[132:135], v[152:153], off
	global_load_dwordx4 v[166:169], v[152:153], off offset:64
	v_ashrrev_i32_e32 v181, 31, v180
	v_lshlrev_b64 v[172:173], 7, v[180:181]
	v_lshl_add_u64 v[136:137], v[146:147], 0, v[172:173]
	s_nop 1
	v_bfe_u32 v153, v227, 4, 2
	v_sub_u32_e32 v152, 0, v153
	v_lshlrev_b32_e32 v152, 4, v152
	v_ashrrev_i32_e32 v153, 31, v152
	v_lshl_add_u64 v[152:153], v[136:137], 0, v[152:153]
	global_load_dwordx4 v[174:177], v[152:153], off
	global_load_dwordx4 v[186:189], v[152:153], off offset:64
	v_or_b32_e32 v170, 32, v158
	v_ashrrev_i32_e32 v171, 31, v170
	v_lshlrev_b64 v[164:165], 7, v[170:171]
	v_lshl_add_u64 v[136:137], v[146:147], 0, v[164:165]
	s_nop 1
	v_bfe_u32 v153, v227, 4, 2
	v_sub_u32_e32 v152, 0, v153
	v_lshlrev_b32_e32 v152, 4, v152
	v_ashrrev_i32_e32 v153, 31, v152
	v_lshl_add_u64 v[152:153], v[136:137], 0, v[152:153]
	global_load_dwordx4 v[190:193], v[152:153], off
	global_load_dwordx4 v[196:199], v[152:153], off offset:64
	v_or_b32_e32 v162, 48, v158
	v_ashrrev_i32_e32 v163, 31, v162
	v_lshlrev_b64 v[160:161], 7, v[162:163]
	v_lshl_add_u64 v[204:205], v[146:147], 0, v[160:161]
	s_nop 1
	v_bfe_u32 v137, v227, 4, 2
	v_sub_u32_e32 v136, 0, v137
	v_lshlrev_b32_e32 v136, 4, v136
	v_ashrrev_i32_e32 v137, 31, v136
	v_lshl_add_u64 v[136:137], v[204:205], 0, v[136:137]
	global_load_dwordx4 v[200:203], v[136:137], off
	s_nop 0
	global_load_dwordx4 v[204:207], v[136:137], off offset:64
	s_lshl_b32 s16, s2, 8
	s_lshl_b32 s17, s2, 3
	s_or_b32 s2, s16, s54
	v_or_b32_e32 v152, s2, v183
	v_ashrrev_i32_e32 v153, 31, v152
	v_lshlrev_b64 v[136:137], 12, v[158:159]
	v_lshlrev_b64 v[152:153], 2, v[152:153]
	v_lshl_add_u64 v[178:179], s[12:13], 0, v[136:137]
	v_lshl_add_u64 v[178:179], v[178:179], 0, v[152:153]
	v_lshl_add_u64 v[154:155], s[8:9], 0, v[152:153]
	v_lshl_add_u64 v[156:157], s[10:11], 0, v[152:153]
	s_nop 1
	v_bfe_u32 v195, v227, 4, 2
	v_sub_u32_e32 v194, 0, v195
	v_lshlrev_b32_e32 v194, 4, v194
	v_ashrrev_i32_e32 v195, 31, v194
	v_lshl_add_u64 v[194:195], v[178:179], 0, v[194:195]
	global_load_dwordx4 v[208:211], v[194:195], off offset:64
	global_load_dwordx4 v[212:215], v[194:195], off
	global_load_dwordx4 v[216:219], v[154:155], off offset:16
	global_load_dwordx4 v[220:223], v[154:155], off
	global_load_dwordx4 v[234:237], v[156:157], off offset:16
	global_load_dwordx4 v[238:241], v[156:157], off
	s_mov_b32 s16, 0x3a800000
	s_mov_b32 s18, 0x3fd744fd
	s_load_dwordx16 s[60:75], s[34:35], 0x38
	s_or_b32 s24, s17, s57
	v_bitop3_b32 v194, s2, 56, v183 bitop3:0xc8
	s_ashr_i32 s40, s2, 6
	s_ashr_i32 s25, s24, 31
	s_waitcnt lgkmcnt(0)
	v_lshl_add_u64 v[136:137], s[74:75], 0, v[136:137]
	v_lshl_add_u64 v[136:137], v[136:137], 0, v[152:153]
	s_ashr_i32 s41, s40, 31
	s_waitcnt vmcnt(12)
	v_permlane32_swap_b32_e32 v132, v166
	v_permlane32_swap_b32_e32 v133, v167
	v_permlane32_swap_b32_e32 v134, v168
	v_permlane32_swap_b32_e32 v135, v169
	v_permlane16_swap_b32_e32 v132, v166
	v_permlane16_swap_b32_e32 v133, v167
	v_permlane16_swap_b32_e32 v134, v168
	v_permlane16_swap_b32_e32 v135, v169
	v_mov_b32_e32 v224, v132
	v_mov_b32_e32 v225, v166
	v_mov_b32_e32 v228, v134
	v_mov_b32_e32 v229, v168
	v_mov_b32_e32 v166, v133
	v_mov_b32_e32 v168, v135
	v_pk_add_f32 v[132:133], v[224:225], v[228:229]
	v_pk_add_f32 v[134:135], v[166:167], v[168:169]
	v_pk_add_f32 v[132:133], v[132:133], v[132:133] op_sel:[0,1] op_sel_hi:[1,0]
	v_pk_add_f32 v[134:135], v[134:135], v[134:135] op_sel:[0,1] op_sel_hi:[1,0]
	s_waitcnt vmcnt(10)
	v_permlane32_swap_b32_e32 v174, v186
	v_permlane32_swap_b32_e32 v175, v187
	v_permlane32_swap_b32_e32 v176, v188
	v_permlane32_swap_b32_e32 v177, v189
	v_permlane16_swap_b32_e32 v174, v186
	v_permlane16_swap_b32_e32 v175, v187
	v_permlane16_swap_b32_e32 v176, v188
	v_permlane16_swap_b32_e32 v177, v189
	v_mov_b32_e32 v166, v174
	v_mov_b32_e32 v167, v186
	v_mov_b32_e32 v168, v176
	v_mov_b32_e32 v169, v188
	v_mov_b32_e32 v0, v132
	v_mov_b32_e32 v133, v134
	v_pk_add_f32 v[166:167], v[166:167], v[168:169]
	v_permlane16_swap_b32_e32 v132, v0
	v_permlane16_swap_b32_e32 v134, v133
	v_mov_b32_e32 v186, v175
	v_mov_b32_e32 v188, v177
	v_pk_add_f32 v[166:167], v[166:167], v[166:167] op_sel:[0,1] op_sel_hi:[1,0]
	v_add_f32_e32 v177, v132, v0
	v_add_f32_e32 v176, v134, v133
	v_pk_add_f32 v[168:169], v[186:187], v[188:189]
	v_mov_b32_e32 v135, v166
	v_mov_b32_e32 v187, v177
	v_mov_b32_e32 v186, v176
	v_permlane16_swap_b32_e32 v166, v135
	v_permlane32_swap_b32_e32 v177, v187
	v_permlane32_swap_b32_e32 v176, v186
	v_add_f32_e32 v133, v166, v135
	v_pk_add_f32 v[166:167], v[176:177], v[186:187]
	v_pk_add_f32 v[168:169], v[168:169], v[168:169] op_sel:[0,1] op_sel_hi:[1,0]
	v_pk_mul_f32 v[224:225], v[166:167], s[16:17] op_sel_hi:[1,0]
	v_mov_b32_e32 v159, v168
	v_fma_f32 v0, -v225, v225, v224
	v_max_f32_e32 v0, 0, v0
	v_permlane16_swap_b32_e32 v168, v159
	v_add_f32_e32 v0, 0x3727c5ac, v0
	s_mov_b32 s16, 0x800000
	v_add_f32_e32 v132, v168, v159
	v_mul_f32_e32 v159, 0x4b800000, v0
	v_cmp_gt_f32_e32 vcc, s16, v0
	s_waitcnt vmcnt(8)
; __device__ __forceinline__ float xsum16(float v) { const auto r = __builtin_amdgcn_permlane16_swap(__float_as_uint(v), __float_as_uint(v), false, false); return __uint_as_float(r[0]) + __uint_as_float(r[1]); }
; __device__ __forceinline__ float xsum32(float v) { const auto r = __builtin_amdgcn_permlane32_swap(__float_as_uint(v), __float_as_uint(v), false, false); return __uint_as_float(r[0]) + __uint_as_float(r[1]); }
; __device__ __forceinline__ size_t blk_off(int r, int c, int K) { return (size_t)(r >> 8) * 256 * K + (size_t)(c >> 6) * (256 * 64) + (size_t)((r & 255) * 64 + (c & 63)); }
; __device__ __forceinline__ u32x4 pack8(const f32x4 a, const f32x4 b) { u32x4 w; w.x = cvt_pk_bf16(a[0], a[1]); w.y = cvt_pk_bf16(a[2], a[3]); w.z = cvt_pk_bf16(b[0], b[1]); w.w = cvt_pk_bf16(b[2], b[3]); return w; }
; __device__ __forceinline__ void row_stats4(const float* st, int rowb, int fq, float (&mu)[4], float (&rs)[4]) {
;     ...
;     for (int m = 0; m < 4; ++m) { float s1 = (a[m][0] + a[m][2]) + (b[m][0] + b[m][2]), s2 = (a[m][1] + a[m][3]) + (b[m][1] + b[m][3]);
;         s1 = xsum32(xsum16(s1)); s2 = xsum32(xsum16(s2));
;         const float mm = s1 * (1.0f / 1024.0f); mu[m] = mm; rs[m] = rsqrtf(fmaxf(s2 * (1.0f / 1024.0f) - mm * mm, 0.f) + LN_EPS_); }
;     __device__ __forceinline__ void operator()(const f32x4 (&acc)[2][2][4][2], const pg8::Unit& u, int wr, int wc, int fr, int fq) const {
;     ...
;                     for (int n = 0; n < 2; ++n) { yv[bj][n] = *(const f32x4*)(Yin + (size_t)row * D_ + col0 + bj * 128 + 4 * n); gq[bj][n] = *(const f32x4*)(g + col0 + bj * 128 + 4 * n); bq_[bj][n] = *(const f32x4*)(b + col0 + bj * 128 + 4 * n); }
;                 asm volatile("" ::: "memory");
;                 float s1 = 0.f, s2 = 0.f;
; #pragma unroll
;                 for (int bj = 0; bj < 2; ++bj) { float* yp = Y + (size_t)row * D_ + col0 + bj * 128; f32x4 v[2];
; #pragma unroll
;                     for (int n = 0; n < 2; ++n) { v[n] = (((yv[bj][n] - mu) * rs) * gq[bj][n] + bq_[bj][n]) * ALPHA_ + acc[ai][bj][m][n] * sc;
;                         *(f32x4*)(yp + 4 * n) = v[n]; s1 += (v[n][0] + v[n][1]) + (v[n][2] + v[n][3]); s2 += (v[n][0] * v[n][0] + v[n][1] * v[n][1]) + (v[n][2] * v[n][2] + v[n][3] * v[n][3]); }
;                     *(u32x4*)(Yb + blk_off(row, col0 + bj * 128, D_)) = pack8(v[0], v[1]); }
	v_permlane32_swap_b32_e32 v190, v196
	v_permlane32_swap_b32_e32 v191, v197
	v_permlane32_swap_b32_e32 v192, v198
	v_permlane32_swap_b32_e32 v193, v199
	v_permlane16_swap_b32_e32 v190, v196
	v_permlane16_swap_b32_e32 v191, v197
	v_permlane16_swap_b32_e32 v192, v198
	v_permlane16_swap_b32_e32 v193, v199
	v_mov_b32_e32 v174, v190
	v_mov_b32_e32 v175, v196
	v_cndmask_b32_e32 v0, v0, v159, vcc
	v_rsq_f32_e32 v0, v0
	v_mov_b32_e32 v166, v192
	v_mov_b32_e32 v167, v198
	v_pk_add_f32 v[166:167], v[174:175], v[166:167]
	v_mul_f32_e32 v159, 0x45800000, v0
	v_pk_add_f32 v[166:167], v[166:167], v[166:167] op_sel:[0,1] op_sel_hi:[1,0]
	v_mov_b32_e32 v196, v191
	v_mov_b32_e32 v198, v193
	v_cndmask_b32_e32 v0, v0, v159, vcc
	v_pk_add_f32 v[168:169], v[196:197], v[198:199]
	v_mov_b32_e32 v159, v166
	v_pk_add_f32 v[168:169], v[168:169], v[168:169] op_sel:[0,1] op_sel_hi:[1,0]
	s_nop 0
	v_permlane16_swap_b32_e32 v166, v159
	v_add_f32_e32 v175, v166, v159
	v_mov_b32_e32 v159, v168
	s_nop 1
	v_permlane16_swap_b32_e32 v168, v159
	s_nop 1
	v_bfe_u32 v135, v227, 4, 2
	v_sub_u32_e32 v134, 0, v135
	v_lshlrev_b32_e32 v134, 4, v134
	v_ashrrev_i32_e32 v135, 31, v134
	v_lshl_add_u64 v[134:135], v[178:179], 0, v[134:135]
	global_load_dwordx4 v[186:189], v[134:135], off offset:576
	global_load_dwordx4 v[190:193], v[134:135], off offset:512
	v_add_f32_e32 v174, v168, v159
	s_waitcnt vmcnt(8)
	v_permlane32_swap_b32_e32 v200, v204
	v_permlane32_swap_b32_e32 v201, v205
	v_permlane32_swap_b32_e32 v202, v206
	v_permlane32_swap_b32_e32 v203, v207
	v_permlane16_swap_b32_e32 v200, v204
	v_permlane16_swap_b32_e32 v201, v205
	v_permlane16_swap_b32_e32 v202, v206
	v_permlane16_swap_b32_e32 v203, v207
	v_mov_b32_e32 v166, v200
	v_mov_b32_e32 v167, v204
	v_mov_b32_e32 v168, v202
	v_mov_b32_e32 v169, v206
	v_mov_b32_e32 v204, v201
	v_mov_b32_e32 v206, v203
	v_pk_add_f32 v[166:167], v[166:167], v[168:169]
	v_pk_add_f32 v[168:169], v[204:205], v[206:207]
	global_load_dwordx4 v[196:199], v[154:155], off offset:528
	global_load_dwordx4 v[200:203], v[154:155], off offset:512
	global_load_dwordx4 v[204:207], v[156:157], off offset:528
	global_load_dwordx4 v[242:245], v[156:157], off offset:512
	s_waitcnt vmcnt(10)
	v_permlane32_swap_b32_e32 v212, v208
	v_permlane32_swap_b32_e32 v213, v209
	v_permlane32_swap_b32_e32 v214, v210
	v_permlane32_swap_b32_e32 v215, v211
	v_permlane16_swap_b32_e32 v212, v208
	v_permlane16_swap_b32_e32 v213, v209
	v_permlane16_swap_b32_e32 v214, v210
	v_permlane16_swap_b32_e32 v215, v211
	v_sub_f32_e32 v179, v215, v225
	v_sub_f32_e32 v178, v214, v225
	v_sub_f32_e32 v213, v213, v225
	v_sub_f32_e32 v212, v212, v225
	v_pk_mul_f32 v[212:213], v[0:1], v[212:213] op_sel_hi:[0,1]
	v_pk_mul_f32 v[178:179], v[0:1], v[178:179] op_sel_hi:[0,1]
	s_waitcnt vmcnt(6)
	v_pk_fma_f32 v[178:179], v[222:223], v[178:179], v[240:241]
	v_pk_fma_f32 v[212:213], v[220:221], v[212:213], v[238:239]
	v_pk_mul_f32 v[178:179], v[178:179], s[18:19] op_sel_hi:[1,0]
	v_pk_mul_f32 v[212:213], v[212:213], s[18:19] op_sel_hi:[1,0]
	v_pk_fma_f32 v[128:129], v[128:129], 0.5, v[178:179] op_sel_hi:[1,0,1]
	v_pk_fma_f32 v[126:127], v[126:127], 0.5, v[212:213] op_sel_hi:[1,0,1]
	v_add_f32_e32 v179, v128, v129
	v_add_f32_e32 v178, v126, v127
	v_add_f32_e32 v178, v178, v179
	v_add_f32_e32 v195, 0, v178
	v_mul_f32_e32 v178, v127, v127
	v_mul_f32_e32 v179, v129, v129
	v_fmac_f32_e32 v178, v126, v126
	v_fmac_f32_e32 v179, v128, v128
	v_add_f32_e32 v212, v178, v179
	v_sub_f32_e32 v179, v211, v225
	v_sub_f32_e32 v178, v210, v225
	v_sub_f32_e32 v209, v209, v225
	v_sub_f32_e32 v208, v208, v225
	v_pk_mul_f32 v[208:209], v[0:1], v[208:209] op_sel_hi:[0,1]
	v_pk_mul_f32 v[178:179], v[0:1], v[178:179] op_sel_hi:[0,1]
	v_pk_fma_f32 v[178:179], v[218:219], v[178:179], v[236:237]
	v_pk_fma_f32 v[208:209], v[216:217], v[208:209], v[234:235]
	v_pk_mul_f32 v[178:179], v[178:179], s[18:19] op_sel_hi:[1,0]
	v_pk_mul_f32 v[208:209], v[208:209], s[18:19] op_sel_hi:[1,0]
	v_pk_add_f32 v[166:167], v[166:167], v[166:167] op_sel:[0,1] op_sel_hi:[1,0]
	v_pk_fma_f32 v[124:125], v[124:125], 0.5, v[178:179] op_sel_hi:[1,0,1]
	v_pk_fma_f32 v[122:123], v[122:123], 0.5, v[208:209] op_sel_hi:[1,0,1]
	v_mov_b32_e32 v159, v166
	v_add_f32_e32 v178, v122, v123
	v_add_f32_e32 v179, v124, v125
	v_pk_add_f32 v[168:169], v[168:169], v[168:169] op_sel:[0,1] op_sel_hi:[1,0]
	v_permlane16_swap_b32_e32 v166, v159
	v_add_f32_e32 v178, v178, v179
	v_add_f32_e32 v167, v166, v159
	v_mov_b32_e32 v159, v168
	v_add_f32_e32 v178, v195, v178
	v_mul_f32_e32 v179, v123, v123
	v_mul_f32_e32 v195, v125, v125
	v_permlane16_swap_b32_e32 v168, v159
	s_ashr_i32 s16, s3, 8
	s_nop 0
	s_nop 1
	v_bfe_u32 v135, v227, 4, 2
	v_sub_u32_e32 v134, 0, v135
	v_lshlrev_b32_e32 v134, 4, v134
	v_ashrrev_i32_e32 v135, 31, v134
	v_lshl_add_u64 v[134:135], v[136:137], 0, v[134:135]
	v_permlane16_swap_b32_e32 v126, v122
	v_permlane16_swap_b32_e32 v127, v123
	v_permlane16_swap_b32_e32 v128, v124
	v_permlane16_swap_b32_e32 v129, v125
	v_permlane32_swap_b32_e32 v126, v122
	v_permlane32_swap_b32_e32 v127, v123
	v_permlane32_swap_b32_e32 v128, v124
	v_permlane32_swap_b32_e32 v129, v125
	global_store_dwordx4 v[134:135], v[126:129], off
	global_store_dwordx4 v[134:135], v[122:125], off offset:64
	s_nop 1
	v_permlane32_swap_b32_e32 v126, v122
	v_permlane32_swap_b32_e32 v127, v123
	v_permlane32_swap_b32_e32 v128, v124
	v_permlane32_swap_b32_e32 v129, v125
	v_permlane16_swap_b32_e32 v126, v122
	v_permlane16_swap_b32_e32 v127, v123
	v_permlane16_swap_b32_e32 v128, v124
	v_permlane16_swap_b32_e32 v129, v125
	v_fmac_f32_e32 v179, v122, v122
	v_fmac_f32_e32 v195, v124, v124
	v_cvt_pk_bf16_f32 v126, v126, v127
	v_cvt_pk_bf16_f32 v127, v128, v129
	v_cvt_pk_bf16_f32 v128, v122, v123
	v_cvt_pk_bf16_f32 v129, v124, v125
	v_add_f32_e32 v166, v168, v159
	s_ashr_i32 s17, s16, 31
	v_lshlrev_b32_e32 v159, 6, v158
	s_movk_i32 s3, 0x33c0
	s_lshl_b64 s[16:17], s[16:17], 19
	v_and_or_b32 v159, v159, s3, v194
	v_readlane_b32 s2, v253, 59
	v_readlane_b32 s3, v253, 60
	s_add_u32 s16, s2, s16
	s_addc_u32 s17, s3, s17
	s_lshl_b64 s[28:29], s[40:41], 15
	s_waitcnt vmcnt(6)
; __device__ __forceinline__ float xsum16(float v) { const auto r = __builtin_amdgcn_permlane16_swap(__float_as_uint(v), __float_as_uint(v), false, false); return __uint_as_float(r[0]) + __uint_as_float(r[1]); }
; __device__ __forceinline__ float xsum32(float v) { const auto r = __builtin_amdgcn_permlane32_swap(__float_as_uint(v), __float_as_uint(v), false, false); return __uint_as_float(r[0]) + __uint_as_float(r[1]); }
; __device__ __forceinline__ size_t blk_off(int r, int c, int K) { return (size_t)(r >> 8) * 256 * K + (size_t)(c >> 6) * (256 * 64) + (size_t)((r & 255) * 64 + (c & 63)); }
; __device__ __forceinline__ u32x4 pack8(const f32x4 a, const f32x4 b) { u32x4 w; w.x = cvt_pk_bf16(a[0], a[1]); w.y = cvt_pk_bf16(a[2], a[3]); w.z = cvt_pk_bf16(b[0], b[1]); w.w = cvt_pk_bf16(b[2], b[3]); return w; }
;     __device__ __forceinline__ void operator()(const f32x4 (&acc)[2][2][4][2], const pg8::Unit& u, int wr, int wc, int fr, int fq) const {
;     ...
;                 for (int bj = 0; bj < 2; ++bj) { float* yp = Y + (size_t)row * D_ + col0 + bj * 128; f32x4 v[2];
; #pragma unroll
;                     for (int n = 0; n < 2; ++n) { v[n] = (((yv[bj][n] - mu) * rs) * gq[bj][n] + bq_[bj][n]) * ALPHA_ + acc[ai][bj][m][n] * sc;
;                         *(f32x4*)(yp + 4 * n) = v[n]; s1 += (v[n][0] + v[n][1]) + (v[n][2] + v[n][3]); s2 += (v[n][0] * v[n][0] + v[n][1] * v[n][1]) + (v[n][2] * v[n][2] + v[n][3] * v[n][3]); }
;                     *(u32x4*)(Yb + blk_off(row, col0 + bj * 128, D_)) = pack8(v[0], v[1]); }
;                 s1 = xsum32(xsum16(s1)); s2 = xsum32(xsum16(s2));
;                 if (fq == 0) *(f32x2*)(stn + (size_t)row * 32 + (u.pn * 4 + wc) * 2) = (f32x2){s1, s2}; asm volatile("" ::: "memory"); } }
	v_permlane32_swap_b32_e32 v190, v186
	v_permlane32_swap_b32_e32 v191, v187
	v_permlane32_swap_b32_e32 v192, v188
	v_permlane32_swap_b32_e32 v193, v189
	v_permlane16_swap_b32_e32 v190, v186
	v_permlane16_swap_b32_e32 v191, v187
	v_permlane16_swap_b32_e32 v192, v188
	v_permlane16_swap_b32_e32 v193, v189
	v_sub_f32_e32 v123, v193, v225
	v_sub_f32_e32 v122, v192, v225
	v_sub_f32_e32 v125, v191, v225
	v_sub_f32_e32 v124, v190, v225
	v_pk_mul_f32 v[124:125], v[0:1], v[124:125] op_sel_hi:[0,1]
	v_pk_mul_f32 v[122:123], v[0:1], v[122:123] op_sel_hi:[0,1]
	s_add_u32 s50, s16, s28
	s_addc_u32 s51, s17, s29
	v_lshlrev_b32_e32 v159, 1, v159
	global_store_dwordx4 v159, v[126:129], s[50:51]
	s_waitcnt vmcnt(3)
	v_pk_fma_f32 v[122:123], v[202:203], v[122:123], v[244:245]
	v_pk_fma_f32 v[124:125], v[200:201], v[124:125], v[242:243]
	v_pk_mul_f32 v[122:123], v[122:123], s[18:19] op_sel_hi:[1,0]
	v_pk_mul_f32 v[124:125], v[124:125], s[18:19] op_sel_hi:[1,0]
	v_pk_fma_f32 v[120:121], v[120:121], 0.5, v[122:123] op_sel_hi:[1,0,1]
	v_pk_fma_f32 v[118:119], v[118:119], 0.5, v[124:125] op_sel_hi:[1,0,1]
	v_add_f32_e32 v123, v120, v121
	v_add_f32_e32 v122, v118, v119
	v_add_f32_e32 v122, v122, v123
	v_add_f32_e32 v126, v178, v122
	v_mul_f32_e32 v122, v119, v119
	v_mul_f32_e32 v123, v121, v121
	v_add_f32_e32 v179, v179, v195
	v_fmac_f32_e32 v122, v118, v118
	v_fmac_f32_e32 v123, v120, v120
	v_add_f32_e32 v179, v212, v179
	v_add_f32_e32 v122, v122, v123
	v_add_f32_e32 v127, v179, v122
	v_sub_f32_e32 v123, v189, v225
	v_sub_f32_e32 v122, v188, v225
	v_sub_f32_e32 v125, v187, v225
	v_sub_f32_e32 v124, v186, v225
	v_pk_mul_f32 v[124:125], v[0:1], v[124:125] op_sel_hi:[0,1]
	v_pk_mul_f32 v[122:123], v[0:1], v[122:123] op_sel_hi:[0,1]
	v_pk_fma_f32 v[122:123], v[198:199], v[122:123], v[206:207]
	v_pk_fma_f32 v[124:125], v[196:197], v[124:125], v[204:205]
	v_pk_mul_f32 v[122:123], v[122:123], s[18:19] op_sel_hi:[1,0]
	v_pk_mul_f32 v[124:125], v[124:125], s[18:19] op_sel_hi:[1,0]
	v_pk_fma_f32 v[116:117], v[116:117], 0.5, v[122:123] op_sel_hi:[1,0,1]
	v_pk_fma_f32 v[114:115], v[114:115], 0.5, v[124:125] op_sel_hi:[1,0,1]
	v_add_f32_e32 v122, v116, v117
	v_add_f32_e32 v0, v114, v115
	v_add_f32_e32 v0, v0, v122
	v_mul_f32_e32 v122, v115, v115
	v_mul_f32_e32 v123, v117, v117
	v_add_f32_e32 v0, v126, v0
	v_fmac_f32_e32 v122, v114, v114
	v_fmac_f32_e32 v123, v116, v116
	s_nop 0
	s_nop 1
	v_bfe_u32 v125, v227, 4, 2
	v_sub_u32_e32 v124, 0, v125
	v_lshlrev_b32_e32 v124, 4, v124
	v_ashrrev_i32_e32 v125, 31, v124
	v_lshl_add_u64 v[124:125], v[136:137], 0, v[124:125]
	v_permlane16_swap_b32_e32 v118, v114
	v_permlane16_swap_b32_e32 v119, v115
	v_permlane16_swap_b32_e32 v120, v116
	v_permlane16_swap_b32_e32 v121, v117
	v_permlane32_swap_b32_e32 v118, v114
	v_permlane32_swap_b32_e32 v119, v115
	v_permlane32_swap_b32_e32 v120, v116
	v_permlane32_swap_b32_e32 v121, v117
	global_store_dwordx4 v[124:125], v[118:121], off offset:512
	global_store_dwordx4 v[124:125], v[114:117], off offset:576
	s_nop 1
	v_permlane32_swap_b32_e32 v118, v114
	v_permlane32_swap_b32_e32 v119, v115
	v_permlane32_swap_b32_e32 v120, v116
	v_permlane32_swap_b32_e32 v121, v117
	v_permlane16_swap_b32_e32 v118, v114
	v_permlane16_swap_b32_e32 v119, v115
	v_permlane16_swap_b32_e32 v120, v116
	v_permlane16_swap_b32_e32 v121, v117
	v_add_f32_e32 v122, v122, v123
	v_cvt_pk_bf16_f32 v118, v118, v119
	v_cvt_pk_bf16_f32 v119, v120, v121
	v_cvt_pk_bf16_f32 v120, v114, v115
	v_mov_b32_e32 v114, v0
	v_add_f32_e32 v122, v127, v122
	s_nop 0
	v_permlane16_swap_b32_e32 v0, v114
	s_or_b32 s2, s40, 2
	v_add_f32_e32 v114, v0, v114
	v_mov_b32_e32 v0, v122
	s_ashr_i32 s3, s2, 31
	s_nop 0
	v_permlane16_swap_b32_e32 v122, v0
	s_lshl_b64 s[40:41], s[2:3], 15
	v_add_f32_e32 v115, v122, v0
	v_mov_b32_e32 v135, v133
	v_mov_b32_e32 v134, v132
	v_mov_b32_e32 v177, v175
	v_mov_b32_e32 v176, v174
	v_mov_b32_e32 v169, v167
	v_mov_b32_e32 v168, v166
	v_cvt_pk_bf16_f32 v121, v116, v117
	s_add_u32 s42, s16, s40
	v_mov_b32_e32 v116, v114
	v_mov_b32_e32 v117, v115
	v_permlane32_swap_b32_e32 v133, v135
	v_permlane32_swap_b32_e32 v132, v134
	v_permlane32_swap_b32_e32 v175, v177
	v_permlane32_swap_b32_e32 v174, v176
	v_permlane32_swap_b32_e32 v167, v169
	v_permlane32_swap_b32_e32 v166, v168
	s_addc_u32 s43, s17, s41
	v_permlane32_swap_b32_e32 v114, v116
	v_permlane32_swap_b32_e32 v115, v117
	global_store_dwordx4 v159, v[118:121], s[42:43]
	s_and_saveexec_b64 s[26:27], s[44:45]
	s_cbranch_execz .LBB0_374
	v_pk_add_f32 v[114:115], v[114:115], v[116:117]
	v_lshl_add_u64 v[116:117], s[30:31], 0, v[130:131]
	v_lshl_add_u64 v[116:117], s[24:25], 2, v[116:117]
	global_store_dwordx2 v[116:117], v[114:115], off
;     __device__ __forceinline__ void operator()(const f32x4 (&acc)[2][2][4][2], const pg8::Unit& u, int wr, int wc, int fr, int fq) const {
;     ...
;             for (int m = 0; m < 4; ++m) { const int row = row0 + ai * 128 + m * 16; const float mu = mu4[m], rs = rs4[m];
;                 f32x4 yv[2][2], gq[2][2], bq_[2][2];
; #pragma unroll
;                 for (int bj = 0; bj < 2; ++bj)
; #pragma unroll
;                     for (int n = 0; n < 2; ++n) { yv[bj][n] = *(const f32x4*)(Yin + (size_t)row * D_ + col0 + bj * 128 + 4 * n); gq[bj][n] = *(const f32x4*)(g + col0 + bj * 128 + 4 * n); bq_[bj][n] = *(const f32x4*)(b + col0 + bj * 128 + 4 * n); }
;                 asm volatile("" ::: "memory");
;                 float s1 = 0.f, s2 = 0.f;
; #pragma unroll
;                 for (int bj = 0; bj < 2; ++bj) { float* yp = Y + (size_t)row * D_ + col0 + bj * 128; f32x4 v[2];
; #pragma unroll
;                     for (int n = 0; n < 2; ++n) { v[n] = (((yv[bj][n] - mu) * rs) * gq[bj][n] + bq_[bj][n]) * ALPHA_ + acc[ai][bj][m][n] * sc;
;                         *(f32x4*)(yp + 4 * n) = v[n]; s1 += (v[n][0] + v[n][1]) + (v[n][2] + v[n][3]); s2 += (v[n][0] * v[n][0] + v[n][1] * v[n][1]) + (v[n][2] * v[n][2] + v[n][3] * v[n][3]); }
.LBB0_374:
	s_or_b64 exec, exec, s[26:27]
	v_pk_add_f32 v[114:115], v[132:133], v[134:135]
	s_mov_b32 s2, 0x3a800000
	v_pk_mul_f32 v[178:179], v[114:115], s[2:3] op_sel_hi:[1,0]
	s_mov_b32 s2, 0x800000
	v_fma_f32 v0, -v179, v179, v178
	v_max_f32_e32 v0, 0, v0
	v_add_f32_e32 v0, 0x3727c5ac, v0
	v_cmp_gt_f32_e32 vcc, s2, v0
	v_mul_f32_e32 v114, 0x4b800000, v0
	v_lshlrev_b64 v[212:213], 12, v[180:181]
	v_cndmask_b32_e32 v0, v0, v114, vcc
	v_rsq_f32_e32 v0, v0
	v_lshlrev_b32_e32 v159, 6, v180
	s_movk_i32 s2, 0x37c0
	v_mul_f32_e32 v114, 0x45800000, v0
	v_cndmask_b32_e32 v0, v0, v114, vcc
	v_lshl_add_u64 v[114:115], s[12:13], 0, v[212:213]
	v_lshl_add_u64 v[118:119], v[114:115], 0, v[152:153]
	s_nop 1
	v_bfe_u32 v117, v227, 4, 2
	v_sub_u32_e32 v116, 0, v117
	v_lshlrev_b32_e32 v116, 4, v116
	v_ashrrev_i32_e32 v117, 31, v116
	v_lshl_add_u64 v[116:117], v[118:119], 0, v[116:117]
	global_load_dwordx4 v[186:189], v[116:117], off offset:64
	global_load_dwordx4 v[190:193], v[116:117], off
	global_load_dwordx4 v[196:199], v[154:155], off offset:16
	global_load_dwordx4 v[200:203], v[154:155], off
	global_load_dwordx4 v[204:207], v[156:157], off offset:16
	global_load_dwordx4 v[208:211], v[156:157], off
	s_nop 1
	v_bfe_u32 v121, v227, 4, 2
	v_sub_u32_e32 v120, 0, v121
	v_lshlrev_b32_e32 v120, 4, v120
	v_ashrrev_i32_e32 v121, 31, v120
	v_lshl_add_u64 v[120:121], v[118:119], 0, v[120:121]
	global_load_dwordx4 v[114:117], v[120:121], off offset:576
	global_load_dwordx4 v[134:137], v[120:121], off offset:512
	s_nop 0
	global_load_dwordx4 v[118:121], v[154:155], off offset:528
	global_load_dwordx4 v[126:129], v[154:155], off offset:512
	global_load_dwordx4 v[122:125], v[156:157], off offset:528
	global_load_dwordx4 v[130:133], v[156:157], off offset:512
	v_and_or_b32 v159, v159, s2, v194
	s_load_dwordx16 s[60:75], s[34:35], 0x38
	s_mov_b32 s2, 0x3fd744fd
	v_lshlrev_b32_e32 v159, 1, v159
	s_waitcnt lgkmcnt(0)
	v_lshl_add_u64 v[180:181], s[74:75], 0, v[212:213]
	v_lshl_add_u64 v[180:181], v[180:181], 0, v[152:153]
	s_waitcnt vmcnt(10)
	v_permlane32_swap_b32_e32 v190, v186
	v_permlane32_swap_b32_e32 v191, v187
	v_permlane32_swap_b32_e32 v192, v188
	v_permlane32_swap_b32_e32 v193, v189
	v_permlane16_swap_b32_e32 v190, v186
	v_permlane16_swap_b32_e32 v191, v187
	v_permlane16_swap_b32_e32 v192, v188
	v_permlane16_swap_b32_e32 v193, v189
	v_sub_f32_e32 v189, v189, v179
	v_sub_f32_e32 v193, v193, v179
	v_sub_f32_e32 v192, v192, v179
	v_sub_f32_e32 v191, v191, v179
	v_sub_f32_e32 v190, v190, v179
	v_pk_mul_f32 v[190:191], v[0:1], v[190:191] op_sel_hi:[0,1]
	v_pk_mul_f32 v[192:193], v[0:1], v[192:193] op_sel_hi:[0,1]
	v_sub_f32_e32 v188, v188, v179
	v_sub_f32_e32 v187, v187, v179
	v_sub_f32_e32 v186, v186, v179
	s_waitcnt vmcnt(6)
	v_pk_fma_f32 v[192:193], v[202:203], v[192:193], v[210:211]
	v_pk_fma_f32 v[190:191], v[200:201], v[190:191], v[208:209]
	v_pk_mul_f32 v[186:187], v[0:1], v[186:187] op_sel_hi:[0,1]
	v_pk_mul_f32 v[188:189], v[0:1], v[188:189] op_sel_hi:[0,1]
	v_pk_mul_f32 v[190:191], v[190:191], s[2:3] op_sel_hi:[1,0]
	v_pk_mul_f32 v[192:193], v[192:193], s[2:3] op_sel_hi:[1,0]
	v_pk_fma_f32 v[188:189], v[198:199], v[188:189], v[206:207]
	v_pk_fma_f32 v[186:187], v[196:197], v[186:187], v[204:205]
	v_pk_fma_f32 v[112:113], v[112:113], 0.5, v[192:193] op_sel_hi:[1,0,1]
	v_pk_fma_f32 v[110:111], v[110:111], 0.5, v[190:191] op_sel_hi:[1,0,1]
	v_pk_mul_f32 v[186:187], v[186:187], s[2:3] op_sel_hi:[1,0]
	v_pk_mul_f32 v[188:189], v[188:189], s[2:3] op_sel_hi:[1,0]
	v_add_f32_e32 v178, v110, v111
	v_add_f32_e32 v190, v112, v113
	v_pk_fma_f32 v[108:109], v[108:109], 0.5, v[188:189] op_sel_hi:[1,0,1]
	v_pk_fma_f32 v[106:107], v[106:107], 0.5, v[186:187] op_sel_hi:[1,0,1]
	v_add_f32_e32 v178, v178, v190
	v_add_f32_e32 v186, v106, v107
	v_add_f32_e32 v187, v108, v109
	v_add_f32_e32 v178, 0, v178
	v_add_f32_e32 v186, v186, v187
	v_mul_f32_e32 v190, v111, v111
	v_mul_f32_e32 v191, v113, v113
	v_add_f32_e32 v178, v178, v186
	v_mul_f32_e32 v186, v107, v107
	v_mul_f32_e32 v187, v109, v109
	s_nop 0
	v_fmac_f32_e32 v190, v110, v110
	v_fmac_f32_e32 v191, v112, v112
	s_nop 1
	v_bfe_u32 v189, v227, 4, 2
	v_sub_u32_e32 v188, 0, v189
	v_lshlrev_b32_e32 v188, 4, v188
	v_ashrrev_i32_e32 v189, 31, v188
	v_lshl_add_u64 v[188:189], v[180:181], 0, v[188:189]
	v_permlane16_swap_b32_e32 v110, v106
	v_permlane16_swap_b32_e32 v111, v107
	v_permlane16_swap_b32_e32 v112, v108
	v_permlane16_swap_b32_e32 v113, v109
	v_permlane32_swap_b32_e32 v110, v106
	v_permlane32_swap_b32_e32 v111, v107
	v_permlane32_swap_b32_e32 v112, v108
	v_permlane32_swap_b32_e32 v113, v109
	global_store_dwordx4 v[188:189], v[110:113], off
	global_store_dwordx4 v[188:189], v[106:109], off offset:64
	s_nop 1
	v_permlane32_swap_b32_e32 v110, v106
	v_permlane32_swap_b32_e32 v111, v107
	v_permlane32_swap_b32_e32 v112, v108
	v_permlane32_swap_b32_e32 v113, v109
	v_permlane16_swap_b32_e32 v110, v106
	v_permlane16_swap_b32_e32 v111, v107
	v_permlane16_swap_b32_e32 v112, v108
	v_permlane16_swap_b32_e32 v113, v109
	v_fmac_f32_e32 v186, v106, v106
	v_fmac_f32_e32 v187, v108, v108
	v_cvt_pk_bf16_f32 v110, v110, v111
	v_cvt_pk_bf16_f32 v111, v112, v113
	v_cvt_pk_bf16_f32 v112, v106, v107
	v_cvt_pk_bf16_f32 v113, v108, v109
	s_waitcnt vmcnt(6)
	v_permlane32_swap_b32_e32 v134, v114
	v_permlane32_swap_b32_e32 v135, v115
	v_permlane32_swap_b32_e32 v136, v116
	v_permlane32_swap_b32_e32 v137, v117
	v_permlane16_swap_b32_e32 v134, v114
	v_permlane16_swap_b32_e32 v135, v115
	v_permlane16_swap_b32_e32 v136, v116
	v_permlane16_swap_b32_e32 v137, v117
	v_sub_f32_e32 v107, v137, v179
	v_sub_f32_e32 v106, v136, v179
	v_sub_f32_e32 v109, v135, v179
	v_sub_f32_e32 v108, v134, v179
	v_pk_mul_f32 v[108:109], v[0:1], v[108:109] op_sel_hi:[0,1]
	v_pk_mul_f32 v[106:107], v[0:1], v[106:107] op_sel_hi:[0,1]
	s_waitcnt vmcnt(2)
; __device__ __forceinline__ float xsum16(float v) { const auto r = __builtin_amdgcn_permlane16_swap(__float_as_uint(v), __float_as_uint(v), false, false); return __uint_as_float(r[0]) + __uint_as_float(r[1]); }
; __device__ __forceinline__ float xsum32(float v) { const auto r = __builtin_amdgcn_permlane32_swap(__float_as_uint(v), __float_as_uint(v), false, false); return __uint_as_float(r[0]) + __uint_as_float(r[1]); }
; __device__ __forceinline__ size_t blk_off(int r, int c, int K) { return (size_t)(r >> 8) * 256 * K + (size_t)(c >> 6) * (256 * 64) + (size_t)((r & 255) * 64 + (c & 63)); }
; __device__ __forceinline__ u32x4 pack8(const f32x4 a, const f32x4 b) { u32x4 w; w.x = cvt_pk_bf16(a[0], a[1]); w.y = cvt_pk_bf16(a[2], a[3]); w.z = cvt_pk_bf16(b[0], b[1]); w.w = cvt_pk_bf16(b[2], b[3]); return w; }
;     __device__ __forceinline__ void operator()(const f32x4 (&acc)[2][2][4][2], const pg8::Unit& u, int wr, int wc, int fr, int fq) const {
;     ...
;                     for (int n = 0; n < 2; ++n) { yv[bj][n] = *(const f32x4*)(Yin + (size_t)row * D_ + col0 + bj * 128 + 4 * n); gq[bj][n] = *(const f32x4*)(g + col0 + bj * 128 + 4 * n); bq_[bj][n] = *(const f32x4*)(b + col0 + bj * 128 + 4 * n); }
;                 asm volatile("" ::: "memory");
;                 float s1 = 0.f, s2 = 0.f;
; #pragma unroll
;                 for (int bj = 0; bj < 2; ++bj) { float* yp = Y + (size_t)row * D_ + col0 + bj * 128; f32x4 v[2];
; #pragma unroll
;                     for (int n = 0; n < 2; ++n) { v[n] = (((yv[bj][n] - mu) * rs) * gq[bj][n] + bq_[bj][n]) * ALPHA_ + acc[ai][bj][m][n] * sc;
;                         *(f32x4*)(yp + 4 * n) = v[n]; s1 += (v[n][0] + v[n][1]) + (v[n][2] + v[n][3]); s2 += (v[n][0] * v[n][0] + v[n][1] * v[n][1]) + (v[n][2] * v[n][2] + v[n][3] * v[n][3]); }
;                     *(u32x4*)(Yb + blk_off(row, col0 + bj * 128, D_)) = pack8(v[0], v[1]); }
;                 s1 = xsum32(xsum16(s1)); s2 = xsum32(xsum16(s2));
;                 if (fq == 0) *(f32x2*)(stn + (size_t)row * 32 + (u.pn * 4 + wc) * 2) = (f32x2){s1, s2}; asm volatile("" ::: "memory"); } }
	v_pk_fma_f32 v[106:107], v[128:129], v[106:107], v[132:133]
	v_pk_fma_f32 v[108:109], v[126:127], v[108:109], v[130:131]
	v_pk_mul_f32 v[106:107], v[106:107], s[2:3] op_sel_hi:[1,0]
	v_pk_mul_f32 v[108:109], v[108:109], s[2:3] op_sel_hi:[1,0]
	v_pk_fma_f32 v[104:105], v[104:105], 0.5, v[106:107] op_sel_hi:[1,0,1]
	v_pk_fma_f32 v[102:103], v[102:103], 0.5, v[108:109] op_sel_hi:[1,0,1]
	v_add_f32_e32 v107, v104, v105
	v_add_f32_e32 v106, v102, v103
	v_add_f32_e32 v106, v106, v107
	global_store_dwordx4 v159, v[110:113], s[50:51]
	v_mul_f32_e32 v107, v105, v105
	v_add_f32_e32 v190, v190, v191
	v_add_f32_e32 v110, v178, v106
	v_mul_f32_e32 v106, v103, v103
	v_add_f32_e32 v186, v186, v187
	v_fmac_f32_e32 v106, v102, v102
	v_fmac_f32_e32 v107, v104, v104
	v_add_f32_e32 v186, v190, v186
	v_add_f32_e32 v106, v106, v107
	v_add_f32_e32 v111, v186, v106
	v_sub_f32_e32 v107, v117, v179
	v_sub_f32_e32 v106, v116, v179
	v_sub_f32_e32 v109, v115, v179
	v_sub_f32_e32 v108, v114, v179
	v_pk_mul_f32 v[108:109], v[0:1], v[108:109] op_sel_hi:[0,1]
	v_pk_mul_f32 v[106:107], v[0:1], v[106:107] op_sel_hi:[0,1]
	v_pk_fma_f32 v[106:107], v[120:121], v[106:107], v[124:125]
	v_pk_fma_f32 v[108:109], v[118:119], v[108:109], v[122:123]
	v_pk_mul_f32 v[106:107], v[106:107], s[2:3] op_sel_hi:[1,0]
	v_pk_mul_f32 v[108:109], v[108:109], s[2:3] op_sel_hi:[1,0]
	v_pk_fma_f32 v[100:101], v[100:101], 0.5, v[106:107] op_sel_hi:[1,0,1]
	v_pk_fma_f32 v[98:99], v[98:99], 0.5, v[108:109] op_sel_hi:[1,0,1]
	v_add_f32_e32 v106, v100, v101
	v_add_f32_e32 v0, v98, v99
	v_add_f32_e32 v0, v0, v106
	v_mul_f32_e32 v106, v99, v99
	v_mul_f32_e32 v107, v101, v101
	v_add_f32_e32 v0, v110, v0
	v_fmac_f32_e32 v106, v98, v98
	v_fmac_f32_e32 v107, v100, v100
	s_nop 0
	s_nop 1
	v_bfe_u32 v109, v227, 4, 2
	v_sub_u32_e32 v108, 0, v109
	v_lshlrev_b32_e32 v108, 4, v108
	v_ashrrev_i32_e32 v109, 31, v108
	v_lshl_add_u64 v[108:109], v[180:181], 0, v[108:109]
	v_permlane16_swap_b32_e32 v102, v98
	v_permlane16_swap_b32_e32 v103, v99
	v_permlane16_swap_b32_e32 v104, v100
	v_permlane16_swap_b32_e32 v105, v101
	v_permlane32_swap_b32_e32 v102, v98
	v_permlane32_swap_b32_e32 v103, v99
	v_permlane32_swap_b32_e32 v104, v100
	v_permlane32_swap_b32_e32 v105, v101
	global_store_dwordx4 v[108:109], v[102:105], off offset:512
	global_store_dwordx4 v[108:109], v[98:101], off offset:576
	s_nop 1
	v_permlane32_swap_b32_e32 v102, v98
	v_permlane32_swap_b32_e32 v103, v99
	v_permlane32_swap_b32_e32 v104, v100
	v_permlane32_swap_b32_e32 v105, v101
	v_permlane16_swap_b32_e32 v102, v98
	v_permlane16_swap_b32_e32 v103, v99
	v_permlane16_swap_b32_e32 v104, v100
	v_permlane16_swap_b32_e32 v105, v101
	v_add_f32_e32 v106, v106, v107
	v_cvt_pk_bf16_f32 v102, v102, v103
	v_cvt_pk_bf16_f32 v103, v104, v105
	v_cvt_pk_bf16_f32 v104, v98, v99
	v_mov_b32_e32 v98, v0
	v_add_f32_e32 v106, v111, v106
	s_nop 0
	v_permlane16_swap_b32_e32 v0, v98
	v_add_f32_e32 v98, v0, v98
	v_mov_b32_e32 v0, v106
	s_nop 1
	v_permlane16_swap_b32_e32 v106, v0
	v_add_f32_e32 v99, v106, v0
	v_cvt_pk_bf16_f32 v105, v100, v101
	v_mov_b32_e32 v100, v98
	v_mov_b32_e32 v101, v99
	s_nop 0
	v_permlane32_swap_b32_e32 v98, v100
	v_permlane32_swap_b32_e32 v99, v101
	global_store_dwordx4 v159, v[102:105], s[42:43]
	s_and_saveexec_b64 s[26:27], s[44:45]
	s_cbranch_execz .LBB0_376
	v_pk_add_f32 v[98:99], v[98:99], v[100:101]
	v_lshl_add_u64 v[100:101], s[30:31], 0, v[172:173]
	v_lshl_add_u64 v[100:101], s[24:25], 2, v[100:101]
	global_store_dwordx2 v[100:101], v[98:99], off
.LBB0_376:
	s_or_b64 exec, exec, s[26:27]
	v_pk_add_f32 v[98:99], v[174:175], v[176:177]
	s_mov_b32 s2, 0x3a800000
	v_pk_mul_f32 v[122:123], v[98:99], s[2:3] op_sel_hi:[1,0]
	s_mov_b32 s2, 0x800000
	v_fma_f32 v0, -v123, v123, v122
	v_max_f32_e32 v0, 0, v0
	v_add_f32_e32 v0, 0x3727c5ac, v0
	v_cmp_gt_f32_e32 vcc, s2, v0
	v_mul_f32_e32 v98, 0x4b800000, v0
	v_lshlrev_b64 v[124:125], 12, v[170:171]
	v_cndmask_b32_e32 v0, v0, v98, vcc
	v_rsq_f32_e32 v0, v0
	s_load_dwordx16 s[60:75], s[34:35], 0x38
	v_lshlrev_b32_e32 v122, 6, v170
	v_mul_f32_e32 v98, 0x45800000, v0
	v_cndmask_b32_e32 v0, v0, v98, vcc
	v_lshl_add_u64 v[98:99], s[12:13], 0, v[124:125]
	v_lshl_add_u64 v[102:103], v[98:99], 0, v[152:153]
	s_nop 1
	v_bfe_u32 v101, v227, 4, 2
	v_sub_u32_e32 v100, 0, v101
	v_lshlrev_b32_e32 v100, 4, v100
	v_ashrrev_i32_e32 v101, 31, v100
	v_lshl_add_u64 v[100:101], v[102:103], 0, v[100:101]
	global_load_dwordx4 v[126:129], v[100:101], off offset:64
	global_load_dwordx4 v[130:133], v[100:101], off
	global_load_dwordx4 v[134:137], v[154:155], off offset:16
	global_load_dwordx4 v[172:175], v[154:155], off
	global_load_dwordx4 v[176:179], v[156:157], off offset:16
	global_load_dwordx4 v[186:189], v[156:157], off
	s_nop 1
	v_bfe_u32 v105, v227, 4, 2
	v_sub_u32_e32 v104, 0, v105
	v_lshlrev_b32_e32 v104, 4, v104
	v_ashrrev_i32_e32 v105, 31, v104
	v_lshl_add_u64 v[104:105], v[102:103], 0, v[104:105]
	global_load_dwordx4 v[98:101], v[104:105], off offset:576
	global_load_dwordx4 v[118:121], v[104:105], off offset:512
	s_nop 0
	global_load_dwordx4 v[102:105], v[154:155], off offset:528
	global_load_dwordx4 v[110:113], v[154:155], off offset:512
	global_load_dwordx4 v[106:109], v[156:157], off offset:528
	global_load_dwordx4 v[114:117], v[156:157], off offset:512
	s_movk_i32 s2, 0x3bc0
	v_and_or_b32 v122, v122, s2, v194
	s_mov_b32 s2, 0x3fd744fd
	s_waitcnt lgkmcnt(0)
	v_lshl_add_u64 v[124:125], s[74:75], 0, v[124:125]
	v_lshl_add_u64 v[124:125], v[124:125], 0, v[152:153]
	v_lshlrev_b32_e32 v122, 1, v122
	s_waitcnt vmcnt(10)
; __device__ __forceinline__ float xsum16(float v) { const auto r = __builtin_amdgcn_permlane16_swap(__float_as_uint(v), __float_as_uint(v), false, false); return __uint_as_float(r[0]) + __uint_as_float(r[1]); }
; __device__ __forceinline__ float xsum32(float v) { const auto r = __builtin_amdgcn_permlane32_swap(__float_as_uint(v), __float_as_uint(v), false, false); return __uint_as_float(r[0]) + __uint_as_float(r[1]); }
; __device__ __forceinline__ size_t blk_off(int r, int c, int K) { return (size_t)(r >> 8) * 256 * K + (size_t)(c >> 6) * (256 * 64) + (size_t)((r & 255) * 64 + (c & 63)); }
; __device__ __forceinline__ u32x4 pack8(const f32x4 a, const f32x4 b) { u32x4 w; w.x = cvt_pk_bf16(a[0], a[1]); w.y = cvt_pk_bf16(a[2], a[3]); w.z = cvt_pk_bf16(b[0], b[1]); w.w = cvt_pk_bf16(b[2], b[3]); return w; }
;     __device__ __forceinline__ void operator()(const f32x4 (&acc)[2][2][4][2], const pg8::Unit& u, int wr, int wc, int fr, int fq) const {
;     ...
;                     for (int n = 0; n < 2; ++n) { yv[bj][n] = *(const f32x4*)(Yin + (size_t)row * D_ + col0 + bj * 128 + 4 * n); gq[bj][n] = *(const f32x4*)(g + col0 + bj * 128 + 4 * n); bq_[bj][n] = *(const f32x4*)(b + col0 + bj * 128 + 4 * n); }
;                 asm volatile("" ::: "memory");
;                 float s1 = 0.f, s2 = 0.f;
; #pragma unroll
;                 for (int bj = 0; bj < 2; ++bj) { float* yp = Y + (size_t)row * D_ + col0 + bj * 128; f32x4 v[2];
; #pragma unroll
;                     for (int n = 0; n < 2; ++n) { v[n] = (((yv[bj][n] - mu) * rs) * gq[bj][n] + bq_[bj][n]) * ALPHA_ + acc[ai][bj][m][n] * sc;
;                         *(f32x4*)(yp + 4 * n) = v[n]; s1 += (v[n][0] + v[n][1]) + (v[n][2] + v[n][3]); s2 += (v[n][0] * v[n][0] + v[n][1] * v[n][1]) + (v[n][2] * v[n][2] + v[n][3] * v[n][3]); }
;                     *(u32x4*)(Yb + blk_off(row, col0 + bj * 128, D_)) = pack8(v[0], v[1]); }
;                 s1 = xsum32(xsum16(s1)); s2 = xsum32(xsum16(s2));
;                 if (fq == 0) *(f32x2*)(stn + (size_t)row * 32 + (u.pn * 4 + wc) * 2) = (f32x2){s1, s2}; asm volatile("" ::: "memory"); } }
	v_permlane32_swap_b32_e32 v130, v126
	v_permlane32_swap_b32_e32 v131, v127
	v_permlane32_swap_b32_e32 v132, v128
	v_permlane32_swap_b32_e32 v133, v129
	v_permlane16_swap_b32_e32 v130, v126
	v_permlane16_swap_b32_e32 v131, v127
	v_permlane16_swap_b32_e32 v132, v128
	v_permlane16_swap_b32_e32 v133, v129
	v_sub_f32_e32 v129, v129, v123
	v_sub_f32_e32 v133, v133, v123
	v_sub_f32_e32 v132, v132, v123
	v_sub_f32_e32 v131, v131, v123
	v_sub_f32_e32 v130, v130, v123
	v_sub_f32_e32 v128, v128, v123
	v_sub_f32_e32 v127, v127, v123
	v_sub_f32_e32 v126, v126, v123
	v_pk_mul_f32 v[130:131], v[0:1], v[130:131] op_sel_hi:[0,1]
	v_pk_mul_f32 v[132:133], v[0:1], v[132:133] op_sel_hi:[0,1]
	v_pk_mul_f32 v[126:127], v[0:1], v[126:127] op_sel_hi:[0,1]
	v_pk_mul_f32 v[128:129], v[0:1], v[128:129] op_sel_hi:[0,1]
	s_waitcnt vmcnt(6)
	v_pk_fma_f32 v[132:133], v[174:175], v[132:133], v[188:189]
	v_pk_fma_f32 v[130:131], v[172:173], v[130:131], v[186:187]
	v_pk_fma_f32 v[128:129], v[136:137], v[128:129], v[178:179]
	v_pk_fma_f32 v[126:127], v[134:135], v[126:127], v[176:177]
	v_pk_mul_f32 v[130:131], v[130:131], s[2:3] op_sel_hi:[1,0]
	v_pk_mul_f32 v[132:133], v[132:133], s[2:3] op_sel_hi:[1,0]
	v_pk_mul_f32 v[126:127], v[126:127], s[2:3] op_sel_hi:[1,0]
	v_pk_mul_f32 v[128:129], v[128:129], s[2:3] op_sel_hi:[1,0]
	v_pk_fma_f32 v[96:97], v[96:97], 0.5, v[132:133] op_sel_hi:[1,0,1]
	v_pk_fma_f32 v[94:95], v[94:95], 0.5, v[130:131] op_sel_hi:[1,0,1]
	v_pk_fma_f32 v[92:93], v[92:93], 0.5, v[128:129] op_sel_hi:[1,0,1]
	v_pk_fma_f32 v[90:91], v[90:91], 0.5, v[126:127] op_sel_hi:[1,0,1]
	v_add_f32_e32 v130, v94, v95
	v_add_f32_e32 v131, v96, v97
	v_add_f32_e32 v126, v90, v91
	v_add_f32_e32 v127, v92, v93
	v_add_f32_e32 v130, v130, v131
	v_mul_f32_e32 v131, v95, v95
	v_mul_f32_e32 v132, v97, v97
	v_add_f32_e32 v126, v126, v127
	v_mul_f32_e32 v127, v91, v91
	v_mul_f32_e32 v128, v93, v93
	s_nop 0
	v_fmac_f32_e32 v131, v94, v94
	v_fmac_f32_e32 v132, v96, v96
	s_nop 1
	v_bfe_u32 v135, v227, 4, 2
	v_sub_u32_e32 v134, 0, v135
	v_lshlrev_b32_e32 v134, 4, v134
	v_ashrrev_i32_e32 v135, 31, v134
	v_lshl_add_u64 v[134:135], v[124:125], 0, v[134:135]
	v_permlane16_swap_b32_e32 v94, v90
	v_permlane16_swap_b32_e32 v95, v91
	v_permlane16_swap_b32_e32 v96, v92
	v_permlane16_swap_b32_e32 v97, v93
	v_permlane32_swap_b32_e32 v94, v90
	v_permlane32_swap_b32_e32 v95, v91
	v_permlane32_swap_b32_e32 v96, v92
	v_permlane32_swap_b32_e32 v97, v93
	global_store_dwordx4 v[134:135], v[94:97], off
	global_store_dwordx4 v[134:135], v[90:93], off offset:64
	s_nop 1
	v_permlane32_swap_b32_e32 v94, v90
	v_permlane32_swap_b32_e32 v95, v91
	v_permlane32_swap_b32_e32 v96, v92
	v_permlane32_swap_b32_e32 v97, v93
	v_permlane16_swap_b32_e32 v94, v90
	v_permlane16_swap_b32_e32 v95, v91
	v_permlane16_swap_b32_e32 v96, v92
	v_permlane16_swap_b32_e32 v97, v93
	v_fmac_f32_e32 v127, v90, v90
	v_fmac_f32_e32 v128, v92, v92
	v_cvt_pk_bf16_f32 v94, v94, v95
	v_cvt_pk_bf16_f32 v95, v96, v97
	v_cvt_pk_bf16_f32 v96, v90, v91
	v_cvt_pk_bf16_f32 v97, v92, v93
	s_waitcnt vmcnt(6)
	v_permlane32_swap_b32_e32 v118, v98
	v_permlane32_swap_b32_e32 v119, v99
	v_permlane32_swap_b32_e32 v120, v100
	v_permlane32_swap_b32_e32 v121, v101
	v_permlane16_swap_b32_e32 v118, v98
	v_permlane16_swap_b32_e32 v119, v99
	v_permlane16_swap_b32_e32 v120, v100
	v_permlane16_swap_b32_e32 v121, v101
	v_sub_f32_e32 v91, v121, v123
	v_sub_f32_e32 v90, v120, v123
	v_sub_f32_e32 v93, v119, v123
	v_sub_f32_e32 v92, v118, v123
	v_pk_mul_f32 v[92:93], v[0:1], v[92:93] op_sel_hi:[0,1]
	v_pk_mul_f32 v[90:91], v[0:1], v[90:91] op_sel_hi:[0,1]
	s_waitcnt vmcnt(2)
	v_pk_fma_f32 v[90:91], v[112:113], v[90:91], v[116:117]
	v_pk_fma_f32 v[92:93], v[110:111], v[92:93], v[114:115]
	v_pk_mul_f32 v[90:91], v[90:91], s[2:3] op_sel_hi:[1,0]
	v_pk_mul_f32 v[92:93], v[92:93], s[2:3] op_sel_hi:[1,0]
	v_pk_fma_f32 v[88:89], v[88:89], 0.5, v[90:91] op_sel_hi:[1,0,1]
	v_pk_fma_f32 v[86:87], v[86:87], 0.5, v[92:93] op_sel_hi:[1,0,1]
	v_add_f32_e32 v130, 0, v130
	v_add_f32_e32 v90, v86, v87
	v_add_f32_e32 v91, v88, v89
	v_add_f32_e32 v126, v130, v126
	v_add_f32_e32 v90, v90, v91
	global_store_dwordx4 v122, v[94:97], s[50:51]
	v_mul_f32_e32 v91, v89, v89
	v_add_f32_e32 v131, v131, v132
	v_add_f32_e32 v94, v126, v90
	v_mul_f32_e32 v90, v87, v87
	v_add_f32_e32 v127, v127, v128
	v_fmac_f32_e32 v90, v86, v86
	v_fmac_f32_e32 v91, v88, v88
	v_add_f32_e32 v127, v131, v127
	v_add_f32_e32 v90, v90, v91
	v_add_f32_e32 v95, v127, v90
	v_sub_f32_e32 v91, v101, v123
	v_sub_f32_e32 v90, v100, v123
	v_sub_f32_e32 v93, v99, v123
	v_sub_f32_e32 v92, v98, v123
	v_pk_mul_f32 v[92:93], v[0:1], v[92:93] op_sel_hi:[0,1]
	v_pk_mul_f32 v[90:91], v[0:1], v[90:91] op_sel_hi:[0,1]
	v_pk_fma_f32 v[90:91], v[104:105], v[90:91], v[108:109]
	v_pk_fma_f32 v[92:93], v[102:103], v[92:93], v[106:107]
	v_pk_mul_f32 v[90:91], v[90:91], s[2:3] op_sel_hi:[1,0]
	v_pk_mul_f32 v[92:93], v[92:93], s[2:3] op_sel_hi:[1,0]
	v_pk_fma_f32 v[84:85], v[84:85], 0.5, v[90:91] op_sel_hi:[1,0,1]
	v_pk_fma_f32 v[82:83], v[82:83], 0.5, v[92:93] op_sel_hi:[1,0,1]
	v_add_f32_e32 v90, v84, v85
	v_add_f32_e32 v0, v82, v83
	v_add_f32_e32 v0, v0, v90
	v_mul_f32_e32 v90, v83, v83
	v_mul_f32_e32 v91, v85, v85
	v_add_f32_e32 v0, v94, v0
	v_fmac_f32_e32 v90, v82, v82
	v_fmac_f32_e32 v91, v84, v84
	s_nop 0
	s_nop 1
	v_bfe_u32 v93, v227, 4, 2
	v_sub_u32_e32 v92, 0, v93
	v_lshlrev_b32_e32 v92, 4, v92
	v_ashrrev_i32_e32 v93, 31, v92
	v_lshl_add_u64 v[92:93], v[124:125], 0, v[92:93]
	v_permlane16_swap_b32_e32 v86, v82
	v_permlane16_swap_b32_e32 v87, v83
	v_permlane16_swap_b32_e32 v88, v84
	v_permlane16_swap_b32_e32 v89, v85
	v_permlane32_swap_b32_e32 v86, v82
	v_permlane32_swap_b32_e32 v87, v83
	v_permlane32_swap_b32_e32 v88, v84
	v_permlane32_swap_b32_e32 v89, v85
	global_store_dwordx4 v[92:93], v[86:89], off offset:512
	global_store_dwordx4 v[92:93], v[82:85], off offset:576
	s_nop 1
	v_permlane32_swap_b32_e32 v86, v82
	v_permlane32_swap_b32_e32 v87, v83
	v_permlane32_swap_b32_e32 v88, v84
	v_permlane32_swap_b32_e32 v89, v85
	v_permlane16_swap_b32_e32 v86, v82
	v_permlane16_swap_b32_e32 v87, v83
	v_permlane16_swap_b32_e32 v88, v84
	v_permlane16_swap_b32_e32 v89, v85
	v_add_f32_e32 v90, v90, v91
	v_cvt_pk_bf16_f32 v86, v86, v87
	v_cvt_pk_bf16_f32 v87, v88, v89
	v_cvt_pk_bf16_f32 v88, v82, v83
	v_mov_b32_e32 v82, v0
	v_add_f32_e32 v90, v95, v90
	s_nop 0
	v_permlane16_swap_b32_e32 v0, v82
	v_add_f32_e32 v82, v0, v82
	v_mov_b32_e32 v0, v90
	s_nop 1
	v_permlane16_swap_b32_e32 v90, v0
	v_add_f32_e32 v83, v90, v0
	v_cvt_pk_bf16_f32 v89, v84, v85
	v_mov_b32_e32 v84, v82
	v_mov_b32_e32 v85, v83
	s_nop 0
	v_permlane32_swap_b32_e32 v82, v84
	v_permlane32_swap_b32_e32 v83, v85
	global_store_dwordx4 v122, v[86:89], s[42:43]
	s_and_saveexec_b64 s[26:27], s[44:45]
	s_cbranch_execz .LBB0_378
	v_pk_add_f32 v[82:83], v[82:83], v[84:85]
	v_lshl_add_u64 v[84:85], s[30:31], 0, v[164:165]
	v_lshl_add_u64 v[84:85], s[24:25], 2, v[84:85]
	global_store_dwordx2 v[84:85], v[82:83], off
;     __device__ __forceinline__ void operator()(const f32x4 (&acc)[2][2][4][2], const pg8::Unit& u, int wr, int wc, int fr, int fq) const {
;     ...
;             for (int m = 0; m < 4; ++m) { const int row = row0 + ai * 128 + m * 16; const float mu = mu4[m], rs = rs4[m];
;                 f32x4 yv[2][2], gq[2][2], bq_[2][2];
; #pragma unroll
;                 for (int bj = 0; bj < 2; ++bj)
; #pragma unroll
;                     for (int n = 0; n < 2; ++n) { yv[bj][n] = *(const f32x4*)(Yin + (size_t)row * D_ + col0 + bj * 128 + 4 * n); gq[bj][n] = *(const f32x4*)(g + col0 + bj * 128 + 4 * n); bq_[bj][n] = *(const f32x4*)(b + col0 + bj * 128 + 4 * n); }
;                 asm volatile("" ::: "memory");
;                 float s1 = 0.f, s2 = 0.f;
; #pragma unroll
;                 for (int bj = 0; bj < 2; ++bj) { float* yp = Y + (size_t)row * D_ + col0 + bj * 128; f32x4 v[2];
; #pragma unroll
;                     for (int n = 0; n < 2; ++n) { v[n] = (((yv[bj][n] - mu) * rs) * gq[bj][n] + bq_[bj][n]) * ALPHA_ + acc[ai][bj][m][n] * sc;
;                         *(f32x4*)(yp + 4 * n) = v[n]; s1 += (v[n][0] + v[n][1]) + (v[n][2] + v[n][3]); s2 += (v[n][0] * v[n][0] + v[n][1] * v[n][1]) + (v[n][2] * v[n][2] + v[n][3] * v[n][3]); }
.LBB0_378:
	s_or_b64 exec, exec, s[26:27]
	v_pk_add_f32 v[82:83], v[166:167], v[168:169]
	s_mov_b32 s2, 0x3a800000
	v_pk_mul_f32 v[106:107], v[82:83], s[2:3] op_sel_hi:[1,0]
	s_mov_b32 s2, 0x800000
	v_fma_f32 v0, -v107, v107, v106
	v_max_f32_e32 v0, 0, v0
	v_add_f32_e32 v0, 0x3727c5ac, v0
	v_cmp_gt_f32_e32 vcc, s2, v0
	v_mul_f32_e32 v82, 0x4b800000, v0
	v_lshlrev_b64 v[108:109], 12, v[162:163]
	v_cndmask_b32_e32 v0, v0, v82, vcc
	v_rsq_f32_e32 v0, v0
	s_load_dwordx16 s[60:75], s[34:35], 0x38
	v_lshlrev_b32_e32 v106, 6, v162
	v_mul_f32_e32 v82, 0x45800000, v0
	v_cndmask_b32_e32 v0, v0, v82, vcc
	v_lshl_add_u64 v[82:83], s[12:13], 0, v[108:109]
	v_lshl_add_u64 v[86:87], v[82:83], 0, v[152:153]
	s_nop 1
	v_bfe_u32 v85, v227, 4, 2
	v_sub_u32_e32 v84, 0, v85
	v_lshlrev_b32_e32 v84, 4, v84
	v_ashrrev_i32_e32 v85, 31, v84
	v_lshl_add_u64 v[84:85], v[86:87], 0, v[84:85]
	global_load_dwordx4 v[110:113], v[84:85], off offset:64
	global_load_dwordx4 v[114:117], v[84:85], off
	global_load_dwordx4 v[118:121], v[154:155], off offset:16
	global_load_dwordx4 v[122:125], v[154:155], off
	global_load_dwordx4 v[126:129], v[156:157], off offset:16
	global_load_dwordx4 v[130:133], v[156:157], off
	s_nop 1
	v_bfe_u32 v89, v227, 4, 2
	v_sub_u32_e32 v88, 0, v89
	v_lshlrev_b32_e32 v88, 4, v88
	v_ashrrev_i32_e32 v89, 31, v88
	v_lshl_add_u64 v[88:89], v[86:87], 0, v[88:89]
	global_load_dwordx4 v[82:85], v[88:89], off offset:576
	global_load_dwordx4 v[102:105], v[88:89], off offset:512
	s_nop 0
	global_load_dwordx4 v[86:89], v[154:155], off offset:528
	global_load_dwordx4 v[94:97], v[154:155], off offset:512
	global_load_dwordx4 v[90:93], v[156:157], off offset:528
	global_load_dwordx4 v[98:101], v[156:157], off offset:512
	s_movk_i32 s2, 0x3fc0
	v_and_or_b32 v106, v106, s2, v194
	s_mov_b32 s2, 0x3fd744fd
	s_waitcnt lgkmcnt(0)
	v_lshl_add_u64 v[108:109], s[74:75], 0, v[108:109]
	v_lshl_add_u64 v[108:109], v[108:109], 0, v[152:153]
	v_lshlrev_b32_e32 v106, 1, v106
	s_waitcnt vmcnt(10)
	v_permlane32_swap_b32_e32 v114, v110
	v_permlane32_swap_b32_e32 v115, v111
	v_permlane32_swap_b32_e32 v116, v112
	v_permlane32_swap_b32_e32 v117, v113
	v_permlane16_swap_b32_e32 v114, v110
	v_permlane16_swap_b32_e32 v115, v111
	v_permlane16_swap_b32_e32 v116, v112
	v_permlane16_swap_b32_e32 v117, v113
	v_sub_f32_e32 v113, v113, v107
	v_sub_f32_e32 v117, v117, v107
	v_sub_f32_e32 v116, v116, v107
	v_sub_f32_e32 v115, v115, v107
	v_sub_f32_e32 v114, v114, v107
	v_sub_f32_e32 v112, v112, v107
	v_sub_f32_e32 v111, v111, v107
	v_sub_f32_e32 v110, v110, v107
	v_pk_mul_f32 v[114:115], v[0:1], v[114:115] op_sel_hi:[0,1]
	v_pk_mul_f32 v[116:117], v[0:1], v[116:117] op_sel_hi:[0,1]
	v_pk_mul_f32 v[110:111], v[0:1], v[110:111] op_sel_hi:[0,1]
	v_pk_mul_f32 v[112:113], v[0:1], v[112:113] op_sel_hi:[0,1]
	s_waitcnt vmcnt(6)
	v_pk_fma_f32 v[116:117], v[124:125], v[116:117], v[132:133]
	v_pk_fma_f32 v[114:115], v[122:123], v[114:115], v[130:131]
	v_pk_fma_f32 v[112:113], v[120:121], v[112:113], v[128:129]
	v_pk_fma_f32 v[110:111], v[118:119], v[110:111], v[126:127]
	v_pk_mul_f32 v[114:115], v[114:115], s[2:3] op_sel_hi:[1,0]
	v_pk_mul_f32 v[116:117], v[116:117], s[2:3] op_sel_hi:[1,0]
	v_pk_mul_f32 v[110:111], v[110:111], s[2:3] op_sel_hi:[1,0]
	v_pk_mul_f32 v[112:113], v[112:113], s[2:3] op_sel_hi:[1,0]
	v_pk_fma_f32 v[80:81], v[80:81], 0.5, v[116:117] op_sel_hi:[1,0,1]
	v_pk_fma_f32 v[78:79], v[78:79], 0.5, v[114:115] op_sel_hi:[1,0,1]
	v_pk_fma_f32 v[76:77], v[76:77], 0.5, v[112:113] op_sel_hi:[1,0,1]
	v_pk_fma_f32 v[74:75], v[74:75], 0.5, v[110:111] op_sel_hi:[1,0,1]
	v_add_f32_e32 v114, v78, v79
	v_add_f32_e32 v115, v80, v81
	v_add_f32_e32 v110, v74, v75
	v_add_f32_e32 v111, v76, v77
	v_add_f32_e32 v114, v114, v115
	v_mul_f32_e32 v115, v79, v79
	v_mul_f32_e32 v116, v81, v81
	v_add_f32_e32 v110, v110, v111
	v_mul_f32_e32 v111, v75, v75
	v_mul_f32_e32 v112, v77, v77
	s_nop 0
	v_fmac_f32_e32 v115, v78, v78
	v_fmac_f32_e32 v116, v80, v80
	s_nop 1
	v_bfe_u32 v119, v227, 4, 2
	v_sub_u32_e32 v118, 0, v119
	v_lshlrev_b32_e32 v118, 4, v118
	v_ashrrev_i32_e32 v119, 31, v118
	v_lshl_add_u64 v[118:119], v[108:109], 0, v[118:119]
	v_permlane16_swap_b32_e32 v78, v74
	v_permlane16_swap_b32_e32 v79, v75
	v_permlane16_swap_b32_e32 v80, v76
	v_permlane16_swap_b32_e32 v81, v77
	v_permlane32_swap_b32_e32 v78, v74
	v_permlane32_swap_b32_e32 v79, v75
	v_permlane32_swap_b32_e32 v80, v76
	v_permlane32_swap_b32_e32 v81, v77
	global_store_dwordx4 v[118:119], v[78:81], off
	global_store_dwordx4 v[118:119], v[74:77], off offset:64
	s_nop 1
	v_permlane32_swap_b32_e32 v78, v74
	v_permlane32_swap_b32_e32 v79, v75
	v_permlane32_swap_b32_e32 v80, v76
	v_permlane32_swap_b32_e32 v81, v77
	v_permlane16_swap_b32_e32 v78, v74
	v_permlane16_swap_b32_e32 v79, v75
	v_permlane16_swap_b32_e32 v80, v76
	v_permlane16_swap_b32_e32 v81, v77
	v_fmac_f32_e32 v111, v74, v74
	v_fmac_f32_e32 v112, v76, v76
	v_cvt_pk_bf16_f32 v78, v78, v79
	v_cvt_pk_bf16_f32 v79, v80, v81
	v_cvt_pk_bf16_f32 v80, v74, v75
	v_cvt_pk_bf16_f32 v81, v76, v77
	s_waitcnt vmcnt(6)
	v_permlane32_swap_b32_e32 v102, v82
	v_permlane32_swap_b32_e32 v103, v83
	v_permlane32_swap_b32_e32 v104, v84
	v_permlane32_swap_b32_e32 v105, v85
	v_permlane16_swap_b32_e32 v102, v82
	v_permlane16_swap_b32_e32 v103, v83
	v_permlane16_swap_b32_e32 v104, v84
	v_permlane16_swap_b32_e32 v105, v85
	v_sub_f32_e32 v75, v105, v107
	v_sub_f32_e32 v74, v104, v107
	v_sub_f32_e32 v77, v103, v107
	v_sub_f32_e32 v76, v102, v107
	v_pk_mul_f32 v[76:77], v[0:1], v[76:77] op_sel_hi:[0,1]
	v_pk_mul_f32 v[74:75], v[0:1], v[74:75] op_sel_hi:[0,1]
	s_waitcnt vmcnt(2)
; __device__ __forceinline__ float xsum16(float v) { const auto r = __builtin_amdgcn_permlane16_swap(__float_as_uint(v), __float_as_uint(v), false, false); return __uint_as_float(r[0]) + __uint_as_float(r[1]); }
; __device__ __forceinline__ void row_stats4(const float* st, int rowb, int fq, float (&mu)[4], float (&rs)[4]) {
;     f32x4 a[4], b[4];
; #pragma unroll
;     for (int m = 0; m < 4; ++m) { const f32x4* p = (const f32x4*)(st + (size_t)(rowb + m * 16) * 32 + fq * 8); a[m] = p[0]; b[m] = p[1]; }
; #pragma unroll
;     for (int m = 0; m < 4; ++m) { float s1 = (a[m][0] + a[m][2]) + (b[m][0] + b[m][2]), s2 = (a[m][1] + a[m][3]) + (b[m][1] + b[m][3]);
;         s1 = xsum32(xsum16(s1)); s2 = xsum32(xsum16(s2));
;         const float mm = s1 * (1.0f / 1024.0f); mu[m] = mm; rs[m] = rsqrtf(fmaxf(s2 * (1.0f / 1024.0f) - mm * mm, 0.f) + LN_EPS_); }
;     __device__ __forceinline__ void operator()(const f32x4 (&acc)[2][2][4][2], const pg8::Unit& u, int wr, int wc, int fr, int fq) const {
;     ...
;             for (int m = 0; m < 4; ++m) { const int row = row0 + ai * 128 + m * 16; const float mu = mu4[m], rs = rs4[m];
;                 f32x4 yv[2][2], gq[2][2], bq_[2][2];
; #pragma unroll
;                 for (int bj = 0; bj < 2; ++bj)
; #pragma unroll
;                     for (int n = 0; n < 2; ++n) { yv[bj][n] = *(const f32x4*)(Yin + (size_t)row * D_ + col0 + bj * 128 + 4 * n); gq[bj][n] = *(const f32x4*)(g + col0 + bj * 128 + 4 * n); bq_[bj][n] = *(const f32x4*)(b + col0 + bj * 128 + 4 * n); }
;                 asm volatile("" ::: "memory");
;                 float s1 = 0.f, s2 = 0.f;
; #pragma unroll
;                 for (int bj = 0; bj < 2; ++bj) { float* yp = Y + (size_t)row * D_ + col0 + bj * 128; f32x4 v[2];
; #pragma unroll
;                     for (int n = 0; n < 2; ++n) { v[n] = (((yv[bj][n] - mu) * rs) * gq[bj][n] + bq_[bj][n]) * ALPHA_ + acc[ai][bj][m][n] * sc;
;                         *(f32x4*)(yp + 4 * n) = v[n]; s1 += (v[n][0] + v[n][1]) + (v[n][2] + v[n][3]); s2 += (v[n][0] * v[n][0] + v[n][1] * v[n][1]) + (v[n][2] * v[n][2] + v[n][3] * v[n][3]); }
;                     *(u32x4*)(Yb + blk_off(row, col0 + bj * 128, D_)) = pack8(v[0], v[1]); }
;                 s1 = xsum32(xsum16(s1)); s2 = xsum32(xsum16(s2));
;                 if (fq == 0) *(f32x2*)(stn + (size_t)row * 32 + (u.pn * 4 + wc) * 2) = (f32x2){s1, s2}; asm volatile("" ::: "memory"); } }
	v_pk_fma_f32 v[74:75], v[96:97], v[74:75], v[100:101]
	v_pk_fma_f32 v[76:77], v[94:95], v[76:77], v[98:99]
	v_pk_mul_f32 v[74:75], v[74:75], s[2:3] op_sel_hi:[1,0]
	v_pk_mul_f32 v[76:77], v[76:77], s[2:3] op_sel_hi:[1,0]
	v_pk_fma_f32 v[72:73], v[72:73], 0.5, v[74:75] op_sel_hi:[1,0,1]
	v_pk_fma_f32 v[70:71], v[70:71], 0.5, v[76:77] op_sel_hi:[1,0,1]
	v_add_f32_e32 v114, 0, v114
	v_add_f32_e32 v74, v70, v71
	v_add_f32_e32 v75, v72, v73
	v_add_f32_e32 v110, v114, v110
	v_add_f32_e32 v74, v74, v75
	global_store_dwordx4 v106, v[78:81], s[50:51]
	v_mul_f32_e32 v75, v73, v73
	v_add_f32_e32 v115, v115, v116
	v_add_f32_e32 v78, v110, v74
	v_mul_f32_e32 v74, v71, v71
	v_add_f32_e32 v111, v111, v112
	v_fmac_f32_e32 v74, v70, v70
	v_fmac_f32_e32 v75, v72, v72
	v_add_f32_e32 v111, v115, v111
	v_add_f32_e32 v74, v74, v75
	v_add_f32_e32 v79, v111, v74
	v_sub_f32_e32 v75, v85, v107
	v_sub_f32_e32 v74, v84, v107
	v_sub_f32_e32 v77, v83, v107
	v_sub_f32_e32 v76, v82, v107
	v_pk_mul_f32 v[76:77], v[0:1], v[76:77] op_sel_hi:[0,1]
	v_pk_mul_f32 v[74:75], v[0:1], v[74:75] op_sel_hi:[0,1]
	v_pk_fma_f32 v[74:75], v[88:89], v[74:75], v[92:93]
	v_pk_fma_f32 v[76:77], v[86:87], v[76:77], v[90:91]
	v_pk_mul_f32 v[74:75], v[74:75], s[2:3] op_sel_hi:[1,0]
	v_pk_mul_f32 v[76:77], v[76:77], s[2:3] op_sel_hi:[1,0]
	v_pk_fma_f32 v[68:69], v[68:69], 0.5, v[74:75] op_sel_hi:[1,0,1]
	v_pk_fma_f32 v[66:67], v[66:67], 0.5, v[76:77] op_sel_hi:[1,0,1]
	v_add_f32_e32 v74, v68, v69
	v_add_f32_e32 v0, v66, v67
	v_add_f32_e32 v0, v0, v74
	v_mul_f32_e32 v74, v67, v67
	v_mul_f32_e32 v75, v69, v69
	v_add_f32_e32 v0, v78, v0
	v_fmac_f32_e32 v74, v66, v66
	v_fmac_f32_e32 v75, v68, v68
	s_nop 0
	s_nop 1
	v_bfe_u32 v77, v227, 4, 2
	v_sub_u32_e32 v76, 0, v77
	v_lshlrev_b32_e32 v76, 4, v76
	v_ashrrev_i32_e32 v77, 31, v76
	v_lshl_add_u64 v[76:77], v[108:109], 0, v[76:77]
	v_permlane16_swap_b32_e32 v70, v66
	v_permlane16_swap_b32_e32 v71, v67
	v_permlane16_swap_b32_e32 v72, v68
	v_permlane16_swap_b32_e32 v73, v69
	v_permlane32_swap_b32_e32 v70, v66
	v_permlane32_swap_b32_e32 v71, v67
	v_permlane32_swap_b32_e32 v72, v68
	v_permlane32_swap_b32_e32 v73, v69
	global_store_dwordx4 v[76:77], v[70:73], off offset:512
	global_store_dwordx4 v[76:77], v[66:69], off offset:576
	s_nop 1
	v_permlane32_swap_b32_e32 v70, v66
	v_permlane32_swap_b32_e32 v71, v67
	v_permlane32_swap_b32_e32 v72, v68
	v_permlane32_swap_b32_e32 v73, v69
	v_permlane16_swap_b32_e32 v70, v66
	v_permlane16_swap_b32_e32 v71, v67
	v_permlane16_swap_b32_e32 v72, v68
	v_permlane16_swap_b32_e32 v73, v69
	v_add_f32_e32 v74, v74, v75
	v_cvt_pk_bf16_f32 v70, v70, v71
	v_cvt_pk_bf16_f32 v71, v72, v73
	v_cvt_pk_bf16_f32 v72, v66, v67
	v_mov_b32_e32 v66, v0
	v_add_f32_e32 v74, v79, v74
	s_nop 0
	v_permlane16_swap_b32_e32 v0, v66
	v_add_f32_e32 v66, v0, v66
	v_mov_b32_e32 v0, v74
	s_nop 1
	v_permlane16_swap_b32_e32 v74, v0
	v_add_f32_e32 v67, v74, v0
	v_cvt_pk_bf16_f32 v73, v68, v69
	v_mov_b32_e32 v68, v66
	v_mov_b32_e32 v69, v67
	s_nop 0
	v_permlane32_swap_b32_e32 v66, v68
	v_permlane32_swap_b32_e32 v67, v69
	global_store_dwordx4 v106, v[70:73], s[42:43]
	s_and_saveexec_b64 s[26:27], s[44:45]
	s_cbranch_execz .LBB0_380
	v_pk_add_f32 v[66:67], v[66:67], v[68:69]
	v_lshl_add_u64 v[68:69], s[30:31], 0, v[160:161]
	v_lshl_add_u64 v[68:69], s[24:25], 2, v[68:69]
	global_store_dwordx2 v[68:69], v[66:67], off
.LBB0_380:
	s_or_b64 exec, exec, s[26:27]
	v_add_u32_e32 v68, 0x80, v158
	v_ashrrev_i32_e32 v69, 31, v68
	v_add_u32_e32 v94, 0x90, v158
	v_lshlrev_b64 v[66:67], 7, v[68:69]
	v_ashrrev_i32_e32 v95, 31, v94
	v_lshl_add_u64 v[74:75], v[146:147], 0, v[66:67]
	v_lshlrev_b64 v[86:87], 7, v[94:95]
	v_add_u32_e32 v76, 0xa0, v158
	s_nop 1
	v_bfe_u32 v83, v227, 4, 2
	v_sub_u32_e32 v82, 0, v83
	v_lshlrev_b32_e32 v82, 4, v82
	v_ashrrev_i32_e32 v83, 31, v82
	v_lshl_add_u64 v[82:83], v[74:75], 0, v[82:83]
	global_load_dwordx4 v[70:73], v[82:83], off
	global_load_dwordx4 v[78:81], v[82:83], off offset:64
	v_lshl_add_u64 v[74:75], v[146:147], 0, v[86:87]
	v_ashrrev_i32_e32 v77, 31, v76
	s_nop 1
	v_bfe_u32 v93, v227, 4, 2
	v_sub_u32_e32 v92, 0, v93
	v_lshlrev_b32_e32 v92, 4, v92
	v_ashrrev_i32_e32 v93, 31, v92
	v_lshl_add_u64 v[92:93], v[74:75], 0, v[92:93]
	global_load_dwordx4 v[82:85], v[92:93], off
	global_load_dwordx4 v[88:91], v[92:93], off offset:64
	v_lshlrev_b64 v[74:75], 7, v[76:77]
	v_lshl_add_u64 v[74:75], v[146:147], 0, v[74:75]
	s_nop 1
	v_bfe_u32 v93, v227, 4, 2
	v_sub_u32_e32 v92, 0, v93
	v_lshlrev_b32_e32 v92, 4, v92
	v_ashrrev_i32_e32 v93, 31, v92
	v_lshl_add_u64 v[92:93], v[74:75], 0, v[92:93]
	global_load_dwordx4 v[96:99], v[92:93], off
	global_load_dwordx4 v[100:103], v[92:93], off offset:64
	v_add_u32_e32 v74, 0xb0, v158
	v_ashrrev_i32_e32 v75, 31, v74
	v_lshlrev_b64 v[92:93], 7, v[74:75]
	v_lshl_add_u64 v[92:93], v[146:147], 0, v[92:93]
	s_nop 1
	v_bfe_u32 v113, v227, 4, 2
	v_sub_u32_e32 v112, 0, v113
	v_lshlrev_b32_e32 v112, 4, v112
	v_ashrrev_i32_e32 v113, 31, v112
	v_lshl_add_u64 v[112:113], v[92:93], 0, v[112:113]
	global_load_dwordx4 v[104:107], v[112:113], off
	global_load_dwordx4 v[108:111], v[112:113], off offset:64
	v_lshlrev_b64 v[136:137], 12, v[68:69]
	v_lshl_add_u64 v[112:113], s[12:13], 0, v[136:137]
	v_lshl_add_u64 v[92:93], v[112:113], 0, v[152:153]
	s_nop 1
	v_bfe_u32 v121, v227, 4, 2
	v_sub_u32_e32 v120, 0, v121
	v_lshlrev_b32_e32 v120, 4, v120
	v_ashrrev_i32_e32 v121, 31, v120
	v_lshl_add_u64 v[120:121], v[92:93], 0, v[120:121]
	global_load_dwordx4 v[112:115], v[120:121], off offset:64
	global_load_dwordx4 v[116:119], v[120:121], off
	global_load_dwordx4 v[120:123], v[154:155], off offset:16
	global_load_dwordx4 v[124:127], v[154:155], off
	global_load_dwordx4 v[128:131], v[156:157], off offset:16
	global_load_dwordx4 v[132:135], v[156:157], off
	s_mov_b32 s2, 0x3a800000
	s_mov_b32 s16, 0x3fd744fd
	s_load_dwordx16 s[60:75], s[34:35], 0x38
	s_waitcnt vmcnt(12)
; __device__ __forceinline__ float xsum16(float v) { const auto r = __builtin_amdgcn_permlane16_swap(__float_as_uint(v), __float_as_uint(v), false, false); return __uint_as_float(r[0]) + __uint_as_float(r[1]); }
; __device__ __forceinline__ float xsum32(float v) { const auto r = __builtin_amdgcn_permlane32_swap(__float_as_uint(v), __float_as_uint(v), false, false); return __uint_as_float(r[0]) + __uint_as_float(r[1]); }
; __device__ __forceinline__ void row_stats4(const float* st, int rowb, int fq, float (&mu)[4], float (&rs)[4]) {
;     ...
;     for (int m = 0; m < 4; ++m) { const f32x4* p = (const f32x4*)(st + (size_t)(rowb + m * 16) * 32 + fq * 8); a[m] = p[0]; b[m] = p[1]; }
; #pragma unroll
;     for (int m = 0; m < 4; ++m) { float s1 = (a[m][0] + a[m][2]) + (b[m][0] + b[m][2]), s2 = (a[m][1] + a[m][3]) + (b[m][1] + b[m][3]);
;         s1 = xsum32(xsum16(s1)); s2 = xsum32(xsum16(s2));
;         const float mm = s1 * (1.0f / 1024.0f); mu[m] = mm; rs[m] = rsqrtf(fmaxf(s2 * (1.0f / 1024.0f) - mm * mm, 0.f) + LN_EPS_); }
;     __device__ __forceinline__ void operator()(const f32x4 (&acc)[2][2][4][2], const pg8::Unit& u, int wr, int wc, int fr, int fq) const {
;     ...
;             for (int m = 0; m < 4; ++m) { const int row = row0 + ai * 128 + m * 16; const float mu = mu4[m], rs = rs4[m];
;                 f32x4 yv[2][2], gq[2][2], bq_[2][2];
; #pragma unroll
;                 for (int bj = 0; bj < 2; ++bj)
; #pragma unroll
;                     for (int n = 0; n < 2; ++n) { yv[bj][n] = *(const f32x4*)(Yin + (size_t)row * D_ + col0 + bj * 128 + 4 * n); gq[bj][n] = *(const f32x4*)(g + col0 + bj * 128 + 4 * n); bq_[bj][n] = *(const f32x4*)(b + col0 + bj * 128 + 4 * n); }
;                 asm volatile("" ::: "memory");
;                 float s1 = 0.f, s2 = 0.f;
; #pragma unroll
;                 for (int bj = 0; bj < 2; ++bj) { float* yp = Y + (size_t)row * D_ + col0 + bj * 128; f32x4 v[2];
; #pragma unroll
;                     for (int n = 0; n < 2; ++n) { v[n] = (((yv[bj][n] - mu) * rs) * gq[bj][n] + bq_[bj][n]) * ALPHA_ + acc[ai][bj][m][n] * sc;
;                         *(f32x4*)(yp + 4 * n) = v[n]; s1 += (v[n][0] + v[n][1]) + (v[n][2] + v[n][3]); s2 += (v[n][0] * v[n][0] + v[n][1] * v[n][1]) + (v[n][2] * v[n][2] + v[n][3] * v[n][3]); }
	v_permlane32_swap_b32_e32 v70, v78
	v_permlane32_swap_b32_e32 v71, v79
	v_permlane32_swap_b32_e32 v72, v80
	v_permlane32_swap_b32_e32 v73, v81
	v_permlane16_swap_b32_e32 v70, v78
	v_permlane16_swap_b32_e32 v71, v79
	v_permlane16_swap_b32_e32 v72, v80
	v_permlane16_swap_b32_e32 v73, v81
	v_mov_b32_e32 v158, v70
	v_mov_b32_e32 v159, v78
	v_mov_b32_e32 v160, v72
	v_mov_b32_e32 v161, v80
	v_mov_b32_e32 v78, v71
	v_mov_b32_e32 v80, v73
	s_waitcnt vmcnt(10)
	v_permlane32_swap_b32_e32 v82, v88
	v_permlane32_swap_b32_e32 v83, v89
	v_permlane32_swap_b32_e32 v84, v90
	v_permlane32_swap_b32_e32 v85, v91
	v_permlane16_swap_b32_e32 v82, v88
	v_permlane16_swap_b32_e32 v83, v89
	v_permlane16_swap_b32_e32 v84, v90
	v_permlane16_swap_b32_e32 v85, v91
	v_mov_b32_e32 v70, v82
	v_mov_b32_e32 v71, v88
	v_mov_b32_e32 v72, v84
	v_mov_b32_e32 v73, v90
	v_mov_b32_e32 v88, v83
	v_mov_b32_e32 v90, v85
	s_waitcnt vmcnt(8)
	v_permlane32_swap_b32_e32 v96, v100
	v_permlane32_swap_b32_e32 v97, v101
	v_permlane32_swap_b32_e32 v98, v102
	v_permlane32_swap_b32_e32 v99, v103
	v_permlane16_swap_b32_e32 v96, v100
	v_permlane16_swap_b32_e32 v97, v101
	v_permlane16_swap_b32_e32 v98, v102
	v_permlane16_swap_b32_e32 v99, v103
	v_mov_b32_e32 v82, v96
	v_mov_b32_e32 v83, v100
	v_mov_b32_e32 v84, v98
	v_mov_b32_e32 v85, v102
	v_mov_b32_e32 v100, v97
	v_pk_add_f32 v[96:97], v[158:159], v[160:161]
	v_pk_add_f32 v[78:79], v[78:79], v[80:81]
	v_pk_add_f32 v[80:81], v[82:83], v[84:85]
	v_pk_add_f32 v[84:85], v[96:97], v[96:97] op_sel:[0,1] op_sel_hi:[1,0]
	v_pk_add_f32 v[78:79], v[78:79], v[78:79] op_sel:[0,1] op_sel_hi:[1,0]
	v_mov_b32_e32 v0, v84
	v_mov_b32_e32 v69, v78
	s_nop 0
	v_permlane16_swap_b32_e32 v84, v0
	v_permlane16_swap_b32_e32 v78, v69
	v_add_f32_e32 v79, v84, v0
	v_add_f32_e32 v78, v78, v69
	v_mov_b32_e32 v85, v79
	v_mov_b32_e32 v84, v78
	s_nop 0
	v_permlane32_swap_b32_e32 v79, v85
	v_permlane32_swap_b32_e32 v78, v84
	v_pk_add_f32 v[78:79], v[78:79], v[84:85]
	v_mov_b32_e32 v102, v99
	v_pk_mul_f32 v[78:79], v[78:79], s[2:3] op_sel_hi:[1,0]
	s_mov_b32 s2, 0x800000
	v_fma_f32 v0, -v79, v79, v78
	v_max_f32_e32 v0, 0, v0
	v_add_f32_e32 v0, 0x3727c5ac, v0
	v_mul_f32_e32 v69, 0x4b800000, v0
	v_cmp_gt_f32_e32 vcc, s2, v0
	v_pk_add_f32 v[82:83], v[100:101], v[102:103]
	v_pk_add_f32 v[80:81], v[80:81], v[80:81] op_sel:[0,1] op_sel_hi:[1,0]
	v_cndmask_b32_e32 v0, v0, v69, vcc
	v_rsq_f32_e32 v0, v0
	v_pk_add_f32 v[82:83], v[82:83], v[82:83] op_sel:[0,1] op_sel_hi:[1,0]
	v_mov_b32_e32 v81, v80
	s_nop 1
	v_permlane16_swap_b32_e32 v80, v81
	v_mul_f32_e32 v69, 0x45800000, v0
	v_cndmask_b32_e32 v78, v0, v69, vcc
	v_mov_b32_e32 v0, v82
	s_nop 1
	v_permlane16_swap_b32_e32 v82, v0
	s_nop 1
	v_bfe_u32 v85, v227, 4, 2
	v_sub_u32_e32 v84, 0, v85
	v_lshlrev_b32_e32 v84, 4, v84
	v_ashrrev_i32_e32 v85, 31, v84
	v_lshl_add_u64 v[84:85], v[92:93], 0, v[84:85]
	global_load_dwordx4 v[96:99], v[84:85], off offset:576
	global_load_dwordx4 v[100:103], v[84:85], off offset:512
	v_pk_add_f32 v[70:71], v[70:71], v[72:73]
	v_pk_add_f32 v[72:73], v[88:89], v[90:91]
	v_add_f32_e32 v89, v80, v81
	v_add_f32_e32 v88, v82, v0
	s_waitcnt vmcnt(8)
	v_permlane32_swap_b32_e32 v104, v108
	v_permlane32_swap_b32_e32 v105, v109
	v_permlane32_swap_b32_e32 v106, v110
	v_permlane32_swap_b32_e32 v107, v111
	v_permlane16_swap_b32_e32 v104, v108
	v_permlane16_swap_b32_e32 v105, v109
	v_permlane16_swap_b32_e32 v106, v110
	v_permlane16_swap_b32_e32 v107, v111
	v_mov_b32_e32 v80, v104
	v_mov_b32_e32 v81, v108
	v_mov_b32_e32 v82, v106
	v_mov_b32_e32 v83, v110
	v_mov_b32_e32 v108, v105
	v_mov_b32_e32 v110, v107
	v_pk_add_f32 v[80:81], v[80:81], v[82:83]
	v_pk_add_f32 v[82:83], v[108:109], v[110:111]
	global_load_dwordx4 v[104:107], v[154:155], off offset:528
	global_load_dwordx4 v[108:111], v[154:155], off offset:512
	global_load_dwordx4 v[158:161], v[156:157], off offset:528
	global_load_dwordx4 v[162:165], v[156:157], off offset:512
	s_waitcnt vmcnt(10)
	v_permlane32_swap_b32_e32 v116, v112
	v_permlane32_swap_b32_e32 v117, v113
	v_permlane32_swap_b32_e32 v118, v114
	v_permlane32_swap_b32_e32 v119, v115
	v_permlane16_swap_b32_e32 v116, v112
	v_permlane16_swap_b32_e32 v117, v113
	v_permlane16_swap_b32_e32 v118, v114
	v_permlane16_swap_b32_e32 v119, v115
	v_sub_f32_e32 v93, v119, v79
	v_sub_f32_e32 v92, v118, v79
	v_sub_f32_e32 v117, v117, v79
	v_sub_f32_e32 v116, v116, v79
	v_pk_mul_f32 v[116:117], v[78:79], v[116:117] op_sel_hi:[0,1]
	v_pk_mul_f32 v[92:93], v[78:79], v[92:93] op_sel_hi:[0,1]
	s_waitcnt vmcnt(6)
	v_pk_fma_f32 v[92:93], v[126:127], v[92:93], v[134:135]
	v_pk_fma_f32 v[116:117], v[124:125], v[116:117], v[132:133]
	v_pk_mul_f32 v[92:93], v[92:93], s[16:17] op_sel_hi:[1,0]
	v_pk_mul_f32 v[116:117], v[116:117], s[16:17] op_sel_hi:[1,0]
	v_pk_fma_f32 v[64:65], v[64:65], 0.5, v[92:93] op_sel_hi:[1,0,1]
	v_pk_fma_f32 v[62:63], v[62:63], 0.5, v[116:117] op_sel_hi:[1,0,1]
	v_add_f32_e32 v93, v64, v65
	v_add_f32_e32 v92, v62, v63
	v_add_f32_e32 v92, v92, v93
	v_add_f32_e32 v116, 0, v92
	v_mul_f32_e32 v92, v63, v63
	v_mul_f32_e32 v93, v65, v65
	v_pk_add_f32 v[80:81], v[80:81], v[80:81] op_sel:[0,1] op_sel_hi:[1,0]
	v_fmac_f32_e32 v92, v62, v62
	v_fmac_f32_e32 v93, v64, v64
	v_mov_b32_e32 v0, v80
	v_add_f32_e32 v117, v92, v93
	v_sub_f32_e32 v93, v115, v79
	v_sub_f32_e32 v92, v114, v79
	v_sub_f32_e32 v113, v113, v79
	v_sub_f32_e32 v112, v112, v79
	v_pk_add_f32 v[82:83], v[82:83], v[82:83] op_sel:[0,1] op_sel_hi:[1,0]
	v_permlane16_swap_b32_e32 v80, v0
	v_pk_mul_f32 v[112:113], v[78:79], v[112:113] op_sel_hi:[0,1]
	v_pk_mul_f32 v[92:93], v[78:79], v[92:93] op_sel_hi:[0,1]
	v_add_f32_e32 v83, v80, v0
	v_mov_b32_e32 v0, v82
	v_pk_fma_f32 v[92:93], v[122:123], v[92:93], v[130:131]
	v_pk_fma_f32 v[112:113], v[120:121], v[112:113], v[128:129]
	v_permlane16_swap_b32_e32 v82, v0
	v_pk_mul_f32 v[112:113], v[112:113], s[16:17] op_sel_hi:[1,0]
	v_pk_mul_f32 v[92:93], v[92:93], s[16:17] op_sel_hi:[1,0]
	v_add_f32_e32 v82, v82, v0
	v_ashrrev_i32_e32 v80, 8, v68
	v_lshlrev_b32_e32 v0, 6, v68
	s_movk_i32 s2, 0x33c0
	v_pk_fma_f32 v[60:61], v[60:61], 0.5, v[92:93] op_sel_hi:[1,0,1]
	v_pk_fma_f32 v[58:59], v[58:59], 0.5, v[112:113] op_sel_hi:[1,0,1]
	v_ashrrev_i32_e32 v81, 31, v80
	v_and_or_b32 v0, v0, s2, v194
	s_waitcnt lgkmcnt(0)
; __device__ __forceinline__ float xsum16(float v) { const auto r = __builtin_amdgcn_permlane16_swap(__float_as_uint(v), __float_as_uint(v), false, false); return __uint_as_float(r[0]) + __uint_as_float(r[1]); }
; __device__ __forceinline__ float xsum32(float v) { const auto r = __builtin_amdgcn_permlane32_swap(__float_as_uint(v), __float_as_uint(v), false, false); return __uint_as_float(r[0]) + __uint_as_float(r[1]); }
; __device__ __forceinline__ size_t blk_off(int r, int c, int K) { return (size_t)(r >> 8) * 256 * K + (size_t)(c >> 6) * (256 * 64) + (size_t)((r & 255) * 64 + (c & 63)); }
; __device__ __forceinline__ u32x4 pack8(const f32x4 a, const f32x4 b) { u32x4 w; w.x = cvt_pk_bf16(a[0], a[1]); w.y = cvt_pk_bf16(a[2], a[3]); w.z = cvt_pk_bf16(b[0], b[1]); w.w = cvt_pk_bf16(b[2], b[3]); return w; }
;     __device__ __forceinline__ void operator()(const f32x4 (&acc)[2][2][4][2], const pg8::Unit& u, int wr, int wc, int fr, int fq) const {
;     ...
;                 for (int bj = 0; bj < 2; ++bj) { float* yp = Y + (size_t)row * D_ + col0 + bj * 128; f32x4 v[2];
; #pragma unroll
;                     for (int n = 0; n < 2; ++n) { v[n] = (((yv[bj][n] - mu) * rs) * gq[bj][n] + bq_[bj][n]) * ALPHA_ + acc[ai][bj][m][n] * sc;
;                         *(f32x4*)(yp + 4 * n) = v[n]; s1 += (v[n][0] + v[n][1]) + (v[n][2] + v[n][3]); s2 += (v[n][0] * v[n][0] + v[n][1] * v[n][1]) + (v[n][2] * v[n][2] + v[n][3] * v[n][3]); }
;                     *(u32x4*)(Yb + blk_off(row, col0 + bj * 128, D_)) = pack8(v[0], v[1]); }
;                 s1 = xsum32(xsum16(s1)); s2 = xsum32(xsum16(s2));
;                 if (fq == 0) *(f32x2*)(stn + (size_t)row * 32 + (u.pn * 4 + wc) * 2) = (f32x2){s1, s2}; asm volatile("" ::: "memory"); } }
	v_lshl_add_u64 v[68:69], s[74:75], 0, v[136:137]
	v_add_f32_e32 v92, v58, v59
	v_add_f32_e32 v93, v60, v61
	v_readlane_b32 s2, v253, 59
	v_lshlrev_b64 v[80:81], 19, v[80:81]
	v_lshl_add_u64 v[68:69], v[68:69], 0, v[152:153]
	v_add_f32_e32 v92, v92, v93
	v_mul_f32_e32 v93, v59, v59
	v_readlane_b32 s3, v253, 60
	s_nop 0
	s_nop 1
	v_bfe_u32 v85, v227, 4, 2
	v_sub_u32_e32 v84, 0, v85
	v_lshlrev_b32_e32 v84, 4, v84
	v_ashrrev_i32_e32 v85, 31, v84
	v_lshl_add_u64 v[84:85], v[68:69], 0, v[84:85]
	v_permlane16_swap_b32_e32 v62, v58
	v_permlane16_swap_b32_e32 v63, v59
	v_permlane16_swap_b32_e32 v64, v60
	v_permlane16_swap_b32_e32 v65, v61
	v_permlane32_swap_b32_e32 v62, v58
	v_permlane32_swap_b32_e32 v63, v59
	v_permlane32_swap_b32_e32 v64, v60
	v_permlane32_swap_b32_e32 v65, v61
	global_store_dwordx4 v[84:85], v[62:65], off
	global_store_dwordx4 v[84:85], v[58:61], off offset:64
	s_nop 1
	v_permlane32_swap_b32_e32 v62, v58
	v_permlane32_swap_b32_e32 v63, v59
	v_permlane32_swap_b32_e32 v64, v60
	v_permlane32_swap_b32_e32 v65, v61
	v_permlane16_swap_b32_e32 v62, v58
	v_permlane16_swap_b32_e32 v63, v59
	v_permlane16_swap_b32_e32 v64, v60
	v_permlane16_swap_b32_e32 v65, v61
	v_fmac_f32_e32 v93, v58, v58
	v_cvt_pk_bf16_f32 v62, v62, v63
	v_cvt_pk_bf16_f32 v63, v64, v65
	v_cvt_pk_bf16_f32 v64, v58, v59
	v_lshl_add_u64 v[58:59], s[2:3], 0, v[80:81]
	v_mul_f32_e32 v112, v61, v61
	v_lshl_add_u64 v[80:81], v[58:59], 0, s[28:29]
	v_lshlrev_b32_e32 v0, 1, v0
	v_fmac_f32_e32 v112, v60, v60
	v_cvt_pk_bf16_f32 v65, v60, v61
	v_lshl_add_u64 v[60:61], v[80:81], 0, v[0:1]
	global_store_dwordx4 v[60:61], v[62:65], off
	s_waitcnt vmcnt(7)
	v_permlane32_swap_b32_e32 v100, v96
	v_permlane32_swap_b32_e32 v101, v97
	v_permlane32_swap_b32_e32 v102, v98
	v_permlane32_swap_b32_e32 v103, v99
	v_permlane16_swap_b32_e32 v100, v96
	v_permlane16_swap_b32_e32 v101, v97
	v_permlane16_swap_b32_e32 v102, v98
	v_permlane16_swap_b32_e32 v103, v99
	v_sub_f32_e32 v61, v103, v79
	v_sub_f32_e32 v60, v102, v79
	v_sub_f32_e32 v63, v101, v79
	v_sub_f32_e32 v62, v100, v79
	v_pk_mul_f32 v[62:63], v[78:79], v[62:63] op_sel_hi:[0,1]
	v_pk_mul_f32 v[60:61], v[78:79], v[60:61] op_sel_hi:[0,1]
	v_add_f32_e32 v92, v116, v92
	s_waitcnt vmcnt(3)
	v_pk_fma_f32 v[60:61], v[110:111], v[60:61], v[164:165]
	v_pk_fma_f32 v[62:63], v[108:109], v[62:63], v[162:163]
	v_pk_mul_f32 v[60:61], v[60:61], s[16:17] op_sel_hi:[1,0]
	v_pk_mul_f32 v[62:63], v[62:63], s[16:17] op_sel_hi:[1,0]
	v_pk_fma_f32 v[56:57], v[56:57], 0.5, v[60:61] op_sel_hi:[1,0,1]
	v_pk_fma_f32 v[54:55], v[54:55], 0.5, v[62:63] op_sel_hi:[1,0,1]
	v_add_f32_e32 v61, v56, v57
	v_add_f32_e32 v60, v54, v55
	v_add_f32_e32 v60, v60, v61
	v_add_f32_e32 v64, v92, v60
	v_mul_f32_e32 v60, v55, v55
	v_mul_f32_e32 v61, v57, v57
	v_add_f32_e32 v93, v93, v112
	v_fmac_f32_e32 v60, v54, v54
	v_fmac_f32_e32 v61, v56, v56
	v_add_f32_e32 v93, v117, v93
	v_add_f32_e32 v60, v60, v61
	v_add_f32_e32 v65, v93, v60
	v_sub_f32_e32 v61, v99, v79
	v_sub_f32_e32 v60, v98, v79
	v_sub_f32_e32 v63, v97, v79
	v_sub_f32_e32 v62, v96, v79
	v_pk_mul_f32 v[62:63], v[78:79], v[62:63] op_sel_hi:[0,1]
	v_pk_mul_f32 v[60:61], v[78:79], v[60:61] op_sel_hi:[0,1]
	v_pk_fma_f32 v[60:61], v[106:107], v[60:61], v[160:161]
	v_pk_fma_f32 v[62:63], v[104:105], v[62:63], v[158:159]
	v_pk_mul_f32 v[60:61], v[60:61], s[16:17] op_sel_hi:[1,0]
	v_pk_mul_f32 v[62:63], v[62:63], s[16:17] op_sel_hi:[1,0]
	v_pk_fma_f32 v[52:53], v[52:53], 0.5, v[60:61] op_sel_hi:[1,0,1]
	v_pk_fma_f32 v[50:51], v[50:51], 0.5, v[62:63] op_sel_hi:[1,0,1]
	v_add_f32_e32 v61, v52, v53
	v_add_f32_e32 v60, v50, v51
	v_add_f32_e32 v60, v60, v61
	v_mul_f32_e32 v61, v51, v51
	v_mul_f32_e32 v62, v53, v53
	v_add_f32_e32 v60, v64, v60
	v_fmac_f32_e32 v61, v50, v50
	v_fmac_f32_e32 v62, v52, v52
	v_lshl_add_u64 v[78:79], v[58:59], 0, s[40:41]
	s_nop 0
	s_nop 1
	v_bfe_u32 v85, v227, 4, 2
	v_sub_u32_e32 v84, 0, v85
	v_lshlrev_b32_e32 v84, 4, v84
	v_ashrrev_i32_e32 v85, 31, v84
	v_lshl_add_u64 v[84:85], v[68:69], 0, v[84:85]
	v_permlane16_swap_b32_e32 v54, v50
	v_permlane16_swap_b32_e32 v55, v51
	v_permlane16_swap_b32_e32 v56, v52
	v_permlane16_swap_b32_e32 v57, v53
	v_permlane32_swap_b32_e32 v54, v50
	v_permlane32_swap_b32_e32 v55, v51
	v_permlane32_swap_b32_e32 v56, v52
	v_permlane32_swap_b32_e32 v57, v53
	global_store_dwordx4 v[84:85], v[54:57], off offset:512
	global_store_dwordx4 v[84:85], v[50:53], off offset:576
	s_nop 1
	v_permlane32_swap_b32_e32 v54, v50
	v_permlane32_swap_b32_e32 v55, v51
	v_permlane32_swap_b32_e32 v56, v52
	v_permlane32_swap_b32_e32 v57, v53
	v_permlane16_swap_b32_e32 v54, v50
	v_permlane16_swap_b32_e32 v55, v51
	v_permlane16_swap_b32_e32 v56, v52
	v_permlane16_swap_b32_e32 v57, v53
	v_add_f32_e32 v61, v61, v62
	v_cvt_pk_bf16_f32 v54, v54, v55
	v_cvt_pk_bf16_f32 v55, v56, v57
	v_cvt_pk_bf16_f32 v56, v50, v51
	v_lshl_add_u64 v[50:51], v[78:79], 0, v[0:1]
	v_mov_b32_e32 v0, v60
	v_pk_add_f32 v[70:71], v[70:71], v[70:71] op_sel:[0,1] op_sel_hi:[1,0]
	v_pk_add_f32 v[72:73], v[72:73], v[72:73] op_sel:[0,1] op_sel_hi:[1,0]
	v_add_f32_e32 v61, v65, v61
	v_cvt_pk_bf16_f32 v57, v52, v53
	v_permlane16_swap_b32_e32 v60, v0
	v_mov_b32_e32 v71, v70
	v_mov_b32_e32 v73, v72
	global_store_dwordx4 v[50:51], v[54:57], off
	v_add_f32_e32 v50, v60, v0
	v_mov_b32_e32 v0, v61
	v_permlane16_swap_b32_e32 v70, v71
	v_permlane16_swap_b32_e32 v72, v73
	v_permlane16_swap_b32_e32 v61, v0
	v_add_f32_e32 v71, v70, v71
	v_add_f32_e32 v70, v72, v73
	v_add_f32_e32 v51, v61, v0
	v_mov_b32_e32 v73, v71
	v_mov_b32_e32 v72, v70
	v_mov_b32_e32 v91, v89
	v_mov_b32_e32 v90, v88
	v_mov_b32_e32 v85, v83
	v_mov_b32_e32 v84, v82
	v_mov_b32_e32 v52, v50
	v_mov_b32_e32 v53, v51
	v_permlane32_swap_b32_e32 v71, v73
	v_permlane32_swap_b32_e32 v70, v72
	v_permlane32_swap_b32_e32 v89, v91
	v_permlane32_swap_b32_e32 v88, v90
	v_permlane32_swap_b32_e32 v83, v85
	v_permlane32_swap_b32_e32 v82, v84
	v_permlane32_swap_b32_e32 v50, v52
	v_permlane32_swap_b32_e32 v51, v53
	s_and_saveexec_b64 s[26:27], s[44:45]
	s_cbranch_execz .LBB0_382
	v_pk_add_f32 v[50:51], v[50:51], v[52:53]
	v_lshl_add_u64 v[52:53], s[30:31], 0, v[66:67]
	v_lshl_add_u64 v[52:53], s[24:25], 2, v[52:53]
	global_store_dwordx2 v[52:53], v[50:51], off
; __device__ __forceinline__ float xsum16(float v) { const auto r = __builtin_amdgcn_permlane16_swap(__float_as_uint(v), __float_as_uint(v), false, false); return __uint_as_float(r[0]) + __uint_as_float(r[1]); }
; __device__ __forceinline__ float xsum32(float v) { const auto r = __builtin_amdgcn_permlane32_swap(__float_as_uint(v), __float_as_uint(v), false, false); return __uint_as_float(r[0]) + __uint_as_float(r[1]); }
; __device__ __forceinline__ size_t blk_off(int r, int c, int K) { return (size_t)(r >> 8) * 256 * K + (size_t)(c >> 6) * (256 * 64) + (size_t)((r & 255) * 64 + (c & 63)); }
; __device__ __forceinline__ u32x4 pack8(const f32x4 a, const f32x4 b) { u32x4 w; w.x = cvt_pk_bf16(a[0], a[1]); w.y = cvt_pk_bf16(a[2], a[3]); w.z = cvt_pk_bf16(b[0], b[1]); w.w = cvt_pk_bf16(b[2], b[3]); return w; }
;     __device__ __forceinline__ void operator()(const f32x4 (&acc)[2][2][4][2], const pg8::Unit& u, int wr, int wc, int fr, int fq) const {
;     ...
;             for (int m = 0; m < 4; ++m) { const int row = row0 + ai * 128 + m * 16; const float mu = mu4[m], rs = rs4[m];
;                 f32x4 yv[2][2], gq[2][2], bq_[2][2];
; #pragma unroll
;                 for (int bj = 0; bj < 2; ++bj)
; #pragma unroll
;                     for (int n = 0; n < 2; ++n) { yv[bj][n] = *(const f32x4*)(Yin + (size_t)row * D_ + col0 + bj * 128 + 4 * n); gq[bj][n] = *(const f32x4*)(g + col0 + bj * 128 + 4 * n); bq_[bj][n] = *(const f32x4*)(b + col0 + bj * 128 + 4 * n); }
;                 asm volatile("" ::: "memory");
;                 float s1 = 0.f, s2 = 0.f;
; #pragma unroll
;                 for (int bj = 0; bj < 2; ++bj) { float* yp = Y + (size_t)row * D_ + col0 + bj * 128; f32x4 v[2];
; #pragma unroll
;                     for (int n = 0; n < 2; ++n) { v[n] = (((yv[bj][n] - mu) * rs) * gq[bj][n] + bq_[bj][n]) * ALPHA_ + acc[ai][bj][m][n] * sc;
;                         *(f32x4*)(yp + 4 * n) = v[n]; s1 += (v[n][0] + v[n][1]) + (v[n][2] + v[n][3]); s2 += (v[n][0] * v[n][0] + v[n][1] * v[n][1]) + (v[n][2] * v[n][2] + v[n][3] * v[n][3]); }
;                     *(u32x4*)(Yb + blk_off(row, col0 + bj * 128, D_)) = pack8(v[0], v[1]); }
;                 s1 = xsum32(xsum16(s1)); s2 = xsum32(xsum16(s2));
;                 if (fq == 0) *(f32x2*)(stn + (size_t)row * 32 + (u.pn * 4 + wc) * 2) = (f32x2){s1, s2}; asm volatile("" ::: "memory"); } }
.LBB0_382:
	s_or_b64 exec, exec, s[26:27]
	v_pk_add_f32 v[50:51], v[70:71], v[72:73]
	s_mov_b32 s2, 0x3a800000
	v_pk_mul_f32 v[92:93], v[50:51], s[2:3] op_sel_hi:[1,0]
	s_mov_b32 s2, 0x800000
	v_fma_f32 v0, -v93, v93, v92
	v_max_f32_e32 v0, 0, v0
	v_add_f32_e32 v0, 0x3727c5ac, v0
	v_cmp_gt_f32_e32 vcc, s2, v0
	v_mul_f32_e32 v50, 0x4b800000, v0
	v_lshlrev_b64 v[120:121], 12, v[94:95]
	v_cndmask_b32_e32 v0, v0, v50, vcc
	v_rsq_f32_e32 v0, v0
	s_movk_i32 s2, 0x37c0
	s_load_dwordx16 s[60:75], s[34:35], 0x38
	v_mul_f32_e32 v50, 0x45800000, v0
	v_cndmask_b32_e32 v92, v0, v50, vcc
	v_lshl_add_u64 v[50:51], s[12:13], 0, v[120:121]
	v_lshl_add_u64 v[54:55], v[50:51], 0, v[152:153]
	s_nop 1
	v_bfe_u32 v53, v227, 4, 2
	v_sub_u32_e32 v52, 0, v53
	v_lshlrev_b32_e32 v52, 4, v52
	v_ashrrev_i32_e32 v53, 31, v52
	v_lshl_add_u64 v[52:53], v[54:55], 0, v[52:53]
	global_load_dwordx4 v[96:99], v[52:53], off offset:64
	global_load_dwordx4 v[100:103], v[52:53], off
	global_load_dwordx4 v[104:107], v[154:155], off offset:16
	global_load_dwordx4 v[108:111], v[154:155], off
	global_load_dwordx4 v[112:115], v[156:157], off offset:16
	global_load_dwordx4 v[116:119], v[156:157], off
	s_nop 1
	v_bfe_u32 v57, v227, 4, 2
	v_sub_u32_e32 v56, 0, v57
	v_lshlrev_b32_e32 v56, 4, v56
	v_ashrrev_i32_e32 v57, 31, v56
	v_lshl_add_u64 v[56:57], v[54:55], 0, v[56:57]
	global_load_dwordx4 v[50:53], v[56:57], off offset:576
	global_load_dwordx4 v[70:73], v[56:57], off offset:512
	s_nop 0
	global_load_dwordx4 v[54:57], v[154:155], off offset:528
	global_load_dwordx4 v[62:65], v[154:155], off offset:512
	global_load_dwordx4 v[58:61], v[156:157], off offset:528
	global_load_dwordx4 v[66:69], v[156:157], off offset:512
	v_lshlrev_b32_e32 v0, 6, v94
	v_and_or_b32 v0, v0, s2, v194
	s_mov_b32 s2, 0x3fd744fd
	s_waitcnt lgkmcnt(0)
	v_lshl_add_u64 v[94:95], s[74:75], 0, v[120:121]
	v_lshlrev_b32_e32 v0, 1, v0
	v_lshl_add_u64 v[94:95], v[94:95], 0, v[152:153]
	s_waitcnt vmcnt(10)
	v_permlane32_swap_b32_e32 v100, v96
	v_permlane32_swap_b32_e32 v101, v97
	v_permlane32_swap_b32_e32 v102, v98
	v_permlane32_swap_b32_e32 v103, v99
	v_permlane16_swap_b32_e32 v100, v96
	v_permlane16_swap_b32_e32 v101, v97
	v_permlane16_swap_b32_e32 v102, v98
	v_permlane16_swap_b32_e32 v103, v99
	v_sub_f32_e32 v103, v103, v93
	v_sub_f32_e32 v102, v102, v93
	v_sub_f32_e32 v101, v101, v93
	v_sub_f32_e32 v100, v100, v93
	v_pk_mul_f32 v[100:101], v[92:93], v[100:101] op_sel_hi:[0,1]
	v_pk_mul_f32 v[102:103], v[92:93], v[102:103] op_sel_hi:[0,1]
	s_waitcnt vmcnt(6)
	v_pk_fma_f32 v[102:103], v[110:111], v[102:103], v[118:119]
	v_pk_fma_f32 v[100:101], v[108:109], v[100:101], v[116:117]
	v_pk_mul_f32 v[102:103], v[102:103], s[2:3] op_sel_hi:[1,0]
	v_pk_mul_f32 v[100:101], v[100:101], s[2:3] op_sel_hi:[1,0]
	v_pk_fma_f32 v[102:103], v[48:49], 0.5, v[102:103] op_sel_hi:[1,0,1]
	v_pk_fma_f32 v[100:101], v[46:47], 0.5, v[100:101] op_sel_hi:[1,0,1]
	v_add_f32_e32 v47, v102, v103
	v_add_f32_e32 v46, v100, v101
	v_add_f32_e32 v46, v46, v47
	v_add_f32_e32 v108, 0, v46
	v_mul_f32_e32 v46, v101, v101
	v_mul_f32_e32 v47, v103, v103
	v_fmac_f32_e32 v46, v100, v100
	v_fmac_f32_e32 v47, v102, v102
	v_add_f32_e32 v109, v46, v47
	v_sub_f32_e32 v47, v99, v93
	v_sub_f32_e32 v46, v98, v93
	v_sub_f32_e32 v49, v97, v93
	v_sub_f32_e32 v48, v96, v93
	v_pk_mul_f32 v[48:49], v[92:93], v[48:49] op_sel_hi:[0,1]
	v_pk_mul_f32 v[46:47], v[92:93], v[46:47] op_sel_hi:[0,1]
	v_pk_fma_f32 v[46:47], v[106:107], v[46:47], v[114:115]
	v_pk_fma_f32 v[48:49], v[104:105], v[48:49], v[112:113]
	v_pk_mul_f32 v[46:47], v[46:47], s[2:3] op_sel_hi:[1,0]
	v_pk_mul_f32 v[48:49], v[48:49], s[2:3] op_sel_hi:[1,0]
	v_pk_fma_f32 v[98:99], v[44:45], 0.5, v[46:47] op_sel_hi:[1,0,1]
	v_pk_fma_f32 v[96:97], v[42:43], 0.5, v[48:49] op_sel_hi:[1,0,1]
	v_add_f32_e32 v43, v98, v99
	v_add_f32_e32 v42, v96, v97
	v_add_f32_e32 v42, v42, v43
	v_add_f32_e32 v47, v108, v42
	v_mul_f32_e32 v42, v97, v97
	v_mul_f32_e32 v43, v99, v99
	v_fmac_f32_e32 v42, v96, v96
	v_fmac_f32_e32 v43, v98, v98
	v_add_f32_e32 v42, v42, v43
	v_add_f32_e32 v46, v109, v42
	v_cvt_pk_bf16_f32 v42, v100, v101
	v_cvt_pk_bf16_f32 v43, v102, v103
	v_cvt_pk_bf16_f32 v44, v96, v97
	v_cvt_pk_bf16_f32 v45, v98, v99
	v_lshl_add_u64 v[48:49], v[80:81], 0, v[0:1]
	s_nop 0
	s_nop 1
	v_bfe_u32 v105, v227, 4, 2
	v_sub_u32_e32 v104, 0, v105
	v_lshlrev_b32_e32 v104, 4, v104
	v_ashrrev_i32_e32 v105, 31, v104
	v_lshl_add_u64 v[104:105], v[94:95], 0, v[104:105]
	v_permlane16_swap_b32_e32 v100, v96
	v_permlane16_swap_b32_e32 v101, v97
	v_permlane16_swap_b32_e32 v102, v98
	v_permlane16_swap_b32_e32 v103, v99
	v_permlane32_swap_b32_e32 v100, v96
	v_permlane32_swap_b32_e32 v101, v97
	v_permlane32_swap_b32_e32 v102, v98
	v_permlane32_swap_b32_e32 v103, v99
	global_store_dwordx4 v[104:105], v[100:103], off
	global_store_dwordx4 v[104:105], v[96:99], off offset:64
	s_nop 1
	v_permlane32_swap_b32_e32 v100, v96
	v_permlane32_swap_b32_e32 v101, v97
	v_permlane32_swap_b32_e32 v102, v98
	v_permlane32_swap_b32_e32 v103, v99
	v_permlane16_swap_b32_e32 v100, v96
	v_permlane16_swap_b32_e32 v101, v97
	v_permlane16_swap_b32_e32 v102, v98
	v_permlane16_swap_b32_e32 v103, v99
	global_store_dwordx4 v[48:49], v[42:45], off
	s_nop 0
	s_waitcnt vmcnt(7)
	v_permlane32_swap_b32_e32 v70, v50
	v_permlane32_swap_b32_e32 v71, v51
	v_permlane32_swap_b32_e32 v72, v52
	v_permlane32_swap_b32_e32 v73, v53
	v_permlane16_swap_b32_e32 v70, v50
	v_permlane16_swap_b32_e32 v71, v51
	v_permlane16_swap_b32_e32 v72, v52
	v_permlane16_swap_b32_e32 v73, v53
	v_sub_f32_e32 v43, v73, v93
	v_sub_f32_e32 v42, v72, v93
	v_sub_f32_e32 v45, v71, v93
	v_sub_f32_e32 v44, v70, v93
	v_pk_mul_f32 v[44:45], v[92:93], v[44:45] op_sel_hi:[0,1]
	v_pk_mul_f32 v[42:43], v[92:93], v[42:43] op_sel_hi:[0,1]
	s_waitcnt vmcnt(3)
; __device__ __forceinline__ float xsum16(float v) { const auto r = __builtin_amdgcn_permlane16_swap(__float_as_uint(v), __float_as_uint(v), false, false); return __uint_as_float(r[0]) + __uint_as_float(r[1]); }
; __device__ __forceinline__ float xsum32(float v) { const auto r = __builtin_amdgcn_permlane32_swap(__float_as_uint(v), __float_as_uint(v), false, false); return __uint_as_float(r[0]) + __uint_as_float(r[1]); }
; __device__ __forceinline__ size_t blk_off(int r, int c, int K) { return (size_t)(r >> 8) * 256 * K + (size_t)(c >> 6) * (256 * 64) + (size_t)((r & 255) * 64 + (c & 63)); }
; __device__ __forceinline__ u32x4 pack8(const f32x4 a, const f32x4 b) { u32x4 w; w.x = cvt_pk_bf16(a[0], a[1]); w.y = cvt_pk_bf16(a[2], a[3]); w.z = cvt_pk_bf16(b[0], b[1]); w.w = cvt_pk_bf16(b[2], b[3]); return w; }
;     __device__ __forceinline__ void operator()(const f32x4 (&acc)[2][2][4][2], const pg8::Unit& u, int wr, int wc, int fr, int fq) const {
;     ...
;             for (int m = 0; m < 4; ++m) { const int row = row0 + ai * 128 + m * 16; const float mu = mu4[m], rs = rs4[m];
;                 f32x4 yv[2][2], gq[2][2], bq_[2][2];
; #pragma unroll
;                 for (int bj = 0; bj < 2; ++bj)
; #pragma unroll
;                     for (int n = 0; n < 2; ++n) { yv[bj][n] = *(const f32x4*)(Yin + (size_t)row * D_ + col0 + bj * 128 + 4 * n); gq[bj][n] = *(const f32x4*)(g + col0 + bj * 128 + 4 * n); bq_[bj][n] = *(const f32x4*)(b + col0 + bj * 128 + 4 * n); }
;                 asm volatile("" ::: "memory");
;                 float s1 = 0.f, s2 = 0.f;
; #pragma unroll
;                 for (int bj = 0; bj < 2; ++bj) { float* yp = Y + (size_t)row * D_ + col0 + bj * 128; f32x4 v[2];
; #pragma unroll
;                     for (int n = 0; n < 2; ++n) { v[n] = (((yv[bj][n] - mu) * rs) * gq[bj][n] + bq_[bj][n]) * ALPHA_ + acc[ai][bj][m][n] * sc;
;                         *(f32x4*)(yp + 4 * n) = v[n]; s1 += (v[n][0] + v[n][1]) + (v[n][2] + v[n][3]); s2 += (v[n][0] * v[n][0] + v[n][1] * v[n][1]) + (v[n][2] * v[n][2] + v[n][3] * v[n][3]); }
;                     *(u32x4*)(Yb + blk_off(row, col0 + bj * 128, D_)) = pack8(v[0], v[1]); }
;                 s1 = xsum32(xsum16(s1)); s2 = xsum32(xsum16(s2));
;                 if (fq == 0) *(f32x2*)(stn + (size_t)row * 32 + (u.pn * 4 + wc) * 2) = (f32x2){s1, s2}; asm volatile("" ::: "memory"); } }
	v_pk_fma_f32 v[42:43], v[64:65], v[42:43], v[68:69]
	v_pk_fma_f32 v[44:45], v[62:63], v[44:45], v[66:67]
	v_pk_mul_f32 v[42:43], v[42:43], s[2:3] op_sel_hi:[1,0]
	v_pk_mul_f32 v[44:45], v[44:45], s[2:3] op_sel_hi:[1,0]
	v_pk_fma_f32 v[40:41], v[40:41], 0.5, v[42:43] op_sel_hi:[1,0,1]
	v_pk_fma_f32 v[38:39], v[38:39], 0.5, v[44:45] op_sel_hi:[1,0,1]
	v_add_f32_e32 v43, v40, v41
	v_add_f32_e32 v42, v38, v39
	v_add_f32_e32 v42, v42, v43
	v_add_f32_e32 v47, v47, v42
	v_mul_f32_e32 v42, v39, v39
	v_mul_f32_e32 v43, v41, v41
	v_fmac_f32_e32 v42, v38, v38
	v_fmac_f32_e32 v43, v40, v40
	v_add_f32_e32 v42, v42, v43
	v_add_f32_e32 v46, v46, v42
	v_sub_f32_e32 v43, v53, v93
	v_sub_f32_e32 v42, v52, v93
	v_sub_f32_e32 v45, v51, v93
	v_sub_f32_e32 v44, v50, v93
	v_pk_mul_f32 v[44:45], v[92:93], v[44:45] op_sel_hi:[0,1]
	v_pk_mul_f32 v[42:43], v[92:93], v[42:43] op_sel_hi:[0,1]
	v_pk_fma_f32 v[42:43], v[56:57], v[42:43], v[60:61]
	v_pk_fma_f32 v[44:45], v[54:55], v[44:45], v[58:59]
	v_pk_mul_f32 v[42:43], v[42:43], s[2:3] op_sel_hi:[1,0]
	v_pk_mul_f32 v[44:45], v[44:45], s[2:3] op_sel_hi:[1,0]
	v_pk_fma_f32 v[36:37], v[36:37], 0.5, v[42:43] op_sel_hi:[1,0,1]
	v_pk_fma_f32 v[34:35], v[34:35], 0.5, v[44:45] op_sel_hi:[1,0,1]
	v_add_f32_e32 v43, v36, v37
	v_add_f32_e32 v42, v34, v35
	v_add_f32_e32 v42, v42, v43
	v_mul_f32_e32 v43, v35, v35
	v_mul_f32_e32 v44, v37, v37
	v_add_f32_e32 v42, v47, v42
	v_fmac_f32_e32 v43, v34, v34
	v_fmac_f32_e32 v44, v36, v36
	s_nop 0
	s_nop 1
	v_bfe_u32 v49, v227, 4, 2
	v_sub_u32_e32 v48, 0, v49
	v_lshlrev_b32_e32 v48, 4, v48
	v_ashrrev_i32_e32 v49, 31, v48
	v_lshl_add_u64 v[48:49], v[94:95], 0, v[48:49]
	v_permlane16_swap_b32_e32 v38, v34
	v_permlane16_swap_b32_e32 v39, v35
	v_permlane16_swap_b32_e32 v40, v36
	v_permlane16_swap_b32_e32 v41, v37
	v_permlane32_swap_b32_e32 v38, v34
	v_permlane32_swap_b32_e32 v39, v35
	v_permlane32_swap_b32_e32 v40, v36
	v_permlane32_swap_b32_e32 v41, v37
	global_store_dwordx4 v[48:49], v[38:41], off offset:512
	global_store_dwordx4 v[48:49], v[34:37], off offset:576
	s_nop 1
	v_permlane32_swap_b32_e32 v38, v34
	v_permlane32_swap_b32_e32 v39, v35
	v_permlane32_swap_b32_e32 v40, v36
	v_permlane32_swap_b32_e32 v41, v37
	v_permlane16_swap_b32_e32 v38, v34
	v_permlane16_swap_b32_e32 v39, v35
	v_permlane16_swap_b32_e32 v40, v36
	v_permlane16_swap_b32_e32 v41, v37
	v_add_f32_e32 v43, v43, v44
	v_cvt_pk_bf16_f32 v38, v38, v39
	v_cvt_pk_bf16_f32 v39, v40, v41
	v_cvt_pk_bf16_f32 v40, v34, v35
	v_lshl_add_u64 v[34:35], v[78:79], 0, v[0:1]
	v_mov_b32_e32 v0, v42
	v_add_f32_e32 v43, v46, v43
	v_cvt_pk_bf16_f32 v41, v36, v37
	v_permlane16_swap_b32_e32 v42, v0
	global_store_dwordx4 v[34:35], v[38:41], off
	v_add_f32_e32 v34, v42, v0
	v_mov_b32_e32 v0, v43
	s_nop 1
	v_permlane16_swap_b32_e32 v43, v0
	v_add_f32_e32 v35, v43, v0
	v_mov_b32_e32 v36, v34
	v_mov_b32_e32 v37, v35
	s_nop 0
	v_permlane32_swap_b32_e32 v34, v36
	v_permlane32_swap_b32_e32 v35, v37
	s_and_saveexec_b64 s[26:27], s[44:45]
	s_cbranch_execz .LBB0_384
	v_pk_add_f32 v[34:35], v[34:35], v[36:37]
	v_lshl_add_u64 v[36:37], s[30:31], 0, v[86:87]
	v_lshl_add_u64 v[36:37], s[24:25], 2, v[36:37]
	global_store_dwordx2 v[36:37], v[34:35], off
.LBB0_384:
	s_or_b64 exec, exec, s[26:27]
	v_pk_add_f32 v[34:35], v[88:89], v[90:91]
	s_mov_b32 s2, 0x3a800000
	v_pk_mul_f32 v[58:59], v[34:35], s[2:3] op_sel_hi:[1,0]
	s_mov_b32 s2, 0x800000
	v_fma_f32 v0, -v59, v59, v58
	v_max_f32_e32 v0, 0, v0
	v_add_f32_e32 v0, 0x3727c5ac, v0
	v_cmp_gt_f32_e32 vcc, s2, v0
	v_mul_f32_e32 v34, 0x4b800000, v0
	v_lshlrev_b64 v[60:61], 12, v[76:77]
	v_cndmask_b32_e32 v0, v0, v34, vcc
	v_rsq_f32_e32 v0, v0
	s_movk_i32 s2, 0x3bc0
	s_load_dwordx16 s[60:75], s[34:35], 0x38
	v_mul_f32_e32 v34, 0x45800000, v0
	v_cndmask_b32_e32 v58, v0, v34, vcc
	v_lshl_add_u64 v[34:35], s[12:13], 0, v[60:61]
	v_lshl_add_u64 v[38:39], v[34:35], 0, v[152:153]
	s_nop 1
	v_bfe_u32 v37, v227, 4, 2
	v_sub_u32_e32 v36, 0, v37
	v_lshlrev_b32_e32 v36, 4, v36
	v_ashrrev_i32_e32 v37, 31, v36
	v_lshl_add_u64 v[36:37], v[38:39], 0, v[36:37]
	global_load_dwordx4 v[62:65], v[36:37], off offset:64
	global_load_dwordx4 v[66:69], v[36:37], off
	global_load_dwordx4 v[70:73], v[154:155], off offset:16
	global_load_dwordx4 v[86:89], v[154:155], off
	global_load_dwordx4 v[90:93], v[156:157], off offset:16
	global_load_dwordx4 v[94:97], v[156:157], off
	s_nop 1
	v_bfe_u32 v41, v227, 4, 2
	v_sub_u32_e32 v40, 0, v41
	v_lshlrev_b32_e32 v40, 4, v40
	v_ashrrev_i32_e32 v41, 31, v40
	v_lshl_add_u64 v[40:41], v[38:39], 0, v[40:41]
	global_load_dwordx4 v[34:37], v[40:41], off offset:576
	global_load_dwordx4 v[54:57], v[40:41], off offset:512
	s_nop 0
	global_load_dwordx4 v[38:41], v[154:155], off offset:528
	global_load_dwordx4 v[46:49], v[154:155], off offset:512
	global_load_dwordx4 v[42:45], v[156:157], off offset:528
	global_load_dwordx4 v[50:53], v[156:157], off offset:512
	v_lshlrev_b32_e32 v0, 6, v76
	v_and_or_b32 v0, v0, s2, v194
	s_mov_b32 s2, 0x3fd744fd
	s_waitcnt lgkmcnt(0)
	v_lshl_add_u64 v[60:61], s[74:75], 0, v[60:61]
	v_lshlrev_b32_e32 v0, 1, v0
	v_lshl_add_u64 v[60:61], v[60:61], 0, v[152:153]
	s_waitcnt vmcnt(10)
	v_permlane32_swap_b32_e32 v66, v62
	v_permlane32_swap_b32_e32 v67, v63
	v_permlane32_swap_b32_e32 v68, v64
	v_permlane32_swap_b32_e32 v69, v65
	v_permlane16_swap_b32_e32 v66, v62
	v_permlane16_swap_b32_e32 v67, v63
	v_permlane16_swap_b32_e32 v68, v64
	v_permlane16_swap_b32_e32 v69, v65
	v_sub_f32_e32 v69, v69, v59
	v_sub_f32_e32 v68, v68, v59
	v_sub_f32_e32 v67, v67, v59
	v_sub_f32_e32 v66, v66, v59
	v_pk_mul_f32 v[66:67], v[58:59], v[66:67] op_sel_hi:[0,1]
	v_pk_mul_f32 v[68:69], v[58:59], v[68:69] op_sel_hi:[0,1]
	s_waitcnt vmcnt(6)
; __device__ __forceinline__ float xsum16(float v) { const auto r = __builtin_amdgcn_permlane16_swap(__float_as_uint(v), __float_as_uint(v), false, false); return __uint_as_float(r[0]) + __uint_as_float(r[1]); }
; __device__ __forceinline__ float xsum32(float v) { const auto r = __builtin_amdgcn_permlane32_swap(__float_as_uint(v), __float_as_uint(v), false, false); return __uint_as_float(r[0]) + __uint_as_float(r[1]); }
; __device__ __forceinline__ size_t blk_off(int r, int c, int K) { return (size_t)(r >> 8) * 256 * K + (size_t)(c >> 6) * (256 * 64) + (size_t)((r & 255) * 64 + (c & 63)); }
; __device__ __forceinline__ u32x4 pack8(const f32x4 a, const f32x4 b) { u32x4 w; w.x = cvt_pk_bf16(a[0], a[1]); w.y = cvt_pk_bf16(a[2], a[3]); w.z = cvt_pk_bf16(b[0], b[1]); w.w = cvt_pk_bf16(b[2], b[3]); return w; }
;     __device__ __forceinline__ void operator()(const f32x4 (&acc)[2][2][4][2], const pg8::Unit& u, int wr, int wc, int fr, int fq) const {
;     ...
;                     for (int n = 0; n < 2; ++n) { yv[bj][n] = *(const f32x4*)(Yin + (size_t)row * D_ + col0 + bj * 128 + 4 * n); gq[bj][n] = *(const f32x4*)(g + col0 + bj * 128 + 4 * n); bq_[bj][n] = *(const f32x4*)(b + col0 + bj * 128 + 4 * n); }
;                 asm volatile("" ::: "memory");
;                 float s1 = 0.f, s2 = 0.f;
; #pragma unroll
;                 for (int bj = 0; bj < 2; ++bj) { float* yp = Y + (size_t)row * D_ + col0 + bj * 128; f32x4 v[2];
; #pragma unroll
;                     for (int n = 0; n < 2; ++n) { v[n] = (((yv[bj][n] - mu) * rs) * gq[bj][n] + bq_[bj][n]) * ALPHA_ + acc[ai][bj][m][n] * sc;
;                         *(f32x4*)(yp + 4 * n) = v[n]; s1 += (v[n][0] + v[n][1]) + (v[n][2] + v[n][3]); s2 += (v[n][0] * v[n][0] + v[n][1] * v[n][1]) + (v[n][2] * v[n][2] + v[n][3] * v[n][3]); }
;                     *(u32x4*)(Yb + blk_off(row, col0 + bj * 128, D_)) = pack8(v[0], v[1]); }
;                 s1 = xsum32(xsum16(s1)); s2 = xsum32(xsum16(s2));
;                 if (fq == 0) *(f32x2*)(stn + (size_t)row * 32 + (u.pn * 4 + wc) * 2) = (f32x2){s1, s2}; asm volatile("" ::: "memory"); } }
	v_pk_fma_f32 v[68:69], v[88:89], v[68:69], v[96:97]
	v_pk_fma_f32 v[66:67], v[86:87], v[66:67], v[94:95]
	v_pk_mul_f32 v[68:69], v[68:69], s[2:3] op_sel_hi:[1,0]
	v_pk_mul_f32 v[66:67], v[66:67], s[2:3] op_sel_hi:[1,0]
	v_pk_fma_f32 v[68:69], v[32:33], 0.5, v[68:69] op_sel_hi:[1,0,1]
	v_pk_fma_f32 v[66:67], v[30:31], 0.5, v[66:67] op_sel_hi:[1,0,1]
	v_add_f32_e32 v31, v68, v69
	v_add_f32_e32 v30, v66, v67
	v_add_f32_e32 v30, v30, v31
	v_add_f32_e32 v86, 0, v30
	v_mul_f32_e32 v30, v67, v67
	v_mul_f32_e32 v31, v69, v69
	v_fmac_f32_e32 v30, v66, v66
	v_fmac_f32_e32 v31, v68, v68
	v_add_f32_e32 v87, v30, v31
	v_sub_f32_e32 v31, v65, v59
	v_sub_f32_e32 v30, v64, v59
	v_sub_f32_e32 v33, v63, v59
	v_sub_f32_e32 v32, v62, v59
	v_pk_mul_f32 v[32:33], v[58:59], v[32:33] op_sel_hi:[0,1]
	v_pk_mul_f32 v[30:31], v[58:59], v[30:31] op_sel_hi:[0,1]
	v_pk_fma_f32 v[30:31], v[72:73], v[30:31], v[92:93]
	v_pk_fma_f32 v[32:33], v[70:71], v[32:33], v[90:91]
	v_pk_mul_f32 v[30:31], v[30:31], s[2:3] op_sel_hi:[1,0]
	v_pk_mul_f32 v[32:33], v[32:33], s[2:3] op_sel_hi:[1,0]
	v_pk_fma_f32 v[64:65], v[28:29], 0.5, v[30:31] op_sel_hi:[1,0,1]
	v_pk_fma_f32 v[62:63], v[26:27], 0.5, v[32:33] op_sel_hi:[1,0,1]
	v_add_f32_e32 v27, v64, v65
	v_add_f32_e32 v26, v62, v63
	v_add_f32_e32 v26, v26, v27
	v_add_f32_e32 v31, v86, v26
	v_mul_f32_e32 v26, v63, v63
	v_mul_f32_e32 v27, v65, v65
	v_fmac_f32_e32 v26, v62, v62
	v_fmac_f32_e32 v27, v64, v64
	v_add_f32_e32 v26, v26, v27
	v_add_f32_e32 v30, v87, v26
	v_cvt_pk_bf16_f32 v26, v66, v67
	v_cvt_pk_bf16_f32 v27, v68, v69
	v_cvt_pk_bf16_f32 v28, v62, v63
	v_cvt_pk_bf16_f32 v29, v64, v65
	v_lshl_add_u64 v[32:33], v[80:81], 0, v[0:1]
	s_nop 0
	s_nop 1
	v_bfe_u32 v71, v227, 4, 2
	v_sub_u32_e32 v70, 0, v71
	v_lshlrev_b32_e32 v70, 4, v70
	v_ashrrev_i32_e32 v71, 31, v70
	v_lshl_add_u64 v[70:71], v[60:61], 0, v[70:71]
	v_permlane16_swap_b32_e32 v66, v62
	v_permlane16_swap_b32_e32 v67, v63
	v_permlane16_swap_b32_e32 v68, v64
	v_permlane16_swap_b32_e32 v69, v65
	v_permlane32_swap_b32_e32 v66, v62
	v_permlane32_swap_b32_e32 v67, v63
	v_permlane32_swap_b32_e32 v68, v64
	v_permlane32_swap_b32_e32 v69, v65
	global_store_dwordx4 v[70:71], v[66:69], off
	global_store_dwordx4 v[70:71], v[62:65], off offset:64
	s_nop 1
	v_permlane32_swap_b32_e32 v66, v62
	v_permlane32_swap_b32_e32 v67, v63
	v_permlane32_swap_b32_e32 v68, v64
	v_permlane32_swap_b32_e32 v69, v65
	v_permlane16_swap_b32_e32 v66, v62
	v_permlane16_swap_b32_e32 v67, v63
	v_permlane16_swap_b32_e32 v68, v64
	v_permlane16_swap_b32_e32 v69, v65
	global_store_dwordx4 v[32:33], v[26:29], off
	s_nop 0
	s_waitcnt vmcnt(7)
	v_permlane32_swap_b32_e32 v54, v34
	v_permlane32_swap_b32_e32 v55, v35
	v_permlane32_swap_b32_e32 v56, v36
	v_permlane32_swap_b32_e32 v57, v37
	v_permlane16_swap_b32_e32 v54, v34
	v_permlane16_swap_b32_e32 v55, v35
	v_permlane16_swap_b32_e32 v56, v36
	v_permlane16_swap_b32_e32 v57, v37
	v_sub_f32_e32 v27, v57, v59
	v_sub_f32_e32 v26, v56, v59
	v_sub_f32_e32 v29, v55, v59
	v_sub_f32_e32 v28, v54, v59
	v_pk_mul_f32 v[28:29], v[58:59], v[28:29] op_sel_hi:[0,1]
	v_pk_mul_f32 v[26:27], v[58:59], v[26:27] op_sel_hi:[0,1]
	s_waitcnt vmcnt(3)
	v_pk_fma_f32 v[26:27], v[48:49], v[26:27], v[52:53]
	v_pk_fma_f32 v[28:29], v[46:47], v[28:29], v[50:51]
	v_pk_mul_f32 v[26:27], v[26:27], s[2:3] op_sel_hi:[1,0]
	v_pk_mul_f32 v[28:29], v[28:29], s[2:3] op_sel_hi:[1,0]
	v_pk_fma_f32 v[24:25], v[24:25], 0.5, v[26:27] op_sel_hi:[1,0,1]
	v_pk_fma_f32 v[22:23], v[22:23], 0.5, v[28:29] op_sel_hi:[1,0,1]
	v_add_f32_e32 v27, v24, v25
	v_add_f32_e32 v26, v22, v23
	v_add_f32_e32 v26, v26, v27
	v_add_f32_e32 v31, v31, v26
	v_mul_f32_e32 v26, v23, v23
	v_mul_f32_e32 v27, v25, v25
	v_fmac_f32_e32 v26, v22, v22
	v_fmac_f32_e32 v27, v24, v24
	v_add_f32_e32 v26, v26, v27
	v_add_f32_e32 v30, v30, v26
	v_sub_f32_e32 v27, v37, v59
	v_sub_f32_e32 v26, v36, v59
	v_sub_f32_e32 v29, v35, v59
	v_sub_f32_e32 v28, v34, v59
	v_pk_mul_f32 v[28:29], v[58:59], v[28:29] op_sel_hi:[0,1]
	v_pk_mul_f32 v[26:27], v[58:59], v[26:27] op_sel_hi:[0,1]
	v_pk_fma_f32 v[26:27], v[40:41], v[26:27], v[44:45]
	v_pk_fma_f32 v[28:29], v[38:39], v[28:29], v[42:43]
	v_pk_mul_f32 v[26:27], v[26:27], s[2:3] op_sel_hi:[1,0]
	v_pk_mul_f32 v[28:29], v[28:29], s[2:3] op_sel_hi:[1,0]
	v_pk_fma_f32 v[20:21], v[20:21], 0.5, v[26:27] op_sel_hi:[1,0,1]
	v_pk_fma_f32 v[18:19], v[18:19], 0.5, v[28:29] op_sel_hi:[1,0,1]
	v_add_f32_e32 v27, v20, v21
	v_add_f32_e32 v26, v18, v19
	v_add_f32_e32 v26, v26, v27
	v_mul_f32_e32 v27, v19, v19
	v_mul_f32_e32 v28, v21, v21
	v_add_f32_e32 v26, v31, v26
	v_fmac_f32_e32 v27, v18, v18
	v_fmac_f32_e32 v28, v20, v20
	s_nop 0
	s_nop 1
	v_bfe_u32 v33, v227, 4, 2
	v_sub_u32_e32 v32, 0, v33
	v_lshlrev_b32_e32 v32, 4, v32
	v_ashrrev_i32_e32 v33, 31, v32
	v_lshl_add_u64 v[32:33], v[60:61], 0, v[32:33]
	v_permlane16_swap_b32_e32 v22, v18
	v_permlane16_swap_b32_e32 v23, v19
	v_permlane16_swap_b32_e32 v24, v20
	v_permlane16_swap_b32_e32 v25, v21
	v_permlane32_swap_b32_e32 v22, v18
	v_permlane32_swap_b32_e32 v23, v19
	v_permlane32_swap_b32_e32 v24, v20
	v_permlane32_swap_b32_e32 v25, v21
	global_store_dwordx4 v[32:33], v[22:25], off offset:512
	global_store_dwordx4 v[32:33], v[18:21], off offset:576
	s_nop 1
	v_permlane32_swap_b32_e32 v22, v18
	v_permlane32_swap_b32_e32 v23, v19
	v_permlane32_swap_b32_e32 v24, v20
	v_permlane32_swap_b32_e32 v25, v21
	v_permlane16_swap_b32_e32 v22, v18
	v_permlane16_swap_b32_e32 v23, v19
	v_permlane16_swap_b32_e32 v24, v20
	v_permlane16_swap_b32_e32 v25, v21
	v_add_f32_e32 v27, v27, v28
	v_cvt_pk_bf16_f32 v22, v22, v23
	v_cvt_pk_bf16_f32 v23, v24, v25
	v_cvt_pk_bf16_f32 v24, v18, v19
	v_lshl_add_u64 v[18:19], v[78:79], 0, v[0:1]
	v_mov_b32_e32 v0, v26
	v_add_f32_e32 v27, v30, v27
	v_cvt_pk_bf16_f32 v25, v20, v21
	v_permlane16_swap_b32_e32 v26, v0
	global_store_dwordx4 v[18:19], v[22:25], off
	v_add_f32_e32 v18, v26, v0
	v_mov_b32_e32 v0, v27
	s_nop 1
	v_permlane16_swap_b32_e32 v27, v0
	v_add_f32_e32 v19, v27, v0
	v_mov_b32_e32 v20, v18
	v_mov_b32_e32 v21, v19
	s_nop 0
	v_permlane32_swap_b32_e32 v18, v20
	v_permlane32_swap_b32_e32 v19, v21
	s_and_saveexec_b64 s[26:27], s[44:45]
	s_cbranch_execz .LBB0_386
	v_pk_add_f32 v[18:19], v[18:19], v[20:21]
	v_lshlrev_b64 v[20:21], 7, v[76:77]
	v_lshl_add_u64 v[20:21], s[30:31], 0, v[20:21]
	v_lshl_add_u64 v[20:21], s[24:25], 2, v[20:21]
	global_store_dwordx2 v[20:21], v[18:19], off
;     __device__ __forceinline__ void operator()(const f32x4 (&acc)[2][2][4][2], const pg8::Unit& u, int wr, int wc, int fr, int fq) const {
;     ...
;             for (int m = 0; m < 4; ++m) { const int row = row0 + ai * 128 + m * 16; const float mu = mu4[m], rs = rs4[m];
;                 f32x4 yv[2][2], gq[2][2], bq_[2][2];
; #pragma unroll
;                 for (int bj = 0; bj < 2; ++bj)
; #pragma unroll
;                     for (int n = 0; n < 2; ++n) { yv[bj][n] = *(const f32x4*)(Yin + (size_t)row * D_ + col0 + bj * 128 + 4 * n); gq[bj][n] = *(const f32x4*)(g + col0 + bj * 128 + 4 * n); bq_[bj][n] = *(const f32x4*)(b + col0 + bj * 128 + 4 * n); }
;                 asm volatile("" ::: "memory");
;                 float s1 = 0.f, s2 = 0.f;
; #pragma unroll
;                 for (int bj = 0; bj < 2; ++bj) { float* yp = Y + (size_t)row * D_ + col0 + bj * 128; f32x4 v[2];
; #pragma unroll
;                     for (int n = 0; n < 2; ++n) { v[n] = (((yv[bj][n] - mu) * rs) * gq[bj][n] + bq_[bj][n]) * ALPHA_ + acc[ai][bj][m][n] * sc;
;                         *(f32x4*)(yp + 4 * n) = v[n]; s1 += (v[n][0] + v[n][1]) + (v[n][2] + v[n][3]); s2 += (v[n][0] * v[n][0] + v[n][1] * v[n][1]) + (v[n][2] * v[n][2] + v[n][3] * v[n][3]); }
.LBB0_386:
	s_or_b64 exec, exec, s[26:27]
	v_lshlrev_b64 v[26:27], 12, v[74:75]
	v_lshl_add_u64 v[18:19], s[12:13], 0, v[26:27]
	v_lshl_add_u64 v[28:29], v[18:19], 0, v[152:153]
	s_nop 1
	v_bfe_u32 v21, v227, 4, 2
	v_sub_u32_e32 v20, 0, v21
	v_lshlrev_b32_e32 v20, 4, v20
	v_ashrrev_i32_e32 v21, 31, v20
	v_lshl_add_u64 v[20:21], v[28:29], 0, v[20:21]
	global_load_dwordx4 v[34:37], v[20:21], off
	global_load_dwordx4 v[38:41], v[20:21], off offset:64
	global_load_dwordx4 v[42:45], v[28:29], off offset:512
	global_load_dwordx4 v[46:49], v[156:157], off
	global_load_dwordx4 v[50:53], v[154:155], off
	global_load_dwordx4 v[54:57], v[154:155], off offset:16
	global_load_dwordx4 v[58:61], v[156:157], off offset:16
	global_load_dwordx4 v[62:65], v[154:155], off offset:512
	global_load_dwordx4 v[66:69], v[156:157], off offset:512
	s_load_dwordx16 s[60:75], s[34:35], 0x38
	v_pk_add_f32 v[18:19], v[82:83], v[84:85]
	s_mov_b32 s2, 0x3a800000
	v_pk_mul_f32 v[32:33], v[18:19], s[2:3] op_sel_hi:[1,0]
	global_load_dwordx4 v[18:21], v[154:155], off offset:528
	global_load_dwordx4 v[22:25], v[156:157], off offset:528
	s_waitcnt lgkmcnt(0)
	v_lshl_add_u64 v[26:27], s[74:75], 0, v[26:27]
	v_lshl_add_u64 v[30:31], v[26:27], 0, v[152:153]
	global_load_dwordx4 v[26:29], v[28:29], off offset:528
	v_fma_f32 v32, -v33, v33, v32
	v_lshlrev_b32_e32 v0, 6, v74
	s_movk_i32 s2, 0x3fc0
	v_max_f32_e32 v32, 0, v32
	v_and_or_b32 v0, v0, s2, v194
	v_add_f32_e32 v32, 0x3727c5ac, v32
	s_mov_b32 s2, 0x800000
	v_mul_f32_e32 v70, 0x4b800000, v32
	v_cmp_gt_f32_e32 vcc, s2, v32
	s_mov_b32 s2, 0x3fd744fd
	v_lshlrev_b32_e32 v0, 1, v0
	v_cndmask_b32_e32 v32, v32, v70, vcc
	v_rsq_f32_e32 v32, v32
	v_lshl_add_u64 v[70:71], v[80:81], 0, v[0:1]
	v_mul_f32_e32 v72, 0x45800000, v32
	v_cndmask_b32_e32 v32, v32, v72, vcc
	s_waitcnt vmcnt(10)
	v_permlane32_swap_b32_e32 v34, v38
	v_permlane32_swap_b32_e32 v35, v39
	v_permlane32_swap_b32_e32 v36, v40
	v_permlane32_swap_b32_e32 v37, v41
	v_permlane16_swap_b32_e32 v34, v38
	v_permlane16_swap_b32_e32 v35, v39
	v_permlane16_swap_b32_e32 v36, v40
	v_permlane16_swap_b32_e32 v37, v41
	v_sub_f32_e32 v37, v37, v33
	v_sub_f32_e32 v36, v36, v33
	v_sub_f32_e32 v35, v35, v33
	v_sub_f32_e32 v34, v34, v33
	v_sub_f32_e32 v41, v41, v33
	v_sub_f32_e32 v40, v40, v33
	v_sub_f32_e32 v39, v39, v33
	v_sub_f32_e32 v38, v38, v33
	v_pk_mul_f32 v[34:35], v[32:33], v[34:35] op_sel_hi:[0,1]
	v_pk_mul_f32 v[36:37], v[32:33], v[36:37] op_sel_hi:[0,1]
	v_pk_mul_f32 v[38:39], v[32:33], v[38:39] op_sel_hi:[0,1]
	v_pk_mul_f32 v[40:41], v[32:33], v[40:41] op_sel_hi:[0,1]
	s_waitcnt vmcnt(7)
	v_pk_fma_f32 v[36:37], v[52:53], v[36:37], v[48:49]
	v_pk_fma_f32 v[34:35], v[50:51], v[34:35], v[46:47]
	s_waitcnt vmcnt(5)
	v_pk_fma_f32 v[40:41], v[56:57], v[40:41], v[60:61]
	v_pk_fma_f32 v[38:39], v[54:55], v[38:39], v[58:59]
	v_pk_mul_f32 v[34:35], v[34:35], s[2:3] op_sel_hi:[1,0]
	v_pk_mul_f32 v[36:37], v[36:37], s[2:3] op_sel_hi:[1,0]
	v_pk_mul_f32 v[38:39], v[38:39], s[2:3] op_sel_hi:[1,0]
	v_pk_mul_f32 v[40:41], v[40:41], s[2:3] op_sel_hi:[1,0]
	v_pk_fma_f32 v[16:17], v[16:17], 0.5, v[36:37] op_sel_hi:[1,0,1]
	v_pk_fma_f32 v[14:15], v[14:15], 0.5, v[34:35] op_sel_hi:[1,0,1]
	v_pk_fma_f32 v[12:13], v[12:13], 0.5, v[40:41] op_sel_hi:[1,0,1]
	v_pk_fma_f32 v[10:11], v[10:11], 0.5, v[38:39] op_sel_hi:[1,0,1]
	v_sub_f32_e32 v45, v45, v33
	v_sub_f32_e32 v44, v44, v33
	v_sub_f32_e32 v43, v43, v33
	v_sub_f32_e32 v42, v42, v33
	v_add_f32_e32 v38, v14, v15
	v_add_f32_e32 v39, v16, v17
	v_mul_f32_e32 v40, v15, v15
	v_mul_f32_e32 v41, v17, v17
	v_mul_f32_e32 v48, v11, v11
	v_mul_f32_e32 v49, v13, v13
	v_pk_mul_f32 v[42:43], v[32:33], v[42:43] op_sel_hi:[0,1]
	v_pk_mul_f32 v[44:45], v[32:33], v[44:45] op_sel_hi:[0,1]
	global_store_dwordx4 v[30:31], v[10:13], off offset:16
	v_add_f32_e32 v46, v10, v11
	v_add_f32_e32 v47, v12, v13
	v_cvt_pk_bf16_f32 v36, v10, v11
	v_add_f32_e32 v11, v38, v39
	v_fmac_f32_e32 v40, v14, v14
	v_fmac_f32_e32 v41, v16, v16
	v_fmac_f32_e32 v48, v10, v10
	v_fmac_f32_e32 v49, v12, v12
	s_waitcnt vmcnt(4)
; __device__ __forceinline__ float xsum16(float v) { const auto r = __builtin_amdgcn_permlane16_swap(__float_as_uint(v), __float_as_uint(v), false, false); return __uint_as_float(r[0]) + __uint_as_float(r[1]); }
; __device__ __forceinline__ float xsum32(float v) { const auto r = __builtin_amdgcn_permlane32_swap(__float_as_uint(v), __float_as_uint(v), false, false); return __uint_as_float(r[0]) + __uint_as_float(r[1]); }
; __device__ __forceinline__ size_t blk_off(int r, int c, int K) { return (size_t)(r >> 8) * 256 * K + (size_t)(c >> 6) * (256 * 64) + (size_t)((r & 255) * 64 + (c & 63)); }
; __device__ __forceinline__ u32x4 pack8(const f32x4 a, const f32x4 b) { u32x4 w; w.x = cvt_pk_bf16(a[0], a[1]); w.y = cvt_pk_bf16(a[2], a[3]); w.z = cvt_pk_bf16(b[0], b[1]); w.w = cvt_pk_bf16(b[2], b[3]); return w; }
;     __device__ __forceinline__ void operator()(const f32x4 (&acc)[2][2][4][2], const pg8::Unit& u, int wr, int wc, int fr, int fq) const {
;     ...
;                 for (int bj = 0; bj < 2; ++bj) { float* yp = Y + (size_t)row * D_ + col0 + bj * 128; f32x4 v[2];
; #pragma unroll
;                     for (int n = 0; n < 2; ++n) { v[n] = (((yv[bj][n] - mu) * rs) * gq[bj][n] + bq_[bj][n]) * ALPHA_ + acc[ai][bj][m][n] * sc;
;                         *(f32x4*)(yp + 4 * n) = v[n]; s1 += (v[n][0] + v[n][1]) + (v[n][2] + v[n][3]); s2 += (v[n][0] * v[n][0] + v[n][1] * v[n][1]) + (v[n][2] * v[n][2] + v[n][3] * v[n][3]); }
;                     *(u32x4*)(Yb + blk_off(row, col0 + bj * 128, D_)) = pack8(v[0], v[1]); }
;                 s1 = xsum32(xsum16(s1)); s2 = xsum32(xsum16(s2));
;                 if (fq == 0) *(f32x2*)(stn + (size_t)row * 32 + (u.pn * 4 + wc) * 2) = (f32x2){s1, s2}; asm volatile("" ::: "memory"); } }
	v_pk_fma_f32 v[44:45], v[64:65], v[44:45], v[68:69]
	v_pk_fma_f32 v[42:43], v[62:63], v[42:43], v[66:67]
	v_cvt_pk_bf16_f32 v37, v12, v13
	v_add_f32_e32 v13, v46, v47
	v_add_f32_e32 v10, 0, v11
	v_add_f32_e32 v11, v40, v41
	v_add_f32_e32 v12, v48, v49
	global_store_dwordx4 v[30:31], v[14:17], off
	v_cvt_pk_bf16_f32 v34, v14, v15
	v_cvt_pk_bf16_f32 v35, v16, v17
	v_add_f32_e32 v14, v10, v13
	v_add_f32_e32 v15, v11, v12
	v_pk_mul_f32 v[10:11], v[42:43], s[2:3] op_sel_hi:[1,0]
	v_pk_mul_f32 v[12:13], v[44:45], s[2:3] op_sel_hi:[1,0]
	v_pk_fma_f32 v[6:7], v[6:7], 0.5, v[10:11] op_sel_hi:[1,0,1]
	v_pk_fma_f32 v[8:9], v[8:9], 0.5, v[12:13] op_sel_hi:[1,0,1]
	v_add_f32_e32 v10, v6, v7
	v_add_f32_e32 v11, v8, v9
	v_add_f32_e32 v10, v10, v11
	v_add_f32_e32 v14, v14, v10
	v_mul_f32_e32 v10, v7, v7
	v_mul_f32_e32 v11, v9, v9
	v_fmac_f32_e32 v10, v6, v6
	v_fmac_f32_e32 v11, v8, v8
	v_add_f32_e32 v10, v10, v11
	v_add_f32_e32 v15, v15, v10
	s_waitcnt vmcnt(2)
	v_sub_f32_e32 v11, v29, v33
	v_sub_f32_e32 v10, v28, v33
	v_sub_f32_e32 v13, v27, v33
	v_sub_f32_e32 v12, v26, v33
	v_pk_mul_f32 v[12:13], v[32:33], v[12:13] op_sel_hi:[0,1]
	v_pk_mul_f32 v[10:11], v[32:33], v[10:11] op_sel_hi:[0,1]
	v_pk_fma_f32 v[10:11], v[20:21], v[10:11], v[24:25]
	v_pk_fma_f32 v[12:13], v[18:19], v[12:13], v[22:23]
	v_pk_mul_f32 v[10:11], v[10:11], s[2:3] op_sel_hi:[1,0]
	v_pk_mul_f32 v[12:13], v[12:13], s[2:3] op_sel_hi:[1,0]
	v_pk_fma_f32 v[4:5], v[4:5], 0.5, v[10:11] op_sel_hi:[1,0,1]
	v_pk_fma_f32 v[2:3], v[2:3], 0.5, v[12:13] op_sel_hi:[1,0,1]
	v_add_f32_e32 v11, v4, v5
	v_add_f32_e32 v10, v2, v3
	v_add_f32_e32 v10, v10, v11
	v_mul_f32_e32 v11, v3, v3
	v_mul_f32_e32 v12, v5, v5
	v_add_f32_e32 v10, v14, v10
	v_fmac_f32_e32 v11, v2, v2
	v_fmac_f32_e32 v12, v4, v4
	global_store_dwordx4 v[70:71], v[34:37], off
	s_nop 0
	s_nop 1
	v_bfe_u32 v17, v227, 4, 2
	v_sub_u32_e32 v16, 0, v17
	v_lshlrev_b32_e32 v16, 4, v16
	v_ashrrev_i32_e32 v17, 31, v16
	v_lshl_add_u64 v[16:17], v[30:31], 0, v[16:17]
	v_permlane16_swap_b32_e32 v6, v2
	v_permlane16_swap_b32_e32 v7, v3
	v_permlane16_swap_b32_e32 v8, v4
	v_permlane16_swap_b32_e32 v9, v5
	v_permlane32_swap_b32_e32 v6, v2
	v_permlane32_swap_b32_e32 v7, v3
	v_permlane32_swap_b32_e32 v8, v4
	v_permlane32_swap_b32_e32 v9, v5
	global_store_dwordx4 v[16:17], v[6:9], off offset:512
	global_store_dwordx4 v[16:17], v[2:5], off offset:576
	s_nop 1
	v_permlane32_swap_b32_e32 v6, v2
	v_permlane32_swap_b32_e32 v7, v3
	v_permlane32_swap_b32_e32 v8, v4
	v_permlane32_swap_b32_e32 v9, v5
	v_permlane16_swap_b32_e32 v6, v2
	v_permlane16_swap_b32_e32 v7, v3
	v_permlane16_swap_b32_e32 v8, v4
	v_permlane16_swap_b32_e32 v9, v5
	v_add_f32_e32 v11, v11, v12
	v_cvt_pk_bf16_f32 v6, v6, v7
	v_cvt_pk_bf16_f32 v7, v8, v9
	v_cvt_pk_bf16_f32 v8, v2, v3
	v_lshl_add_u64 v[2:3], v[78:79], 0, v[0:1]
	v_mov_b32_e32 v0, v10
	v_add_f32_e32 v11, v15, v11
	v_cvt_pk_bf16_f32 v9, v4, v5
	v_permlane16_swap_b32_e32 v10, v0
	global_store_dwordx4 v[2:3], v[6:9], off
	v_add_f32_e32 v2, v10, v0
	v_mov_b32_e32 v0, v11
	s_nop 1
	v_permlane16_swap_b32_e32 v11, v0
	v_add_f32_e32 v3, v11, v0
	v_mov_b32_e32 v4, v2
	v_mov_b32_e32 v5, v3
	s_nop 0
	v_permlane32_swap_b32_e32 v2, v4
	v_permlane32_swap_b32_e32 v3, v5
	s_and_saveexec_b64 s[26:27], s[44:45]
	s_cbranch_execz .LBB0_388
	v_pk_add_f32 v[2:3], v[2:3], v[4:5]
	v_lshlrev_b64 v[4:5], 7, v[74:75]
	v_lshl_add_u64 v[4:5], s[30:31], 0, v[4:5]
	v_lshl_add_u64 v[4:5], s[24:25], 2, v[4:5]
	global_store_dwordx2 v[4:5], v[2:3], off

; __device__ __forceinline__ float xsum16(float v) { const auto r = __builtin_amdgcn_permlane16_swap(__float_as_uint(v), __float_as_uint(v), false, false); return __uint_as_float(r[0]) + __uint_as_float(r[1]); }
; __device__ __forceinline__ float xsum32(float v) { const auto r = __builtin_amdgcn_permlane32_swap(__float_as_uint(v), __float_as_uint(v), false, false); return __uint_as_float(r[0]) + __uint_as_float(r[1]); }
; __device__ __forceinline__ void row_stats4(const float* st, int rowb, int fq, float (&mu)[4], float (&rs)[4]) {
;     f32x4 a[4], b[4];
; #pragma unroll
;     for (int m = 0; m < 4; ++m) { const f32x4* p = (const f32x4*)(st + (size_t)(rowb + m * 16) * 32 + fq * 8); a[m] = p[0]; b[m] = p[1]; }
; #pragma unroll
;     for (int m = 0; m < 4; ++m) { float s1 = (a[m][0] + a[m][2]) + (b[m][0] + b[m][2]), s2 = (a[m][1] + a[m][3]) + (b[m][1] + b[m][3]);
;         s1 = xsum32(xsum16(s1)); s2 = xsum32(xsum16(s2));
;         const float mm = s1 * (1.0f / 1024.0f); mu[m] = mm; rs[m] = rsqrtf(fmaxf(s2 * (1.0f / 1024.0f) - mm * mm, 0.f) + LN_EPS_); }
;     __device__ __forceinline__ void operator()(const f32x4 (&acc)[2][2][4][2], const pg8::Unit& u, int wr, int wc, int fr, int fq) const {
;     ...
;         for (int ai = 0; ai < 2; ++ai) { float mu4[4], rs4[4]; row_stats4(stp, row0 + ai * 128, fq, mu4, rs4);
; #pragma unroll
;             for (int m = 0; m < 4; ++m) { const int row = row0 + ai * 128 + m * 16; const float mu = mu4[m], rs = rs4[m];
;                 f32x4 yv[2][2], gq[2][2], bq_[2][2];
; #pragma unroll
;                 for (int bj = 0; bj < 2; ++bj)
; #pragma unroll
;                     for (int n = 0; n < 2; ++n) { yv[bj][n] = *(const f32x4*)(Yin + (size_t)row * D_ + col0 + bj * 128 + 4 * n); gq[bj][n] = *(const f32x4*)(g + col0 + bj * 128 + 4 * n); bq_[bj][n] = *(const f32x4*)(b + col0 + bj * 128 + 4 * n); }
.LBB0_1535:
	s_lshl_b32 s3, s3, 8
	s_add_i32 s3, s3, s0
	v_or_b32_e32 v158, s3, v184
	v_ashrrev_i32_e32 v159, 31, v158
	v_lshlrev_b64 v[130:131], 7, v[158:159]
	v_lshl_add_u64 v[136:137], v[146:147], 0, v[130:131]
	v_or_b32_e32 v180, 16, v158
	s_nop 1
	v_bfe_u32 v153, v227, 4, 2
	v_sub_u32_e32 v152, 0, v153
	v_lshlrev_b32_e32 v152, 4, v152
	v_ashrrev_i32_e32 v153, 31, v152
	v_lshl_add_u64 v[152:153], v[136:137], 0, v[152:153]
	global_load_dwordx4 v[132:135], v[152:153], off
	global_load_dwordx4 v[166:169], v[152:153], off offset:64
	v_ashrrev_i32_e32 v181, 31, v180
	v_lshlrev_b64 v[172:173], 7, v[180:181]
	v_lshl_add_u64 v[136:137], v[146:147], 0, v[172:173]
	s_nop 1
	v_bfe_u32 v153, v227, 4, 2
	v_sub_u32_e32 v152, 0, v153
	v_lshlrev_b32_e32 v152, 4, v152
	v_ashrrev_i32_e32 v153, 31, v152
	v_lshl_add_u64 v[152:153], v[136:137], 0, v[152:153]
	global_load_dwordx4 v[174:177], v[152:153], off
	global_load_dwordx4 v[186:189], v[152:153], off offset:64
	v_or_b32_e32 v170, 32, v158
	v_ashrrev_i32_e32 v171, 31, v170
	v_lshlrev_b64 v[164:165], 7, v[170:171]
	v_lshl_add_u64 v[136:137], v[146:147], 0, v[164:165]
	s_nop 1
	v_bfe_u32 v153, v227, 4, 2
	v_sub_u32_e32 v152, 0, v153
	v_lshlrev_b32_e32 v152, 4, v152
	v_ashrrev_i32_e32 v153, 31, v152
	v_lshl_add_u64 v[152:153], v[136:137], 0, v[152:153]
	global_load_dwordx4 v[190:193], v[152:153], off
	global_load_dwordx4 v[198:201], v[152:153], off offset:64
	v_or_b32_e32 v162, 48, v158
	v_ashrrev_i32_e32 v163, 31, v162
	v_lshlrev_b64 v[160:161], 7, v[162:163]
	v_lshl_add_u64 v[182:183], v[146:147], 0, v[160:161]
	s_nop 1
	v_bfe_u32 v137, v227, 4, 2
	v_sub_u32_e32 v136, 0, v137
	v_lshlrev_b32_e32 v136, 4, v136
	v_ashrrev_i32_e32 v137, 31, v136
	v_lshl_add_u64 v[136:137], v[182:183], 0, v[136:137]
	global_load_dwordx4 v[202:205], v[136:137], off
	global_load_dwordx4 v[206:209], v[136:137], off offset:64
	s_load_dwordx16 s[64:79], s[34:35], 0x38
	s_lshl_b32 s1, s2, 8
	s_lshl_b32 s14, s2, 3
	s_or_b32 s2, s1, s57
	v_or_b32_e32 v152, s2, v185
	v_ashrrev_i32_e32 v153, 31, v152
	v_lshlrev_b64 v[136:137], 12, v[158:159]
	v_lshlrev_b64 v[178:179], 2, v[152:153]
	s_waitcnt lgkmcnt(0)
	v_lshl_add_u64 v[136:137], s[78:79], 0, v[136:137]
	v_lshl_add_u64 v[156:157], s[8:9], 0, v[178:179]
	v_lshl_add_u64 v[154:155], s[10:11], 0, v[178:179]
	v_lshl_add_u64 v[136:137], v[136:137], 0, v[178:179]
	s_or_b32 s52, s14, s61
	s_mov_b32 s14, 0x3a800000
	s_nop 1
	v_bfe_u32 v179, v227, 4, 2
	v_sub_u32_e32 v178, 0, v179
	v_lshlrev_b32_e32 v178, 4, v178
	v_ashrrev_i32_e32 v179, 31, v178
	v_lshl_add_u64 v[178:179], v[136:137], 0, v[178:179]
	global_load_dwordx4 v[210:213], v[178:179], off offset:64
	global_load_dwordx4 v[214:217], v[178:179], off
	global_load_dwordx4 v[218:221], v[156:157], off offset:16
	global_load_dwordx4 v[222:225], v[156:157], off
	global_load_dwordx4 v[234:237], v[154:155], off offset:16
	global_load_dwordx4 v[238:241], v[154:155], off
	s_mov_b32 s1, 0x800000
	s_mov_b32 s18, 0x3fd744fd
	v_bitop3_b32 v196, s2, 56, v185 bitop3:0xc8
	s_ashr_i32 s2, s2, 6
	s_ashr_i32 s53, s52, 31
	v_readlane_b32 s16, v253, 59
	v_readlane_b32 s17, v253, 60
	s_waitcnt vmcnt(12)
	v_permlane32_swap_b32_e32 v132, v166
	v_permlane32_swap_b32_e32 v133, v167
	v_permlane32_swap_b32_e32 v134, v168
	v_permlane32_swap_b32_e32 v135, v169
	v_permlane16_swap_b32_e32 v132, v166
	v_permlane16_swap_b32_e32 v133, v167
	v_permlane16_swap_b32_e32 v134, v168
	v_permlane16_swap_b32_e32 v135, v169
	v_mov_b32_e32 v178, v132
	v_mov_b32_e32 v179, v166
	v_mov_b32_e32 v182, v134
	v_mov_b32_e32 v183, v168
	v_mov_b32_e32 v166, v133
	v_mov_b32_e32 v168, v135
	v_pk_add_f32 v[132:133], v[178:179], v[182:183]
	v_pk_add_f32 v[134:135], v[166:167], v[168:169]
	v_pk_add_f32 v[132:133], v[132:133], v[132:133] op_sel:[0,1] op_sel_hi:[1,0]
	v_pk_add_f32 v[134:135], v[134:135], v[134:135] op_sel:[0,1] op_sel_hi:[1,0]
	s_waitcnt vmcnt(10)
	v_permlane32_swap_b32_e32 v174, v186
	v_permlane32_swap_b32_e32 v175, v187
	v_permlane32_swap_b32_e32 v176, v188
	v_permlane32_swap_b32_e32 v177, v189
	v_permlane16_swap_b32_e32 v174, v186
	v_permlane16_swap_b32_e32 v175, v187
	v_permlane16_swap_b32_e32 v176, v188
	v_permlane16_swap_b32_e32 v177, v189
	v_mov_b32_e32 v166, v174
	v_mov_b32_e32 v167, v186
	v_mov_b32_e32 v168, v176
	v_mov_b32_e32 v169, v188
	v_mov_b32_e32 v0, v132
	v_mov_b32_e32 v133, v134
	v_pk_add_f32 v[166:167], v[166:167], v[168:169]
	v_permlane16_swap_b32_e32 v132, v0
	v_permlane16_swap_b32_e32 v134, v133
	v_mov_b32_e32 v188, v177
	v_pk_add_f32 v[166:167], v[166:167], v[166:167] op_sel:[0,1] op_sel_hi:[1,0]
	v_add_f32_e32 v177, v132, v0
	v_add_f32_e32 v176, v134, v133
	v_mov_b32_e32 v135, v166
	v_mov_b32_e32 v179, v177
	v_mov_b32_e32 v178, v176
	v_permlane16_swap_b32_e32 v166, v135
	v_permlane32_swap_b32_e32 v177, v179
	v_permlane32_swap_b32_e32 v176, v178
	v_mov_b32_e32 v186, v175
	v_add_f32_e32 v133, v166, v135
	v_pk_add_f32 v[166:167], v[176:177], v[178:179]
	v_pk_add_f32 v[168:169], v[186:187], v[188:189]
	v_pk_mul_f32 v[178:179], v[166:167], s[14:15] op_sel_hi:[1,0]
	v_pk_add_f32 v[168:169], v[168:169], v[168:169] op_sel:[0,1] op_sel_hi:[1,0]
	v_fma_f32 v0, -v179, v179, v178
	v_mov_b32_e32 v159, v168
	v_max_f32_e32 v0, 0, v0
	s_nop 0
	v_permlane16_swap_b32_e32 v168, v159
	v_add_f32_e32 v0, 0x3727c5ac, v0
	v_add_f32_e32 v132, v168, v159
	v_mul_f32_e32 v159, 0x4b800000, v0
	v_cmp_gt_f32_e32 vcc, s1, v0
	s_waitcnt vmcnt(8)
; __device__ __forceinline__ float xsum16(float v) { const auto r = __builtin_amdgcn_permlane16_swap(__float_as_uint(v), __float_as_uint(v), false, false); return __uint_as_float(r[0]) + __uint_as_float(r[1]); }
; __device__ __forceinline__ float xsum32(float v) { const auto r = __builtin_amdgcn_permlane32_swap(__float_as_uint(v), __float_as_uint(v), false, false); return __uint_as_float(r[0]) + __uint_as_float(r[1]); }
; __device__ __forceinline__ size_t blk_off(int r, int c, int K) { return (size_t)(r >> 8) * 256 * K + (size_t)(c >> 6) * (256 * 64) + (size_t)((r & 255) * 64 + (c & 63)); }
; __device__ __forceinline__ void row_stats4(const float* st, int rowb, int fq, float (&mu)[4], float (&rs)[4]) {
;     f32x4 a[4], b[4];
; #pragma unroll
;     for (int m = 0; m < 4; ++m) { const f32x4* p = (const f32x4*)(st + (size_t)(rowb + m * 16) * 32 + fq * 8); a[m] = p[0]; b[m] = p[1]; }
; #pragma unroll
;     for (int m = 0; m < 4; ++m) { float s1 = (a[m][0] + a[m][2]) + (b[m][0] + b[m][2]), s2 = (a[m][1] + a[m][3]) + (b[m][1] + b[m][3]);
;         s1 = xsum32(xsum16(s1)); s2 = xsum32(xsum16(s2));
;         const float mm = s1 * (1.0f / 1024.0f); mu[m] = mm; rs[m] = rsqrtf(fmaxf(s2 * (1.0f / 1024.0f) - mm * mm, 0.f) + LN_EPS_); }
;     __device__ __forceinline__ void operator()(const f32x4 (&acc)[2][2][4][2], const pg8::Unit& u, int wr, int wc, int fr, int fq) const {
;     ...
;                     for (int n = 0; n < 2; ++n) { yv[bj][n] = *(const f32x4*)(Yin + (size_t)row * D_ + col0 + bj * 128 + 4 * n); gq[bj][n] = *(const f32x4*)(g + col0 + bj * 128 + 4 * n); bq_[bj][n] = *(const f32x4*)(b + col0 + bj * 128 + 4 * n); }
;                 asm volatile("" ::: "memory");
;                 float s1 = 0.f, s2 = 0.f;
; #pragma unroll
;                 for (int bj = 0; bj < 2; ++bj) { float* yp = Y + (size_t)row * D_ + col0 + bj * 128; f32x4 v[2];
; #pragma unroll
;                     for (int n = 0; n < 2; ++n) { v[n] = (((yv[bj][n] - mu) * rs) * gq[bj][n] + bq_[bj][n]) * ALPHA_ + acc[ai][bj][m][n] * sc;
;                         *(f32x4*)(yp + 4 * n) = v[n]; s1 += (v[n][0] + v[n][1]) + (v[n][2] + v[n][3]); s2 += (v[n][0] * v[n][0] + v[n][1] * v[n][1]) + (v[n][2] * v[n][2] + v[n][3] * v[n][3]); }
;                     *(u32x4*)(Yb + blk_off(row, col0 + bj * 128, D_)) = pack8(v[0], v[1]); }
	v_permlane32_swap_b32_e32 v190, v198
	v_permlane32_swap_b32_e32 v191, v199
	v_permlane32_swap_b32_e32 v192, v200
	v_permlane32_swap_b32_e32 v193, v201
	v_permlane16_swap_b32_e32 v190, v198
	v_permlane16_swap_b32_e32 v191, v199
	v_permlane16_swap_b32_e32 v192, v200
	v_permlane16_swap_b32_e32 v193, v201
	v_mov_b32_e32 v174, v190
	v_mov_b32_e32 v175, v198
	v_cndmask_b32_e32 v0, v0, v159, vcc
	v_rsq_f32_e32 v0, v0
	v_mov_b32_e32 v166, v192
	v_mov_b32_e32 v167, v200
	v_pk_add_f32 v[166:167], v[174:175], v[166:167]
	v_mul_f32_e32 v159, 0x45800000, v0
	v_pk_add_f32 v[166:167], v[166:167], v[166:167] op_sel:[0,1] op_sel_hi:[1,0]
	v_mov_b32_e32 v198, v191
	v_mov_b32_e32 v200, v193
	v_cndmask_b32_e32 v0, v0, v159, vcc
	v_pk_add_f32 v[168:169], v[198:199], v[200:201]
	v_mov_b32_e32 v159, v166
	v_pk_add_f32 v[168:169], v[168:169], v[168:169] op_sel:[0,1] op_sel_hi:[1,0]
	s_nop 0
	v_permlane16_swap_b32_e32 v166, v159
	v_add_f32_e32 v175, v166, v159
	v_mov_b32_e32 v159, v168
	s_nop 1
	v_permlane16_swap_b32_e32 v168, v159
	s_nop 1
	v_bfe_u32 v135, v227, 4, 2
	v_sub_u32_e32 v134, 0, v135
	v_lshlrev_b32_e32 v134, 4, v134
	v_ashrrev_i32_e32 v135, 31, v134
	v_lshl_add_u64 v[134:135], v[136:137], 0, v[134:135]
	global_load_dwordx4 v[186:189], v[134:135], off offset:576
	global_load_dwordx4 v[190:193], v[134:135], off offset:512
	v_add_f32_e32 v174, v168, v159
	s_waitcnt vmcnt(8)
	v_permlane32_swap_b32_e32 v202, v206
	v_permlane32_swap_b32_e32 v203, v207
	v_permlane32_swap_b32_e32 v204, v208
	v_permlane32_swap_b32_e32 v205, v209
	v_permlane16_swap_b32_e32 v202, v206
	v_permlane16_swap_b32_e32 v203, v207
	v_permlane16_swap_b32_e32 v204, v208
	v_permlane16_swap_b32_e32 v205, v209
	v_mov_b32_e32 v166, v202
	v_mov_b32_e32 v167, v206
	v_mov_b32_e32 v168, v204
	v_mov_b32_e32 v169, v208
	v_mov_b32_e32 v206, v203
	v_mov_b32_e32 v208, v205
	v_pk_add_f32 v[166:167], v[166:167], v[168:169]
	v_pk_add_f32 v[168:169], v[206:207], v[208:209]
	global_load_dwordx4 v[198:201], v[156:157], off offset:528
	global_load_dwordx4 v[202:205], v[156:157], off offset:512
	global_load_dwordx4 v[206:209], v[154:155], off offset:528
	global_load_dwordx4 v[242:245], v[154:155], off offset:512
	s_waitcnt vmcnt(10)
	v_permlane32_swap_b32_e32 v214, v210
	v_permlane32_swap_b32_e32 v215, v211
	v_permlane32_swap_b32_e32 v216, v212
	v_permlane32_swap_b32_e32 v217, v213
	v_permlane16_swap_b32_e32 v214, v210
	v_permlane16_swap_b32_e32 v215, v211
	v_permlane16_swap_b32_e32 v216, v212
	v_permlane16_swap_b32_e32 v217, v213
	v_sub_f32_e32 v183, v215, v179
	v_sub_f32_e32 v182, v214, v179
	v_sub_f32_e32 v215, v217, v179
	v_sub_f32_e32 v214, v216, v179
	v_pk_mul_f32 v[214:215], v[0:1], v[214:215] op_sel_hi:[0,1]
	v_pk_mul_f32 v[182:183], v[0:1], v[182:183] op_sel_hi:[0,1]
	s_waitcnt vmcnt(6)
	v_pk_fma_f32 v[182:183], v[222:223], v[182:183], v[238:239]
	v_pk_fma_f32 v[214:215], v[224:225], v[214:215], v[240:241]
	v_pk_fma_f32 v[126:127], v[182:183], s[18:19], v[126:127] op_sel_hi:[1,0,1]
	v_pk_fma_f32 v[128:129], v[214:215], s[18:19], v[128:129] op_sel_hi:[1,0,1]
	v_add_f32_e32 v178, v126, v127
	v_add_f32_e32 v182, v128, v129
	v_add_f32_e32 v178, v178, v182
	v_mul_f32_e32 v182, v127, v127
	v_mul_f32_e32 v183, v129, v129
	v_fmac_f32_e32 v182, v126, v126
	v_fmac_f32_e32 v183, v128, v128
	v_add_f32_e32 v197, v182, v183
	v_sub_f32_e32 v183, v211, v179
	v_sub_f32_e32 v182, v210, v179
	v_sub_f32_e32 v211, v213, v179
	v_sub_f32_e32 v210, v212, v179
	v_pk_mul_f32 v[210:211], v[0:1], v[210:211] op_sel_hi:[0,1]
	v_pk_mul_f32 v[182:183], v[0:1], v[182:183] op_sel_hi:[0,1]
	v_pk_fma_f32 v[182:183], v[218:219], v[182:183], v[234:235]
	v_pk_fma_f32 v[210:211], v[220:221], v[210:211], v[236:237]
	v_pk_add_f32 v[166:167], v[166:167], v[166:167] op_sel:[0,1] op_sel_hi:[1,0]
	v_pk_fma_f32 v[124:125], v[210:211], s[18:19], v[124:125] op_sel_hi:[1,0,1]
	v_pk_fma_f32 v[122:123], v[182:183], s[18:19], v[122:123] op_sel_hi:[1,0,1]
	v_mov_b32_e32 v159, v166
	v_add_f32_e32 v182, v122, v123
	v_add_f32_e32 v183, v124, v125
	v_pk_add_f32 v[168:169], v[168:169], v[168:169] op_sel:[0,1] op_sel_hi:[1,0]
	v_permlane16_swap_b32_e32 v166, v159
	v_add_f32_e32 v178, 0, v178
	v_add_f32_e32 v182, v182, v183
	v_add_f32_e32 v167, v166, v159
	v_mov_b32_e32 v159, v168
	s_ashr_i32 s14, s3, 8
	v_add_f32_e32 v178, v178, v182
	v_mul_f32_e32 v182, v123, v123
	v_mul_f32_e32 v183, v125, v125
	v_permlane16_swap_b32_e32 v168, v159
	s_ashr_i32 s15, s14, 31
	s_nop 0
	s_nop 1
	v_bfe_u32 v135, v227, 4, 2
	v_sub_u32_e32 v134, 0, v135
	v_lshlrev_b32_e32 v134, 4, v134
	v_ashrrev_i32_e32 v135, 31, v134
	v_lshl_add_u64 v[134:135], v[136:137], 0, v[134:135]
	v_permlane16_swap_b32_e32 v126, v122
	v_permlane16_swap_b32_e32 v127, v123
	v_permlane16_swap_b32_e32 v128, v124
	v_permlane16_swap_b32_e32 v129, v125
	v_permlane32_swap_b32_e32 v126, v122
	v_permlane32_swap_b32_e32 v127, v123
	v_permlane32_swap_b32_e32 v128, v124
	v_permlane32_swap_b32_e32 v129, v125
	global_store_dwordx4 v[134:135], v[126:129], off
	global_store_dwordx4 v[134:135], v[122:125], off offset:64
	s_nop 1
	v_permlane32_swap_b32_e32 v126, v122
	v_permlane32_swap_b32_e32 v127, v123
	v_permlane32_swap_b32_e32 v128, v124
	v_permlane32_swap_b32_e32 v129, v125
	v_permlane16_swap_b32_e32 v126, v122
	v_permlane16_swap_b32_e32 v127, v123
	v_permlane16_swap_b32_e32 v128, v124
	v_permlane16_swap_b32_e32 v129, v125
	v_fmac_f32_e32 v182, v122, v122
	v_fmac_f32_e32 v183, v124, v124
	v_cvt_pk_bf16_f32 v126, v126, v127
	v_cvt_pk_bf16_f32 v127, v128, v129
	v_cvt_pk_bf16_f32 v128, v122, v123
	v_cvt_pk_bf16_f32 v129, v124, v125
	v_add_f32_e32 v166, v168, v159
	s_lshl_b64 s[14:15], s[14:15], 19
	v_lshlrev_b32_e32 v159, 6, v158
	s_movk_i32 s1, 0x33c0
	s_ashr_i32 s3, s2, 31
	v_and_or_b32 v159, v159, s1, v196
	s_add_u32 s1, s16, s14
	s_addc_u32 s14, s17, s15
	s_lshl_b64 s[24:25], s[2:3], 15
	s_add_u32 s42, s1, s24
	s_addc_u32 s43, s14, s25
	v_lshlrev_b32_e32 v159, 1, v159
	global_store_dwordx4 v159, v[126:129], s[42:43]
	v_add_f32_e32 v182, v182, v183
	s_waitcnt vmcnt(7)
; __device__ __forceinline__ float xsum16(float v) { const auto r = __builtin_amdgcn_permlane16_swap(__float_as_uint(v), __float_as_uint(v), false, false); return __uint_as_float(r[0]) + __uint_as_float(r[1]); }
; __device__ __forceinline__ float xsum32(float v) { const auto r = __builtin_amdgcn_permlane32_swap(__float_as_uint(v), __float_as_uint(v), false, false); return __uint_as_float(r[0]) + __uint_as_float(r[1]); }
; __device__ __forceinline__ size_t blk_off(int r, int c, int K) { return (size_t)(r >> 8) * 256 * K + (size_t)(c >> 6) * (256 * 64) + (size_t)((r & 255) * 64 + (c & 63)); }
; __device__ __forceinline__ u32x4 pack8(const f32x4 a, const f32x4 b) { u32x4 w; w.x = cvt_pk_bf16(a[0], a[1]); w.y = cvt_pk_bf16(a[2], a[3]); w.z = cvt_pk_bf16(b[0], b[1]); w.w = cvt_pk_bf16(b[2], b[3]); return w; }
;     __device__ __forceinline__ void operator()(const f32x4 (&acc)[2][2][4][2], const pg8::Unit& u, int wr, int wc, int fr, int fq) const {
;     ...
;                 for (int bj = 0; bj < 2; ++bj) { float* yp = Y + (size_t)row * D_ + col0 + bj * 128; f32x4 v[2];
; #pragma unroll
;                     for (int n = 0; n < 2; ++n) { v[n] = (((yv[bj][n] - mu) * rs) * gq[bj][n] + bq_[bj][n]) * ALPHA_ + acc[ai][bj][m][n] * sc;
;                         *(f32x4*)(yp + 4 * n) = v[n]; s1 += (v[n][0] + v[n][1]) + (v[n][2] + v[n][3]); s2 += (v[n][0] * v[n][0] + v[n][1] * v[n][1]) + (v[n][2] * v[n][2] + v[n][3] * v[n][3]); }
;                     *(u32x4*)(Yb + blk_off(row, col0 + bj * 128, D_)) = pack8(v[0], v[1]); }
;                 s1 = xsum32(xsum16(s1)); s2 = xsum32(xsum16(s2));
;                 if (fq == 0) *(f32x2*)(stn + (size_t)row * 32 + (u.pn * 4 + wc) * 2) = (f32x2){s1, s2}; asm volatile("" ::: "memory"); } }
	v_permlane32_swap_b32_e32 v190, v186
	v_permlane32_swap_b32_e32 v191, v187
	v_permlane32_swap_b32_e32 v192, v188
	v_permlane32_swap_b32_e32 v193, v189
	v_permlane16_swap_b32_e32 v190, v186
	v_permlane16_swap_b32_e32 v191, v187
	v_permlane16_swap_b32_e32 v192, v188
	v_permlane16_swap_b32_e32 v193, v189
	v_sub_f32_e32 v123, v191, v179
	v_sub_f32_e32 v122, v190, v179
	v_sub_f32_e32 v125, v193, v179
	v_sub_f32_e32 v124, v192, v179
	v_pk_mul_f32 v[124:125], v[0:1], v[124:125] op_sel_hi:[0,1]
	v_pk_mul_f32 v[122:123], v[0:1], v[122:123] op_sel_hi:[0,1]
	v_add_f32_e32 v182, v197, v182
	s_or_b32 s2, s2, 2
	s_ashr_i32 s3, s2, 31
	s_lshl_b64 s[28:29], s[2:3], 15
	s_waitcnt vmcnt(3)
	v_pk_fma_f32 v[122:123], v[202:203], v[122:123], v[242:243]
	v_pk_fma_f32 v[124:125], v[204:205], v[124:125], v[244:245]
	v_pk_fma_f32 v[118:119], v[122:123], s[18:19], v[118:119] op_sel_hi:[1,0,1]
	v_pk_fma_f32 v[120:121], v[124:125], s[18:19], v[120:121] op_sel_hi:[1,0,1]
	v_add_f32_e32 v122, v118, v119
	v_add_f32_e32 v123, v120, v121
	v_add_f32_e32 v122, v122, v123
	v_add_f32_e32 v126, v178, v122
	v_mul_f32_e32 v122, v119, v119
	v_mul_f32_e32 v123, v121, v121
	v_fmac_f32_e32 v122, v118, v118
	v_fmac_f32_e32 v123, v120, v120
	v_add_f32_e32 v122, v122, v123
	v_add_f32_e32 v127, v182, v122
	v_sub_f32_e32 v123, v187, v179
	v_sub_f32_e32 v122, v186, v179
	v_sub_f32_e32 v125, v189, v179
	v_sub_f32_e32 v124, v188, v179
	v_pk_mul_f32 v[124:125], v[0:1], v[124:125] op_sel_hi:[0,1]
	v_pk_mul_f32 v[122:123], v[0:1], v[122:123] op_sel_hi:[0,1]
	v_pk_fma_f32 v[122:123], v[198:199], v[122:123], v[206:207]
	v_pk_fma_f32 v[124:125], v[200:201], v[124:125], v[208:209]
	v_pk_fma_f32 v[114:115], v[122:123], s[18:19], v[114:115] op_sel_hi:[1,0,1]
	v_pk_fma_f32 v[116:117], v[124:125], s[18:19], v[116:117] op_sel_hi:[1,0,1]
	v_add_f32_e32 v0, v114, v115
	v_add_f32_e32 v122, v116, v117
	v_add_f32_e32 v0, v0, v122
	v_mul_f32_e32 v122, v115, v115
	v_mul_f32_e32 v123, v117, v117
	v_add_f32_e32 v0, v126, v0
	v_fmac_f32_e32 v122, v114, v114
	v_fmac_f32_e32 v123, v116, v116
	s_nop 0
	s_nop 1
	v_bfe_u32 v125, v227, 4, 2
	v_sub_u32_e32 v124, 0, v125
	v_lshlrev_b32_e32 v124, 4, v124
	v_ashrrev_i32_e32 v125, 31, v124
	v_lshl_add_u64 v[124:125], v[136:137], 0, v[124:125]
	v_permlane16_swap_b32_e32 v118, v114
	v_permlane16_swap_b32_e32 v119, v115
	v_permlane16_swap_b32_e32 v120, v116
	v_permlane16_swap_b32_e32 v121, v117
	v_permlane32_swap_b32_e32 v118, v114
	v_permlane32_swap_b32_e32 v119, v115
	v_permlane32_swap_b32_e32 v120, v116
	v_permlane32_swap_b32_e32 v121, v117
	global_store_dwordx4 v[124:125], v[118:121], off offset:512
	global_store_dwordx4 v[124:125], v[114:117], off offset:576
	s_nop 1
	v_permlane32_swap_b32_e32 v118, v114
	v_permlane32_swap_b32_e32 v119, v115
	v_permlane32_swap_b32_e32 v120, v116
	v_permlane32_swap_b32_e32 v121, v117
	v_permlane16_swap_b32_e32 v118, v114
	v_permlane16_swap_b32_e32 v119, v115
	v_permlane16_swap_b32_e32 v120, v116
	v_permlane16_swap_b32_e32 v121, v117
	v_add_f32_e32 v122, v122, v123
	v_cvt_pk_bf16_f32 v118, v118, v119
	v_cvt_pk_bf16_f32 v119, v120, v121
	v_cvt_pk_bf16_f32 v120, v114, v115
	v_mov_b32_e32 v114, v0
	v_add_f32_e32 v122, v127, v122
	s_nop 0
	v_permlane16_swap_b32_e32 v0, v114
	v_add_f32_e32 v114, v0, v114
	v_mov_b32_e32 v0, v122
	s_nop 1
	v_permlane16_swap_b32_e32 v122, v0
	v_add_f32_e32 v115, v122, v0
	v_mov_b32_e32 v135, v133
	v_mov_b32_e32 v134, v132
	v_mov_b32_e32 v177, v175
	v_mov_b32_e32 v176, v174
	v_mov_b32_e32 v169, v167
	v_mov_b32_e32 v168, v166
	v_cvt_pk_bf16_f32 v121, v116, v117
	s_add_u32 s40, s1, s28
	v_mov_b32_e32 v116, v114
	v_mov_b32_e32 v117, v115
	v_permlane32_swap_b32_e32 v133, v135
	v_permlane32_swap_b32_e32 v132, v134
	v_permlane32_swap_b32_e32 v175, v177
	v_permlane32_swap_b32_e32 v174, v176
	v_permlane32_swap_b32_e32 v167, v169
	v_permlane32_swap_b32_e32 v166, v168
	s_addc_u32 s41, s14, s29
	v_permlane32_swap_b32_e32 v114, v116
	v_permlane32_swap_b32_e32 v115, v117
	global_store_dwordx4 v159, v[118:121], s[40:41]
	s_and_saveexec_b64 s[26:27], s[44:45]
	s_cbranch_execz .LBB0_1537
	v_pk_add_f32 v[114:115], v[114:115], v[116:117]
	v_lshl_add_u64 v[116:117], s[6:7], 0, v[130:131]
	v_lshl_add_u64 v[116:117], s[52:53], 2, v[116:117]
	global_store_dwordx2 v[116:117], v[114:115], off
; __device__ __forceinline__ size_t blk_off(int r, int c, int K) { return (size_t)(r >> 8) * 256 * K + (size_t)(c >> 6) * (256 * 64) + (size_t)((r & 255) * 64 + (c & 63)); }
; __device__ __forceinline__ u32x4 pack8(const f32x4 a, const f32x4 b) { u32x4 w; w.x = cvt_pk_bf16(a[0], a[1]); w.y = cvt_pk_bf16(a[2], a[3]); w.z = cvt_pk_bf16(b[0], b[1]); w.w = cvt_pk_bf16(b[2], b[3]); return w; }
;     __device__ __forceinline__ void operator()(const f32x4 (&acc)[2][2][4][2], const pg8::Unit& u, int wr, int wc, int fr, int fq) const {
;     ...
;             for (int m = 0; m < 4; ++m) { const int row = row0 + ai * 128 + m * 16; const float mu = mu4[m], rs = rs4[m];
;                 f32x4 yv[2][2], gq[2][2], bq_[2][2];
; #pragma unroll
;                 for (int bj = 0; bj < 2; ++bj)
; #pragma unroll
;                     for (int n = 0; n < 2; ++n) { yv[bj][n] = *(const f32x4*)(Yin + (size_t)row * D_ + col0 + bj * 128 + 4 * n); gq[bj][n] = *(const f32x4*)(g + col0 + bj * 128 + 4 * n); bq_[bj][n] = *(const f32x4*)(b + col0 + bj * 128 + 4 * n); }
;                 asm volatile("" ::: "memory");
;                 float s1 = 0.f, s2 = 0.f;
; #pragma unroll
;                 for (int bj = 0; bj < 2; ++bj) { float* yp = Y + (size_t)row * D_ + col0 + bj * 128; f32x4 v[2];
; #pragma unroll
;                     for (int n = 0; n < 2; ++n) { v[n] = (((yv[bj][n] - mu) * rs) * gq[bj][n] + bq_[bj][n]) * ALPHA_ + acc[ai][bj][m][n] * sc;
;                         *(f32x4*)(yp + 4 * n) = v[n]; s1 += (v[n][0] + v[n][1]) + (v[n][2] + v[n][3]); s2 += (v[n][0] * v[n][0] + v[n][1] * v[n][1]) + (v[n][2] * v[n][2] + v[n][3] * v[n][3]); }
;                     *(u32x4*)(Yb + blk_off(row, col0 + bj * 128, D_)) = pack8(v[0], v[1]); }
.LBB0_1537:
	s_or_b64 exec, exec, s[26:27]
	v_pk_add_f32 v[114:115], v[132:133], v[134:135]
	s_mov_b32 s2, 0x3a800000
	v_pk_mul_f32 v[178:179], v[114:115], s[2:3] op_sel_hi:[1,0]
	s_mov_b32 s1, 0x800000
	v_fma_f32 v0, -v179, v179, v178
	v_max_f32_e32 v0, 0, v0
	v_add_f32_e32 v0, 0x3727c5ac, v0
	v_cmp_gt_f32_e32 vcc, s1, v0
	v_mul_f32_e32 v114, 0x4b800000, v0
	s_load_dwordx16 s[64:79], s[34:35], 0x38
	v_cndmask_b32_e32 v0, v0, v114, vcc
	v_rsq_f32_e32 v0, v0
	v_lshlrev_b32_e32 v159, 6, v180
	s_mov_b32 s2, 0x3fd744fd
	v_mul_f32_e32 v114, 0x45800000, v0
	v_cndmask_b32_e32 v0, v0, v114, vcc
	v_lshlrev_b64 v[114:115], 12, v[180:181]
	s_waitcnt lgkmcnt(0)
	v_lshl_add_u64 v[114:115], s[78:79], 0, v[114:115]
	v_lshl_add_u64 v[182:183], v[152:153], 2, v[114:115]
	s_nop 1
	v_bfe_u32 v117, v227, 4, 2
	v_sub_u32_e32 v116, 0, v117
	v_lshlrev_b32_e32 v116, 4, v116
	v_ashrrev_i32_e32 v117, 31, v116
	v_lshl_add_u64 v[116:117], v[182:183], 0, v[116:117]
	global_load_dwordx4 v[186:189], v[116:117], off offset:64
	global_load_dwordx4 v[190:193], v[116:117], off
	global_load_dwordx4 v[198:201], v[156:157], off offset:16
	global_load_dwordx4 v[202:205], v[156:157], off
	global_load_dwordx4 v[206:209], v[154:155], off offset:16
	global_load_dwordx4 v[210:213], v[154:155], off
	s_nop 1
	v_bfe_u32 v119, v227, 4, 2
	v_sub_u32_e32 v118, 0, v119
	v_lshlrev_b32_e32 v118, 4, v118
	v_ashrrev_i32_e32 v119, 31, v118
	v_lshl_add_u64 v[118:119], v[182:183], 0, v[118:119]
	global_load_dwordx4 v[114:117], v[118:119], off offset:576
	global_load_dwordx4 v[134:137], v[118:119], off offset:512
	global_load_dwordx4 v[118:121], v[156:157], off offset:528
	global_load_dwordx4 v[126:129], v[156:157], off offset:512
	global_load_dwordx4 v[122:125], v[154:155], off offset:528
	global_load_dwordx4 v[130:133], v[154:155], off offset:512
	s_movk_i32 s1, 0x37c0
	v_and_or_b32 v159, v159, s1, v196
	v_lshlrev_b32_e32 v159, 1, v159
	s_waitcnt vmcnt(10)
	v_permlane32_swap_b32_e32 v190, v186
	v_permlane32_swap_b32_e32 v191, v187
	v_permlane32_swap_b32_e32 v192, v188
	v_permlane32_swap_b32_e32 v193, v189
	v_permlane16_swap_b32_e32 v190, v186
	v_permlane16_swap_b32_e32 v191, v187
	v_permlane16_swap_b32_e32 v192, v188
	v_permlane16_swap_b32_e32 v193, v189
	v_sub_f32_e32 v181, v191, v179
	v_sub_f32_e32 v180, v190, v179
	v_sub_f32_e32 v191, v193, v179
	v_sub_f32_e32 v190, v192, v179
	v_pk_mul_f32 v[190:191], v[0:1], v[190:191] op_sel_hi:[0,1]
	v_pk_mul_f32 v[180:181], v[0:1], v[180:181] op_sel_hi:[0,1]
	s_waitcnt vmcnt(6)
	v_pk_fma_f32 v[180:181], v[202:203], v[180:181], v[210:211]
	v_pk_fma_f32 v[190:191], v[204:205], v[190:191], v[212:213]
	v_pk_fma_f32 v[110:111], v[180:181], s[2:3], v[110:111] op_sel_hi:[1,0,1]
	v_pk_fma_f32 v[112:113], v[190:191], s[2:3], v[112:113] op_sel_hi:[1,0,1]
	v_add_f32_e32 v178, v110, v111
	v_add_f32_e32 v180, v112, v113
	v_add_f32_e32 v178, v178, v180
	v_mul_f32_e32 v180, v111, v111
	v_mul_f32_e32 v181, v113, v113
	v_fmac_f32_e32 v180, v110, v110
	v_fmac_f32_e32 v181, v112, v112
	v_add_f32_e32 v190, v180, v181
	v_sub_f32_e32 v181, v187, v179
	v_sub_f32_e32 v180, v186, v179
	v_sub_f32_e32 v187, v189, v179
	v_sub_f32_e32 v186, v188, v179
	v_pk_mul_f32 v[186:187], v[0:1], v[186:187] op_sel_hi:[0,1]
	v_pk_mul_f32 v[180:181], v[0:1], v[180:181] op_sel_hi:[0,1]
	v_pk_fma_f32 v[180:181], v[198:199], v[180:181], v[206:207]
	v_pk_fma_f32 v[186:187], v[200:201], v[186:187], v[208:209]
	v_pk_fma_f32 v[106:107], v[180:181], s[2:3], v[106:107] op_sel_hi:[1,0,1]
	v_pk_fma_f32 v[108:109], v[186:187], s[2:3], v[108:109] op_sel_hi:[1,0,1]
	v_add_f32_e32 v180, v106, v107
	v_add_f32_e32 v181, v108, v109
	v_add_f32_e32 v178, 0, v178
	v_add_f32_e32 v180, v180, v181
	v_add_f32_e32 v178, v178, v180
	v_mul_f32_e32 v180, v107, v107
	v_mul_f32_e32 v181, v109, v109
	s_nop 0
	s_nop 1
	v_bfe_u32 v187, v227, 4, 2
	v_sub_u32_e32 v186, 0, v187
	v_lshlrev_b32_e32 v186, 4, v186
	v_ashrrev_i32_e32 v187, 31, v186
	v_lshl_add_u64 v[186:187], v[182:183], 0, v[186:187]
	v_permlane16_swap_b32_e32 v110, v106
	v_permlane16_swap_b32_e32 v111, v107
	v_permlane16_swap_b32_e32 v112, v108
	v_permlane16_swap_b32_e32 v113, v109
	v_permlane32_swap_b32_e32 v110, v106
	v_permlane32_swap_b32_e32 v111, v107
	v_permlane32_swap_b32_e32 v112, v108
	v_permlane32_swap_b32_e32 v113, v109
	global_store_dwordx4 v[186:187], v[110:113], off
	global_store_dwordx4 v[186:187], v[106:109], off offset:64
	s_nop 1
	v_permlane32_swap_b32_e32 v110, v106
	v_permlane32_swap_b32_e32 v111, v107
	v_permlane32_swap_b32_e32 v112, v108
	v_permlane32_swap_b32_e32 v113, v109
	v_permlane16_swap_b32_e32 v110, v106
	v_permlane16_swap_b32_e32 v111, v107
	v_permlane16_swap_b32_e32 v112, v108
	v_permlane16_swap_b32_e32 v113, v109
	v_fmac_f32_e32 v180, v106, v106
	v_fmac_f32_e32 v181, v108, v108
	v_cvt_pk_bf16_f32 v110, v110, v111
	v_cvt_pk_bf16_f32 v111, v112, v113
	v_cvt_pk_bf16_f32 v112, v106, v107
	v_cvt_pk_bf16_f32 v113, v108, v109
	s_waitcnt vmcnt(6)
	v_permlane32_swap_b32_e32 v134, v114
	v_permlane32_swap_b32_e32 v135, v115
	v_permlane32_swap_b32_e32 v136, v116
	v_permlane32_swap_b32_e32 v137, v117
	v_permlane16_swap_b32_e32 v134, v114
	v_permlane16_swap_b32_e32 v135, v115
	v_permlane16_swap_b32_e32 v136, v116
	v_permlane16_swap_b32_e32 v137, v117
	v_sub_f32_e32 v107, v135, v179
	v_sub_f32_e32 v106, v134, v179
	v_sub_f32_e32 v109, v137, v179
	v_sub_f32_e32 v108, v136, v179
	v_pk_mul_f32 v[108:109], v[0:1], v[108:109] op_sel_hi:[0,1]
	v_pk_mul_f32 v[106:107], v[0:1], v[106:107] op_sel_hi:[0,1]
	s_waitcnt vmcnt(2)
; __device__ __forceinline__ float xsum16(float v) { const auto r = __builtin_amdgcn_permlane16_swap(__float_as_uint(v), __float_as_uint(v), false, false); return __uint_as_float(r[0]) + __uint_as_float(r[1]); }
; __device__ __forceinline__ float xsum32(float v) { const auto r = __builtin_amdgcn_permlane32_swap(__float_as_uint(v), __float_as_uint(v), false, false); return __uint_as_float(r[0]) + __uint_as_float(r[1]); }
; __device__ __forceinline__ size_t blk_off(int r, int c, int K) { return (size_t)(r >> 8) * 256 * K + (size_t)(c >> 6) * (256 * 64) + (size_t)((r & 255) * 64 + (c & 63)); }
; __device__ __forceinline__ u32x4 pack8(const f32x4 a, const f32x4 b) { u32x4 w; w.x = cvt_pk_bf16(a[0], a[1]); w.y = cvt_pk_bf16(a[2], a[3]); w.z = cvt_pk_bf16(b[0], b[1]); w.w = cvt_pk_bf16(b[2], b[3]); return w; }
;     __device__ __forceinline__ void operator()(const f32x4 (&acc)[2][2][4][2], const pg8::Unit& u, int wr, int wc, int fr, int fq) const {
;     ...
;             for (int m = 0; m < 4; ++m) { const int row = row0 + ai * 128 + m * 16; const float mu = mu4[m], rs = rs4[m];
;                 f32x4 yv[2][2], gq[2][2], bq_[2][2];
; #pragma unroll
;                 for (int bj = 0; bj < 2; ++bj)
; #pragma unroll
;                     for (int n = 0; n < 2; ++n) { yv[bj][n] = *(const f32x4*)(Yin + (size_t)row * D_ + col0 + bj * 128 + 4 * n); gq[bj][n] = *(const f32x4*)(g + col0 + bj * 128 + 4 * n); bq_[bj][n] = *(const f32x4*)(b + col0 + bj * 128 + 4 * n); }
;                 asm volatile("" ::: "memory");
;                 float s1 = 0.f, s2 = 0.f;
; #pragma unroll
;                 for (int bj = 0; bj < 2; ++bj) { float* yp = Y + (size_t)row * D_ + col0 + bj * 128; f32x4 v[2];
; #pragma unroll
;                     for (int n = 0; n < 2; ++n) { v[n] = (((yv[bj][n] - mu) * rs) * gq[bj][n] + bq_[bj][n]) * ALPHA_ + acc[ai][bj][m][n] * sc;
;                         *(f32x4*)(yp + 4 * n) = v[n]; s1 += (v[n][0] + v[n][1]) + (v[n][2] + v[n][3]); s2 += (v[n][0] * v[n][0] + v[n][1] * v[n][1]) + (v[n][2] * v[n][2] + v[n][3] * v[n][3]); }
;                     *(u32x4*)(Yb + blk_off(row, col0 + bj * 128, D_)) = pack8(v[0], v[1]); }
;                 s1 = xsum32(xsum16(s1)); s2 = xsum32(xsum16(s2));
;                 if (fq == 0) *(f32x2*)(stn + (size_t)row * 32 + (u.pn * 4 + wc) * 2) = (f32x2){s1, s2}; asm volatile("" ::: "memory"); } }
	v_pk_fma_f32 v[106:107], v[126:127], v[106:107], v[130:131]
	v_pk_fma_f32 v[108:109], v[128:129], v[108:109], v[132:133]
	v_pk_fma_f32 v[102:103], v[106:107], s[2:3], v[102:103] op_sel_hi:[1,0,1]
	v_pk_fma_f32 v[104:105], v[108:109], s[2:3], v[104:105] op_sel_hi:[1,0,1]
	v_add_f32_e32 v106, v102, v103
	v_add_f32_e32 v107, v104, v105
	v_add_f32_e32 v106, v106, v107
	global_store_dwordx4 v159, v[110:113], s[42:43]
	v_mul_f32_e32 v107, v105, v105
	v_add_f32_e32 v180, v180, v181
	v_add_f32_e32 v110, v178, v106
	v_mul_f32_e32 v106, v103, v103
	v_fmac_f32_e32 v106, v102, v102
	v_fmac_f32_e32 v107, v104, v104
	v_add_f32_e32 v180, v190, v180
	v_add_f32_e32 v106, v106, v107
	v_add_f32_e32 v111, v180, v106
	v_sub_f32_e32 v107, v115, v179
	v_sub_f32_e32 v106, v114, v179
	v_sub_f32_e32 v109, v117, v179
	v_sub_f32_e32 v108, v116, v179
	v_pk_mul_f32 v[108:109], v[0:1], v[108:109] op_sel_hi:[0,1]
	v_pk_mul_f32 v[106:107], v[0:1], v[106:107] op_sel_hi:[0,1]
	v_pk_fma_f32 v[106:107], v[118:119], v[106:107], v[122:123]
	v_pk_fma_f32 v[108:109], v[120:121], v[108:109], v[124:125]
	v_pk_fma_f32 v[98:99], v[106:107], s[2:3], v[98:99] op_sel_hi:[1,0,1]
	v_pk_fma_f32 v[100:101], v[108:109], s[2:3], v[100:101] op_sel_hi:[1,0,1]
	v_add_f32_e32 v0, v98, v99
	v_add_f32_e32 v106, v100, v101
	v_add_f32_e32 v0, v0, v106
	v_mul_f32_e32 v106, v99, v99
	v_mul_f32_e32 v107, v101, v101
	v_add_f32_e32 v0, v110, v0
	v_fmac_f32_e32 v106, v98, v98
	v_fmac_f32_e32 v107, v100, v100
	s_nop 0
	s_nop 1
	v_bfe_u32 v109, v227, 4, 2
	v_sub_u32_e32 v108, 0, v109
	v_lshlrev_b32_e32 v108, 4, v108
	v_ashrrev_i32_e32 v109, 31, v108
	v_lshl_add_u64 v[108:109], v[182:183], 0, v[108:109]
	v_permlane16_swap_b32_e32 v102, v98
	v_permlane16_swap_b32_e32 v103, v99
	v_permlane16_swap_b32_e32 v104, v100
	v_permlane16_swap_b32_e32 v105, v101
	v_permlane32_swap_b32_e32 v102, v98
	v_permlane32_swap_b32_e32 v103, v99
	v_permlane32_swap_b32_e32 v104, v100
	v_permlane32_swap_b32_e32 v105, v101
	global_store_dwordx4 v[108:109], v[102:105], off offset:512
	global_store_dwordx4 v[108:109], v[98:101], off offset:576
	s_nop 1
	v_permlane32_swap_b32_e32 v102, v98
	v_permlane32_swap_b32_e32 v103, v99
	v_permlane32_swap_b32_e32 v104, v100
	v_permlane32_swap_b32_e32 v105, v101
	v_permlane16_swap_b32_e32 v102, v98
	v_permlane16_swap_b32_e32 v103, v99
	v_permlane16_swap_b32_e32 v104, v100
	v_permlane16_swap_b32_e32 v105, v101
	v_add_f32_e32 v106, v106, v107
	v_cvt_pk_bf16_f32 v102, v102, v103
	v_cvt_pk_bf16_f32 v103, v104, v105
	v_cvt_pk_bf16_f32 v104, v98, v99
	v_mov_b32_e32 v98, v0
	v_add_f32_e32 v106, v111, v106
	s_nop 0
	v_permlane16_swap_b32_e32 v0, v98
	v_add_f32_e32 v98, v0, v98
	v_mov_b32_e32 v0, v106
	s_nop 1
	v_permlane16_swap_b32_e32 v106, v0
	v_add_f32_e32 v99, v106, v0
	v_cvt_pk_bf16_f32 v105, v100, v101
	v_mov_b32_e32 v100, v98
	v_mov_b32_e32 v101, v99
	s_nop 0
	v_permlane32_swap_b32_e32 v98, v100
	v_permlane32_swap_b32_e32 v99, v101
	global_store_dwordx4 v159, v[102:105], s[40:41]
	s_and_saveexec_b64 s[26:27], s[44:45]
	s_cbranch_execz .LBB0_1539
	v_pk_add_f32 v[98:99], v[98:99], v[100:101]
	v_lshl_add_u64 v[100:101], s[6:7], 0, v[172:173]
	v_lshl_add_u64 v[100:101], s[52:53], 2, v[100:101]
	global_store_dwordx2 v[100:101], v[98:99], off
.LBB0_1539:
	s_or_b64 exec, exec, s[26:27]
	v_pk_add_f32 v[98:99], v[174:175], v[176:177]
	s_mov_b32 s2, 0x3a800000
	v_pk_mul_f32 v[122:123], v[98:99], s[2:3] op_sel_hi:[1,0]
	s_mov_b32 s1, 0x800000
	v_fma_f32 v0, -v123, v123, v122
	v_max_f32_e32 v0, 0, v0
	v_add_f32_e32 v0, 0x3727c5ac, v0
	v_cmp_gt_f32_e32 vcc, s1, v0
	v_mul_f32_e32 v98, 0x4b800000, v0
	s_load_dwordx16 s[64:79], s[34:35], 0x38
	v_cndmask_b32_e32 v0, v0, v98, vcc
	v_rsq_f32_e32 v0, v0
	s_mov_b32 s2, 0x3fd744fd
	v_lshlrev_b32_e32 v122, 6, v170
	v_mul_f32_e32 v98, 0x45800000, v0
	v_cndmask_b32_e32 v0, v0, v98, vcc
	v_lshlrev_b64 v[98:99], 12, v[170:171]
	s_waitcnt lgkmcnt(0)
	v_lshl_add_u64 v[98:99], s[78:79], 0, v[98:99]
	v_lshl_add_u64 v[124:125], v[152:153], 2, v[98:99]
	s_nop 1
	v_bfe_u32 v101, v227, 4, 2
	v_sub_u32_e32 v100, 0, v101
	v_lshlrev_b32_e32 v100, 4, v100
	v_ashrrev_i32_e32 v101, 31, v100
	v_lshl_add_u64 v[100:101], v[124:125], 0, v[100:101]
	global_load_dwordx4 v[126:129], v[100:101], off offset:64
	global_load_dwordx4 v[130:133], v[100:101], off
	global_load_dwordx4 v[134:137], v[156:157], off offset:16
	global_load_dwordx4 v[172:175], v[156:157], off
	global_load_dwordx4 v[176:179], v[154:155], off offset:16
	global_load_dwordx4 v[180:183], v[154:155], off
	s_nop 1
	v_bfe_u32 v103, v227, 4, 2
	v_sub_u32_e32 v102, 0, v103
	v_lshlrev_b32_e32 v102, 4, v102
	v_ashrrev_i32_e32 v103, 31, v102
	v_lshl_add_u64 v[102:103], v[124:125], 0, v[102:103]
	global_load_dwordx4 v[98:101], v[102:103], off offset:576
	global_load_dwordx4 v[118:121], v[102:103], off offset:512
	global_load_dwordx4 v[102:105], v[156:157], off offset:528
	global_load_dwordx4 v[110:113], v[156:157], off offset:512
	global_load_dwordx4 v[106:109], v[154:155], off offset:528
	global_load_dwordx4 v[114:117], v[154:155], off offset:512
	s_movk_i32 s1, 0x3bc0
	v_and_or_b32 v122, v122, s1, v196
	v_lshlrev_b32_e32 v122, 1, v122
	s_waitcnt vmcnt(10)
	v_permlane32_swap_b32_e32 v130, v126
	v_permlane32_swap_b32_e32 v131, v127
	v_permlane32_swap_b32_e32 v132, v128
	v_permlane32_swap_b32_e32 v133, v129
	v_permlane16_swap_b32_e32 v130, v126
	v_permlane16_swap_b32_e32 v131, v127
	v_permlane16_swap_b32_e32 v132, v128
	v_permlane16_swap_b32_e32 v133, v129
	v_sub_f32_e32 v127, v127, v123
	v_sub_f32_e32 v131, v131, v123
	v_sub_f32_e32 v130, v130, v123
	v_sub_f32_e32 v133, v133, v123
	v_sub_f32_e32 v132, v132, v123
	v_sub_f32_e32 v126, v126, v123
	v_sub_f32_e32 v129, v129, v123
	v_sub_f32_e32 v128, v128, v123
	v_pk_mul_f32 v[132:133], v[0:1], v[132:133] op_sel_hi:[0,1]
	v_pk_mul_f32 v[130:131], v[0:1], v[130:131] op_sel_hi:[0,1]
	v_pk_mul_f32 v[128:129], v[0:1], v[128:129] op_sel_hi:[0,1]
	v_pk_mul_f32 v[126:127], v[0:1], v[126:127] op_sel_hi:[0,1]
	s_waitcnt vmcnt(6)
; __device__ __forceinline__ float xsum16(float v) { const auto r = __builtin_amdgcn_permlane16_swap(__float_as_uint(v), __float_as_uint(v), false, false); return __uint_as_float(r[0]) + __uint_as_float(r[1]); }
; __device__ __forceinline__ float xsum32(float v) { const auto r = __builtin_amdgcn_permlane32_swap(__float_as_uint(v), __float_as_uint(v), false, false); return __uint_as_float(r[0]) + __uint_as_float(r[1]); }
; __device__ __forceinline__ size_t blk_off(int r, int c, int K) { return (size_t)(r >> 8) * 256 * K + (size_t)(c >> 6) * (256 * 64) + (size_t)((r & 255) * 64 + (c & 63)); }
; __device__ __forceinline__ u32x4 pack8(const f32x4 a, const f32x4 b) { u32x4 w; w.x = cvt_pk_bf16(a[0], a[1]); w.y = cvt_pk_bf16(a[2], a[3]); w.z = cvt_pk_bf16(b[0], b[1]); w.w = cvt_pk_bf16(b[2], b[3]); return w; }
;     __device__ __forceinline__ void operator()(const f32x4 (&acc)[2][2][4][2], const pg8::Unit& u, int wr, int wc, int fr, int fq) const {
;     ...
;                     for (int n = 0; n < 2; ++n) { yv[bj][n] = *(const f32x4*)(Yin + (size_t)row * D_ + col0 + bj * 128 + 4 * n); gq[bj][n] = *(const f32x4*)(g + col0 + bj * 128 + 4 * n); bq_[bj][n] = *(const f32x4*)(b + col0 + bj * 128 + 4 * n); }
;                 asm volatile("" ::: "memory");
;                 float s1 = 0.f, s2 = 0.f;
; #pragma unroll
;                 for (int bj = 0; bj < 2; ++bj) { float* yp = Y + (size_t)row * D_ + col0 + bj * 128; f32x4 v[2];
; #pragma unroll
;                     for (int n = 0; n < 2; ++n) { v[n] = (((yv[bj][n] - mu) * rs) * gq[bj][n] + bq_[bj][n]) * ALPHA_ + acc[ai][bj][m][n] * sc;
;                         *(f32x4*)(yp + 4 * n) = v[n]; s1 += (v[n][0] + v[n][1]) + (v[n][2] + v[n][3]); s2 += (v[n][0] * v[n][0] + v[n][1] * v[n][1]) + (v[n][2] * v[n][2] + v[n][3] * v[n][3]); }
;                     *(u32x4*)(Yb + blk_off(row, col0 + bj * 128, D_)) = pack8(v[0], v[1]); }
;                 s1 = xsum32(xsum16(s1)); s2 = xsum32(xsum16(s2));
;                 if (fq == 0) *(f32x2*)(stn + (size_t)row * 32 + (u.pn * 4 + wc) * 2) = (f32x2){s1, s2}; asm volatile("" ::: "memory"); } }
	v_pk_fma_f32 v[130:131], v[172:173], v[130:131], v[180:181]
	v_pk_fma_f32 v[132:133], v[174:175], v[132:133], v[182:183]
	v_pk_fma_f32 v[126:127], v[134:135], v[126:127], v[176:177]
	v_pk_fma_f32 v[128:129], v[136:137], v[128:129], v[178:179]
	v_pk_fma_f32 v[96:97], v[132:133], s[2:3], v[96:97] op_sel_hi:[1,0,1]
	v_pk_fma_f32 v[94:95], v[130:131], s[2:3], v[94:95] op_sel_hi:[1,0,1]
	v_pk_fma_f32 v[92:93], v[128:129], s[2:3], v[92:93] op_sel_hi:[1,0,1]
	v_pk_fma_f32 v[90:91], v[126:127], s[2:3], v[90:91] op_sel_hi:[1,0,1]
	v_add_f32_e32 v130, v94, v95
	v_add_f32_e32 v131, v96, v97
	v_add_f32_e32 v126, v90, v91
	v_add_f32_e32 v127, v92, v93
	v_add_f32_e32 v130, v130, v131
	v_mul_f32_e32 v131, v95, v95
	v_mul_f32_e32 v132, v97, v97
	v_add_f32_e32 v126, v126, v127
	v_mul_f32_e32 v127, v91, v91
	v_mul_f32_e32 v128, v93, v93
	s_nop 0
	v_fmac_f32_e32 v131, v94, v94
	v_fmac_f32_e32 v132, v96, v96
	s_nop 1
	v_bfe_u32 v135, v227, 4, 2
	v_sub_u32_e32 v134, 0, v135
	v_lshlrev_b32_e32 v134, 4, v134
	v_ashrrev_i32_e32 v135, 31, v134
	v_lshl_add_u64 v[134:135], v[124:125], 0, v[134:135]
	v_permlane16_swap_b32_e32 v94, v90
	v_permlane16_swap_b32_e32 v95, v91
	v_permlane16_swap_b32_e32 v96, v92
	v_permlane16_swap_b32_e32 v97, v93
	v_permlane32_swap_b32_e32 v94, v90
	v_permlane32_swap_b32_e32 v95, v91
	v_permlane32_swap_b32_e32 v96, v92
	v_permlane32_swap_b32_e32 v97, v93
	global_store_dwordx4 v[134:135], v[94:97], off
	global_store_dwordx4 v[134:135], v[90:93], off offset:64
	s_nop 1
	v_permlane32_swap_b32_e32 v94, v90
	v_permlane32_swap_b32_e32 v95, v91
	v_permlane32_swap_b32_e32 v96, v92
	v_permlane32_swap_b32_e32 v97, v93
	v_permlane16_swap_b32_e32 v94, v90
	v_permlane16_swap_b32_e32 v95, v91
	v_permlane16_swap_b32_e32 v96, v92
	v_permlane16_swap_b32_e32 v97, v93
	v_fmac_f32_e32 v127, v90, v90
	v_fmac_f32_e32 v128, v92, v92
	v_cvt_pk_bf16_f32 v94, v94, v95
	v_cvt_pk_bf16_f32 v95, v96, v97
	v_cvt_pk_bf16_f32 v96, v90, v91
	v_cvt_pk_bf16_f32 v97, v92, v93
	s_waitcnt vmcnt(6)
	v_permlane32_swap_b32_e32 v118, v98
	v_permlane32_swap_b32_e32 v119, v99
	v_permlane32_swap_b32_e32 v120, v100
	v_permlane32_swap_b32_e32 v121, v101
	v_permlane16_swap_b32_e32 v118, v98
	v_permlane16_swap_b32_e32 v119, v99
	v_permlane16_swap_b32_e32 v120, v100
	v_permlane16_swap_b32_e32 v121, v101
	v_sub_f32_e32 v91, v119, v123
	v_sub_f32_e32 v90, v118, v123
	v_sub_f32_e32 v93, v121, v123
	v_sub_f32_e32 v92, v120, v123
	v_pk_mul_f32 v[92:93], v[0:1], v[92:93] op_sel_hi:[0,1]
	v_pk_mul_f32 v[90:91], v[0:1], v[90:91] op_sel_hi:[0,1]
	s_waitcnt vmcnt(2)
	v_pk_fma_f32 v[90:91], v[110:111], v[90:91], v[114:115]
	v_pk_fma_f32 v[92:93], v[112:113], v[92:93], v[116:117]
	v_pk_fma_f32 v[86:87], v[90:91], s[2:3], v[86:87] op_sel_hi:[1,0,1]
	v_pk_fma_f32 v[88:89], v[92:93], s[2:3], v[88:89] op_sel_hi:[1,0,1]
	v_add_f32_e32 v130, 0, v130
	v_add_f32_e32 v90, v86, v87
	v_add_f32_e32 v91, v88, v89
	v_add_f32_e32 v126, v130, v126
	v_add_f32_e32 v90, v90, v91
	global_store_dwordx4 v122, v[94:97], s[42:43]
	v_mul_f32_e32 v91, v89, v89
	v_add_f32_e32 v131, v131, v132
	v_add_f32_e32 v94, v126, v90
	v_mul_f32_e32 v90, v87, v87
	v_add_f32_e32 v127, v127, v128
	v_fmac_f32_e32 v90, v86, v86
	v_fmac_f32_e32 v91, v88, v88
	v_add_f32_e32 v127, v131, v127
	v_add_f32_e32 v90, v90, v91
	v_add_f32_e32 v95, v127, v90
	v_sub_f32_e32 v91, v99, v123
	v_sub_f32_e32 v90, v98, v123
	v_sub_f32_e32 v93, v101, v123
	v_sub_f32_e32 v92, v100, v123
	v_pk_mul_f32 v[92:93], v[0:1], v[92:93] op_sel_hi:[0,1]
	v_pk_mul_f32 v[90:91], v[0:1], v[90:91] op_sel_hi:[0,1]
	v_pk_fma_f32 v[90:91], v[102:103], v[90:91], v[106:107]
	v_pk_fma_f32 v[92:93], v[104:105], v[92:93], v[108:109]
	v_pk_fma_f32 v[82:83], v[90:91], s[2:3], v[82:83] op_sel_hi:[1,0,1]
	v_pk_fma_f32 v[84:85], v[92:93], s[2:3], v[84:85] op_sel_hi:[1,0,1]
	v_add_f32_e32 v0, v82, v83
	v_add_f32_e32 v90, v84, v85
	v_add_f32_e32 v0, v0, v90
	v_mul_f32_e32 v90, v83, v83
	v_mul_f32_e32 v91, v85, v85
	v_add_f32_e32 v0, v94, v0
	v_fmac_f32_e32 v90, v82, v82
	v_fmac_f32_e32 v91, v84, v84
	s_nop 0
	s_nop 1
	v_bfe_u32 v93, v227, 4, 2
	v_sub_u32_e32 v92, 0, v93
	v_lshlrev_b32_e32 v92, 4, v92
	v_ashrrev_i32_e32 v93, 31, v92
	v_lshl_add_u64 v[92:93], v[124:125], 0, v[92:93]
	v_permlane16_swap_b32_e32 v86, v82
	v_permlane16_swap_b32_e32 v87, v83
	v_permlane16_swap_b32_e32 v88, v84
	v_permlane16_swap_b32_e32 v89, v85
	v_permlane32_swap_b32_e32 v86, v82
	v_permlane32_swap_b32_e32 v87, v83
	v_permlane32_swap_b32_e32 v88, v84
	v_permlane32_swap_b32_e32 v89, v85
	global_store_dwordx4 v[92:93], v[86:89], off offset:512
	global_store_dwordx4 v[92:93], v[82:85], off offset:576
	s_nop 1
	v_permlane32_swap_b32_e32 v86, v82
	v_permlane32_swap_b32_e32 v87, v83
	v_permlane32_swap_b32_e32 v88, v84
	v_permlane32_swap_b32_e32 v89, v85
	v_permlane16_swap_b32_e32 v86, v82
	v_permlane16_swap_b32_e32 v87, v83
	v_permlane16_swap_b32_e32 v88, v84
	v_permlane16_swap_b32_e32 v89, v85
	v_add_f32_e32 v90, v90, v91
	v_cvt_pk_bf16_f32 v86, v86, v87
	v_cvt_pk_bf16_f32 v87, v88, v89
	v_cvt_pk_bf16_f32 v88, v82, v83
	v_mov_b32_e32 v82, v0
	v_add_f32_e32 v90, v95, v90
	s_nop 0
	v_permlane16_swap_b32_e32 v0, v82
	v_add_f32_e32 v82, v0, v82
	v_mov_b32_e32 v0, v90
	s_nop 1
	v_permlane16_swap_b32_e32 v90, v0
	v_add_f32_e32 v83, v90, v0
	v_cvt_pk_bf16_f32 v89, v84, v85
	v_mov_b32_e32 v84, v82
	v_mov_b32_e32 v85, v83
	s_nop 0
	v_permlane32_swap_b32_e32 v82, v84
	v_permlane32_swap_b32_e32 v83, v85
	global_store_dwordx4 v122, v[86:89], s[40:41]
	s_and_saveexec_b64 s[26:27], s[44:45]
	s_cbranch_execz .LBB0_1541
	v_pk_add_f32 v[82:83], v[82:83], v[84:85]
	v_lshl_add_u64 v[84:85], s[6:7], 0, v[164:165]
	v_lshl_add_u64 v[84:85], s[52:53], 2, v[84:85]
	global_store_dwordx2 v[84:85], v[82:83], off
; __device__ __forceinline__ size_t blk_off(int r, int c, int K) { return (size_t)(r >> 8) * 256 * K + (size_t)(c >> 6) * (256 * 64) + (size_t)((r & 255) * 64 + (c & 63)); }
; __device__ __forceinline__ u32x4 pack8(const f32x4 a, const f32x4 b) { u32x4 w; w.x = cvt_pk_bf16(a[0], a[1]); w.y = cvt_pk_bf16(a[2], a[3]); w.z = cvt_pk_bf16(b[0], b[1]); w.w = cvt_pk_bf16(b[2], b[3]); return w; }
;     __device__ __forceinline__ void operator()(const f32x4 (&acc)[2][2][4][2], const pg8::Unit& u, int wr, int wc, int fr, int fq) const {
;     ...
;             for (int m = 0; m < 4; ++m) { const int row = row0 + ai * 128 + m * 16; const float mu = mu4[m], rs = rs4[m];
;                 f32x4 yv[2][2], gq[2][2], bq_[2][2];
; #pragma unroll
;                 for (int bj = 0; bj < 2; ++bj)
; #pragma unroll
;                     for (int n = 0; n < 2; ++n) { yv[bj][n] = *(const f32x4*)(Yin + (size_t)row * D_ + col0 + bj * 128 + 4 * n); gq[bj][n] = *(const f32x4*)(g + col0 + bj * 128 + 4 * n); bq_[bj][n] = *(const f32x4*)(b + col0 + bj * 128 + 4 * n); }
;                 asm volatile("" ::: "memory");
;                 float s1 = 0.f, s2 = 0.f;
; #pragma unroll
;                 for (int bj = 0; bj < 2; ++bj) { float* yp = Y + (size_t)row * D_ + col0 + bj * 128; f32x4 v[2];
; #pragma unroll
;                     for (int n = 0; n < 2; ++n) { v[n] = (((yv[bj][n] - mu) * rs) * gq[bj][n] + bq_[bj][n]) * ALPHA_ + acc[ai][bj][m][n] * sc;
;                         *(f32x4*)(yp + 4 * n) = v[n]; s1 += (v[n][0] + v[n][1]) + (v[n][2] + v[n][3]); s2 += (v[n][0] * v[n][0] + v[n][1] * v[n][1]) + (v[n][2] * v[n][2] + v[n][3] * v[n][3]); }
;                     *(u32x4*)(Yb + blk_off(row, col0 + bj * 128, D_)) = pack8(v[0], v[1]); }
.LBB0_1541:
	s_or_b64 exec, exec, s[26:27]
	v_pk_add_f32 v[82:83], v[166:167], v[168:169]
	s_mov_b32 s2, 0x3a800000
	v_pk_mul_f32 v[106:107], v[82:83], s[2:3] op_sel_hi:[1,0]
	s_mov_b32 s1, 0x800000
	v_fma_f32 v0, -v107, v107, v106
	v_max_f32_e32 v0, 0, v0
	v_add_f32_e32 v0, 0x3727c5ac, v0
	v_cmp_gt_f32_e32 vcc, s1, v0
	v_mul_f32_e32 v82, 0x4b800000, v0
	s_load_dwordx16 s[64:79], s[34:35], 0x38
	v_cndmask_b32_e32 v0, v0, v82, vcc
	v_rsq_f32_e32 v0, v0
	s_mov_b32 s2, 0x3fd744fd
	v_lshlrev_b32_e32 v106, 6, v162
	v_mul_f32_e32 v82, 0x45800000, v0
	v_cndmask_b32_e32 v0, v0, v82, vcc
	v_lshlrev_b64 v[82:83], 12, v[162:163]
	s_waitcnt lgkmcnt(0)
	v_lshl_add_u64 v[82:83], s[78:79], 0, v[82:83]
	v_lshl_add_u64 v[108:109], v[152:153], 2, v[82:83]
	s_nop 1
	v_bfe_u32 v85, v227, 4, 2
	v_sub_u32_e32 v84, 0, v85
	v_lshlrev_b32_e32 v84, 4, v84
	v_ashrrev_i32_e32 v85, 31, v84
	v_lshl_add_u64 v[84:85], v[108:109], 0, v[84:85]
	global_load_dwordx4 v[110:113], v[84:85], off offset:64
	global_load_dwordx4 v[114:117], v[84:85], off
	global_load_dwordx4 v[118:121], v[156:157], off offset:16
	global_load_dwordx4 v[122:125], v[156:157], off
	global_load_dwordx4 v[126:129], v[154:155], off offset:16
	global_load_dwordx4 v[130:133], v[154:155], off
	s_nop 1
	v_bfe_u32 v87, v227, 4, 2
	v_sub_u32_e32 v86, 0, v87
	v_lshlrev_b32_e32 v86, 4, v86
	v_ashrrev_i32_e32 v87, 31, v86
	v_lshl_add_u64 v[86:87], v[108:109], 0, v[86:87]
	global_load_dwordx4 v[82:85], v[86:87], off offset:576
	global_load_dwordx4 v[102:105], v[86:87], off offset:512
	global_load_dwordx4 v[86:89], v[156:157], off offset:528
	global_load_dwordx4 v[94:97], v[156:157], off offset:512
	global_load_dwordx4 v[90:93], v[154:155], off offset:528
	global_load_dwordx4 v[98:101], v[154:155], off offset:512
	s_movk_i32 s1, 0x3fc0
	v_and_or_b32 v106, v106, s1, v196
	v_lshlrev_b32_e32 v106, 1, v106
	s_waitcnt vmcnt(10)
	v_permlane32_swap_b32_e32 v114, v110
	v_permlane32_swap_b32_e32 v115, v111
	v_permlane32_swap_b32_e32 v116, v112
	v_permlane32_swap_b32_e32 v117, v113
	v_permlane16_swap_b32_e32 v114, v110
	v_permlane16_swap_b32_e32 v115, v111
	v_permlane16_swap_b32_e32 v116, v112
	v_permlane16_swap_b32_e32 v117, v113
	v_sub_f32_e32 v111, v111, v107
	v_sub_f32_e32 v115, v115, v107
	v_sub_f32_e32 v114, v114, v107
	v_sub_f32_e32 v117, v117, v107
	v_sub_f32_e32 v116, v116, v107
	v_sub_f32_e32 v110, v110, v107
	v_sub_f32_e32 v113, v113, v107
	v_sub_f32_e32 v112, v112, v107
	v_pk_mul_f32 v[116:117], v[0:1], v[116:117] op_sel_hi:[0,1]
	v_pk_mul_f32 v[114:115], v[0:1], v[114:115] op_sel_hi:[0,1]
	v_pk_mul_f32 v[112:113], v[0:1], v[112:113] op_sel_hi:[0,1]
	v_pk_mul_f32 v[110:111], v[0:1], v[110:111] op_sel_hi:[0,1]
	s_waitcnt vmcnt(6)
	v_pk_fma_f32 v[114:115], v[122:123], v[114:115], v[130:131]
	v_pk_fma_f32 v[116:117], v[124:125], v[116:117], v[132:133]
	v_pk_fma_f32 v[110:111], v[118:119], v[110:111], v[126:127]
	v_pk_fma_f32 v[112:113], v[120:121], v[112:113], v[128:129]
	v_pk_fma_f32 v[80:81], v[116:117], s[2:3], v[80:81] op_sel_hi:[1,0,1]
	v_pk_fma_f32 v[78:79], v[114:115], s[2:3], v[78:79] op_sel_hi:[1,0,1]
	v_pk_fma_f32 v[76:77], v[112:113], s[2:3], v[76:77] op_sel_hi:[1,0,1]
	v_pk_fma_f32 v[74:75], v[110:111], s[2:3], v[74:75] op_sel_hi:[1,0,1]
	v_add_f32_e32 v114, v78, v79
	v_add_f32_e32 v115, v80, v81
	v_add_f32_e32 v110, v74, v75
	v_add_f32_e32 v111, v76, v77
	v_add_f32_e32 v114, v114, v115
	v_mul_f32_e32 v115, v79, v79
	v_mul_f32_e32 v116, v81, v81
	v_add_f32_e32 v110, v110, v111
	v_mul_f32_e32 v111, v75, v75
	v_mul_f32_e32 v112, v77, v77
	s_nop 0
	v_fmac_f32_e32 v115, v78, v78
	v_fmac_f32_e32 v116, v80, v80
	s_nop 1
	v_bfe_u32 v119, v227, 4, 2
	v_sub_u32_e32 v118, 0, v119
	v_lshlrev_b32_e32 v118, 4, v118
	v_ashrrev_i32_e32 v119, 31, v118
	v_lshl_add_u64 v[118:119], v[108:109], 0, v[118:119]
	v_permlane16_swap_b32_e32 v78, v74
	v_permlane16_swap_b32_e32 v79, v75
	v_permlane16_swap_b32_e32 v80, v76
	v_permlane16_swap_b32_e32 v81, v77
	v_permlane32_swap_b32_e32 v78, v74
	v_permlane32_swap_b32_e32 v79, v75
	v_permlane32_swap_b32_e32 v80, v76
	v_permlane32_swap_b32_e32 v81, v77
	global_store_dwordx4 v[118:119], v[78:81], off
	global_store_dwordx4 v[118:119], v[74:77], off offset:64
	s_nop 1
	v_permlane32_swap_b32_e32 v78, v74
	v_permlane32_swap_b32_e32 v79, v75
	v_permlane32_swap_b32_e32 v80, v76
	v_permlane32_swap_b32_e32 v81, v77
	v_permlane16_swap_b32_e32 v78, v74
	v_permlane16_swap_b32_e32 v79, v75
	v_permlane16_swap_b32_e32 v80, v76
	v_permlane16_swap_b32_e32 v81, v77
	v_fmac_f32_e32 v111, v74, v74
	v_fmac_f32_e32 v112, v76, v76
	v_cvt_pk_bf16_f32 v78, v78, v79
	v_cvt_pk_bf16_f32 v79, v80, v81
	v_cvt_pk_bf16_f32 v80, v74, v75
	v_cvt_pk_bf16_f32 v81, v76, v77
	s_waitcnt vmcnt(6)
	v_permlane32_swap_b32_e32 v102, v82
	v_permlane32_swap_b32_e32 v103, v83
	v_permlane32_swap_b32_e32 v104, v84
	v_permlane32_swap_b32_e32 v105, v85
	v_permlane16_swap_b32_e32 v102, v82
	v_permlane16_swap_b32_e32 v103, v83
	v_permlane16_swap_b32_e32 v104, v84
	v_permlane16_swap_b32_e32 v105, v85
	v_sub_f32_e32 v75, v103, v107
	v_sub_f32_e32 v74, v102, v107
	v_sub_f32_e32 v77, v105, v107
	v_sub_f32_e32 v76, v104, v107
	v_pk_mul_f32 v[76:77], v[0:1], v[76:77] op_sel_hi:[0,1]
	v_pk_mul_f32 v[74:75], v[0:1], v[74:75] op_sel_hi:[0,1]
	s_waitcnt vmcnt(2)
; __device__ __forceinline__ float xsum16(float v) { const auto r = __builtin_amdgcn_permlane16_swap(__float_as_uint(v), __float_as_uint(v), false, false); return __uint_as_float(r[0]) + __uint_as_float(r[1]); }
; __device__ __forceinline__ float xsum32(float v) { const auto r = __builtin_amdgcn_permlane32_swap(__float_as_uint(v), __float_as_uint(v), false, false); return __uint_as_float(r[0]) + __uint_as_float(r[1]); }
; __device__ __forceinline__ size_t blk_off(int r, int c, int K) { return (size_t)(r >> 8) * 256 * K + (size_t)(c >> 6) * (256 * 64) + (size_t)((r & 255) * 64 + (c & 63)); }
; __device__ __forceinline__ u32x4 pack8(const f32x4 a, const f32x4 b) { u32x4 w; w.x = cvt_pk_bf16(a[0], a[1]); w.y = cvt_pk_bf16(a[2], a[3]); w.z = cvt_pk_bf16(b[0], b[1]); w.w = cvt_pk_bf16(b[2], b[3]); return w; }
; __device__ __forceinline__ void row_stats4(const float* st, int rowb, int fq, float (&mu)[4], float (&rs)[4]) {
;     f32x4 a[4], b[4];
; #pragma unroll
;     for (int m = 0; m < 4; ++m) { const f32x4* p = (const f32x4*)(st + (size_t)(rowb + m * 16) * 32 + fq * 8); a[m] = p[0]; b[m] = p[1]; }
; #pragma unroll
;     for (int m = 0; m < 4; ++m) { float s1 = (a[m][0] + a[m][2]) + (b[m][0] + b[m][2]), s2 = (a[m][1] + a[m][3]) + (b[m][1] + b[m][3]);
;         s1 = xsum32(xsum16(s1)); s2 = xsum32(xsum16(s2));
;         const float mm = s1 * (1.0f / 1024.0f); mu[m] = mm; rs[m] = rsqrtf(fmaxf(s2 * (1.0f / 1024.0f) - mm * mm, 0.f) + LN_EPS_); }
;     __device__ __forceinline__ void operator()(const f32x4 (&acc)[2][2][4][2], const pg8::Unit& u, int wr, int wc, int fr, int fq) const {
;     ...
;                 for (int bj = 0; bj < 2; ++bj) { float* yp = Y + (size_t)row * D_ + col0 + bj * 128; f32x4 v[2];
; #pragma unroll
;                     for (int n = 0; n < 2; ++n) { v[n] = (((yv[bj][n] - mu) * rs) * gq[bj][n] + bq_[bj][n]) * ALPHA_ + acc[ai][bj][m][n] * sc;
;                         *(f32x4*)(yp + 4 * n) = v[n]; s1 += (v[n][0] + v[n][1]) + (v[n][2] + v[n][3]); s2 += (v[n][0] * v[n][0] + v[n][1] * v[n][1]) + (v[n][2] * v[n][2] + v[n][3] * v[n][3]); }
;                     *(u32x4*)(Yb + blk_off(row, col0 + bj * 128, D_)) = pack8(v[0], v[1]); }
;                 s1 = xsum32(xsum16(s1)); s2 = xsum32(xsum16(s2));
;                 if (fq == 0) *(f32x2*)(stn + (size_t)row * 32 + (u.pn * 4 + wc) * 2) = (f32x2){s1, s2}; asm volatile("" ::: "memory"); } }
	v_pk_fma_f32 v[74:75], v[94:95], v[74:75], v[98:99]
	v_pk_fma_f32 v[76:77], v[96:97], v[76:77], v[100:101]
	v_pk_fma_f32 v[70:71], v[74:75], s[2:3], v[70:71] op_sel_hi:[1,0,1]
	v_pk_fma_f32 v[72:73], v[76:77], s[2:3], v[72:73] op_sel_hi:[1,0,1]
	v_add_f32_e32 v114, 0, v114
	v_add_f32_e32 v74, v70, v71
	v_add_f32_e32 v75, v72, v73
	v_add_f32_e32 v110, v114, v110
	v_add_f32_e32 v74, v74, v75
	global_store_dwordx4 v106, v[78:81], s[42:43]
	v_mul_f32_e32 v75, v73, v73
	v_add_f32_e32 v115, v115, v116
	v_add_f32_e32 v78, v110, v74
	v_mul_f32_e32 v74, v71, v71
	v_add_f32_e32 v111, v111, v112
	v_fmac_f32_e32 v74, v70, v70
	v_fmac_f32_e32 v75, v72, v72
	v_add_f32_e32 v111, v115, v111
	v_add_f32_e32 v74, v74, v75
	v_add_f32_e32 v79, v111, v74
	v_sub_f32_e32 v75, v83, v107
	v_sub_f32_e32 v74, v82, v107
	v_sub_f32_e32 v77, v85, v107
	v_sub_f32_e32 v76, v84, v107
	v_pk_mul_f32 v[76:77], v[0:1], v[76:77] op_sel_hi:[0,1]
	v_pk_mul_f32 v[74:75], v[0:1], v[74:75] op_sel_hi:[0,1]
	v_pk_fma_f32 v[74:75], v[86:87], v[74:75], v[90:91]
	v_pk_fma_f32 v[76:77], v[88:89], v[76:77], v[92:93]
	v_pk_fma_f32 v[66:67], v[74:75], s[2:3], v[66:67] op_sel_hi:[1,0,1]
	v_pk_fma_f32 v[68:69], v[76:77], s[2:3], v[68:69] op_sel_hi:[1,0,1]
	v_add_f32_e32 v0, v66, v67
	v_add_f32_e32 v74, v68, v69
	v_add_f32_e32 v0, v0, v74
	v_mul_f32_e32 v74, v67, v67
	v_mul_f32_e32 v75, v69, v69
	v_add_f32_e32 v0, v78, v0
	v_fmac_f32_e32 v74, v66, v66
	v_fmac_f32_e32 v75, v68, v68
	s_nop 0
	s_nop 1
	v_bfe_u32 v77, v227, 4, 2
	v_sub_u32_e32 v76, 0, v77
	v_lshlrev_b32_e32 v76, 4, v76
	v_ashrrev_i32_e32 v77, 31, v76
	v_lshl_add_u64 v[76:77], v[108:109], 0, v[76:77]
	v_permlane16_swap_b32_e32 v70, v66
	v_permlane16_swap_b32_e32 v71, v67
	v_permlane16_swap_b32_e32 v72, v68
	v_permlane16_swap_b32_e32 v73, v69
	v_permlane32_swap_b32_e32 v70, v66
	v_permlane32_swap_b32_e32 v71, v67
	v_permlane32_swap_b32_e32 v72, v68
	v_permlane32_swap_b32_e32 v73, v69
	global_store_dwordx4 v[76:77], v[70:73], off offset:512
	global_store_dwordx4 v[76:77], v[66:69], off offset:576
	s_nop 1
	v_permlane32_swap_b32_e32 v70, v66
	v_permlane32_swap_b32_e32 v71, v67
	v_permlane32_swap_b32_e32 v72, v68
	v_permlane32_swap_b32_e32 v73, v69
	v_permlane16_swap_b32_e32 v70, v66
	v_permlane16_swap_b32_e32 v71, v67
	v_permlane16_swap_b32_e32 v72, v68
	v_permlane16_swap_b32_e32 v73, v69
	v_add_f32_e32 v74, v74, v75
	v_cvt_pk_bf16_f32 v70, v70, v71
	v_cvt_pk_bf16_f32 v71, v72, v73
	v_cvt_pk_bf16_f32 v72, v66, v67
	v_mov_b32_e32 v66, v0
	v_add_f32_e32 v74, v79, v74
	s_nop 0
	v_permlane16_swap_b32_e32 v0, v66
	v_add_f32_e32 v66, v0, v66
	v_mov_b32_e32 v0, v74
	s_nop 1
	v_permlane16_swap_b32_e32 v74, v0
	v_add_f32_e32 v67, v74, v0
	v_cvt_pk_bf16_f32 v73, v68, v69
	v_mov_b32_e32 v68, v66
	v_mov_b32_e32 v69, v67
	s_nop 0
	v_permlane32_swap_b32_e32 v66, v68
	v_permlane32_swap_b32_e32 v67, v69
	global_store_dwordx4 v106, v[70:73], s[40:41]
	s_and_saveexec_b64 s[26:27], s[44:45]
	s_cbranch_execz .LBB0_1543
	v_pk_add_f32 v[66:67], v[66:67], v[68:69]
	v_lshl_add_u64 v[68:69], s[6:7], 0, v[160:161]
	v_lshl_add_u64 v[68:69], s[52:53], 2, v[68:69]
	global_store_dwordx2 v[68:69], v[66:67], off
.LBB0_1543:
	s_or_b64 exec, exec, s[26:27]
	v_add_u32_e32 v118, 0x80, v158
	v_ashrrev_i32_e32 v119, 31, v118
	v_lshlrev_b64 v[110:111], 7, v[118:119]
	v_lshl_add_u64 v[70:71], v[146:147], 0, v[110:111]
	s_nop 1
	v_bfe_u32 v75, v227, 4, 2
	v_sub_u32_e32 v74, 0, v75
	v_lshlrev_b32_e32 v74, 4, v74
	v_ashrrev_i32_e32 v75, 31, v74
	v_lshl_add_u64 v[74:75], v[70:71], 0, v[74:75]
	global_load_dwordx4 v[66:69], v[74:75], off
	s_nop 0
	global_load_dwordx4 v[70:73], v[74:75], off offset:64
	v_add_u32_e32 v108, 0x90, v158
	v_ashrrev_i32_e32 v109, 31, v108
	v_lshlrev_b64 v[102:103], 7, v[108:109]
	v_lshl_add_u64 v[78:79], v[146:147], 0, v[102:103]
	s_nop 1
	v_bfe_u32 v83, v227, 4, 2
	v_sub_u32_e32 v82, 0, v83
	v_lshlrev_b32_e32 v82, 4, v82
	v_ashrrev_i32_e32 v83, 31, v82
	v_lshl_add_u64 v[82:83], v[78:79], 0, v[82:83]
	global_load_dwordx4 v[74:77], v[82:83], off
	s_nop 0
	global_load_dwordx4 v[78:81], v[82:83], off offset:64
	v_add_u32_e32 v96, 0xa0, v158
	v_ashrrev_i32_e32 v97, 31, v96
	v_lshlrev_b64 v[82:83], 7, v[96:97]
	v_lshl_add_u64 v[86:87], v[146:147], 0, v[82:83]
	s_nop 1
	v_bfe_u32 v91, v227, 4, 2
	v_sub_u32_e32 v90, 0, v91
	v_lshlrev_b32_e32 v90, 4, v90
	v_ashrrev_i32_e32 v91, 31, v90
	v_lshl_add_u64 v[90:91], v[86:87], 0, v[90:91]
	global_load_dwordx4 v[82:85], v[90:91], off
	s_nop 0
	global_load_dwordx4 v[86:89], v[90:91], off offset:64
	v_add_u32_e32 v94, 0xb0, v158
	v_ashrrev_i32_e32 v95, 31, v94
	v_lshlrev_b64 v[90:91], 7, v[94:95]
	v_lshl_add_u64 v[98:99], v[146:147], 0, v[90:91]
	s_nop 1
	v_bfe_u32 v105, v227, 4, 2
	v_sub_u32_e32 v104, 0, v105
	v_lshlrev_b32_e32 v104, 4, v104
	v_ashrrev_i32_e32 v105, 31, v104
	v_lshl_add_u64 v[104:105], v[98:99], 0, v[104:105]
	global_load_dwordx4 v[90:93], v[104:105], off
	s_nop 0
	global_load_dwordx4 v[98:101], v[104:105], off offset:64
	s_mov_b32 s2, 0x3a800000
	s_mov_b32 s1, 0x800000
	s_load_dwordx16 s[64:79], s[34:35], 0x38
	s_mov_b32 s14, 0x3fd744fd
	s_waitcnt vmcnt(6)
	v_permlane32_swap_b32_e32 v66, v70
	v_permlane32_swap_b32_e32 v67, v71
	v_permlane32_swap_b32_e32 v68, v72
	v_permlane32_swap_b32_e32 v69, v73
	v_permlane16_swap_b32_e32 v66, v70
	v_permlane16_swap_b32_e32 v67, v71
	v_permlane16_swap_b32_e32 v68, v72
	v_permlane16_swap_b32_e32 v69, v73
	v_mov_b32_e32 v104, v66
	v_mov_b32_e32 v105, v70
	v_mov_b32_e32 v106, v68
	v_mov_b32_e32 v107, v72
	v_pk_add_f32 v[104:105], v[104:105], v[106:107]
	v_mov_b32_e32 v70, v67
	v_pk_add_f32 v[104:105], v[104:105], v[104:105] op_sel:[0,1] op_sel_hi:[1,0]
	v_mov_b32_e32 v72, v69
	v_pk_add_f32 v[66:67], v[70:71], v[72:73]
	v_mov_b32_e32 v0, v104
	v_pk_add_f32 v[66:67], v[66:67], v[66:67] op_sel:[0,1] op_sel_hi:[1,0]
	s_nop 0
	v_permlane16_swap_b32_e32 v104, v0
	v_add_f32_e32 v67, v104, v0
	v_mov_b32_e32 v0, v66
	s_nop 1
	v_permlane16_swap_b32_e32 v66, v0
	v_add_f32_e32 v66, v66, v0
	v_mov_b32_e32 v69, v67
	v_mov_b32_e32 v68, v66
	s_nop 0
	v_permlane32_swap_b32_e32 v67, v69
	v_permlane32_swap_b32_e32 v66, v68
	v_pk_add_f32 v[66:67], v[66:67], v[68:69]
	s_waitcnt vmcnt(4)
; __device__ __forceinline__ float xsum16(float v) { const auto r = __builtin_amdgcn_permlane16_swap(__float_as_uint(v), __float_as_uint(v), false, false); return __uint_as_float(r[0]) + __uint_as_float(r[1]); }
; __device__ __forceinline__ float xsum32(float v) { const auto r = __builtin_amdgcn_permlane32_swap(__float_as_uint(v), __float_as_uint(v), false, false); return __uint_as_float(r[0]) + __uint_as_float(r[1]); }
; __device__ __forceinline__ void row_stats4(const float* st, int rowb, int fq, float (&mu)[4], float (&rs)[4]) {
;     f32x4 a[4], b[4];
; #pragma unroll
;     for (int m = 0; m < 4; ++m) { const f32x4* p = (const f32x4*)(st + (size_t)(rowb + m * 16) * 32 + fq * 8); a[m] = p[0]; b[m] = p[1]; }
; #pragma unroll
;     for (int m = 0; m < 4; ++m) { float s1 = (a[m][0] + a[m][2]) + (b[m][0] + b[m][2]), s2 = (a[m][1] + a[m][3]) + (b[m][1] + b[m][3]);
;         s1 = xsum32(xsum16(s1)); s2 = xsum32(xsum16(s2));
;         const float mm = s1 * (1.0f / 1024.0f); mu[m] = mm; rs[m] = rsqrtf(fmaxf(s2 * (1.0f / 1024.0f) - mm * mm, 0.f) + LN_EPS_); }
;     __device__ __forceinline__ void operator()(const f32x4 (&acc)[2][2][4][2], const pg8::Unit& u, int wr, int wc, int fr, int fq) const {
;     ...
;             for (int m = 0; m < 4; ++m) { const int row = row0 + ai * 128 + m * 16; const float mu = mu4[m], rs = rs4[m];
;                 f32x4 yv[2][2], gq[2][2], bq_[2][2];
; #pragma unroll
;                 for (int bj = 0; bj < 2; ++bj)
; #pragma unroll
;                     for (int n = 0; n < 2; ++n) { yv[bj][n] = *(const f32x4*)(Yin + (size_t)row * D_ + col0 + bj * 128 + 4 * n); gq[bj][n] = *(const f32x4*)(g + col0 + bj * 128 + 4 * n); bq_[bj][n] = *(const f32x4*)(b + col0 + bj * 128 + 4 * n); }
;                 asm volatile("" ::: "memory");
;                 float s1 = 0.f, s2 = 0.f;
; #pragma unroll
;                 for (int bj = 0; bj < 2; ++bj) { float* yp = Y + (size_t)row * D_ + col0 + bj * 128; f32x4 v[2];
; #pragma unroll
;                     for (int n = 0; n < 2; ++n) { v[n] = (((yv[bj][n] - mu) * rs) * gq[bj][n] + bq_[bj][n]) * ALPHA_ + acc[ai][bj][m][n] * sc;
	v_permlane32_swap_b32_e32 v74, v78
	v_permlane32_swap_b32_e32 v75, v79
	v_permlane32_swap_b32_e32 v76, v80
	v_permlane32_swap_b32_e32 v77, v81
	v_permlane16_swap_b32_e32 v74, v78
	v_permlane16_swap_b32_e32 v75, v79
	v_permlane16_swap_b32_e32 v76, v80
	v_permlane16_swap_b32_e32 v77, v81
	v_mov_b32_e32 v68, v76
	v_pk_mul_f32 v[116:117], v[66:67], s[2:3] op_sel_hi:[1,0]
	v_mov_b32_e32 v67, v78
	v_fma_f32 v0, -v117, v117, v116
	v_max_f32_e32 v0, 0, v0
	v_add_f32_e32 v0, 0x3727c5ac, v0
	v_cmp_gt_f32_e32 vcc, s1, v0
	v_mul_f32_e32 v66, 0x4b800000, v0
	v_mov_b32_e32 v69, v80
	v_cndmask_b32_e32 v0, v0, v66, vcc
	v_rsq_f32_e32 v0, v0
	v_mov_b32_e32 v78, v75
	v_mov_b32_e32 v80, v77
	v_readlane_b32 s2, v253, 59
	v_mul_f32_e32 v66, 0x45800000, v0
	v_cndmask_b32_e32 v116, v0, v66, vcc
	v_mov_b32_e32 v66, v74
	v_pk_add_f32 v[66:67], v[66:67], v[68:69]
	v_pk_add_f32 v[68:69], v[78:79], v[80:81]
	v_pk_add_f32 v[66:67], v[66:67], v[66:67] op_sel:[0,1] op_sel_hi:[1,0]
	v_pk_add_f32 v[68:69], v[68:69], v[68:69] op_sel:[0,1] op_sel_hi:[1,0]
	v_mov_b32_e32 v0, v66
	s_nop 1
	v_permlane16_swap_b32_e32 v66, v0
	v_add_f32_e32 v113, v66, v0
	v_mov_b32_e32 v0, v68
	s_nop 1
	v_permlane16_swap_b32_e32 v68, v0
	v_add_f32_e32 v112, v68, v0
	s_waitcnt vmcnt(2)
	v_permlane32_swap_b32_e32 v82, v86
	v_permlane32_swap_b32_e32 v83, v87
	v_permlane32_swap_b32_e32 v84, v88
	v_permlane32_swap_b32_e32 v85, v89
	v_permlane16_swap_b32_e32 v82, v86
	v_permlane16_swap_b32_e32 v83, v87
	v_permlane16_swap_b32_e32 v84, v88
	v_permlane16_swap_b32_e32 v85, v89
	v_mov_b32_e32 v66, v82
	v_mov_b32_e32 v67, v86
	v_mov_b32_e32 v68, v84
	v_mov_b32_e32 v69, v88
	v_pk_add_f32 v[66:67], v[66:67], v[68:69]
	v_mov_b32_e32 v86, v83
	v_pk_add_f32 v[66:67], v[66:67], v[66:67] op_sel:[0,1] op_sel_hi:[1,0]
	v_mov_b32_e32 v88, v85
	v_pk_add_f32 v[68:69], v[86:87], v[88:89]
	v_mov_b32_e32 v0, v66
	v_pk_add_f32 v[68:69], v[68:69], v[68:69] op_sel:[0,1] op_sel_hi:[1,0]
	s_nop 0
	v_permlane16_swap_b32_e32 v66, v0
	v_add_f32_e32 v105, v66, v0
	v_mov_b32_e32 v0, v68
	s_nop 1
	v_permlane16_swap_b32_e32 v68, v0
	v_add_f32_e32 v104, v68, v0
	s_waitcnt vmcnt(0)
	v_permlane32_swap_b32_e32 v90, v98
	v_permlane32_swap_b32_e32 v91, v99
	v_permlane32_swap_b32_e32 v92, v100
	v_permlane32_swap_b32_e32 v93, v101
	v_permlane16_swap_b32_e32 v90, v98
	v_permlane16_swap_b32_e32 v91, v99
	v_permlane16_swap_b32_e32 v92, v100
	v_permlane16_swap_b32_e32 v93, v101
	v_mov_b32_e32 v66, v90
	v_mov_b32_e32 v67, v98
	v_mov_b32_e32 v68, v92
	v_mov_b32_e32 v69, v100
	v_pk_add_f32 v[66:67], v[66:67], v[68:69]
	v_mov_b32_e32 v98, v91
	v_pk_add_f32 v[66:67], v[66:67], v[66:67] op_sel:[0,1] op_sel_hi:[1,0]
	v_mov_b32_e32 v100, v93
	v_mov_b32_e32 v0, v66
	s_nop 1
	v_permlane16_swap_b32_e32 v66, v0
	v_pk_add_f32 v[68:69], v[98:99], v[100:101]
	v_add_f32_e32 v99, v66, v0
	v_ashrrev_i32_e32 v66, 8, v118
	v_ashrrev_i32_e32 v67, 31, v66
	v_pk_add_f32 v[68:69], v[68:69], v[68:69] op_sel:[0,1] op_sel_hi:[1,0]
	v_lshlrev_b64 v[120:121], 19, v[66:67]
	v_lshlrev_b64 v[66:67], 12, v[118:119]
	v_mov_b32_e32 v0, v68
	s_waitcnt lgkmcnt(0)
	v_lshl_add_u64 v[66:67], s[78:79], 0, v[66:67]
	v_permlane16_swap_b32_e32 v68, v0
	v_lshl_add_u64 v[122:123], v[152:153], 2, v[66:67]
	v_add_f32_e32 v98, v68, v0
	s_nop 1
	v_bfe_u32 v71, v227, 4, 2
	v_sub_u32_e32 v70, 0, v71
	v_lshlrev_b32_e32 v70, 4, v70
	v_ashrrev_i32_e32 v71, 31, v70
	v_lshl_add_u64 v[70:71], v[122:123], 0, v[70:71]
	global_load_dwordx4 v[74:77], v[70:71], off offset:64
	global_load_dwordx4 v[86:89], v[70:71], off
	global_load_dwordx4 v[66:69], v[156:157], off offset:16
	global_load_dwordx4 v[78:81], v[156:157], off
	global_load_dwordx4 v[70:73], v[154:155], off offset:16
	global_load_dwordx4 v[82:85], v[154:155], off
	s_nop 1
	v_bfe_u32 v101, v227, 4, 2
	v_sub_u32_e32 v100, 0, v101
	v_lshlrev_b32_e32 v100, 4, v100
	v_ashrrev_i32_e32 v101, 31, v100
	v_lshl_add_u64 v[100:101], v[122:123], 0, v[100:101]
	global_load_dwordx4 v[90:93], v[100:101], off offset:576
	global_load_dwordx4 v[124:127], v[100:101], off offset:512
	global_load_dwordx4 v[128:131], v[156:157], off offset:528
	global_load_dwordx4 v[132:135], v[156:157], off offset:512
	global_load_dwordx4 v[158:161], v[154:155], off offset:528
	global_load_dwordx4 v[162:165], v[154:155], off offset:512
	v_lshlrev_b32_e32 v0, 6, v118
	s_movk_i32 s1, 0x33c0
	v_readlane_b32 s3, v253, 60
	v_and_or_b32 v0, v0, s1, v196
	v_lshlrev_b32_e32 v0, 1, v0
	v_mov_b32_e32 v115, v113
	v_mov_b32_e32 v114, v112
	v_mov_b32_e32 v107, v105
	v_mov_b32_e32 v106, v104
	v_mov_b32_e32 v101, v99
	v_mov_b32_e32 v100, v98
	v_permlane32_swap_b32_e32 v113, v115
	v_permlane32_swap_b32_e32 v112, v114
	v_permlane32_swap_b32_e32 v105, v107
	v_permlane32_swap_b32_e32 v104, v106
	v_permlane32_swap_b32_e32 v99, v101
	v_permlane32_swap_b32_e32 v98, v100
	s_waitcnt vmcnt(10)
	v_permlane32_swap_b32_e32 v86, v74
	v_permlane32_swap_b32_e32 v87, v75
	v_permlane32_swap_b32_e32 v88, v76
	v_permlane32_swap_b32_e32 v89, v77
	v_permlane16_swap_b32_e32 v86, v74
	v_permlane16_swap_b32_e32 v87, v75
	v_permlane16_swap_b32_e32 v88, v76
	v_permlane16_swap_b32_e32 v89, v77
	v_sub_f32_e32 v75, v75, v117
	v_sub_f32_e32 v87, v87, v117
	v_sub_f32_e32 v86, v86, v117
	v_sub_f32_e32 v89, v89, v117
	v_sub_f32_e32 v88, v88, v117
	v_sub_f32_e32 v74, v74, v117
	v_sub_f32_e32 v77, v77, v117
	v_sub_f32_e32 v76, v76, v117
	v_pk_mul_f32 v[88:89], v[116:117], v[88:89] op_sel_hi:[0,1]
	v_pk_mul_f32 v[86:87], v[116:117], v[86:87] op_sel_hi:[0,1]
	v_pk_mul_f32 v[76:77], v[116:117], v[76:77] op_sel_hi:[0,1]
	v_pk_mul_f32 v[74:75], v[116:117], v[74:75] op_sel_hi:[0,1]
	s_waitcnt vmcnt(6)
; __device__ __forceinline__ float xsum16(float v) { const auto r = __builtin_amdgcn_permlane16_swap(__float_as_uint(v), __float_as_uint(v), false, false); return __uint_as_float(r[0]) + __uint_as_float(r[1]); }
; __device__ __forceinline__ float xsum32(float v) { const auto r = __builtin_amdgcn_permlane32_swap(__float_as_uint(v), __float_as_uint(v), false, false); return __uint_as_float(r[0]) + __uint_as_float(r[1]); }
; __device__ __forceinline__ size_t blk_off(int r, int c, int K) { return (size_t)(r >> 8) * 256 * K + (size_t)(c >> 6) * (256 * 64) + (size_t)((r & 255) * 64 + (c & 63)); }
; __device__ __forceinline__ u32x4 pack8(const f32x4 a, const f32x4 b) { u32x4 w; w.x = cvt_pk_bf16(a[0], a[1]); w.y = cvt_pk_bf16(a[2], a[3]); w.z = cvt_pk_bf16(b[0], b[1]); w.w = cvt_pk_bf16(b[2], b[3]); return w; }
;     __device__ __forceinline__ void operator()(const f32x4 (&acc)[2][2][4][2], const pg8::Unit& u, int wr, int wc, int fr, int fq) const {
;     ...
;                 for (int bj = 0; bj < 2; ++bj) { float* yp = Y + (size_t)row * D_ + col0 + bj * 128; f32x4 v[2];
; #pragma unroll
;                     for (int n = 0; n < 2; ++n) { v[n] = (((yv[bj][n] - mu) * rs) * gq[bj][n] + bq_[bj][n]) * ALPHA_ + acc[ai][bj][m][n] * sc;
;                         *(f32x4*)(yp + 4 * n) = v[n]; s1 += (v[n][0] + v[n][1]) + (v[n][2] + v[n][3]); s2 += (v[n][0] * v[n][0] + v[n][1] * v[n][1]) + (v[n][2] * v[n][2] + v[n][3] * v[n][3]); }
;                     *(u32x4*)(Yb + blk_off(row, col0 + bj * 128, D_)) = pack8(v[0], v[1]); }
;                 s1 = xsum32(xsum16(s1)); s2 = xsum32(xsum16(s2));
;                 if (fq == 0) *(f32x2*)(stn + (size_t)row * 32 + (u.pn * 4 + wc) * 2) = (f32x2){s1, s2}; asm volatile("" ::: "memory"); } }
	v_pk_fma_f32 v[78:79], v[78:79], v[86:87], v[82:83]
	v_pk_fma_f32 v[80:81], v[80:81], v[88:89], v[84:85]
	v_pk_fma_f32 v[66:67], v[66:67], v[74:75], v[70:71]
	v_pk_fma_f32 v[68:69], v[68:69], v[76:77], v[72:73]
	v_pk_fma_f32 v[64:65], v[80:81], s[14:15], v[64:65] op_sel_hi:[1,0,1]
	v_pk_fma_f32 v[62:63], v[78:79], s[14:15], v[62:63] op_sel_hi:[1,0,1]
	v_pk_fma_f32 v[60:61], v[68:69], s[14:15], v[60:61] op_sel_hi:[1,0,1]
	v_pk_fma_f32 v[58:59], v[66:67], s[14:15], v[58:59] op_sel_hi:[1,0,1]
	v_add_f32_e32 v78, v62, v63
	v_add_f32_e32 v79, v64, v65
	v_add_f32_e32 v66, v58, v59
	v_add_f32_e32 v67, v60, v61
	v_add_f32_e32 v78, v78, v79
	v_mul_f32_e32 v79, v63, v63
	v_mul_f32_e32 v80, v65, v65
	v_add_f32_e32 v66, v66, v67
	v_mul_f32_e32 v67, v59, v59
	s_nop 0
	v_fmac_f32_e32 v79, v62, v62
	v_fmac_f32_e32 v80, v64, v64
	s_nop 1
	v_bfe_u32 v69, v227, 4, 2
	v_sub_u32_e32 v68, 0, v69
	v_lshlrev_b32_e32 v68, 4, v68
	v_ashrrev_i32_e32 v69, 31, v68
	v_lshl_add_u64 v[68:69], v[122:123], 0, v[68:69]
	v_permlane16_swap_b32_e32 v62, v58
	v_permlane16_swap_b32_e32 v63, v59
	v_permlane16_swap_b32_e32 v64, v60
	v_permlane16_swap_b32_e32 v65, v61
	v_permlane32_swap_b32_e32 v62, v58
	v_permlane32_swap_b32_e32 v63, v59
	v_permlane32_swap_b32_e32 v64, v60
	v_permlane32_swap_b32_e32 v65, v61
	global_store_dwordx4 v[68:69], v[62:65], off
	global_store_dwordx4 v[68:69], v[58:61], off offset:64
	s_nop 1
	v_permlane32_swap_b32_e32 v62, v58
	v_permlane32_swap_b32_e32 v63, v59
	v_permlane32_swap_b32_e32 v64, v60
	v_permlane32_swap_b32_e32 v65, v61
	v_permlane16_swap_b32_e32 v62, v58
	v_permlane16_swap_b32_e32 v63, v59
	v_permlane16_swap_b32_e32 v64, v60
	v_permlane16_swap_b32_e32 v65, v61
	v_fmac_f32_e32 v67, v58, v58
	v_cvt_pk_bf16_f32 v62, v62, v63
	v_cvt_pk_bf16_f32 v63, v64, v65
	v_cvt_pk_bf16_f32 v64, v58, v59
	v_lshl_add_u64 v[58:59], s[2:3], 0, v[120:121]
	v_mul_f32_e32 v68, v61, v61
	v_lshl_add_u64 v[76:77], v[58:59], 0, s[24:25]
	v_fmac_f32_e32 v68, v60, v60
	v_cvt_pk_bf16_f32 v65, v60, v61
	v_lshl_add_u64 v[60:61], v[76:77], 0, v[0:1]
	global_store_dwordx4 v[60:61], v[62:65], off
	s_waitcnt vmcnt(7)
	v_permlane32_swap_b32_e32 v124, v90
	v_permlane32_swap_b32_e32 v125, v91
	v_permlane32_swap_b32_e32 v126, v92
	v_permlane32_swap_b32_e32 v127, v93
	v_permlane16_swap_b32_e32 v124, v90
	v_permlane16_swap_b32_e32 v125, v91
	v_permlane16_swap_b32_e32 v126, v92
	v_permlane16_swap_b32_e32 v127, v93
	v_sub_f32_e32 v61, v125, v117
	v_sub_f32_e32 v60, v124, v117
	v_sub_f32_e32 v63, v127, v117
	v_sub_f32_e32 v62, v126, v117
	v_pk_mul_f32 v[62:63], v[116:117], v[62:63] op_sel_hi:[0,1]
	v_pk_mul_f32 v[60:61], v[116:117], v[60:61] op_sel_hi:[0,1]
	s_waitcnt vmcnt(3)
	v_pk_fma_f32 v[60:61], v[132:133], v[60:61], v[162:163]
	v_pk_fma_f32 v[62:63], v[134:135], v[62:63], v[164:165]
	v_pk_fma_f32 v[54:55], v[60:61], s[14:15], v[54:55] op_sel_hi:[1,0,1]
	v_pk_fma_f32 v[56:57], v[62:63], s[14:15], v[56:57] op_sel_hi:[1,0,1]
	v_add_f32_e32 v78, 0, v78
	v_add_f32_e32 v60, v54, v55
	v_add_f32_e32 v61, v56, v57
	v_add_f32_e32 v66, v78, v66
	v_add_f32_e32 v60, v60, v61
	v_add_f32_e32 v64, v66, v60
	v_mul_f32_e32 v60, v55, v55
	v_mul_f32_e32 v61, v57, v57
	v_add_f32_e32 v79, v79, v80
	v_add_f32_e32 v67, v67, v68
	v_fmac_f32_e32 v60, v54, v54
	v_fmac_f32_e32 v61, v56, v56
	v_add_f32_e32 v67, v79, v67
	v_add_f32_e32 v60, v60, v61
	v_add_f32_e32 v65, v67, v60
	v_sub_f32_e32 v61, v91, v117
	v_sub_f32_e32 v60, v90, v117
	v_sub_f32_e32 v63, v93, v117
	v_sub_f32_e32 v62, v92, v117
	v_pk_mul_f32 v[62:63], v[116:117], v[62:63] op_sel_hi:[0,1]
	v_pk_mul_f32 v[60:61], v[116:117], v[60:61] op_sel_hi:[0,1]
	v_pk_fma_f32 v[60:61], v[128:129], v[60:61], v[158:159]
	v_pk_fma_f32 v[62:63], v[130:131], v[62:63], v[160:161]
	v_pk_fma_f32 v[50:51], v[60:61], s[14:15], v[50:51] op_sel_hi:[1,0,1]
	v_pk_fma_f32 v[52:53], v[62:63], s[14:15], v[52:53] op_sel_hi:[1,0,1]
	v_add_f32_e32 v60, v50, v51
	v_add_f32_e32 v61, v52, v53
	v_add_f32_e32 v60, v60, v61
	v_mul_f32_e32 v61, v51, v51
	v_mul_f32_e32 v62, v53, v53
	v_add_f32_e32 v60, v64, v60
	v_fmac_f32_e32 v61, v50, v50
	v_fmac_f32_e32 v62, v52, v52
	v_lshl_add_u64 v[74:75], v[58:59], 0, s[28:29]
	s_nop 0
	s_nop 1
	v_bfe_u32 v67, v227, 4, 2
	v_sub_u32_e32 v66, 0, v67
	v_lshlrev_b32_e32 v66, 4, v66
	v_ashrrev_i32_e32 v67, 31, v66
	v_lshl_add_u64 v[66:67], v[122:123], 0, v[66:67]
	v_permlane16_swap_b32_e32 v54, v50
	v_permlane16_swap_b32_e32 v55, v51
	v_permlane16_swap_b32_e32 v56, v52
	v_permlane16_swap_b32_e32 v57, v53
	v_permlane32_swap_b32_e32 v54, v50
	v_permlane32_swap_b32_e32 v55, v51
	v_permlane32_swap_b32_e32 v56, v52
	v_permlane32_swap_b32_e32 v57, v53
	global_store_dwordx4 v[66:67], v[54:57], off offset:512
	global_store_dwordx4 v[66:67], v[50:53], off offset:576
	s_nop 1
	v_permlane32_swap_b32_e32 v54, v50
	v_permlane32_swap_b32_e32 v55, v51
	v_permlane32_swap_b32_e32 v56, v52
	v_permlane32_swap_b32_e32 v57, v53
	v_permlane16_swap_b32_e32 v54, v50
	v_permlane16_swap_b32_e32 v55, v51
	v_permlane16_swap_b32_e32 v56, v52
	v_permlane16_swap_b32_e32 v57, v53
	v_add_f32_e32 v61, v61, v62
	v_cvt_pk_bf16_f32 v54, v54, v55
	v_cvt_pk_bf16_f32 v55, v56, v57
	v_cvt_pk_bf16_f32 v56, v50, v51
	v_lshl_add_u64 v[50:51], v[74:75], 0, v[0:1]
	v_mov_b32_e32 v0, v60
	v_add_f32_e32 v61, v65, v61
	v_cvt_pk_bf16_f32 v57, v52, v53
	v_permlane16_swap_b32_e32 v60, v0
	global_store_dwordx4 v[50:51], v[54:57], off
	v_add_f32_e32 v50, v60, v0
	v_mov_b32_e32 v0, v61
	s_nop 1
	v_permlane16_swap_b32_e32 v61, v0
	v_add_f32_e32 v51, v61, v0
	v_mov_b32_e32 v52, v50
	v_mov_b32_e32 v53, v51
	s_nop 0
	v_permlane32_swap_b32_e32 v50, v52
	v_permlane32_swap_b32_e32 v51, v53
	s_and_saveexec_b64 s[24:25], s[44:45]
	s_cbranch_execz .LBB0_1545
	v_pk_add_f32 v[50:51], v[50:51], v[52:53]
	v_lshl_add_u64 v[52:53], s[6:7], 0, v[110:111]
	v_lshl_add_u64 v[52:53], s[52:53], 2, v[52:53]
	global_store_dwordx2 v[52:53], v[50:51], off
; __device__ __forceinline__ size_t blk_off(int r, int c, int K) { return (size_t)(r >> 8) * 256 * K + (size_t)(c >> 6) * (256 * 64) + (size_t)((r & 255) * 64 + (c & 63)); }
; __device__ __forceinline__ u32x4 pack8(const f32x4 a, const f32x4 b) { u32x4 w; w.x = cvt_pk_bf16(a[0], a[1]); w.y = cvt_pk_bf16(a[2], a[3]); w.z = cvt_pk_bf16(b[0], b[1]); w.w = cvt_pk_bf16(b[2], b[3]); return w; }
;     __device__ __forceinline__ void operator()(const f32x4 (&acc)[2][2][4][2], const pg8::Unit& u, int wr, int wc, int fr, int fq) const {
;     ...
;             for (int m = 0; m < 4; ++m) { const int row = row0 + ai * 128 + m * 16; const float mu = mu4[m], rs = rs4[m];
;                 f32x4 yv[2][2], gq[2][2], bq_[2][2];
; #pragma unroll
;                 for (int bj = 0; bj < 2; ++bj)
; #pragma unroll
;                     for (int n = 0; n < 2; ++n) { yv[bj][n] = *(const f32x4*)(Yin + (size_t)row * D_ + col0 + bj * 128 + 4 * n); gq[bj][n] = *(const f32x4*)(g + col0 + bj * 128 + 4 * n); bq_[bj][n] = *(const f32x4*)(b + col0 + bj * 128 + 4 * n); }
;                 asm volatile("" ::: "memory");
;                 float s1 = 0.f, s2 = 0.f;
; #pragma unroll
;                 for (int bj = 0; bj < 2; ++bj) { float* yp = Y + (size_t)row * D_ + col0 + bj * 128; f32x4 v[2];
; #pragma unroll
;                     for (int n = 0; n < 2; ++n) { v[n] = (((yv[bj][n] - mu) * rs) * gq[bj][n] + bq_[bj][n]) * ALPHA_ + acc[ai][bj][m][n] * sc;
;                         *(f32x4*)(yp + 4 * n) = v[n]; s1 += (v[n][0] + v[n][1]) + (v[n][2] + v[n][3]); s2 += (v[n][0] * v[n][0] + v[n][1] * v[n][1]) + (v[n][2] * v[n][2] + v[n][3] * v[n][3]); }
;                     *(u32x4*)(Yb + blk_off(row, col0 + bj * 128, D_)) = pack8(v[0], v[1]); }
.LBB0_1545:
	s_or_b64 exec, exec, s[24:25]
	v_pk_add_f32 v[50:51], v[112:113], v[114:115]
	s_mov_b32 s2, 0x3a800000
	v_pk_mul_f32 v[78:79], v[50:51], s[2:3] op_sel_hi:[1,0]
	s_mov_b32 s1, 0x800000
	v_fma_f32 v0, -v79, v79, v78
	v_max_f32_e32 v0, 0, v0
	v_add_f32_e32 v0, 0x3727c5ac, v0
	v_cmp_gt_f32_e32 vcc, s1, v0
	v_mul_f32_e32 v50, 0x4b800000, v0
	s_load_dwordx16 s[64:79], s[34:35], 0x38
	v_cndmask_b32_e32 v0, v0, v50, vcc
	v_rsq_f32_e32 v0, v0
	s_mov_b32 s2, 0x3fd744fd
	s_movk_i32 s1, 0x37c0
	v_mul_f32_e32 v50, 0x45800000, v0
	v_cndmask_b32_e32 v78, v0, v50, vcc
	v_lshlrev_b64 v[50:51], 12, v[108:109]
	s_waitcnt lgkmcnt(0)
	v_lshl_add_u64 v[50:51], s[78:79], 0, v[50:51]
	v_lshl_add_u64 v[80:81], v[152:153], 2, v[50:51]
	s_nop 1
	v_bfe_u32 v53, v227, 4, 2
	v_sub_u32_e32 v52, 0, v53
	v_lshlrev_b32_e32 v52, 4, v52
	v_ashrrev_i32_e32 v53, 31, v52
	v_lshl_add_u64 v[52:53], v[80:81], 0, v[52:53]
	global_load_dwordx4 v[82:85], v[52:53], off offset:64
	global_load_dwordx4 v[86:89], v[52:53], off
	global_load_dwordx4 v[90:93], v[156:157], off offset:16
	global_load_dwordx4 v[110:113], v[156:157], off
	global_load_dwordx4 v[114:117], v[154:155], off offset:16
	global_load_dwordx4 v[118:121], v[154:155], off
	s_nop 1
	v_bfe_u32 v55, v227, 4, 2
	v_sub_u32_e32 v54, 0, v55
	v_lshlrev_b32_e32 v54, 4, v54
	v_ashrrev_i32_e32 v55, 31, v54
	v_lshl_add_u64 v[54:55], v[80:81], 0, v[54:55]
	global_load_dwordx4 v[50:53], v[54:55], off offset:576
	global_load_dwordx4 v[70:73], v[54:55], off offset:512
	global_load_dwordx4 v[54:57], v[156:157], off offset:528
	global_load_dwordx4 v[62:65], v[156:157], off offset:512
	global_load_dwordx4 v[58:61], v[154:155], off offset:528
	global_load_dwordx4 v[66:69], v[154:155], off offset:512
	v_lshlrev_b32_e32 v0, 6, v108
	v_and_or_b32 v0, v0, s1, v196
	v_lshlrev_b32_e32 v0, 1, v0
	s_waitcnt vmcnt(10)
	v_permlane32_swap_b32_e32 v86, v82
	v_permlane32_swap_b32_e32 v87, v83
	v_permlane32_swap_b32_e32 v88, v84
	v_permlane32_swap_b32_e32 v89, v85
	v_permlane16_swap_b32_e32 v86, v82
	v_permlane16_swap_b32_e32 v87, v83
	v_permlane16_swap_b32_e32 v88, v84
	v_permlane16_swap_b32_e32 v89, v85
	v_sub_f32_e32 v87, v87, v79
	v_sub_f32_e32 v86, v86, v79
	v_sub_f32_e32 v89, v89, v79
	v_sub_f32_e32 v88, v88, v79
	v_pk_mul_f32 v[88:89], v[78:79], v[88:89] op_sel_hi:[0,1]
	v_pk_mul_f32 v[86:87], v[78:79], v[86:87] op_sel_hi:[0,1]
	s_waitcnt vmcnt(6)
	v_pk_fma_f32 v[86:87], v[110:111], v[86:87], v[118:119]
	v_pk_fma_f32 v[88:89], v[112:113], v[88:89], v[120:121]
	v_pk_fma_f32 v[86:87], v[86:87], s[2:3], v[46:47] op_sel_hi:[1,0,1]
	v_pk_fma_f32 v[88:89], v[88:89], s[2:3], v[48:49] op_sel_hi:[1,0,1]
	v_add_f32_e32 v46, v86, v87
	v_add_f32_e32 v47, v88, v89
	v_add_f32_e32 v46, v46, v47
	v_add_f32_e32 v108, 0, v46
	v_mul_f32_e32 v46, v87, v87
	v_mul_f32_e32 v47, v89, v89
	v_fmac_f32_e32 v46, v86, v86
	v_fmac_f32_e32 v47, v88, v88
	v_add_f32_e32 v109, v46, v47
	v_sub_f32_e32 v47, v83, v79
	v_sub_f32_e32 v46, v82, v79
	v_sub_f32_e32 v49, v85, v79
	v_sub_f32_e32 v48, v84, v79
	v_pk_mul_f32 v[48:49], v[78:79], v[48:49] op_sel_hi:[0,1]
	v_pk_mul_f32 v[46:47], v[78:79], v[46:47] op_sel_hi:[0,1]
	v_pk_fma_f32 v[46:47], v[90:91], v[46:47], v[114:115]
	v_pk_fma_f32 v[48:49], v[92:93], v[48:49], v[116:117]
	v_pk_fma_f32 v[82:83], v[46:47], s[2:3], v[42:43] op_sel_hi:[1,0,1]
	v_pk_fma_f32 v[84:85], v[48:49], s[2:3], v[44:45] op_sel_hi:[1,0,1]
	v_add_f32_e32 v42, v82, v83
	v_add_f32_e32 v43, v84, v85
	v_add_f32_e32 v42, v42, v43
	v_add_f32_e32 v47, v108, v42
	v_mul_f32_e32 v42, v83, v83
	v_mul_f32_e32 v43, v85, v85
	v_fmac_f32_e32 v42, v82, v82
	v_fmac_f32_e32 v43, v84, v84
	v_add_f32_e32 v42, v42, v43
	v_add_f32_e32 v46, v109, v42
	v_cvt_pk_bf16_f32 v42, v86, v87
	v_cvt_pk_bf16_f32 v43, v88, v89
	v_cvt_pk_bf16_f32 v44, v82, v83
	v_cvt_pk_bf16_f32 v45, v84, v85
	v_lshl_add_u64 v[48:49], v[76:77], 0, v[0:1]
	s_nop 0
	s_nop 1
	v_bfe_u32 v91, v227, 4, 2
	v_sub_u32_e32 v90, 0, v91
	v_lshlrev_b32_e32 v90, 4, v90
	v_ashrrev_i32_e32 v91, 31, v90
	v_lshl_add_u64 v[90:91], v[80:81], 0, v[90:91]
	v_permlane16_swap_b32_e32 v86, v82
	v_permlane16_swap_b32_e32 v87, v83
	v_permlane16_swap_b32_e32 v88, v84
	v_permlane16_swap_b32_e32 v89, v85
	v_permlane32_swap_b32_e32 v86, v82
	v_permlane32_swap_b32_e32 v87, v83
	v_permlane32_swap_b32_e32 v88, v84
	v_permlane32_swap_b32_e32 v89, v85
	global_store_dwordx4 v[90:91], v[86:89], off
	global_store_dwordx4 v[90:91], v[82:85], off offset:64
	s_nop 1
	v_permlane32_swap_b32_e32 v86, v82
	v_permlane32_swap_b32_e32 v87, v83
	v_permlane32_swap_b32_e32 v88, v84
	v_permlane32_swap_b32_e32 v89, v85
	v_permlane16_swap_b32_e32 v86, v82
	v_permlane16_swap_b32_e32 v87, v83
	v_permlane16_swap_b32_e32 v88, v84
	v_permlane16_swap_b32_e32 v89, v85
	global_store_dwordx4 v[48:49], v[42:45], off
	s_nop 0
	s_waitcnt vmcnt(7)
	v_permlane32_swap_b32_e32 v70, v50
	v_permlane32_swap_b32_e32 v71, v51
	v_permlane32_swap_b32_e32 v72, v52
	v_permlane32_swap_b32_e32 v73, v53
	v_permlane16_swap_b32_e32 v70, v50
	v_permlane16_swap_b32_e32 v71, v51
	v_permlane16_swap_b32_e32 v72, v52
	v_permlane16_swap_b32_e32 v73, v53
	v_sub_f32_e32 v43, v71, v79
	v_sub_f32_e32 v42, v70, v79
	v_sub_f32_e32 v45, v73, v79
	v_sub_f32_e32 v44, v72, v79
	v_pk_mul_f32 v[44:45], v[78:79], v[44:45] op_sel_hi:[0,1]
	v_pk_mul_f32 v[42:43], v[78:79], v[42:43] op_sel_hi:[0,1]
	s_waitcnt vmcnt(3)
; __device__ __forceinline__ float xsum16(float v) { const auto r = __builtin_amdgcn_permlane16_swap(__float_as_uint(v), __float_as_uint(v), false, false); return __uint_as_float(r[0]) + __uint_as_float(r[1]); }
; __device__ __forceinline__ float xsum32(float v) { const auto r = __builtin_amdgcn_permlane32_swap(__float_as_uint(v), __float_as_uint(v), false, false); return __uint_as_float(r[0]) + __uint_as_float(r[1]); }
; __device__ __forceinline__ size_t blk_off(int r, int c, int K) { return (size_t)(r >> 8) * 256 * K + (size_t)(c >> 6) * (256 * 64) + (size_t)((r & 255) * 64 + (c & 63)); }
; __device__ __forceinline__ u32x4 pack8(const f32x4 a, const f32x4 b) { u32x4 w; w.x = cvt_pk_bf16(a[0], a[1]); w.y = cvt_pk_bf16(a[2], a[3]); w.z = cvt_pk_bf16(b[0], b[1]); w.w = cvt_pk_bf16(b[2], b[3]); return w; }
;     __device__ __forceinline__ void operator()(const f32x4 (&acc)[2][2][4][2], const pg8::Unit& u, int wr, int wc, int fr, int fq) const {
;     ...
;                     for (int n = 0; n < 2; ++n) { yv[bj][n] = *(const f32x4*)(Yin + (size_t)row * D_ + col0 + bj * 128 + 4 * n); gq[bj][n] = *(const f32x4*)(g + col0 + bj * 128 + 4 * n); bq_[bj][n] = *(const f32x4*)(b + col0 + bj * 128 + 4 * n); }
;                 asm volatile("" ::: "memory");
;                 float s1 = 0.f, s2 = 0.f;
; #pragma unroll
;                 for (int bj = 0; bj < 2; ++bj) { float* yp = Y + (size_t)row * D_ + col0 + bj * 128; f32x4 v[2];
; #pragma unroll
;                     for (int n = 0; n < 2; ++n) { v[n] = (((yv[bj][n] - mu) * rs) * gq[bj][n] + bq_[bj][n]) * ALPHA_ + acc[ai][bj][m][n] * sc;
;                         *(f32x4*)(yp + 4 * n) = v[n]; s1 += (v[n][0] + v[n][1]) + (v[n][2] + v[n][3]); s2 += (v[n][0] * v[n][0] + v[n][1] * v[n][1]) + (v[n][2] * v[n][2] + v[n][3] * v[n][3]); }
;                     *(u32x4*)(Yb + blk_off(row, col0 + bj * 128, D_)) = pack8(v[0], v[1]); }
;                 s1 = xsum32(xsum16(s1)); s2 = xsum32(xsum16(s2));
;                 if (fq == 0) *(f32x2*)(stn + (size_t)row * 32 + (u.pn * 4 + wc) * 2) = (f32x2){s1, s2}; asm volatile("" ::: "memory"); } }
	v_pk_fma_f32 v[42:43], v[62:63], v[42:43], v[66:67]
	v_pk_fma_f32 v[44:45], v[64:65], v[44:45], v[68:69]
	v_pk_fma_f32 v[38:39], v[42:43], s[2:3], v[38:39] op_sel_hi:[1,0,1]
	v_pk_fma_f32 v[40:41], v[44:45], s[2:3], v[40:41] op_sel_hi:[1,0,1]
	v_add_f32_e32 v42, v38, v39
	v_add_f32_e32 v43, v40, v41
	v_add_f32_e32 v42, v42, v43
	v_add_f32_e32 v47, v47, v42
	v_mul_f32_e32 v42, v39, v39
	v_mul_f32_e32 v43, v41, v41
	v_fmac_f32_e32 v42, v38, v38
	v_fmac_f32_e32 v43, v40, v40
	v_add_f32_e32 v42, v42, v43
	v_add_f32_e32 v46, v46, v42
	v_sub_f32_e32 v43, v51, v79
	v_sub_f32_e32 v42, v50, v79
	v_sub_f32_e32 v45, v53, v79
	v_sub_f32_e32 v44, v52, v79
	v_pk_mul_f32 v[44:45], v[78:79], v[44:45] op_sel_hi:[0,1]
	v_pk_mul_f32 v[42:43], v[78:79], v[42:43] op_sel_hi:[0,1]
	v_pk_fma_f32 v[42:43], v[54:55], v[42:43], v[58:59]
	v_pk_fma_f32 v[44:45], v[56:57], v[44:45], v[60:61]
	v_pk_fma_f32 v[34:35], v[42:43], s[2:3], v[34:35] op_sel_hi:[1,0,1]
	v_pk_fma_f32 v[36:37], v[44:45], s[2:3], v[36:37] op_sel_hi:[1,0,1]
	v_add_f32_e32 v42, v34, v35
	v_add_f32_e32 v43, v36, v37
	v_add_f32_e32 v42, v42, v43
	v_mul_f32_e32 v43, v35, v35
	v_mul_f32_e32 v44, v37, v37
	v_add_f32_e32 v42, v47, v42
	v_fmac_f32_e32 v43, v34, v34
	v_fmac_f32_e32 v44, v36, v36
	s_nop 0
	s_nop 1
	v_bfe_u32 v49, v227, 4, 2
	v_sub_u32_e32 v48, 0, v49
	v_lshlrev_b32_e32 v48, 4, v48
	v_ashrrev_i32_e32 v49, 31, v48
	v_lshl_add_u64 v[48:49], v[80:81], 0, v[48:49]
	v_permlane16_swap_b32_e32 v38, v34
	v_permlane16_swap_b32_e32 v39, v35
	v_permlane16_swap_b32_e32 v40, v36
	v_permlane16_swap_b32_e32 v41, v37
	v_permlane32_swap_b32_e32 v38, v34
	v_permlane32_swap_b32_e32 v39, v35
	v_permlane32_swap_b32_e32 v40, v36
	v_permlane32_swap_b32_e32 v41, v37
	global_store_dwordx4 v[48:49], v[38:41], off offset:512
	global_store_dwordx4 v[48:49], v[34:37], off offset:576
	s_nop 1
	v_permlane32_swap_b32_e32 v38, v34
	v_permlane32_swap_b32_e32 v39, v35
	v_permlane32_swap_b32_e32 v40, v36
	v_permlane32_swap_b32_e32 v41, v37
	v_permlane16_swap_b32_e32 v38, v34
	v_permlane16_swap_b32_e32 v39, v35
	v_permlane16_swap_b32_e32 v40, v36
	v_permlane16_swap_b32_e32 v41, v37
	v_add_f32_e32 v43, v43, v44
	v_cvt_pk_bf16_f32 v38, v38, v39
	v_cvt_pk_bf16_f32 v39, v40, v41
	v_cvt_pk_bf16_f32 v40, v34, v35
	v_lshl_add_u64 v[34:35], v[74:75], 0, v[0:1]
	v_mov_b32_e32 v0, v42
	v_add_f32_e32 v43, v46, v43
	v_cvt_pk_bf16_f32 v41, v36, v37
	v_permlane16_swap_b32_e32 v42, v0
	global_store_dwordx4 v[34:35], v[38:41], off
	v_add_f32_e32 v34, v42, v0
	v_mov_b32_e32 v0, v43
	s_nop 1
	v_permlane16_swap_b32_e32 v43, v0
	v_add_f32_e32 v35, v43, v0
	v_mov_b32_e32 v36, v34
	v_mov_b32_e32 v37, v35
	s_nop 0
	v_permlane32_swap_b32_e32 v34, v36
	v_permlane32_swap_b32_e32 v35, v37
	s_and_saveexec_b64 s[24:25], s[44:45]
	s_cbranch_execz .LBB0_1547
	v_pk_add_f32 v[34:35], v[34:35], v[36:37]
	v_lshl_add_u64 v[36:37], s[6:7], 0, v[102:103]
	v_lshl_add_u64 v[36:37], s[52:53], 2, v[36:37]
	global_store_dwordx2 v[36:37], v[34:35], off
.LBB0_1547:
	s_or_b64 exec, exec, s[24:25]
	v_pk_add_f32 v[34:35], v[104:105], v[106:107]
	s_mov_b32 s2, 0x3a800000
	v_pk_mul_f32 v[58:59], v[34:35], s[2:3] op_sel_hi:[1,0]
	s_mov_b32 s1, 0x800000
	v_fma_f32 v0, -v59, v59, v58
	v_max_f32_e32 v0, 0, v0
	v_add_f32_e32 v0, 0x3727c5ac, v0
	v_cmp_gt_f32_e32 vcc, s1, v0
	v_mul_f32_e32 v34, 0x4b800000, v0
	s_load_dwordx16 s[64:79], s[34:35], 0x38
	v_cndmask_b32_e32 v0, v0, v34, vcc
	v_rsq_f32_e32 v0, v0
	s_mov_b32 s2, 0x3fd744fd
	s_movk_i32 s1, 0x3bc0
	v_mul_f32_e32 v34, 0x45800000, v0
	v_cndmask_b32_e32 v58, v0, v34, vcc
	v_lshlrev_b64 v[34:35], 12, v[96:97]
	s_waitcnt lgkmcnt(0)
	v_lshl_add_u64 v[34:35], s[78:79], 0, v[34:35]
	v_lshl_add_u64 v[60:61], v[152:153], 2, v[34:35]
	s_nop 1
	v_bfe_u32 v37, v227, 4, 2
	v_sub_u32_e32 v36, 0, v37
	v_lshlrev_b32_e32 v36, 4, v36
	v_ashrrev_i32_e32 v37, 31, v36
	v_lshl_add_u64 v[36:37], v[60:61], 0, v[36:37]
	global_load_dwordx4 v[62:65], v[36:37], off offset:64
	global_load_dwordx4 v[66:69], v[36:37], off
	global_load_dwordx4 v[70:73], v[156:157], off offset:16
	global_load_dwordx4 v[78:81], v[156:157], off
	global_load_dwordx4 v[82:85], v[154:155], off offset:16
	global_load_dwordx4 v[86:89], v[154:155], off
	s_nop 1
	v_bfe_u32 v39, v227, 4, 2
	v_sub_u32_e32 v38, 0, v39
	v_lshlrev_b32_e32 v38, 4, v38
	v_ashrrev_i32_e32 v39, 31, v38
	v_lshl_add_u64 v[38:39], v[60:61], 0, v[38:39]
	global_load_dwordx4 v[34:37], v[38:39], off offset:576
	global_load_dwordx4 v[54:57], v[38:39], off offset:512
	global_load_dwordx4 v[38:41], v[156:157], off offset:528
	global_load_dwordx4 v[46:49], v[156:157], off offset:512
	global_load_dwordx4 v[42:45], v[154:155], off offset:528
	global_load_dwordx4 v[50:53], v[154:155], off offset:512
	v_lshlrev_b32_e32 v0, 6, v96
	v_and_or_b32 v0, v0, s1, v196
	v_lshlrev_b32_e32 v0, 1, v0
	s_waitcnt vmcnt(10)
	v_permlane32_swap_b32_e32 v66, v62
	v_permlane32_swap_b32_e32 v67, v63
	v_permlane32_swap_b32_e32 v68, v64
	v_permlane32_swap_b32_e32 v69, v65
	v_permlane16_swap_b32_e32 v66, v62
	v_permlane16_swap_b32_e32 v67, v63
	v_permlane16_swap_b32_e32 v68, v64
	v_permlane16_swap_b32_e32 v69, v65
	v_sub_f32_e32 v67, v67, v59
	v_sub_f32_e32 v66, v66, v59
	v_sub_f32_e32 v69, v69, v59
	v_sub_f32_e32 v68, v68, v59
	v_pk_mul_f32 v[68:69], v[58:59], v[68:69] op_sel_hi:[0,1]
	v_pk_mul_f32 v[66:67], v[58:59], v[66:67] op_sel_hi:[0,1]
	s_waitcnt vmcnt(6)
; __device__ __forceinline__ float xsum16(float v) { const auto r = __builtin_amdgcn_permlane16_swap(__float_as_uint(v), __float_as_uint(v), false, false); return __uint_as_float(r[0]) + __uint_as_float(r[1]); }
; __device__ __forceinline__ float xsum32(float v) { const auto r = __builtin_amdgcn_permlane32_swap(__float_as_uint(v), __float_as_uint(v), false, false); return __uint_as_float(r[0]) + __uint_as_float(r[1]); }
; __device__ __forceinline__ size_t blk_off(int r, int c, int K) { return (size_t)(r >> 8) * 256 * K + (size_t)(c >> 6) * (256 * 64) + (size_t)((r & 255) * 64 + (c & 63)); }
; __device__ __forceinline__ u32x4 pack8(const f32x4 a, const f32x4 b) { u32x4 w; w.x = cvt_pk_bf16(a[0], a[1]); w.y = cvt_pk_bf16(a[2], a[3]); w.z = cvt_pk_bf16(b[0], b[1]); w.w = cvt_pk_bf16(b[2], b[3]); return w; }
;     __device__ __forceinline__ void operator()(const f32x4 (&acc)[2][2][4][2], const pg8::Unit& u, int wr, int wc, int fr, int fq) const {
;     ...
;                     for (int n = 0; n < 2; ++n) { yv[bj][n] = *(const f32x4*)(Yin + (size_t)row * D_ + col0 + bj * 128 + 4 * n); gq[bj][n] = *(const f32x4*)(g + col0 + bj * 128 + 4 * n); bq_[bj][n] = *(const f32x4*)(b + col0 + bj * 128 + 4 * n); }
;                 asm volatile("" ::: "memory");
;                 float s1 = 0.f, s2 = 0.f;
; #pragma unroll
;                 for (int bj = 0; bj < 2; ++bj) { float* yp = Y + (size_t)row * D_ + col0 + bj * 128; f32x4 v[2];
; #pragma unroll
;                     for (int n = 0; n < 2; ++n) { v[n] = (((yv[bj][n] - mu) * rs) * gq[bj][n] + bq_[bj][n]) * ALPHA_ + acc[ai][bj][m][n] * sc;
;                         *(f32x4*)(yp + 4 * n) = v[n]; s1 += (v[n][0] + v[n][1]) + (v[n][2] + v[n][3]); s2 += (v[n][0] * v[n][0] + v[n][1] * v[n][1]) + (v[n][2] * v[n][2] + v[n][3] * v[n][3]); }
;                     *(u32x4*)(Yb + blk_off(row, col0 + bj * 128, D_)) = pack8(v[0], v[1]); }
;                 s1 = xsum32(xsum16(s1)); s2 = xsum32(xsum16(s2));
;                 if (fq == 0) *(f32x2*)(stn + (size_t)row * 32 + (u.pn * 4 + wc) * 2) = (f32x2){s1, s2}; asm volatile("" ::: "memory"); } }
	v_pk_fma_f32 v[66:67], v[78:79], v[66:67], v[86:87]
	v_pk_fma_f32 v[68:69], v[80:81], v[68:69], v[88:89]
	v_pk_fma_f32 v[66:67], v[66:67], s[2:3], v[30:31] op_sel_hi:[1,0,1]
	v_pk_fma_f32 v[68:69], v[68:69], s[2:3], v[32:33] op_sel_hi:[1,0,1]
	v_add_f32_e32 v30, v66, v67
	v_add_f32_e32 v31, v68, v69
	v_add_f32_e32 v30, v30, v31
	v_add_f32_e32 v78, 0, v30
	v_mul_f32_e32 v30, v67, v67
	v_mul_f32_e32 v31, v69, v69
	v_fmac_f32_e32 v30, v66, v66
	v_fmac_f32_e32 v31, v68, v68
	v_add_f32_e32 v79, v30, v31
	v_sub_f32_e32 v31, v63, v59
	v_sub_f32_e32 v30, v62, v59
	v_sub_f32_e32 v33, v65, v59
	v_sub_f32_e32 v32, v64, v59
	v_pk_mul_f32 v[32:33], v[58:59], v[32:33] op_sel_hi:[0,1]
	v_pk_mul_f32 v[30:31], v[58:59], v[30:31] op_sel_hi:[0,1]
	v_pk_fma_f32 v[30:31], v[70:71], v[30:31], v[82:83]
	v_pk_fma_f32 v[32:33], v[72:73], v[32:33], v[84:85]
	v_pk_fma_f32 v[62:63], v[30:31], s[2:3], v[26:27] op_sel_hi:[1,0,1]
	v_pk_fma_f32 v[64:65], v[32:33], s[2:3], v[28:29] op_sel_hi:[1,0,1]
	v_add_f32_e32 v26, v62, v63
	v_add_f32_e32 v27, v64, v65
	v_add_f32_e32 v26, v26, v27
	v_add_f32_e32 v31, v78, v26
	v_mul_f32_e32 v26, v63, v63
	v_mul_f32_e32 v27, v65, v65
	v_fmac_f32_e32 v26, v62, v62
	v_fmac_f32_e32 v27, v64, v64
	v_add_f32_e32 v26, v26, v27
	v_add_f32_e32 v30, v79, v26
	v_cvt_pk_bf16_f32 v26, v66, v67
	v_cvt_pk_bf16_f32 v27, v68, v69
	v_cvt_pk_bf16_f32 v28, v62, v63
	v_cvt_pk_bf16_f32 v29, v64, v65
	v_lshl_add_u64 v[32:33], v[76:77], 0, v[0:1]
	s_nop 0
	s_nop 1
	v_bfe_u32 v71, v227, 4, 2
	v_sub_u32_e32 v70, 0, v71
	v_lshlrev_b32_e32 v70, 4, v70
	v_ashrrev_i32_e32 v71, 31, v70
	v_lshl_add_u64 v[70:71], v[60:61], 0, v[70:71]
	v_permlane16_swap_b32_e32 v66, v62
	v_permlane16_swap_b32_e32 v67, v63
	v_permlane16_swap_b32_e32 v68, v64
	v_permlane16_swap_b32_e32 v69, v65
	v_permlane32_swap_b32_e32 v66, v62
	v_permlane32_swap_b32_e32 v67, v63
	v_permlane32_swap_b32_e32 v68, v64
	v_permlane32_swap_b32_e32 v69, v65
	global_store_dwordx4 v[70:71], v[66:69], off
	global_store_dwordx4 v[70:71], v[62:65], off offset:64
	s_nop 1
	v_permlane32_swap_b32_e32 v66, v62
	v_permlane32_swap_b32_e32 v67, v63
	v_permlane32_swap_b32_e32 v68, v64
	v_permlane32_swap_b32_e32 v69, v65
	v_permlane16_swap_b32_e32 v66, v62
	v_permlane16_swap_b32_e32 v67, v63
	v_permlane16_swap_b32_e32 v68, v64
	v_permlane16_swap_b32_e32 v69, v65
	global_store_dwordx4 v[32:33], v[26:29], off
	s_nop 0
	s_waitcnt vmcnt(7)
	v_permlane32_swap_b32_e32 v54, v34
	v_permlane32_swap_b32_e32 v55, v35
	v_permlane32_swap_b32_e32 v56, v36
	v_permlane32_swap_b32_e32 v57, v37
	v_permlane16_swap_b32_e32 v54, v34
	v_permlane16_swap_b32_e32 v55, v35
	v_permlane16_swap_b32_e32 v56, v36
	v_permlane16_swap_b32_e32 v57, v37
	v_sub_f32_e32 v27, v55, v59
	v_sub_f32_e32 v26, v54, v59
	v_sub_f32_e32 v29, v57, v59
	v_sub_f32_e32 v28, v56, v59
	v_pk_mul_f32 v[28:29], v[58:59], v[28:29] op_sel_hi:[0,1]
	v_pk_mul_f32 v[26:27], v[58:59], v[26:27] op_sel_hi:[0,1]
	s_waitcnt vmcnt(3)
	v_pk_fma_f32 v[26:27], v[46:47], v[26:27], v[50:51]
	v_pk_fma_f32 v[28:29], v[48:49], v[28:29], v[52:53]
	v_pk_fma_f32 v[22:23], v[26:27], s[2:3], v[22:23] op_sel_hi:[1,0,1]
	v_pk_fma_f32 v[24:25], v[28:29], s[2:3], v[24:25] op_sel_hi:[1,0,1]
	v_add_f32_e32 v26, v22, v23
	v_add_f32_e32 v27, v24, v25
	v_add_f32_e32 v26, v26, v27
	v_add_f32_e32 v31, v31, v26
	v_mul_f32_e32 v26, v23, v23
	v_mul_f32_e32 v27, v25, v25
	v_fmac_f32_e32 v26, v22, v22
	v_fmac_f32_e32 v27, v24, v24
	v_add_f32_e32 v26, v26, v27
	v_add_f32_e32 v30, v30, v26
	v_sub_f32_e32 v27, v35, v59
	v_sub_f32_e32 v26, v34, v59
	v_sub_f32_e32 v29, v37, v59
	v_sub_f32_e32 v28, v36, v59
	v_pk_mul_f32 v[28:29], v[58:59], v[28:29] op_sel_hi:[0,1]
	v_pk_mul_f32 v[26:27], v[58:59], v[26:27] op_sel_hi:[0,1]
	v_pk_fma_f32 v[26:27], v[38:39], v[26:27], v[42:43]
	v_pk_fma_f32 v[28:29], v[40:41], v[28:29], v[44:45]
	v_pk_fma_f32 v[18:19], v[26:27], s[2:3], v[18:19] op_sel_hi:[1,0,1]
	v_pk_fma_f32 v[20:21], v[28:29], s[2:3], v[20:21] op_sel_hi:[1,0,1]
	v_add_f32_e32 v26, v18, v19
	v_add_f32_e32 v27, v20, v21
	v_add_f32_e32 v26, v26, v27
	v_mul_f32_e32 v27, v19, v19
	v_mul_f32_e32 v28, v21, v21
	v_add_f32_e32 v26, v31, v26
	v_fmac_f32_e32 v27, v18, v18
	v_fmac_f32_e32 v28, v20, v20
	s_nop 0
	s_nop 1
	v_bfe_u32 v33, v227, 4, 2
	v_sub_u32_e32 v32, 0, v33
	v_lshlrev_b32_e32 v32, 4, v32
	v_ashrrev_i32_e32 v33, 31, v32
	v_lshl_add_u64 v[32:33], v[60:61], 0, v[32:33]
	v_permlane16_swap_b32_e32 v22, v18
	v_permlane16_swap_b32_e32 v23, v19
	v_permlane16_swap_b32_e32 v24, v20
	v_permlane16_swap_b32_e32 v25, v21
	v_permlane32_swap_b32_e32 v22, v18
	v_permlane32_swap_b32_e32 v23, v19
	v_permlane32_swap_b32_e32 v24, v20
	v_permlane32_swap_b32_e32 v25, v21
	global_store_dwordx4 v[32:33], v[22:25], off offset:512
	global_store_dwordx4 v[32:33], v[18:21], off offset:576
	s_nop 1
	v_permlane32_swap_b32_e32 v22, v18
	v_permlane32_swap_b32_e32 v23, v19
	v_permlane32_swap_b32_e32 v24, v20
	v_permlane32_swap_b32_e32 v25, v21
	v_permlane16_swap_b32_e32 v22, v18
	v_permlane16_swap_b32_e32 v23, v19
	v_permlane16_swap_b32_e32 v24, v20
	v_permlane16_swap_b32_e32 v25, v21
	v_add_f32_e32 v27, v27, v28
	v_cvt_pk_bf16_f32 v22, v22, v23
	v_cvt_pk_bf16_f32 v23, v24, v25
	v_cvt_pk_bf16_f32 v24, v18, v19
	v_lshl_add_u64 v[18:19], v[74:75], 0, v[0:1]
	v_mov_b32_e32 v0, v26
	v_add_f32_e32 v27, v30, v27
	v_cvt_pk_bf16_f32 v25, v20, v21
	v_permlane16_swap_b32_e32 v26, v0
	global_store_dwordx4 v[18:19], v[22:25], off
	v_add_f32_e32 v18, v26, v0
	v_mov_b32_e32 v0, v27
	s_nop 1
	v_permlane16_swap_b32_e32 v27, v0
	v_add_f32_e32 v19, v27, v0
	v_mov_b32_e32 v20, v18
	v_mov_b32_e32 v21, v19
	s_nop 0
	v_permlane32_swap_b32_e32 v18, v20
	v_permlane32_swap_b32_e32 v19, v21
	s_and_saveexec_b64 s[24:25], s[44:45]
	s_cbranch_execz .LBB0_1549
	v_pk_add_f32 v[18:19], v[18:19], v[20:21]
	v_lshlrev_b64 v[20:21], 7, v[96:97]
	v_lshl_add_u64 v[20:21], s[6:7], 0, v[20:21]
	v_lshl_add_u64 v[20:21], s[52:53], 2, v[20:21]
	global_store_dwordx2 v[20:21], v[18:19], off
; __device__ __forceinline__ size_t blk_off(int r, int c, int K) { return (size_t)(r >> 8) * 256 * K + (size_t)(c >> 6) * (256 * 64) + (size_t)((r & 255) * 64 + (c & 63)); }
; __device__ __forceinline__ u32x4 pack8(const f32x4 a, const f32x4 b) { u32x4 w; w.x = cvt_pk_bf16(a[0], a[1]); w.y = cvt_pk_bf16(a[2], a[3]); w.z = cvt_pk_bf16(b[0], b[1]); w.w = cvt_pk_bf16(b[2], b[3]); return w; }
; __device__ __forceinline__ void row_stats4(const float* st, int rowb, int fq, float (&mu)[4], float (&rs)[4]) {
;     ...
;         const float mm = s1 * (1.0f / 1024.0f); mu[m] = mm; rs[m] = rsqrtf(fmaxf(s2 * (1.0f / 1024.0f) - mm * mm, 0.f) + LN_EPS_); }
;     __device__ __forceinline__ void operator()(const f32x4 (&acc)[2][2][4][2], const pg8::Unit& u, int wr, int wc, int fr, int fq) const {
;     ...
;             for (int m = 0; m < 4; ++m) { const int row = row0 + ai * 128 + m * 16; const float mu = mu4[m], rs = rs4[m];
;                 f32x4 yv[2][2], gq[2][2], bq_[2][2];
; #pragma unroll
;                 for (int bj = 0; bj < 2; ++bj)
; #pragma unroll
;                     for (int n = 0; n < 2; ++n) { yv[bj][n] = *(const f32x4*)(Yin + (size_t)row * D_ + col0 + bj * 128 + 4 * n); gq[bj][n] = *(const f32x4*)(g + col0 + bj * 128 + 4 * n); bq_[bj][n] = *(const f32x4*)(b + col0 + bj * 128 + 4 * n); }
;                 asm volatile("" ::: "memory");
;                 float s1 = 0.f, s2 = 0.f;
; #pragma unroll
;                 for (int bj = 0; bj < 2; ++bj) { float* yp = Y + (size_t)row * D_ + col0 + bj * 128; f32x4 v[2];
; #pragma unroll
;                     for (int n = 0; n < 2; ++n) { v[n] = (((yv[bj][n] - mu) * rs) * gq[bj][n] + bq_[bj][n]) * ALPHA_ + acc[ai][bj][m][n] * sc;
;                         *(f32x4*)(yp + 4 * n) = v[n]; s1 += (v[n][0] + v[n][1]) + (v[n][2] + v[n][3]); s2 += (v[n][0] * v[n][0] + v[n][1] * v[n][1]) + (v[n][2] * v[n][2] + v[n][3] * v[n][3]); }
;                     *(u32x4*)(Yb + blk_off(row, col0 + bj * 128, D_)) = pack8(v[0], v[1]); }
.LBB0_1549:
	s_or_b64 exec, exec, s[24:25]
	v_pk_add_f32 v[18:19], v[98:99], v[100:101]
	s_mov_b32 s2, 0x3a800000
	v_pk_mul_f32 v[42:43], v[18:19], s[2:3] op_sel_hi:[1,0]
	s_mov_b32 s1, 0x800000
	v_fma_f32 v0, -v43, v43, v42
	v_max_f32_e32 v0, 0, v0
	v_add_f32_e32 v0, 0x3727c5ac, v0
	v_cmp_gt_f32_e32 vcc, s1, v0
	v_mul_f32_e32 v18, 0x4b800000, v0
	s_load_dwordx16 s[64:79], s[34:35], 0x38
	v_cndmask_b32_e32 v0, v0, v18, vcc
	v_rsq_f32_e32 v0, v0
	s_mov_b32 s2, 0x3fd744fd
	s_movk_i32 s1, 0x3fc0
	v_mul_f32_e32 v18, 0x45800000, v0
	v_cndmask_b32_e32 v42, v0, v18, vcc
	v_lshlrev_b64 v[18:19], 12, v[94:95]
	s_waitcnt lgkmcnt(0)
	v_lshl_add_u64 v[18:19], s[78:79], 0, v[18:19]
	v_lshl_add_u64 v[44:45], v[152:153], 2, v[18:19]
	s_nop 1
	v_bfe_u32 v21, v227, 4, 2
	v_sub_u32_e32 v20, 0, v21
	v_lshlrev_b32_e32 v20, 4, v20
	v_ashrrev_i32_e32 v21, 31, v20
	v_lshl_add_u64 v[20:21], v[44:45], 0, v[20:21]
	global_load_dwordx4 v[46:49], v[20:21], off offset:64
	global_load_dwordx4 v[50:53], v[20:21], off
	global_load_dwordx4 v[54:57], v[156:157], off offset:16
	global_load_dwordx4 v[58:61], v[156:157], off
	global_load_dwordx4 v[62:65], v[154:155], off offset:16
	global_load_dwordx4 v[66:69], v[154:155], off
	s_nop 1
	v_bfe_u32 v23, v227, 4, 2
	v_sub_u32_e32 v22, 0, v23
	v_lshlrev_b32_e32 v22, 4, v22
	v_ashrrev_i32_e32 v23, 31, v22
	v_lshl_add_u64 v[22:23], v[44:45], 0, v[22:23]
	global_load_dwordx4 v[18:21], v[22:23], off offset:576
	global_load_dwordx4 v[38:41], v[22:23], off offset:512
	global_load_dwordx4 v[22:25], v[156:157], off offset:528
	global_load_dwordx4 v[30:33], v[156:157], off offset:512
	global_load_dwordx4 v[26:29], v[154:155], off offset:528
	global_load_dwordx4 v[34:37], v[154:155], off offset:512
	v_lshlrev_b32_e32 v0, 6, v94
	v_and_or_b32 v0, v0, s1, v196
	v_lshlrev_b32_e32 v0, 1, v0
	s_waitcnt vmcnt(10)
	v_permlane32_swap_b32_e32 v50, v46
	v_permlane32_swap_b32_e32 v51, v47
	v_permlane32_swap_b32_e32 v52, v48
	v_permlane32_swap_b32_e32 v53, v49
	v_permlane16_swap_b32_e32 v50, v46
	v_permlane16_swap_b32_e32 v51, v47
	v_permlane16_swap_b32_e32 v52, v48
	v_permlane16_swap_b32_e32 v53, v49
	v_sub_f32_e32 v51, v51, v43
	v_sub_f32_e32 v50, v50, v43
	v_sub_f32_e32 v53, v53, v43
	v_sub_f32_e32 v52, v52, v43
	v_pk_mul_f32 v[52:53], v[42:43], v[52:53] op_sel_hi:[0,1]
	v_pk_mul_f32 v[50:51], v[42:43], v[50:51] op_sel_hi:[0,1]
	s_waitcnt vmcnt(6)
	v_pk_fma_f32 v[50:51], v[58:59], v[50:51], v[66:67]
	v_pk_fma_f32 v[52:53], v[60:61], v[52:53], v[68:69]
	v_pk_fma_f32 v[50:51], v[50:51], s[2:3], v[14:15] op_sel_hi:[1,0,1]
	v_pk_fma_f32 v[52:53], v[52:53], s[2:3], v[16:17] op_sel_hi:[1,0,1]
	v_add_f32_e32 v14, v50, v51
	v_add_f32_e32 v15, v52, v53
	v_add_f32_e32 v14, v14, v15
	v_add_f32_e32 v58, 0, v14
	v_mul_f32_e32 v14, v51, v51
	v_mul_f32_e32 v15, v53, v53
	v_fmac_f32_e32 v14, v50, v50
	v_fmac_f32_e32 v15, v52, v52
	v_add_f32_e32 v59, v14, v15
	v_sub_f32_e32 v15, v47, v43
	v_sub_f32_e32 v14, v46, v43
	v_sub_f32_e32 v17, v49, v43
	v_sub_f32_e32 v16, v48, v43
	v_pk_mul_f32 v[16:17], v[42:43], v[16:17] op_sel_hi:[0,1]
	v_pk_mul_f32 v[14:15], v[42:43], v[14:15] op_sel_hi:[0,1]
	v_pk_fma_f32 v[14:15], v[54:55], v[14:15], v[62:63]
	v_pk_fma_f32 v[16:17], v[56:57], v[16:17], v[64:65]
	v_pk_fma_f32 v[46:47], v[14:15], s[2:3], v[10:11] op_sel_hi:[1,0,1]
	v_pk_fma_f32 v[48:49], v[16:17], s[2:3], v[12:13] op_sel_hi:[1,0,1]
	v_add_f32_e32 v10, v46, v47
	v_add_f32_e32 v11, v48, v49
	v_add_f32_e32 v10, v10, v11
	v_add_f32_e32 v15, v58, v10
	v_mul_f32_e32 v10, v47, v47
	v_mul_f32_e32 v11, v49, v49
	v_fmac_f32_e32 v10, v46, v46
	v_fmac_f32_e32 v11, v48, v48
	v_add_f32_e32 v10, v10, v11
	v_add_f32_e32 v14, v59, v10
	v_cvt_pk_bf16_f32 v10, v50, v51
	v_cvt_pk_bf16_f32 v11, v52, v53
	v_cvt_pk_bf16_f32 v12, v46, v47
	v_cvt_pk_bf16_f32 v13, v48, v49
	v_lshl_add_u64 v[16:17], v[76:77], 0, v[0:1]
	s_nop 0
	s_nop 1
	v_bfe_u32 v55, v227, 4, 2
	v_sub_u32_e32 v54, 0, v55
	v_lshlrev_b32_e32 v54, 4, v54
	v_ashrrev_i32_e32 v55, 31, v54
	v_lshl_add_u64 v[54:55], v[44:45], 0, v[54:55]
	v_permlane16_swap_b32_e32 v50, v46
	v_permlane16_swap_b32_e32 v51, v47
	v_permlane16_swap_b32_e32 v52, v48
	v_permlane16_swap_b32_e32 v53, v49
	v_permlane32_swap_b32_e32 v50, v46
	v_permlane32_swap_b32_e32 v51, v47
	v_permlane32_swap_b32_e32 v52, v48
	v_permlane32_swap_b32_e32 v53, v49
	global_store_dwordx4 v[54:55], v[50:53], off
	global_store_dwordx4 v[54:55], v[46:49], off offset:64
	s_nop 1
	v_permlane32_swap_b32_e32 v50, v46
	v_permlane32_swap_b32_e32 v51, v47
	v_permlane32_swap_b32_e32 v52, v48
	v_permlane32_swap_b32_e32 v53, v49
	v_permlane16_swap_b32_e32 v50, v46
	v_permlane16_swap_b32_e32 v51, v47
	v_permlane16_swap_b32_e32 v52, v48
	v_permlane16_swap_b32_e32 v53, v49
	global_store_dwordx4 v[16:17], v[10:13], off
	s_nop 0
	s_waitcnt vmcnt(7)
; __device__ __forceinline__ float xsum16(float v) { const auto r = __builtin_amdgcn_permlane16_swap(__float_as_uint(v), __float_as_uint(v), false, false); return __uint_as_float(r[0]) + __uint_as_float(r[1]); }
; __device__ __forceinline__ float xsum32(float v) { const auto r = __builtin_amdgcn_permlane32_swap(__float_as_uint(v), __float_as_uint(v), false, false); return __uint_as_float(r[0]) + __uint_as_float(r[1]); }
; __device__ __forceinline__ size_t blk_off(int r, int c, int K) { return (size_t)(r >> 8) * 256 * K + (size_t)(c >> 6) * (256 * 64) + (size_t)((r & 255) * 64 + (c & 63)); }
; __device__ __forceinline__ u32x4 pack8(const f32x4 a, const f32x4 b) { u32x4 w; w.x = cvt_pk_bf16(a[0], a[1]); w.y = cvt_pk_bf16(a[2], a[3]); w.z = cvt_pk_bf16(b[0], b[1]); w.w = cvt_pk_bf16(b[2], b[3]); return w; }
;     __device__ __forceinline__ void operator()(const f32x4 (&acc)[2][2][4][2], const pg8::Unit& u, int wr, int wc, int fr, int fq) const {
;     ...
;                 for (int bj = 0; bj < 2; ++bj) { float* yp = Y + (size_t)row * D_ + col0 + bj * 128; f32x4 v[2];
; #pragma unroll
;                     for (int n = 0; n < 2; ++n) { v[n] = (((yv[bj][n] - mu) * rs) * gq[bj][n] + bq_[bj][n]) * ALPHA_ + acc[ai][bj][m][n] * sc;
;                         *(f32x4*)(yp + 4 * n) = v[n]; s1 += (v[n][0] + v[n][1]) + (v[n][2] + v[n][3]); s2 += (v[n][0] * v[n][0] + v[n][1] * v[n][1]) + (v[n][2] * v[n][2] + v[n][3] * v[n][3]); }
;                     *(u32x4*)(Yb + blk_off(row, col0 + bj * 128, D_)) = pack8(v[0], v[1]); }
;                 s1 = xsum32(xsum16(s1)); s2 = xsum32(xsum16(s2));
;                 if (fq == 0) *(f32x2*)(stn + (size_t)row * 32 + (u.pn * 4 + wc) * 2) = (f32x2){s1, s2}; asm volatile("" ::: "memory"); } }
	v_permlane32_swap_b32_e32 v38, v18
	v_permlane32_swap_b32_e32 v39, v19
	v_permlane32_swap_b32_e32 v40, v20
	v_permlane32_swap_b32_e32 v41, v21
	v_permlane16_swap_b32_e32 v38, v18
	v_permlane16_swap_b32_e32 v39, v19
	v_permlane16_swap_b32_e32 v40, v20
	v_permlane16_swap_b32_e32 v41, v21
	v_sub_f32_e32 v11, v39, v43
	v_sub_f32_e32 v10, v38, v43
	v_sub_f32_e32 v13, v41, v43
	v_sub_f32_e32 v12, v40, v43
	v_pk_mul_f32 v[12:13], v[42:43], v[12:13] op_sel_hi:[0,1]
	v_pk_mul_f32 v[10:11], v[42:43], v[10:11] op_sel_hi:[0,1]
	s_waitcnt vmcnt(3)
	v_pk_fma_f32 v[10:11], v[30:31], v[10:11], v[34:35]
	v_pk_fma_f32 v[12:13], v[32:33], v[12:13], v[36:37]
	v_pk_fma_f32 v[6:7], v[10:11], s[2:3], v[6:7] op_sel_hi:[1,0,1]
	v_pk_fma_f32 v[8:9], v[12:13], s[2:3], v[8:9] op_sel_hi:[1,0,1]
	v_add_f32_e32 v10, v6, v7
	v_add_f32_e32 v11, v8, v9
	v_add_f32_e32 v10, v10, v11
	v_add_f32_e32 v15, v15, v10
	v_mul_f32_e32 v10, v7, v7
	v_mul_f32_e32 v11, v9, v9
	v_fmac_f32_e32 v10, v6, v6
	v_fmac_f32_e32 v11, v8, v8
	v_add_f32_e32 v10, v10, v11
	v_add_f32_e32 v14, v14, v10
	v_sub_f32_e32 v11, v19, v43
	v_sub_f32_e32 v10, v18, v43
	v_sub_f32_e32 v13, v21, v43
	v_sub_f32_e32 v12, v20, v43
	v_pk_mul_f32 v[12:13], v[42:43], v[12:13] op_sel_hi:[0,1]
	v_pk_mul_f32 v[10:11], v[42:43], v[10:11] op_sel_hi:[0,1]
	v_pk_fma_f32 v[10:11], v[22:23], v[10:11], v[26:27]
	v_pk_fma_f32 v[12:13], v[24:25], v[12:13], v[28:29]
	v_pk_fma_f32 v[2:3], v[10:11], s[2:3], v[2:3] op_sel_hi:[1,0,1]
	v_pk_fma_f32 v[4:5], v[12:13], s[2:3], v[4:5] op_sel_hi:[1,0,1]
	v_add_f32_e32 v10, v2, v3
	v_add_f32_e32 v11, v4, v5
	v_add_f32_e32 v10, v10, v11
	v_mul_f32_e32 v11, v3, v3
	v_mul_f32_e32 v12, v5, v5
	v_add_f32_e32 v10, v15, v10
	v_fmac_f32_e32 v11, v2, v2
	v_fmac_f32_e32 v12, v4, v4
	s_nop 0
	s_nop 1
	v_bfe_u32 v17, v227, 4, 2
	v_sub_u32_e32 v16, 0, v17
	v_lshlrev_b32_e32 v16, 4, v16
	v_ashrrev_i32_e32 v17, 31, v16
	v_lshl_add_u64 v[16:17], v[44:45], 0, v[16:17]
	v_permlane16_swap_b32_e32 v6, v2
	v_permlane16_swap_b32_e32 v7, v3
	v_permlane16_swap_b32_e32 v8, v4
	v_permlane16_swap_b32_e32 v9, v5
	v_permlane32_swap_b32_e32 v6, v2
	v_permlane32_swap_b32_e32 v7, v3
	v_permlane32_swap_b32_e32 v8, v4
	v_permlane32_swap_b32_e32 v9, v5
	global_store_dwordx4 v[16:17], v[6:9], off offset:512
	global_store_dwordx4 v[16:17], v[2:5], off offset:576
	s_nop 1
	v_permlane32_swap_b32_e32 v6, v2
	v_permlane32_swap_b32_e32 v7, v3
	v_permlane32_swap_b32_e32 v8, v4
	v_permlane32_swap_b32_e32 v9, v5
	v_permlane16_swap_b32_e32 v6, v2
	v_permlane16_swap_b32_e32 v7, v3
	v_permlane16_swap_b32_e32 v8, v4
	v_permlane16_swap_b32_e32 v9, v5
	v_add_f32_e32 v11, v11, v12
	v_cvt_pk_bf16_f32 v6, v6, v7
	v_cvt_pk_bf16_f32 v7, v8, v9
	v_cvt_pk_bf16_f32 v8, v2, v3
	v_lshl_add_u64 v[2:3], v[74:75], 0, v[0:1]
	v_mov_b32_e32 v0, v10
	v_add_f32_e32 v11, v14, v11
	v_cvt_pk_bf16_f32 v9, v4, v5
	v_permlane16_swap_b32_e32 v10, v0
	global_store_dwordx4 v[2:3], v[6:9], off
	v_add_f32_e32 v2, v10, v0
	v_mov_b32_e32 v0, v11
	s_nop 1
	v_permlane16_swap_b32_e32 v11, v0
	v_add_f32_e32 v3, v11, v0
	v_mov_b32_e32 v4, v2
	v_mov_b32_e32 v5, v3
	s_nop 0
	v_permlane32_swap_b32_e32 v2, v4
	v_permlane32_swap_b32_e32 v3, v5
	s_and_saveexec_b64 s[24:25], s[44:45]
	s_cbranch_execz .LBB0_1551
	v_pk_add_f32 v[2:3], v[2:3], v[4:5]
	v_lshlrev_b64 v[4:5], 7, v[94:95]
	v_lshl_add_u64 v[4:5], s[6:7], 0, v[4:5]
	v_lshl_add_u64 v[4:5], s[52:53], 2, v[4:5]
	global_store_dwordx2 v[4:5], v[2:3], off

; __device__ __forceinline__ float xsum16(float v) { const auto r = __builtin_amdgcn_permlane16_swap(__float_as_uint(v), __float_as_uint(v), false, false); return __uint_as_float(r[0]) + __uint_as_float(r[1]); }
; __device__ __forceinline__ float xsum32(float v) { const auto r = __builtin_amdgcn_permlane32_swap(__float_as_uint(v), __float_as_uint(v), false, false); return __uint_as_float(r[0]) + __uint_as_float(r[1]); }
; __device__ __forceinline__ void row_stats4(const float* st, int rowb, int fq, float (&mu)[4], float (&rs)[4]) {
;     f32x4 a[4], b[4];
; #pragma unroll
;     for (int m = 0; m < 4; ++m) { const f32x4* p = (const f32x4*)(st + (size_t)(rowb + m * 16) * 32 + fq * 8); a[m] = p[0]; b[m] = p[1]; }
; #pragma unroll
;     for (int m = 0; m < 4; ++m) { float s1 = (a[m][0] + a[m][2]) + (b[m][0] + b[m][2]), s2 = (a[m][1] + a[m][3]) + (b[m][1] + b[m][3]);
;         s1 = xsum32(xsum16(s1)); s2 = xsum32(xsum16(s2));
;         const float mm = s1 * (1.0f / 1024.0f); mu[m] = mm; rs[m] = rsqrtf(fmaxf(s2 * (1.0f / 1024.0f) - mm * mm, 0.f) + LN_EPS_); }
;     __device__ __forceinline__ void operator()(const f32x4 (&acc)[2][2][4][2], const pg8::Unit& u, int wr, int wc, int fr, int fq) const {
;     ...
;         for (int ai = 0; ai < 2; ++ai) { float mu4[4], rs4[4]; row_stats4(stp, row0 + ai * 128, fq, mu4, rs4);
; #pragma unroll
;             for (int m = 0; m < 4; ++m) { const int row = row0 + ai * 128 + m * 16; const float mu = mu4[m], rs = rs4[m];
;                 f32x4 yv[2][2], gq[2][2], bq_[2][2];
; #pragma unroll
;                 for (int bj = 0; bj < 2; ++bj)
; #pragma unroll
;                     for (int n = 0; n < 2; ++n) { yv[bj][n] = *(const f32x4*)(Yin + (size_t)row * D_ + col0 + bj * 128 + 4 * n); gq[bj][n] = *(const f32x4*)(g + col0 + bj * 128 + 4 * n); bq_[bj][n] = *(const f32x4*)(b + col0 + bj * 128 + 4 * n); }
.LBB0_1703:
	s_lshl_b32 s3, s3, 8
	s_add_i32 s3, s3, s0
	v_or_b32_e32 v158, s3, v184
	v_ashrrev_i32_e32 v159, 31, v158
	v_lshlrev_b64 v[130:131], 7, v[158:159]
	v_lshl_add_u64 v[136:137], v[146:147], 0, v[130:131]
	v_or_b32_e32 v182, 16, v158
	s_nop 1
	v_bfe_u32 v153, v227, 4, 2
	v_sub_u32_e32 v152, 0, v153
	v_lshlrev_b32_e32 v152, 4, v152
	v_ashrrev_i32_e32 v153, 31, v152
	v_lshl_add_u64 v[152:153], v[136:137], 0, v[152:153]
	global_load_dwordx4 v[132:135], v[152:153], off
	global_load_dwordx4 v[166:169], v[152:153], off offset:64
	v_ashrrev_i32_e32 v183, 31, v182
	v_lshlrev_b64 v[172:173], 7, v[182:183]
	v_lshl_add_u64 v[136:137], v[146:147], 0, v[172:173]
	s_nop 1
	v_bfe_u32 v153, v227, 4, 2
	v_sub_u32_e32 v152, 0, v153
	v_lshlrev_b32_e32 v152, 4, v152
	v_ashrrev_i32_e32 v153, 31, v152
	v_lshl_add_u64 v[152:153], v[136:137], 0, v[152:153]
	global_load_dwordx4 v[174:177], v[152:153], off
	global_load_dwordx4 v[178:181], v[152:153], off offset:64
	v_or_b32_e32 v170, 32, v158
	v_ashrrev_i32_e32 v171, 31, v170
	v_lshlrev_b64 v[164:165], 7, v[170:171]
	v_lshl_add_u64 v[136:137], v[146:147], 0, v[164:165]
	s_nop 1
	v_bfe_u32 v153, v227, 4, 2
	v_sub_u32_e32 v152, 0, v153
	v_lshlrev_b32_e32 v152, 4, v152
	v_ashrrev_i32_e32 v153, 31, v152
	v_lshl_add_u64 v[152:153], v[136:137], 0, v[152:153]
	global_load_dwordx4 v[186:189], v[152:153], off
	global_load_dwordx4 v[190:193], v[152:153], off offset:64
	s_load_dwordx16 s[60:75], s[34:35], 0x38
	s_lshl_b32 s1, s2, 8
	s_lshl_b32 s16, s2, 3
	s_or_b32 s2, s1, s53
	v_or_b32_e32 v162, 48, v158
	v_or_b32_e32 v152, s2, v185
	v_ashrrev_i32_e32 v163, 31, v162
	v_ashrrev_i32_e32 v153, 31, v152
	v_lshlrev_b64 v[136:137], 12, v[158:159]
	v_lshlrev_b64 v[160:161], 7, v[162:163]
	v_lshlrev_b64 v[198:199], 2, v[152:153]
	s_waitcnt lgkmcnt(0)
	v_lshl_add_u64 v[136:137], s[74:75], 0, v[136:137]
	v_lshl_add_u64 v[202:203], v[146:147], 0, v[160:161]
	v_lshl_add_u64 v[156:157], s[10:11], 0, v[198:199]
	v_lshl_add_u64 v[154:155], s[12:13], 0, v[198:199]
	v_lshl_add_u64 v[136:137], v[136:137], 0, v[198:199]
	s_nop 1
	v_bfe_u32 v197, v227, 4, 2
	v_sub_u32_e32 v196, 0, v197
	v_lshlrev_b32_e32 v196, 4, v196
	v_ashrrev_i32_e32 v197, 31, v196
	v_lshl_add_u64 v[196:197], v[202:203], 0, v[196:197]
	global_load_dwordx4 v[198:201], v[196:197], off
	s_nop 0
	global_load_dwordx4 v[202:205], v[196:197], off offset:64
	s_or_b32 s38, s16, s15
	s_mov_b32 s16, 0x3a800000
	s_mov_b32 s1, 0x800000
	s_nop 1
	v_bfe_u32 v197, v227, 4, 2
	v_sub_u32_e32 v196, 0, v197
	v_lshlrev_b32_e32 v196, 4, v196
	v_ashrrev_i32_e32 v197, 31, v196
	v_lshl_add_u64 v[196:197], v[136:137], 0, v[196:197]
	global_load_dwordx4 v[206:209], v[196:197], off offset:64
	global_load_dwordx4 v[210:213], v[196:197], off
	global_load_dwordx4 v[214:217], v[156:157], off offset:16
	global_load_dwordx4 v[218:221], v[156:157], off
	global_load_dwordx4 v[222:225], v[154:155], off offset:16
	global_load_dwordx4 v[234:237], v[154:155], off
	s_mov_b32 s18, 0x3fd744fd
	s_ashr_i32 s44, s2, 6
	v_bitop3_b32 v196, s2, 56, v185 bitop3:0xc8
	s_ashr_i32 s39, s38, 31
	s_ashr_i32 s45, s44, 31
	s_waitcnt vmcnt(12)
	v_permlane32_swap_b32_e32 v132, v166
	v_permlane32_swap_b32_e32 v133, v167
	v_permlane32_swap_b32_e32 v134, v168
	v_permlane32_swap_b32_e32 v135, v169
	v_permlane16_swap_b32_e32 v132, v166
	v_permlane16_swap_b32_e32 v133, v167
	v_permlane16_swap_b32_e32 v134, v168
	v_permlane16_swap_b32_e32 v135, v169
	v_mov_b32_e32 v228, v132
	v_mov_b32_e32 v229, v166
	v_mov_b32_e32 v238, v134
	v_mov_b32_e32 v239, v168
	v_mov_b32_e32 v166, v133
	v_mov_b32_e32 v168, v135
	v_pk_add_f32 v[132:133], v[228:229], v[238:239]
	v_pk_add_f32 v[134:135], v[166:167], v[168:169]
	v_pk_add_f32 v[132:133], v[132:133], v[132:133] op_sel:[0,1] op_sel_hi:[1,0]
	v_pk_add_f32 v[134:135], v[134:135], v[134:135] op_sel:[0,1] op_sel_hi:[1,0]
	s_waitcnt vmcnt(10)
	v_permlane32_swap_b32_e32 v174, v178
	v_permlane32_swap_b32_e32 v175, v179
	v_permlane32_swap_b32_e32 v176, v180
	v_permlane32_swap_b32_e32 v177, v181
	v_permlane16_swap_b32_e32 v174, v178
	v_permlane16_swap_b32_e32 v175, v179
	v_permlane16_swap_b32_e32 v176, v180
	v_permlane16_swap_b32_e32 v177, v181
	v_mov_b32_e32 v166, v174
	v_mov_b32_e32 v167, v178
	v_mov_b32_e32 v168, v176
	v_mov_b32_e32 v169, v180
	v_mov_b32_e32 v0, v132
	v_mov_b32_e32 v133, v134
	v_pk_add_f32 v[166:167], v[166:167], v[168:169]
	v_permlane16_swap_b32_e32 v132, v0
	v_permlane16_swap_b32_e32 v134, v133
	v_mov_b32_e32 v178, v175
	v_mov_b32_e32 v180, v177
	v_pk_add_f32 v[166:167], v[166:167], v[166:167] op_sel:[0,1] op_sel_hi:[1,0]
	v_add_f32_e32 v177, v132, v0
	v_add_f32_e32 v176, v134, v133
	v_pk_add_f32 v[168:169], v[178:179], v[180:181]
	v_mov_b32_e32 v135, v166
	v_mov_b32_e32 v179, v177
	v_mov_b32_e32 v178, v176
	v_permlane16_swap_b32_e32 v166, v135
	v_permlane32_swap_b32_e32 v177, v179
	v_permlane32_swap_b32_e32 v176, v178
	v_add_f32_e32 v133, v166, v135
	v_pk_add_f32 v[166:167], v[176:177], v[178:179]
	v_pk_add_f32 v[168:169], v[168:169], v[168:169] op_sel:[0,1] op_sel_hi:[1,0]
	v_pk_mul_f32 v[228:229], v[166:167], s[16:17] op_sel_hi:[1,0]
	v_mov_b32_e32 v159, v168
	v_fma_f32 v0, -v229, v229, v228
	v_max_f32_e32 v0, 0, v0
	v_permlane16_swap_b32_e32 v168, v159
	v_add_f32_e32 v0, 0x3727c5ac, v0
	v_add_f32_e32 v132, v168, v159
	v_mul_f32_e32 v159, 0x4b800000, v0
	v_cmp_gt_f32_e32 vcc, s1, v0
	s_waitcnt vmcnt(8)
; __device__ __forceinline__ float xsum16(float v) { const auto r = __builtin_amdgcn_permlane16_swap(__float_as_uint(v), __float_as_uint(v), false, false); return __uint_as_float(r[0]) + __uint_as_float(r[1]); }
; __device__ __forceinline__ float xsum32(float v) { const auto r = __builtin_amdgcn_permlane32_swap(__float_as_uint(v), __float_as_uint(v), false, false); return __uint_as_float(r[0]) + __uint_as_float(r[1]); }
; __device__ __forceinline__ size_t blk_off(int r, int c, int K) { return (size_t)(r >> 8) * 256 * K + (size_t)(c >> 6) * (256 * 64) + (size_t)((r & 255) * 64 + (c & 63)); }
; __device__ __forceinline__ void row_stats4(const float* st, int rowb, int fq, float (&mu)[4], float (&rs)[4]) {
;     ...
;     for (int m = 0; m < 4; ++m) { const f32x4* p = (const f32x4*)(st + (size_t)(rowb + m * 16) * 32 + fq * 8); a[m] = p[0]; b[m] = p[1]; }
; #pragma unroll
;     for (int m = 0; m < 4; ++m) { float s1 = (a[m][0] + a[m][2]) + (b[m][0] + b[m][2]), s2 = (a[m][1] + a[m][3]) + (b[m][1] + b[m][3]);
;         s1 = xsum32(xsum16(s1)); s2 = xsum32(xsum16(s2));
;         const float mm = s1 * (1.0f / 1024.0f); mu[m] = mm; rs[m] = rsqrtf(fmaxf(s2 * (1.0f / 1024.0f) - mm * mm, 0.f) + LN_EPS_); }
;     __device__ __forceinline__ void operator()(const f32x4 (&acc)[2][2][4][2], const pg8::Unit& u, int wr, int wc, int fr, int fq) const {
;     ...
;                     for (int n = 0; n < 2; ++n) { yv[bj][n] = *(const f32x4*)(Yin + (size_t)row * D_ + col0 + bj * 128 + 4 * n); gq[bj][n] = *(const f32x4*)(g + col0 + bj * 128 + 4 * n); bq_[bj][n] = *(const f32x4*)(b + col0 + bj * 128 + 4 * n); }
;                 asm volatile("" ::: "memory");
;                 float s1 = 0.f, s2 = 0.f;
; #pragma unroll
;                 for (int bj = 0; bj < 2; ++bj) { float* yp = Y + (size_t)row * D_ + col0 + bj * 128; f32x4 v[2];
; #pragma unroll
;                     for (int n = 0; n < 2; ++n) { v[n] = (((yv[bj][n] - mu) * rs) * gq[bj][n] + bq_[bj][n]) * ALPHA_ + acc[ai][bj][m][n] * sc;
;                         *(f32x4*)(yp + 4 * n) = v[n]; s1 += (v[n][0] + v[n][1]) + (v[n][2] + v[n][3]); s2 += (v[n][0] * v[n][0] + v[n][1] * v[n][1]) + (v[n][2] * v[n][2] + v[n][3] * v[n][3]); }
;                     *(u32x4*)(Yb + blk_off(row, col0 + bj * 128, D_)) = pack8(v[0], v[1]); }
	v_permlane32_swap_b32_e32 v186, v190
	v_permlane32_swap_b32_e32 v187, v191
	v_permlane32_swap_b32_e32 v188, v192
	v_permlane32_swap_b32_e32 v189, v193
	v_permlane16_swap_b32_e32 v186, v190
	v_permlane16_swap_b32_e32 v187, v191
	v_permlane16_swap_b32_e32 v188, v192
	v_permlane16_swap_b32_e32 v189, v193
	v_mov_b32_e32 v174, v186
	v_mov_b32_e32 v175, v190
	v_cndmask_b32_e32 v0, v0, v159, vcc
	v_rsq_f32_e32 v0, v0
	v_mov_b32_e32 v166, v188
	v_mov_b32_e32 v167, v192
	v_pk_add_f32 v[166:167], v[174:175], v[166:167]
	v_mul_f32_e32 v159, 0x45800000, v0
	v_pk_add_f32 v[166:167], v[166:167], v[166:167] op_sel:[0,1] op_sel_hi:[1,0]
	v_mov_b32_e32 v190, v187
	v_mov_b32_e32 v192, v189
	v_cndmask_b32_e32 v0, v0, v159, vcc
	v_pk_add_f32 v[168:169], v[190:191], v[192:193]
	v_mov_b32_e32 v159, v166
	v_pk_add_f32 v[168:169], v[168:169], v[168:169] op_sel:[0,1] op_sel_hi:[1,0]
	s_nop 0
	v_permlane16_swap_b32_e32 v166, v159
	v_add_f32_e32 v175, v166, v159
	v_mov_b32_e32 v159, v168
	s_nop 1
	v_permlane16_swap_b32_e32 v168, v159
	s_nop 1
	v_bfe_u32 v135, v227, 4, 2
	v_sub_u32_e32 v134, 0, v135
	v_lshlrev_b32_e32 v134, 4, v134
	v_ashrrev_i32_e32 v135, 31, v134
	v_lshl_add_u64 v[134:135], v[136:137], 0, v[134:135]
	global_load_dwordx4 v[178:181], v[134:135], off offset:576
	global_load_dwordx4 v[186:189], v[134:135], off offset:512
	v_add_f32_e32 v174, v168, v159
	s_waitcnt vmcnt(8)
	v_permlane32_swap_b32_e32 v198, v202
	v_permlane32_swap_b32_e32 v199, v203
	v_permlane32_swap_b32_e32 v200, v204
	v_permlane32_swap_b32_e32 v201, v205
	v_permlane16_swap_b32_e32 v198, v202
	v_permlane16_swap_b32_e32 v199, v203
	v_permlane16_swap_b32_e32 v200, v204
	v_permlane16_swap_b32_e32 v201, v205
	v_mov_b32_e32 v166, v198
	v_mov_b32_e32 v167, v202
	v_mov_b32_e32 v168, v200
	v_mov_b32_e32 v169, v204
	v_mov_b32_e32 v202, v199
	v_mov_b32_e32 v204, v201
	v_pk_add_f32 v[166:167], v[166:167], v[168:169]
	v_pk_add_f32 v[168:169], v[202:203], v[204:205]
	global_load_dwordx4 v[190:193], v[156:157], off offset:528
	global_load_dwordx4 v[198:201], v[156:157], off offset:512
	global_load_dwordx4 v[202:205], v[154:155], off offset:528
	global_load_dwordx4 v[238:241], v[154:155], off offset:512
	s_waitcnt vmcnt(10)
	v_permlane32_swap_b32_e32 v210, v206
	v_permlane32_swap_b32_e32 v211, v207
	v_permlane32_swap_b32_e32 v212, v208
	v_permlane32_swap_b32_e32 v213, v209
	v_permlane16_swap_b32_e32 v210, v206
	v_permlane16_swap_b32_e32 v211, v207
	v_permlane16_swap_b32_e32 v212, v208
	v_permlane16_swap_b32_e32 v213, v209
	v_sub_f32_e32 v213, v213, v229
	v_sub_f32_e32 v212, v212, v229
	v_sub_f32_e32 v211, v211, v229
	v_sub_f32_e32 v210, v210, v229
	v_pk_mul_f32 v[210:211], v[0:1], v[210:211] op_sel_hi:[0,1]
	v_pk_mul_f32 v[212:213], v[0:1], v[212:213] op_sel_hi:[0,1]
	v_sub_f32_e32 v209, v209, v229
	v_sub_f32_e32 v208, v208, v229
	v_sub_f32_e32 v207, v207, v229
	v_sub_f32_e32 v206, v206, v229
	s_waitcnt vmcnt(6)
	v_pk_fma_f32 v[212:213], v[220:221], v[212:213], v[236:237]
	v_pk_fma_f32 v[210:211], v[218:219], v[210:211], v[234:235]
	v_pk_mul_f32 v[206:207], v[0:1], v[206:207] op_sel_hi:[0,1]
	v_pk_mul_f32 v[208:209], v[0:1], v[208:209] op_sel_hi:[0,1]
	v_pk_mul_f32 v[210:211], v[210:211], s[18:19] op_sel_hi:[1,0]
	v_pk_mul_f32 v[212:213], v[212:213], s[18:19] op_sel_hi:[1,0]
	v_pk_fma_f32 v[208:209], v[216:217], v[208:209], v[224:225]
	v_pk_fma_f32 v[206:207], v[214:215], v[206:207], v[222:223]
	v_pk_fma_f32 v[128:129], v[128:129], 0.5, v[212:213] op_sel_hi:[1,0,1]
	v_pk_fma_f32 v[126:127], v[126:127], 0.5, v[210:211] op_sel_hi:[1,0,1]
	v_pk_mul_f32 v[206:207], v[206:207], s[18:19] op_sel_hi:[1,0]
	v_pk_mul_f32 v[208:209], v[208:209], s[18:19] op_sel_hi:[1,0]
	v_add_f32_e32 v197, v126, v127
	v_add_f32_e32 v210, v128, v129
	v_pk_fma_f32 v[124:125], v[124:125], 0.5, v[208:209] op_sel_hi:[1,0,1]
	v_pk_fma_f32 v[122:123], v[122:123], 0.5, v[206:207] op_sel_hi:[1,0,1]
	v_pk_add_f32 v[166:167], v[166:167], v[166:167] op_sel:[0,1] op_sel_hi:[1,0]
	v_add_f32_e32 v197, v197, v210
	v_add_f32_e32 v206, v122, v123
	v_add_f32_e32 v207, v124, v125
	v_mov_b32_e32 v159, v166
	v_add_f32_e32 v197, 0, v197
	v_add_f32_e32 v206, v206, v207
	v_pk_add_f32 v[168:169], v[168:169], v[168:169] op_sel:[0,1] op_sel_hi:[1,0]
	v_permlane16_swap_b32_e32 v166, v159
	v_mul_f32_e32 v210, v127, v127
	v_mul_f32_e32 v211, v129, v129
	v_add_f32_e32 v197, v197, v206
	v_mul_f32_e32 v206, v123, v123
	v_mul_f32_e32 v207, v125, v125
	v_add_f32_e32 v167, v166, v159
	v_mov_b32_e32 v159, v168
	s_ashr_i32 s16, s3, 8
	s_nop 0
	v_fmac_f32_e32 v210, v126, v126
	v_fmac_f32_e32 v211, v128, v128
	s_nop 1
	v_bfe_u32 v135, v227, 4, 2
	v_sub_u32_e32 v134, 0, v135
	v_lshlrev_b32_e32 v134, 4, v134
	v_ashrrev_i32_e32 v135, 31, v134
	v_lshl_add_u64 v[134:135], v[136:137], 0, v[134:135]
	v_permlane16_swap_b32_e32 v126, v122
	v_permlane16_swap_b32_e32 v127, v123
	v_permlane16_swap_b32_e32 v128, v124
	v_permlane16_swap_b32_e32 v129, v125
	v_permlane32_swap_b32_e32 v126, v122
	v_permlane32_swap_b32_e32 v127, v123
	v_permlane32_swap_b32_e32 v128, v124
	v_permlane32_swap_b32_e32 v129, v125
	global_store_dwordx4 v[134:135], v[126:129], off
	global_store_dwordx4 v[134:135], v[122:125], off offset:64
	s_nop 1
	v_permlane32_swap_b32_e32 v126, v122
	v_permlane32_swap_b32_e32 v127, v123
	v_permlane32_swap_b32_e32 v128, v124
	v_permlane32_swap_b32_e32 v129, v125
	v_permlane16_swap_b32_e32 v126, v122
	v_permlane16_swap_b32_e32 v127, v123
	v_permlane16_swap_b32_e32 v128, v124
	v_permlane16_swap_b32_e32 v129, v125
	v_fmac_f32_e32 v206, v122, v122
	v_fmac_f32_e32 v207, v124, v124
	v_cvt_pk_bf16_f32 v126, v126, v127
	v_cvt_pk_bf16_f32 v127, v128, v129
	v_cvt_pk_bf16_f32 v128, v122, v123
	v_cvt_pk_bf16_f32 v129, v124, v125
	v_permlane16_swap_b32_e32 v168, v159
	s_ashr_i32 s17, s16, 31
	v_add_f32_e32 v166, v168, v159
	s_lshl_b64 s[16:17], s[16:17], 19
	v_lshlrev_b32_e32 v159, 6, v158
	s_movk_i32 s1, 0x33c0
	v_readlane_b32 s2, v253, 59
	v_and_or_b32 v159, v159, s1, v196
	v_readlane_b32 s3, v253, 60
	s_add_u32 s1, s2, s16
	s_addc_u32 s16, s3, s17
	s_lshl_b64 s[24:25], s[44:45], 15
	s_add_u32 s48, s1, s24
	s_waitcnt vmcnt(6)
; __device__ __forceinline__ float xsum16(float v) { const auto r = __builtin_amdgcn_permlane16_swap(__float_as_uint(v), __float_as_uint(v), false, false); return __uint_as_float(r[0]) + __uint_as_float(r[1]); }
; __device__ __forceinline__ float xsum32(float v) { const auto r = __builtin_amdgcn_permlane32_swap(__float_as_uint(v), __float_as_uint(v), false, false); return __uint_as_float(r[0]) + __uint_as_float(r[1]); }
; __device__ __forceinline__ size_t blk_off(int r, int c, int K) { return (size_t)(r >> 8) * 256 * K + (size_t)(c >> 6) * (256 * 64) + (size_t)((r & 255) * 64 + (c & 63)); }
; __device__ __forceinline__ u32x4 pack8(const f32x4 a, const f32x4 b) { u32x4 w; w.x = cvt_pk_bf16(a[0], a[1]); w.y = cvt_pk_bf16(a[2], a[3]); w.z = cvt_pk_bf16(b[0], b[1]); w.w = cvt_pk_bf16(b[2], b[3]); return w; }
;     __device__ __forceinline__ void operator()(const f32x4 (&acc)[2][2][4][2], const pg8::Unit& u, int wr, int wc, int fr, int fq) const {
;     ...
;                 for (int bj = 0; bj < 2; ++bj) { float* yp = Y + (size_t)row * D_ + col0 + bj * 128; f32x4 v[2];
; #pragma unroll
;                     for (int n = 0; n < 2; ++n) { v[n] = (((yv[bj][n] - mu) * rs) * gq[bj][n] + bq_[bj][n]) * ALPHA_ + acc[ai][bj][m][n] * sc;
;                         *(f32x4*)(yp + 4 * n) = v[n]; s1 += (v[n][0] + v[n][1]) + (v[n][2] + v[n][3]); s2 += (v[n][0] * v[n][0] + v[n][1] * v[n][1]) + (v[n][2] * v[n][2] + v[n][3] * v[n][3]); }
;                     *(u32x4*)(Yb + blk_off(row, col0 + bj * 128, D_)) = pack8(v[0], v[1]); }
;                 s1 = xsum32(xsum16(s1)); s2 = xsum32(xsum16(s2));
;                 if (fq == 0) *(f32x2*)(stn + (size_t)row * 32 + (u.pn * 4 + wc) * 2) = (f32x2){s1, s2}; asm volatile("" ::: "memory"); } }
	v_permlane32_swap_b32_e32 v186, v178
	v_permlane32_swap_b32_e32 v187, v179
	v_permlane32_swap_b32_e32 v188, v180
	v_permlane32_swap_b32_e32 v189, v181
	v_permlane16_swap_b32_e32 v186, v178
	v_permlane16_swap_b32_e32 v187, v179
	v_permlane16_swap_b32_e32 v188, v180
	v_permlane16_swap_b32_e32 v189, v181
	v_sub_f32_e32 v123, v189, v229
	v_sub_f32_e32 v122, v188, v229
	v_sub_f32_e32 v125, v187, v229
	v_sub_f32_e32 v124, v186, v229
	v_pk_mul_f32 v[124:125], v[0:1], v[124:125] op_sel_hi:[0,1]
	v_pk_mul_f32 v[122:123], v[0:1], v[122:123] op_sel_hi:[0,1]
	s_addc_u32 s49, s16, s25
	v_lshlrev_b32_e32 v159, 1, v159
	global_store_dwordx4 v159, v[126:129], s[48:49]
	v_add_f32_e32 v210, v210, v211
	s_waitcnt vmcnt(3)
	v_pk_fma_f32 v[122:123], v[200:201], v[122:123], v[240:241]
	v_pk_fma_f32 v[124:125], v[198:199], v[124:125], v[238:239]
	v_pk_mul_f32 v[122:123], v[122:123], s[18:19] op_sel_hi:[1,0]
	v_pk_mul_f32 v[124:125], v[124:125], s[18:19] op_sel_hi:[1,0]
	v_pk_fma_f32 v[120:121], v[120:121], 0.5, v[122:123] op_sel_hi:[1,0,1]
	v_pk_fma_f32 v[118:119], v[118:119], 0.5, v[124:125] op_sel_hi:[1,0,1]
	v_add_f32_e32 v123, v120, v121
	v_add_f32_e32 v122, v118, v119
	v_add_f32_e32 v122, v122, v123
	v_add_f32_e32 v126, v197, v122
	v_mul_f32_e32 v122, v119, v119
	v_mul_f32_e32 v123, v121, v121
	v_add_f32_e32 v206, v206, v207
	v_fmac_f32_e32 v122, v118, v118
	v_fmac_f32_e32 v123, v120, v120
	v_add_f32_e32 v206, v210, v206
	v_add_f32_e32 v122, v122, v123
	v_add_f32_e32 v127, v206, v122
	v_sub_f32_e32 v123, v181, v229
	v_sub_f32_e32 v122, v180, v229
	v_sub_f32_e32 v125, v179, v229
	v_sub_f32_e32 v124, v178, v229
	v_pk_mul_f32 v[124:125], v[0:1], v[124:125] op_sel_hi:[0,1]
	v_pk_mul_f32 v[122:123], v[0:1], v[122:123] op_sel_hi:[0,1]
	v_pk_fma_f32 v[122:123], v[192:193], v[122:123], v[204:205]
	v_pk_fma_f32 v[124:125], v[190:191], v[124:125], v[202:203]
	v_pk_mul_f32 v[122:123], v[122:123], s[18:19] op_sel_hi:[1,0]
	v_pk_mul_f32 v[124:125], v[124:125], s[18:19] op_sel_hi:[1,0]
	v_pk_fma_f32 v[116:117], v[116:117], 0.5, v[122:123] op_sel_hi:[1,0,1]
	v_pk_fma_f32 v[114:115], v[114:115], 0.5, v[124:125] op_sel_hi:[1,0,1]
	v_add_f32_e32 v122, v116, v117
	v_add_f32_e32 v0, v114, v115
	v_add_f32_e32 v0, v0, v122
	v_mul_f32_e32 v122, v115, v115
	v_mul_f32_e32 v123, v117, v117
	v_add_f32_e32 v0, v126, v0
	v_fmac_f32_e32 v122, v114, v114
	v_fmac_f32_e32 v123, v116, v116
	s_nop 0
	s_nop 1
	v_bfe_u32 v125, v227, 4, 2
	v_sub_u32_e32 v124, 0, v125
	v_lshlrev_b32_e32 v124, 4, v124
	v_ashrrev_i32_e32 v125, 31, v124
	v_lshl_add_u64 v[124:125], v[136:137], 0, v[124:125]
	v_permlane16_swap_b32_e32 v118, v114
	v_permlane16_swap_b32_e32 v119, v115
	v_permlane16_swap_b32_e32 v120, v116
	v_permlane16_swap_b32_e32 v121, v117
	v_permlane32_swap_b32_e32 v118, v114
	v_permlane32_swap_b32_e32 v119, v115
	v_permlane32_swap_b32_e32 v120, v116
	v_permlane32_swap_b32_e32 v121, v117
	global_store_dwordx4 v[124:125], v[118:121], off offset:512
	global_store_dwordx4 v[124:125], v[114:117], off offset:576
	s_nop 1
	v_permlane32_swap_b32_e32 v118, v114
	v_permlane32_swap_b32_e32 v119, v115
	v_permlane32_swap_b32_e32 v120, v116
	v_permlane32_swap_b32_e32 v121, v117
	v_permlane16_swap_b32_e32 v118, v114
	v_permlane16_swap_b32_e32 v119, v115
	v_permlane16_swap_b32_e32 v120, v116
	v_permlane16_swap_b32_e32 v121, v117
	v_add_f32_e32 v122, v122, v123
	v_cvt_pk_bf16_f32 v118, v118, v119
	v_cvt_pk_bf16_f32 v119, v120, v121
	v_cvt_pk_bf16_f32 v120, v114, v115
	v_mov_b32_e32 v114, v0
	v_add_f32_e32 v122, v127, v122
	s_nop 0
	v_permlane16_swap_b32_e32 v0, v114
	s_or_b32 s2, s44, 2
	v_add_f32_e32 v114, v0, v114
	v_mov_b32_e32 v0, v122
	s_ashr_i32 s3, s2, 31
	s_nop 0
	v_permlane16_swap_b32_e32 v122, v0
	s_lshl_b64 s[44:45], s[2:3], 15
	v_add_f32_e32 v115, v122, v0
	v_mov_b32_e32 v135, v133
	v_mov_b32_e32 v134, v132
	v_mov_b32_e32 v177, v175
	v_mov_b32_e32 v176, v174
	v_mov_b32_e32 v169, v167
	v_mov_b32_e32 v168, v166
	v_cvt_pk_bf16_f32 v121, v116, v117
	s_add_u32 s46, s1, s44
	v_mov_b32_e32 v116, v114
	v_mov_b32_e32 v117, v115
	v_permlane32_swap_b32_e32 v133, v135
	v_permlane32_swap_b32_e32 v132, v134
	v_permlane32_swap_b32_e32 v175, v177
	v_permlane32_swap_b32_e32 v174, v176
	v_permlane32_swap_b32_e32 v167, v169
	v_permlane32_swap_b32_e32 v166, v168
	s_addc_u32 s47, s16, s45
	v_permlane32_swap_b32_e32 v114, v116
	v_permlane32_swap_b32_e32 v115, v117
	global_store_dwordx4 v159, v[118:121], s[46:47]
	s_and_saveexec_b64 s[26:27], s[40:41]
	s_cbranch_execz .LBB0_1705
	v_pk_add_f32 v[114:115], v[114:115], v[116:117]
	v_lshl_add_u64 v[116:117], s[8:9], 0, v[130:131]
	v_lshl_add_u64 v[116:117], s[38:39], 2, v[116:117]
	global_store_dwordx2 v[116:117], v[114:115], off
; __device__ __forceinline__ size_t blk_off(int r, int c, int K) { return (size_t)(r >> 8) * 256 * K + (size_t)(c >> 6) * (256 * 64) + (size_t)((r & 255) * 64 + (c & 63)); }
; __device__ __forceinline__ u32x4 pack8(const f32x4 a, const f32x4 b) { u32x4 w; w.x = cvt_pk_bf16(a[0], a[1]); w.y = cvt_pk_bf16(a[2], a[3]); w.z = cvt_pk_bf16(b[0], b[1]); w.w = cvt_pk_bf16(b[2], b[3]); return w; }
; __device__ __forceinline__ void row_stats4(const float* st, int rowb, int fq, float (&mu)[4], float (&rs)[4]) {
;     ...
;         const float mm = s1 * (1.0f / 1024.0f); mu[m] = mm; rs[m] = rsqrtf(fmaxf(s2 * (1.0f / 1024.0f) - mm * mm, 0.f) + LN_EPS_); }
;     __device__ __forceinline__ void operator()(const f32x4 (&acc)[2][2][4][2], const pg8::Unit& u, int wr, int wc, int fr, int fq) const {
;     ...
;             for (int m = 0; m < 4; ++m) { const int row = row0 + ai * 128 + m * 16; const float mu = mu4[m], rs = rs4[m];
;                 f32x4 yv[2][2], gq[2][2], bq_[2][2];
; #pragma unroll
;                 for (int bj = 0; bj < 2; ++bj)
; #pragma unroll
;                     for (int n = 0; n < 2; ++n) { yv[bj][n] = *(const f32x4*)(Yin + (size_t)row * D_ + col0 + bj * 128 + 4 * n); gq[bj][n] = *(const f32x4*)(g + col0 + bj * 128 + 4 * n); bq_[bj][n] = *(const f32x4*)(b + col0 + bj * 128 + 4 * n); }
;                 asm volatile("" ::: "memory");
;                 float s1 = 0.f, s2 = 0.f;
; #pragma unroll
;                 for (int bj = 0; bj < 2; ++bj) { float* yp = Y + (size_t)row * D_ + col0 + bj * 128; f32x4 v[2];
; #pragma unroll
;                     for (int n = 0; n < 2; ++n) { v[n] = (((yv[bj][n] - mu) * rs) * gq[bj][n] + bq_[bj][n]) * ALPHA_ + acc[ai][bj][m][n] * sc;
;                         *(f32x4*)(yp + 4 * n) = v[n]; s1 += (v[n][0] + v[n][1]) + (v[n][2] + v[n][3]); s2 += (v[n][0] * v[n][0] + v[n][1] * v[n][1]) + (v[n][2] * v[n][2] + v[n][3] * v[n][3]); }
;                     *(u32x4*)(Yb + blk_off(row, col0 + bj * 128, D_)) = pack8(v[0], v[1]); }
.LBB0_1705:
	s_or_b64 exec, exec, s[26:27]
	v_pk_add_f32 v[114:115], v[132:133], v[134:135]
	s_mov_b32 s2, 0x3a800000
	v_pk_mul_f32 v[178:179], v[114:115], s[2:3] op_sel_hi:[1,0]
	s_mov_b32 s1, 0x800000
	v_fma_f32 v0, -v179, v179, v178
	v_max_f32_e32 v0, 0, v0
	v_add_f32_e32 v0, 0x3727c5ac, v0
	v_cmp_gt_f32_e32 vcc, s1, v0
	v_mul_f32_e32 v114, 0x4b800000, v0
	s_load_dwordx16 s[60:75], s[34:35], 0x38
	v_cndmask_b32_e32 v0, v0, v114, vcc
	v_rsq_f32_e32 v0, v0
	v_lshlrev_b32_e32 v159, 6, v182
	s_mov_b32 s2, 0x3fd744fd
	v_mul_f32_e32 v114, 0x45800000, v0
	v_cndmask_b32_e32 v0, v0, v114, vcc
	v_lshlrev_b64 v[114:115], 12, v[182:183]
	s_waitcnt lgkmcnt(0)
	v_lshl_add_u64 v[114:115], s[74:75], 0, v[114:115]
	v_lshl_add_u64 v[180:181], v[152:153], 2, v[114:115]
	s_nop 1
	v_bfe_u32 v117, v227, 4, 2
	v_sub_u32_e32 v116, 0, v117
	v_lshlrev_b32_e32 v116, 4, v116
	v_ashrrev_i32_e32 v117, 31, v116
	v_lshl_add_u64 v[116:117], v[180:181], 0, v[116:117]
	global_load_dwordx4 v[186:189], v[116:117], off offset:64
	global_load_dwordx4 v[190:193], v[116:117], off
	global_load_dwordx4 v[198:201], v[156:157], off offset:16
	global_load_dwordx4 v[202:205], v[156:157], off
	global_load_dwordx4 v[206:209], v[154:155], off offset:16
	global_load_dwordx4 v[210:213], v[154:155], off
	s_nop 1
	v_bfe_u32 v119, v227, 4, 2
	v_sub_u32_e32 v118, 0, v119
	v_lshlrev_b32_e32 v118, 4, v118
	v_ashrrev_i32_e32 v119, 31, v118
	v_lshl_add_u64 v[118:119], v[180:181], 0, v[118:119]
	global_load_dwordx4 v[114:117], v[118:119], off offset:576
	global_load_dwordx4 v[134:137], v[118:119], off offset:512
	global_load_dwordx4 v[118:121], v[156:157], off offset:528
	global_load_dwordx4 v[126:129], v[156:157], off offset:512
	global_load_dwordx4 v[122:125], v[154:155], off offset:528
	global_load_dwordx4 v[130:133], v[154:155], off offset:512
	s_movk_i32 s1, 0x37c0
	v_and_or_b32 v159, v159, s1, v196
	v_lshlrev_b32_e32 v159, 1, v159
	s_waitcnt vmcnt(10)
	v_permlane32_swap_b32_e32 v190, v186
	v_permlane32_swap_b32_e32 v191, v187
	v_permlane32_swap_b32_e32 v192, v188
	v_permlane32_swap_b32_e32 v193, v189
	v_permlane16_swap_b32_e32 v190, v186
	v_permlane16_swap_b32_e32 v191, v187
	v_permlane16_swap_b32_e32 v192, v188
	v_permlane16_swap_b32_e32 v193, v189
	v_sub_f32_e32 v187, v187, v179
	v_sub_f32_e32 v183, v193, v179
	v_sub_f32_e32 v182, v192, v179
	v_sub_f32_e32 v191, v191, v179
	v_sub_f32_e32 v190, v190, v179
	v_pk_mul_f32 v[190:191], v[0:1], v[190:191] op_sel_hi:[0,1]
	v_pk_mul_f32 v[182:183], v[0:1], v[182:183] op_sel_hi:[0,1]
	s_waitcnt vmcnt(6)
	v_pk_fma_f32 v[182:183], v[204:205], v[182:183], v[212:213]
	v_pk_fma_f32 v[190:191], v[202:203], v[190:191], v[210:211]
	v_pk_mul_f32 v[182:183], v[182:183], s[2:3] op_sel_hi:[1,0]
	v_pk_mul_f32 v[190:191], v[190:191], s[2:3] op_sel_hi:[1,0]
	v_pk_fma_f32 v[112:113], v[112:113], 0.5, v[182:183] op_sel_hi:[1,0,1]
	v_pk_fma_f32 v[110:111], v[110:111], 0.5, v[190:191] op_sel_hi:[1,0,1]
	v_add_f32_e32 v182, v112, v113
	v_add_f32_e32 v178, v110, v111
	v_add_f32_e32 v178, v178, v182
	v_mul_f32_e32 v182, v111, v111
	v_mul_f32_e32 v183, v113, v113
	v_fmac_f32_e32 v182, v110, v110
	v_fmac_f32_e32 v183, v112, v112
	v_add_f32_e32 v190, v182, v183
	v_sub_f32_e32 v183, v189, v179
	v_sub_f32_e32 v182, v188, v179
	v_sub_f32_e32 v186, v186, v179
	v_pk_mul_f32 v[186:187], v[0:1], v[186:187] op_sel_hi:[0,1]
	v_pk_mul_f32 v[182:183], v[0:1], v[182:183] op_sel_hi:[0,1]
	v_pk_fma_f32 v[182:183], v[200:201], v[182:183], v[208:209]
	v_pk_fma_f32 v[186:187], v[198:199], v[186:187], v[206:207]
	v_pk_mul_f32 v[182:183], v[182:183], s[2:3] op_sel_hi:[1,0]
	v_pk_mul_f32 v[186:187], v[186:187], s[2:3] op_sel_hi:[1,0]
	v_pk_fma_f32 v[108:109], v[108:109], 0.5, v[182:183] op_sel_hi:[1,0,1]
	v_pk_fma_f32 v[106:107], v[106:107], 0.5, v[186:187] op_sel_hi:[1,0,1]
	v_add_f32_e32 v183, v108, v109
	v_add_f32_e32 v182, v106, v107
	v_add_f32_e32 v178, 0, v178
	v_add_f32_e32 v182, v182, v183
	v_add_f32_e32 v178, v178, v182
	v_mul_f32_e32 v182, v107, v107
	v_mul_f32_e32 v183, v109, v109
	s_nop 0
	s_nop 1
	v_bfe_u32 v187, v227, 4, 2
	v_sub_u32_e32 v186, 0, v187
	v_lshlrev_b32_e32 v186, 4, v186
	v_ashrrev_i32_e32 v187, 31, v186
	v_lshl_add_u64 v[186:187], v[180:181], 0, v[186:187]
	v_permlane16_swap_b32_e32 v110, v106
	v_permlane16_swap_b32_e32 v111, v107
	v_permlane16_swap_b32_e32 v112, v108
	v_permlane16_swap_b32_e32 v113, v109
	v_permlane32_swap_b32_e32 v110, v106
	v_permlane32_swap_b32_e32 v111, v107
	v_permlane32_swap_b32_e32 v112, v108
	v_permlane32_swap_b32_e32 v113, v109
	global_store_dwordx4 v[186:187], v[110:113], off
	global_store_dwordx4 v[186:187], v[106:109], off offset:64
	s_nop 1
	v_permlane32_swap_b32_e32 v110, v106
	v_permlane32_swap_b32_e32 v111, v107
	v_permlane32_swap_b32_e32 v112, v108
	v_permlane32_swap_b32_e32 v113, v109
	v_permlane16_swap_b32_e32 v110, v106
	v_permlane16_swap_b32_e32 v111, v107
	v_permlane16_swap_b32_e32 v112, v108
	v_permlane16_swap_b32_e32 v113, v109
	v_fmac_f32_e32 v182, v106, v106
	v_fmac_f32_e32 v183, v108, v108
	v_cvt_pk_bf16_f32 v110, v110, v111
	v_cvt_pk_bf16_f32 v111, v112, v113
	v_cvt_pk_bf16_f32 v112, v106, v107
	v_cvt_pk_bf16_f32 v113, v108, v109
	s_waitcnt vmcnt(6)
	v_permlane32_swap_b32_e32 v134, v114
	v_permlane32_swap_b32_e32 v135, v115
	v_permlane32_swap_b32_e32 v136, v116
	v_permlane32_swap_b32_e32 v137, v117
	v_permlane16_swap_b32_e32 v134, v114
	v_permlane16_swap_b32_e32 v135, v115
	v_permlane16_swap_b32_e32 v136, v116
	v_permlane16_swap_b32_e32 v137, v117
	v_sub_f32_e32 v107, v137, v179
	v_sub_f32_e32 v106, v136, v179
	v_sub_f32_e32 v109, v135, v179
	v_sub_f32_e32 v108, v134, v179
	v_pk_mul_f32 v[108:109], v[0:1], v[108:109] op_sel_hi:[0,1]
	v_pk_mul_f32 v[106:107], v[0:1], v[106:107] op_sel_hi:[0,1]
	s_waitcnt vmcnt(2)
; __device__ __forceinline__ float xsum16(float v) { const auto r = __builtin_amdgcn_permlane16_swap(__float_as_uint(v), __float_as_uint(v), false, false); return __uint_as_float(r[0]) + __uint_as_float(r[1]); }
; __device__ __forceinline__ float xsum32(float v) { const auto r = __builtin_amdgcn_permlane32_swap(__float_as_uint(v), __float_as_uint(v), false, false); return __uint_as_float(r[0]) + __uint_as_float(r[1]); }
; __device__ __forceinline__ size_t blk_off(int r, int c, int K) { return (size_t)(r >> 8) * 256 * K + (size_t)(c >> 6) * (256 * 64) + (size_t)((r & 255) * 64 + (c & 63)); }
; __device__ __forceinline__ u32x4 pack8(const f32x4 a, const f32x4 b) { u32x4 w; w.x = cvt_pk_bf16(a[0], a[1]); w.y = cvt_pk_bf16(a[2], a[3]); w.z = cvt_pk_bf16(b[0], b[1]); w.w = cvt_pk_bf16(b[2], b[3]); return w; }
;     __device__ __forceinline__ void operator()(const f32x4 (&acc)[2][2][4][2], const pg8::Unit& u, int wr, int wc, int fr, int fq) const {
;     ...
;             for (int m = 0; m < 4; ++m) { const int row = row0 + ai * 128 + m * 16; const float mu = mu4[m], rs = rs4[m];
;                 f32x4 yv[2][2], gq[2][2], bq_[2][2];
; #pragma unroll
;                 for (int bj = 0; bj < 2; ++bj)
; #pragma unroll
;                     for (int n = 0; n < 2; ++n) { yv[bj][n] = *(const f32x4*)(Yin + (size_t)row * D_ + col0 + bj * 128 + 4 * n); gq[bj][n] = *(const f32x4*)(g + col0 + bj * 128 + 4 * n); bq_[bj][n] = *(const f32x4*)(b + col0 + bj * 128 + 4 * n); }
;     ...
;                 for (int bj = 0; bj < 2; ++bj) { float* yp = Y + (size_t)row * D_ + col0 + bj * 128; f32x4 v[2];
; #pragma unroll
;                     for (int n = 0; n < 2; ++n) { v[n] = (((yv[bj][n] - mu) * rs) * gq[bj][n] + bq_[bj][n]) * ALPHA_ + acc[ai][bj][m][n] * sc;
;                         *(f32x4*)(yp + 4 * n) = v[n]; s1 += (v[n][0] + v[n][1]) + (v[n][2] + v[n][3]); s2 += (v[n][0] * v[n][0] + v[n][1] * v[n][1]) + (v[n][2] * v[n][2] + v[n][3] * v[n][3]); }
;                     *(u32x4*)(Yb + blk_off(row, col0 + bj * 128, D_)) = pack8(v[0], v[1]); }
;                 s1 = xsum32(xsum16(s1)); s2 = xsum32(xsum16(s2));
;                 if (fq == 0) *(f32x2*)(stn + (size_t)row * 32 + (u.pn * 4 + wc) * 2) = (f32x2){s1, s2}; asm volatile("" ::: "memory"); } }
	v_pk_fma_f32 v[106:107], v[128:129], v[106:107], v[132:133]
	v_pk_fma_f32 v[108:109], v[126:127], v[108:109], v[130:131]
	v_pk_mul_f32 v[106:107], v[106:107], s[2:3] op_sel_hi:[1,0]
	v_pk_mul_f32 v[108:109], v[108:109], s[2:3] op_sel_hi:[1,0]
	v_pk_fma_f32 v[104:105], v[104:105], 0.5, v[106:107] op_sel_hi:[1,0,1]
	v_pk_fma_f32 v[102:103], v[102:103], 0.5, v[108:109] op_sel_hi:[1,0,1]
	v_add_f32_e32 v107, v104, v105
	v_add_f32_e32 v106, v102, v103
	v_add_f32_e32 v106, v106, v107
	global_store_dwordx4 v159, v[110:113], s[48:49]
	v_mul_f32_e32 v107, v105, v105
	v_add_f32_e32 v182, v182, v183
	v_add_f32_e32 v110, v178, v106
	v_mul_f32_e32 v106, v103, v103
	v_fmac_f32_e32 v106, v102, v102
	v_fmac_f32_e32 v107, v104, v104
	v_add_f32_e32 v182, v190, v182
	v_add_f32_e32 v106, v106, v107
	v_add_f32_e32 v111, v182, v106
	v_sub_f32_e32 v107, v117, v179
	v_sub_f32_e32 v106, v116, v179
	v_sub_f32_e32 v109, v115, v179
	v_sub_f32_e32 v108, v114, v179
	v_pk_mul_f32 v[108:109], v[0:1], v[108:109] op_sel_hi:[0,1]
	v_pk_mul_f32 v[106:107], v[0:1], v[106:107] op_sel_hi:[0,1]
	v_pk_fma_f32 v[106:107], v[120:121], v[106:107], v[124:125]
	v_pk_fma_f32 v[108:109], v[118:119], v[108:109], v[122:123]
	v_pk_mul_f32 v[106:107], v[106:107], s[2:3] op_sel_hi:[1,0]
	v_pk_mul_f32 v[108:109], v[108:109], s[2:3] op_sel_hi:[1,0]
	v_pk_fma_f32 v[100:101], v[100:101], 0.5, v[106:107] op_sel_hi:[1,0,1]
	v_pk_fma_f32 v[98:99], v[98:99], 0.5, v[108:109] op_sel_hi:[1,0,1]
	v_add_f32_e32 v106, v100, v101
	v_add_f32_e32 v0, v98, v99
	v_add_f32_e32 v0, v0, v106
	v_mul_f32_e32 v106, v99, v99
	v_mul_f32_e32 v107, v101, v101
	v_add_f32_e32 v0, v110, v0
	v_fmac_f32_e32 v106, v98, v98
	v_fmac_f32_e32 v107, v100, v100
	s_nop 0
	s_nop 1
	v_bfe_u32 v109, v227, 4, 2
	v_sub_u32_e32 v108, 0, v109
	v_lshlrev_b32_e32 v108, 4, v108
	v_ashrrev_i32_e32 v109, 31, v108
	v_lshl_add_u64 v[108:109], v[180:181], 0, v[108:109]
	v_permlane16_swap_b32_e32 v102, v98
	v_permlane16_swap_b32_e32 v103, v99
	v_permlane16_swap_b32_e32 v104, v100
	v_permlane16_swap_b32_e32 v105, v101
	v_permlane32_swap_b32_e32 v102, v98
	v_permlane32_swap_b32_e32 v103, v99
	v_permlane32_swap_b32_e32 v104, v100
	v_permlane32_swap_b32_e32 v105, v101
	global_store_dwordx4 v[108:109], v[102:105], off offset:512
	global_store_dwordx4 v[108:109], v[98:101], off offset:576
	s_nop 1
	v_permlane32_swap_b32_e32 v102, v98
	v_permlane32_swap_b32_e32 v103, v99
	v_permlane32_swap_b32_e32 v104, v100
	v_permlane32_swap_b32_e32 v105, v101
	v_permlane16_swap_b32_e32 v102, v98
	v_permlane16_swap_b32_e32 v103, v99
	v_permlane16_swap_b32_e32 v104, v100
	v_permlane16_swap_b32_e32 v105, v101
	v_add_f32_e32 v106, v106, v107
	v_cvt_pk_bf16_f32 v102, v102, v103
	v_cvt_pk_bf16_f32 v103, v104, v105
	v_cvt_pk_bf16_f32 v104, v98, v99
	v_mov_b32_e32 v98, v0
	v_add_f32_e32 v106, v111, v106
	s_nop 0
	v_permlane16_swap_b32_e32 v0, v98
	v_add_f32_e32 v98, v0, v98
	v_mov_b32_e32 v0, v106
	s_nop 1
	v_permlane16_swap_b32_e32 v106, v0
	v_add_f32_e32 v99, v106, v0
	v_cvt_pk_bf16_f32 v105, v100, v101
	v_mov_b32_e32 v100, v98
	v_mov_b32_e32 v101, v99
	s_nop 0
	v_permlane32_swap_b32_e32 v98, v100
	v_permlane32_swap_b32_e32 v99, v101
	global_store_dwordx4 v159, v[102:105], s[46:47]
	s_and_saveexec_b64 s[26:27], s[40:41]
	s_cbranch_execz .LBB0_1707
	v_pk_add_f32 v[98:99], v[98:99], v[100:101]
	v_lshl_add_u64 v[100:101], s[8:9], 0, v[172:173]
	v_lshl_add_u64 v[100:101], s[38:39], 2, v[100:101]
	global_store_dwordx2 v[100:101], v[98:99], off
.LBB0_1707:
	s_or_b64 exec, exec, s[26:27]
	v_pk_add_f32 v[98:99], v[174:175], v[176:177]
	s_mov_b32 s2, 0x3a800000
	v_pk_mul_f32 v[122:123], v[98:99], s[2:3] op_sel_hi:[1,0]
	s_mov_b32 s1, 0x800000
	v_fma_f32 v0, -v123, v123, v122
	v_max_f32_e32 v0, 0, v0
	v_add_f32_e32 v0, 0x3727c5ac, v0
	v_cmp_gt_f32_e32 vcc, s1, v0
	v_mul_f32_e32 v98, 0x4b800000, v0
	s_load_dwordx16 s[60:75], s[34:35], 0x38
	v_cndmask_b32_e32 v0, v0, v98, vcc
	v_rsq_f32_e32 v0, v0
	s_mov_b32 s2, 0x3fd744fd
	v_lshlrev_b32_e32 v122, 6, v170
	v_mul_f32_e32 v98, 0x45800000, v0
	v_cndmask_b32_e32 v0, v0, v98, vcc
	v_lshlrev_b64 v[98:99], 12, v[170:171]
	s_waitcnt lgkmcnt(0)
	v_lshl_add_u64 v[98:99], s[74:75], 0, v[98:99]
	v_lshl_add_u64 v[124:125], v[152:153], 2, v[98:99]
	s_nop 1
	v_bfe_u32 v101, v227, 4, 2
	v_sub_u32_e32 v100, 0, v101
	v_lshlrev_b32_e32 v100, 4, v100
	v_ashrrev_i32_e32 v101, 31, v100
	v_lshl_add_u64 v[100:101], v[124:125], 0, v[100:101]
	global_load_dwordx4 v[126:129], v[100:101], off offset:64
	global_load_dwordx4 v[130:133], v[100:101], off
	global_load_dwordx4 v[134:137], v[156:157], off offset:16
	global_load_dwordx4 v[172:175], v[156:157], off
	global_load_dwordx4 v[176:179], v[154:155], off offset:16
	global_load_dwordx4 v[180:183], v[154:155], off
	s_nop 1
	v_bfe_u32 v103, v227, 4, 2
	v_sub_u32_e32 v102, 0, v103
	v_lshlrev_b32_e32 v102, 4, v102
	v_ashrrev_i32_e32 v103, 31, v102
	v_lshl_add_u64 v[102:103], v[124:125], 0, v[102:103]
	global_load_dwordx4 v[98:101], v[102:103], off offset:576
	global_load_dwordx4 v[118:121], v[102:103], off offset:512
	global_load_dwordx4 v[102:105], v[156:157], off offset:528
	global_load_dwordx4 v[110:113], v[156:157], off offset:512
	global_load_dwordx4 v[106:109], v[154:155], off offset:528
	global_load_dwordx4 v[114:117], v[154:155], off offset:512
	s_movk_i32 s1, 0x3bc0
	v_and_or_b32 v122, v122, s1, v196
	v_lshlrev_b32_e32 v122, 1, v122
	s_waitcnt vmcnt(10)
; __device__ __forceinline__ float xsum16(float v) { const auto r = __builtin_amdgcn_permlane16_swap(__float_as_uint(v), __float_as_uint(v), false, false); return __uint_as_float(r[0]) + __uint_as_float(r[1]); }
; __device__ __forceinline__ float xsum32(float v) { const auto r = __builtin_amdgcn_permlane32_swap(__float_as_uint(v), __float_as_uint(v), false, false); return __uint_as_float(r[0]) + __uint_as_float(r[1]); }
; __device__ __forceinline__ size_t blk_off(int r, int c, int K) { return (size_t)(r >> 8) * 256 * K + (size_t)(c >> 6) * (256 * 64) + (size_t)((r & 255) * 64 + (c & 63)); }
; __device__ __forceinline__ u32x4 pack8(const f32x4 a, const f32x4 b) { u32x4 w; w.x = cvt_pk_bf16(a[0], a[1]); w.y = cvt_pk_bf16(a[2], a[3]); w.z = cvt_pk_bf16(b[0], b[1]); w.w = cvt_pk_bf16(b[2], b[3]); return w; }
;     __device__ __forceinline__ void operator()(const f32x4 (&acc)[2][2][4][2], const pg8::Unit& u, int wr, int wc, int fr, int fq) const {
;     ...
;                 for (int bj = 0; bj < 2; ++bj) { float* yp = Y + (size_t)row * D_ + col0 + bj * 128; f32x4 v[2];
; #pragma unroll
;                     for (int n = 0; n < 2; ++n) { v[n] = (((yv[bj][n] - mu) * rs) * gq[bj][n] + bq_[bj][n]) * ALPHA_ + acc[ai][bj][m][n] * sc;
;                         *(f32x4*)(yp + 4 * n) = v[n]; s1 += (v[n][0] + v[n][1]) + (v[n][2] + v[n][3]); s2 += (v[n][0] * v[n][0] + v[n][1] * v[n][1]) + (v[n][2] * v[n][2] + v[n][3] * v[n][3]); }
;                     *(u32x4*)(Yb + blk_off(row, col0 + bj * 128, D_)) = pack8(v[0], v[1]); }
;                 s1 = xsum32(xsum16(s1)); s2 = xsum32(xsum16(s2));
;                 if (fq == 0) *(f32x2*)(stn + (size_t)row * 32 + (u.pn * 4 + wc) * 2) = (f32x2){s1, s2}; asm volatile("" ::: "memory"); } }
	v_permlane32_swap_b32_e32 v130, v126
	v_permlane32_swap_b32_e32 v131, v127
	v_permlane32_swap_b32_e32 v132, v128
	v_permlane32_swap_b32_e32 v133, v129
	v_permlane16_swap_b32_e32 v130, v126
	v_permlane16_swap_b32_e32 v131, v127
	v_permlane16_swap_b32_e32 v132, v128
	v_permlane16_swap_b32_e32 v133, v129
	v_sub_f32_e32 v129, v129, v123
	v_sub_f32_e32 v133, v133, v123
	v_sub_f32_e32 v132, v132, v123
	v_sub_f32_e32 v131, v131, v123
	v_sub_f32_e32 v130, v130, v123
	v_sub_f32_e32 v128, v128, v123
	v_sub_f32_e32 v127, v127, v123
	v_sub_f32_e32 v126, v126, v123
	v_pk_mul_f32 v[130:131], v[0:1], v[130:131] op_sel_hi:[0,1]
	v_pk_mul_f32 v[132:133], v[0:1], v[132:133] op_sel_hi:[0,1]
	v_pk_mul_f32 v[126:127], v[0:1], v[126:127] op_sel_hi:[0,1]
	v_pk_mul_f32 v[128:129], v[0:1], v[128:129] op_sel_hi:[0,1]
	s_waitcnt vmcnt(6)
	v_pk_fma_f32 v[132:133], v[174:175], v[132:133], v[182:183]
	v_pk_fma_f32 v[130:131], v[172:173], v[130:131], v[180:181]
	v_pk_fma_f32 v[128:129], v[136:137], v[128:129], v[178:179]
	v_pk_fma_f32 v[126:127], v[134:135], v[126:127], v[176:177]
	v_pk_mul_f32 v[130:131], v[130:131], s[2:3] op_sel_hi:[1,0]
	v_pk_mul_f32 v[132:133], v[132:133], s[2:3] op_sel_hi:[1,0]
	v_pk_mul_f32 v[126:127], v[126:127], s[2:3] op_sel_hi:[1,0]
	v_pk_mul_f32 v[128:129], v[128:129], s[2:3] op_sel_hi:[1,0]
	v_pk_fma_f32 v[96:97], v[96:97], 0.5, v[132:133] op_sel_hi:[1,0,1]
	v_pk_fma_f32 v[94:95], v[94:95], 0.5, v[130:131] op_sel_hi:[1,0,1]
	v_pk_fma_f32 v[92:93], v[92:93], 0.5, v[128:129] op_sel_hi:[1,0,1]
	v_pk_fma_f32 v[90:91], v[90:91], 0.5, v[126:127] op_sel_hi:[1,0,1]
	v_add_f32_e32 v130, v94, v95
	v_add_f32_e32 v131, v96, v97
	v_add_f32_e32 v126, v90, v91
	v_add_f32_e32 v127, v92, v93
	v_add_f32_e32 v130, v130, v131
	v_mul_f32_e32 v131, v95, v95
	v_mul_f32_e32 v132, v97, v97
	v_add_f32_e32 v126, v126, v127
	v_mul_f32_e32 v127, v91, v91
	v_mul_f32_e32 v128, v93, v93
	s_nop 0
	v_fmac_f32_e32 v131, v94, v94
	v_fmac_f32_e32 v132, v96, v96
	s_nop 1
	v_bfe_u32 v135, v227, 4, 2
	v_sub_u32_e32 v134, 0, v135
	v_lshlrev_b32_e32 v134, 4, v134
	v_ashrrev_i32_e32 v135, 31, v134
	v_lshl_add_u64 v[134:135], v[124:125], 0, v[134:135]
	v_permlane16_swap_b32_e32 v94, v90
	v_permlane16_swap_b32_e32 v95, v91
	v_permlane16_swap_b32_e32 v96, v92
	v_permlane16_swap_b32_e32 v97, v93
	v_permlane32_swap_b32_e32 v94, v90
	v_permlane32_swap_b32_e32 v95, v91
	v_permlane32_swap_b32_e32 v96, v92
	v_permlane32_swap_b32_e32 v97, v93
	global_store_dwordx4 v[134:135], v[94:97], off
	global_store_dwordx4 v[134:135], v[90:93], off offset:64
	s_nop 1
	v_permlane32_swap_b32_e32 v94, v90
	v_permlane32_swap_b32_e32 v95, v91
	v_permlane32_swap_b32_e32 v96, v92
	v_permlane32_swap_b32_e32 v97, v93
	v_permlane16_swap_b32_e32 v94, v90
	v_permlane16_swap_b32_e32 v95, v91
	v_permlane16_swap_b32_e32 v96, v92
	v_permlane16_swap_b32_e32 v97, v93
	v_fmac_f32_e32 v127, v90, v90
	v_fmac_f32_e32 v128, v92, v92
	v_cvt_pk_bf16_f32 v94, v94, v95
	v_cvt_pk_bf16_f32 v95, v96, v97
	v_cvt_pk_bf16_f32 v96, v90, v91
	v_cvt_pk_bf16_f32 v97, v92, v93
	s_waitcnt vmcnt(6)
	v_permlane32_swap_b32_e32 v118, v98
	v_permlane32_swap_b32_e32 v119, v99
	v_permlane32_swap_b32_e32 v120, v100
	v_permlane32_swap_b32_e32 v121, v101
	v_permlane16_swap_b32_e32 v118, v98
	v_permlane16_swap_b32_e32 v119, v99
	v_permlane16_swap_b32_e32 v120, v100
	v_permlane16_swap_b32_e32 v121, v101
	v_sub_f32_e32 v91, v121, v123
	v_sub_f32_e32 v90, v120, v123
	v_sub_f32_e32 v93, v119, v123
	v_sub_f32_e32 v92, v118, v123
	v_pk_mul_f32 v[92:93], v[0:1], v[92:93] op_sel_hi:[0,1]
	v_pk_mul_f32 v[90:91], v[0:1], v[90:91] op_sel_hi:[0,1]
	s_waitcnt vmcnt(2)
	v_pk_fma_f32 v[90:91], v[112:113], v[90:91], v[116:117]
	v_pk_fma_f32 v[92:93], v[110:111], v[92:93], v[114:115]
	v_pk_mul_f32 v[90:91], v[90:91], s[2:3] op_sel_hi:[1,0]
	v_pk_mul_f32 v[92:93], v[92:93], s[2:3] op_sel_hi:[1,0]
	v_pk_fma_f32 v[88:89], v[88:89], 0.5, v[90:91] op_sel_hi:[1,0,1]
	v_pk_fma_f32 v[86:87], v[86:87], 0.5, v[92:93] op_sel_hi:[1,0,1]
	v_add_f32_e32 v130, 0, v130
	v_add_f32_e32 v90, v86, v87
	v_add_f32_e32 v91, v88, v89
	v_add_f32_e32 v126, v130, v126
	v_add_f32_e32 v90, v90, v91
	global_store_dwordx4 v122, v[94:97], s[48:49]
	v_mul_f32_e32 v91, v89, v89
	v_add_f32_e32 v131, v131, v132
	v_add_f32_e32 v94, v126, v90
	v_mul_f32_e32 v90, v87, v87
	v_add_f32_e32 v127, v127, v128
	v_fmac_f32_e32 v90, v86, v86
	v_fmac_f32_e32 v91, v88, v88
	v_add_f32_e32 v127, v131, v127
	v_add_f32_e32 v90, v90, v91
	v_add_f32_e32 v95, v127, v90
	v_sub_f32_e32 v91, v101, v123
	v_sub_f32_e32 v90, v100, v123
	v_sub_f32_e32 v93, v99, v123
	v_sub_f32_e32 v92, v98, v123
	v_pk_mul_f32 v[92:93], v[0:1], v[92:93] op_sel_hi:[0,1]
	v_pk_mul_f32 v[90:91], v[0:1], v[90:91] op_sel_hi:[0,1]
	v_pk_fma_f32 v[90:91], v[104:105], v[90:91], v[108:109]
	v_pk_fma_f32 v[92:93], v[102:103], v[92:93], v[106:107]
	v_pk_mul_f32 v[90:91], v[90:91], s[2:3] op_sel_hi:[1,0]
	v_pk_mul_f32 v[92:93], v[92:93], s[2:3] op_sel_hi:[1,0]
	v_pk_fma_f32 v[84:85], v[84:85], 0.5, v[90:91] op_sel_hi:[1,0,1]
	v_pk_fma_f32 v[82:83], v[82:83], 0.5, v[92:93] op_sel_hi:[1,0,1]
	v_add_f32_e32 v90, v84, v85
	v_add_f32_e32 v0, v82, v83
	v_add_f32_e32 v0, v0, v90
	v_mul_f32_e32 v90, v83, v83
	v_mul_f32_e32 v91, v85, v85
	v_add_f32_e32 v0, v94, v0
	v_fmac_f32_e32 v90, v82, v82
	v_fmac_f32_e32 v91, v84, v84
	s_nop 0
	s_nop 1
	v_bfe_u32 v93, v227, 4, 2
	v_sub_u32_e32 v92, 0, v93
	v_lshlrev_b32_e32 v92, 4, v92
	v_ashrrev_i32_e32 v93, 31, v92
	v_lshl_add_u64 v[92:93], v[124:125], 0, v[92:93]
	v_permlane16_swap_b32_e32 v86, v82
	v_permlane16_swap_b32_e32 v87, v83
	v_permlane16_swap_b32_e32 v88, v84
	v_permlane16_swap_b32_e32 v89, v85
	v_permlane32_swap_b32_e32 v86, v82
	v_permlane32_swap_b32_e32 v87, v83
	v_permlane32_swap_b32_e32 v88, v84
	v_permlane32_swap_b32_e32 v89, v85
	global_store_dwordx4 v[92:93], v[86:89], off offset:512
	global_store_dwordx4 v[92:93], v[82:85], off offset:576
	s_nop 1
	v_permlane32_swap_b32_e32 v86, v82
	v_permlane32_swap_b32_e32 v87, v83
	v_permlane32_swap_b32_e32 v88, v84
	v_permlane32_swap_b32_e32 v89, v85
	v_permlane16_swap_b32_e32 v86, v82
	v_permlane16_swap_b32_e32 v87, v83
	v_permlane16_swap_b32_e32 v88, v84
	v_permlane16_swap_b32_e32 v89, v85
	v_add_f32_e32 v90, v90, v91
	v_cvt_pk_bf16_f32 v86, v86, v87
	v_cvt_pk_bf16_f32 v87, v88, v89
	v_cvt_pk_bf16_f32 v88, v82, v83
	v_mov_b32_e32 v82, v0
	v_add_f32_e32 v90, v95, v90
	s_nop 0
	v_permlane16_swap_b32_e32 v0, v82
	v_add_f32_e32 v82, v0, v82
	v_mov_b32_e32 v0, v90
	s_nop 1
	v_permlane16_swap_b32_e32 v90, v0
	v_add_f32_e32 v83, v90, v0
	v_cvt_pk_bf16_f32 v89, v84, v85
	v_mov_b32_e32 v84, v82
	v_mov_b32_e32 v85, v83
	s_nop 0
	v_permlane32_swap_b32_e32 v82, v84
	v_permlane32_swap_b32_e32 v83, v85
	global_store_dwordx4 v122, v[86:89], s[46:47]
	s_and_saveexec_b64 s[26:27], s[40:41]
	s_cbranch_execz .LBB0_1709
	v_pk_add_f32 v[82:83], v[82:83], v[84:85]
	v_lshl_add_u64 v[84:85], s[8:9], 0, v[164:165]
	v_lshl_add_u64 v[84:85], s[38:39], 2, v[84:85]
	global_store_dwordx2 v[84:85], v[82:83], off
; __device__ __forceinline__ size_t blk_off(int r, int c, int K) { return (size_t)(r >> 8) * 256 * K + (size_t)(c >> 6) * (256 * 64) + (size_t)((r & 255) * 64 + (c & 63)); }
; __device__ __forceinline__ u32x4 pack8(const f32x4 a, const f32x4 b) { u32x4 w; w.x = cvt_pk_bf16(a[0], a[1]); w.y = cvt_pk_bf16(a[2], a[3]); w.z = cvt_pk_bf16(b[0], b[1]); w.w = cvt_pk_bf16(b[2], b[3]); return w; }
; __device__ __forceinline__ void row_stats4(const float* st, int rowb, int fq, float (&mu)[4], float (&rs)[4]) {
;     ...
;         const float mm = s1 * (1.0f / 1024.0f); mu[m] = mm; rs[m] = rsqrtf(fmaxf(s2 * (1.0f / 1024.0f) - mm * mm, 0.f) + LN_EPS_); }
;     __device__ __forceinline__ void operator()(const f32x4 (&acc)[2][2][4][2], const pg8::Unit& u, int wr, int wc, int fr, int fq) const {
;     ...
;             for (int m = 0; m < 4; ++m) { const int row = row0 + ai * 128 + m * 16; const float mu = mu4[m], rs = rs4[m];
;                 f32x4 yv[2][2], gq[2][2], bq_[2][2];
; #pragma unroll
;                 for (int bj = 0; bj < 2; ++bj)
; #pragma unroll
;                     for (int n = 0; n < 2; ++n) { yv[bj][n] = *(const f32x4*)(Yin + (size_t)row * D_ + col0 + bj * 128 + 4 * n); gq[bj][n] = *(const f32x4*)(g + col0 + bj * 128 + 4 * n); bq_[bj][n] = *(const f32x4*)(b + col0 + bj * 128 + 4 * n); }
;                 asm volatile("" ::: "memory");
;                 float s1 = 0.f, s2 = 0.f;
; #pragma unroll
;                 for (int bj = 0; bj < 2; ++bj) { float* yp = Y + (size_t)row * D_ + col0 + bj * 128; f32x4 v[2];
; #pragma unroll
;                     for (int n = 0; n < 2; ++n) { v[n] = (((yv[bj][n] - mu) * rs) * gq[bj][n] + bq_[bj][n]) * ALPHA_ + acc[ai][bj][m][n] * sc;
;                         *(f32x4*)(yp + 4 * n) = v[n]; s1 += (v[n][0] + v[n][1]) + (v[n][2] + v[n][3]); s2 += (v[n][0] * v[n][0] + v[n][1] * v[n][1]) + (v[n][2] * v[n][2] + v[n][3] * v[n][3]); }
;                     *(u32x4*)(Yb + blk_off(row, col0 + bj * 128, D_)) = pack8(v[0], v[1]); }
.LBB0_1709:
	s_or_b64 exec, exec, s[26:27]
	v_pk_add_f32 v[82:83], v[166:167], v[168:169]
	s_mov_b32 s2, 0x3a800000
	v_pk_mul_f32 v[106:107], v[82:83], s[2:3] op_sel_hi:[1,0]
	s_mov_b32 s1, 0x800000
	v_fma_f32 v0, -v107, v107, v106
	v_max_f32_e32 v0, 0, v0
	v_add_f32_e32 v0, 0x3727c5ac, v0
	v_cmp_gt_f32_e32 vcc, s1, v0
	v_mul_f32_e32 v82, 0x4b800000, v0
	s_load_dwordx16 s[60:75], s[34:35], 0x38
	v_cndmask_b32_e32 v0, v0, v82, vcc
	v_rsq_f32_e32 v0, v0
	s_mov_b32 s2, 0x3fd744fd
	v_lshlrev_b32_e32 v106, 6, v162
	v_mul_f32_e32 v82, 0x45800000, v0
	v_cndmask_b32_e32 v0, v0, v82, vcc
	v_lshlrev_b64 v[82:83], 12, v[162:163]
	s_waitcnt lgkmcnt(0)
	v_lshl_add_u64 v[82:83], s[74:75], 0, v[82:83]
	v_lshl_add_u64 v[108:109], v[152:153], 2, v[82:83]
	s_nop 1
	v_bfe_u32 v85, v227, 4, 2
	v_sub_u32_e32 v84, 0, v85
	v_lshlrev_b32_e32 v84, 4, v84
	v_ashrrev_i32_e32 v85, 31, v84
	v_lshl_add_u64 v[84:85], v[108:109], 0, v[84:85]
	global_load_dwordx4 v[110:113], v[84:85], off offset:64
	global_load_dwordx4 v[114:117], v[84:85], off
	global_load_dwordx4 v[118:121], v[156:157], off offset:16
	global_load_dwordx4 v[122:125], v[156:157], off
	global_load_dwordx4 v[126:129], v[154:155], off offset:16
	global_load_dwordx4 v[130:133], v[154:155], off
	s_nop 1
	v_bfe_u32 v87, v227, 4, 2
	v_sub_u32_e32 v86, 0, v87
	v_lshlrev_b32_e32 v86, 4, v86
	v_ashrrev_i32_e32 v87, 31, v86
	v_lshl_add_u64 v[86:87], v[108:109], 0, v[86:87]
	global_load_dwordx4 v[82:85], v[86:87], off offset:576
	global_load_dwordx4 v[102:105], v[86:87], off offset:512
	global_load_dwordx4 v[86:89], v[156:157], off offset:528
	global_load_dwordx4 v[94:97], v[156:157], off offset:512
	global_load_dwordx4 v[90:93], v[154:155], off offset:528
	global_load_dwordx4 v[98:101], v[154:155], off offset:512
	s_movk_i32 s1, 0x3fc0
	v_and_or_b32 v106, v106, s1, v196
	v_lshlrev_b32_e32 v106, 1, v106
	s_waitcnt vmcnt(10)
	v_permlane32_swap_b32_e32 v114, v110
	v_permlane32_swap_b32_e32 v115, v111
	v_permlane32_swap_b32_e32 v116, v112
	v_permlane32_swap_b32_e32 v117, v113
	v_permlane16_swap_b32_e32 v114, v110
	v_permlane16_swap_b32_e32 v115, v111
	v_permlane16_swap_b32_e32 v116, v112
	v_permlane16_swap_b32_e32 v117, v113
	v_sub_f32_e32 v113, v113, v107
	v_sub_f32_e32 v117, v117, v107
	v_sub_f32_e32 v116, v116, v107
	v_sub_f32_e32 v115, v115, v107
	v_sub_f32_e32 v114, v114, v107
	v_sub_f32_e32 v112, v112, v107
	v_sub_f32_e32 v111, v111, v107
	v_sub_f32_e32 v110, v110, v107
	v_pk_mul_f32 v[114:115], v[0:1], v[114:115] op_sel_hi:[0,1]
	v_pk_mul_f32 v[116:117], v[0:1], v[116:117] op_sel_hi:[0,1]
	v_pk_mul_f32 v[110:111], v[0:1], v[110:111] op_sel_hi:[0,1]
	v_pk_mul_f32 v[112:113], v[0:1], v[112:113] op_sel_hi:[0,1]
	s_waitcnt vmcnt(6)
	v_pk_fma_f32 v[116:117], v[124:125], v[116:117], v[132:133]
	v_pk_fma_f32 v[114:115], v[122:123], v[114:115], v[130:131]
	v_pk_fma_f32 v[112:113], v[120:121], v[112:113], v[128:129]
	v_pk_fma_f32 v[110:111], v[118:119], v[110:111], v[126:127]
	v_pk_mul_f32 v[114:115], v[114:115], s[2:3] op_sel_hi:[1,0]
	v_pk_mul_f32 v[116:117], v[116:117], s[2:3] op_sel_hi:[1,0]
	v_pk_mul_f32 v[110:111], v[110:111], s[2:3] op_sel_hi:[1,0]
	v_pk_mul_f32 v[112:113], v[112:113], s[2:3] op_sel_hi:[1,0]
	v_pk_fma_f32 v[80:81], v[80:81], 0.5, v[116:117] op_sel_hi:[1,0,1]
	v_pk_fma_f32 v[78:79], v[78:79], 0.5, v[114:115] op_sel_hi:[1,0,1]
	v_pk_fma_f32 v[76:77], v[76:77], 0.5, v[112:113] op_sel_hi:[1,0,1]
	v_pk_fma_f32 v[74:75], v[74:75], 0.5, v[110:111] op_sel_hi:[1,0,1]
	v_add_f32_e32 v114, v78, v79
	v_add_f32_e32 v115, v80, v81
	v_add_f32_e32 v110, v74, v75
	v_add_f32_e32 v111, v76, v77
	v_add_f32_e32 v114, v114, v115
	v_mul_f32_e32 v115, v79, v79
	v_mul_f32_e32 v116, v81, v81
	v_add_f32_e32 v110, v110, v111
	v_mul_f32_e32 v111, v75, v75
	v_mul_f32_e32 v112, v77, v77
	s_nop 0
	v_fmac_f32_e32 v115, v78, v78
	v_fmac_f32_e32 v116, v80, v80
	s_nop 1
	v_bfe_u32 v119, v227, 4, 2
	v_sub_u32_e32 v118, 0, v119
	v_lshlrev_b32_e32 v118, 4, v118
	v_ashrrev_i32_e32 v119, 31, v118
	v_lshl_add_u64 v[118:119], v[108:109], 0, v[118:119]
	v_permlane16_swap_b32_e32 v78, v74
	v_permlane16_swap_b32_e32 v79, v75
	v_permlane16_swap_b32_e32 v80, v76
	v_permlane16_swap_b32_e32 v81, v77
	v_permlane32_swap_b32_e32 v78, v74
	v_permlane32_swap_b32_e32 v79, v75
	v_permlane32_swap_b32_e32 v80, v76
	v_permlane32_swap_b32_e32 v81, v77
	global_store_dwordx4 v[118:119], v[78:81], off
	global_store_dwordx4 v[118:119], v[74:77], off offset:64
	s_nop 1
	v_permlane32_swap_b32_e32 v78, v74
	v_permlane32_swap_b32_e32 v79, v75
	v_permlane32_swap_b32_e32 v80, v76
	v_permlane32_swap_b32_e32 v81, v77
	v_permlane16_swap_b32_e32 v78, v74
	v_permlane16_swap_b32_e32 v79, v75
	v_permlane16_swap_b32_e32 v80, v76
	v_permlane16_swap_b32_e32 v81, v77
	v_fmac_f32_e32 v111, v74, v74
	v_fmac_f32_e32 v112, v76, v76
	v_cvt_pk_bf16_f32 v78, v78, v79
	v_cvt_pk_bf16_f32 v79, v80, v81
	v_cvt_pk_bf16_f32 v80, v74, v75
	v_cvt_pk_bf16_f32 v81, v76, v77
	s_waitcnt vmcnt(6)
	v_permlane32_swap_b32_e32 v102, v82
	v_permlane32_swap_b32_e32 v103, v83
	v_permlane32_swap_b32_e32 v104, v84
	v_permlane32_swap_b32_e32 v105, v85
	v_permlane16_swap_b32_e32 v102, v82
	v_permlane16_swap_b32_e32 v103, v83
	v_permlane16_swap_b32_e32 v104, v84
	v_permlane16_swap_b32_e32 v105, v85
	v_sub_f32_e32 v75, v105, v107
	v_sub_f32_e32 v74, v104, v107
	v_sub_f32_e32 v77, v103, v107
	v_sub_f32_e32 v76, v102, v107
	v_pk_mul_f32 v[76:77], v[0:1], v[76:77] op_sel_hi:[0,1]
	v_pk_mul_f32 v[74:75], v[0:1], v[74:75] op_sel_hi:[0,1]
	s_waitcnt vmcnt(2)
; __device__ __forceinline__ float xsum16(float v) { const auto r = __builtin_amdgcn_permlane16_swap(__float_as_uint(v), __float_as_uint(v), false, false); return __uint_as_float(r[0]) + __uint_as_float(r[1]); }
; __device__ __forceinline__ float xsum32(float v) { const auto r = __builtin_amdgcn_permlane32_swap(__float_as_uint(v), __float_as_uint(v), false, false); return __uint_as_float(r[0]) + __uint_as_float(r[1]); }
; __device__ __forceinline__ size_t blk_off(int r, int c, int K) { return (size_t)(r >> 8) * 256 * K + (size_t)(c >> 6) * (256 * 64) + (size_t)((r & 255) * 64 + (c & 63)); }
; __device__ __forceinline__ u32x4 pack8(const f32x4 a, const f32x4 b) { u32x4 w; w.x = cvt_pk_bf16(a[0], a[1]); w.y = cvt_pk_bf16(a[2], a[3]); w.z = cvt_pk_bf16(b[0], b[1]); w.w = cvt_pk_bf16(b[2], b[3]); return w; }
; __device__ __forceinline__ void row_stats4(const float* st, int rowb, int fq, float (&mu)[4], float (&rs)[4]) {
;     f32x4 a[4], b[4];
; #pragma unroll
;     for (int m = 0; m < 4; ++m) { const f32x4* p = (const f32x4*)(st + (size_t)(rowb + m * 16) * 32 + fq * 8); a[m] = p[0]; b[m] = p[1]; }
; #pragma unroll
;     for (int m = 0; m < 4; ++m) { float s1 = (a[m][0] + a[m][2]) + (b[m][0] + b[m][2]), s2 = (a[m][1] + a[m][3]) + (b[m][1] + b[m][3]);
;     __device__ __forceinline__ void operator()(const f32x4 (&acc)[2][2][4][2], const pg8::Unit& u, int wr, int wc, int fr, int fq) const {
;     ...
;                 for (int bj = 0; bj < 2; ++bj) { float* yp = Y + (size_t)row * D_ + col0 + bj * 128; f32x4 v[2];
; #pragma unroll
;                     for (int n = 0; n < 2; ++n) { v[n] = (((yv[bj][n] - mu) * rs) * gq[bj][n] + bq_[bj][n]) * ALPHA_ + acc[ai][bj][m][n] * sc;
;                         *(f32x4*)(yp + 4 * n) = v[n]; s1 += (v[n][0] + v[n][1]) + (v[n][2] + v[n][3]); s2 += (v[n][0] * v[n][0] + v[n][1] * v[n][1]) + (v[n][2] * v[n][2] + v[n][3] * v[n][3]); }
;                     *(u32x4*)(Yb + blk_off(row, col0 + bj * 128, D_)) = pack8(v[0], v[1]); }
;                 s1 = xsum32(xsum16(s1)); s2 = xsum32(xsum16(s2));
;                 if (fq == 0) *(f32x2*)(stn + (size_t)row * 32 + (u.pn * 4 + wc) * 2) = (f32x2){s1, s2}; asm volatile("" ::: "memory"); } }
	v_pk_fma_f32 v[74:75], v[96:97], v[74:75], v[100:101]
	v_pk_fma_f32 v[76:77], v[94:95], v[76:77], v[98:99]
	v_pk_mul_f32 v[74:75], v[74:75], s[2:3] op_sel_hi:[1,0]
	v_pk_mul_f32 v[76:77], v[76:77], s[2:3] op_sel_hi:[1,0]
	v_pk_fma_f32 v[72:73], v[72:73], 0.5, v[74:75] op_sel_hi:[1,0,1]
	v_pk_fma_f32 v[70:71], v[70:71], 0.5, v[76:77] op_sel_hi:[1,0,1]
	v_add_f32_e32 v114, 0, v114
	v_add_f32_e32 v74, v70, v71
	v_add_f32_e32 v75, v72, v73
	v_add_f32_e32 v110, v114, v110
	v_add_f32_e32 v74, v74, v75
	global_store_dwordx4 v106, v[78:81], s[48:49]
	v_mul_f32_e32 v75, v73, v73
	v_add_f32_e32 v115, v115, v116
	v_add_f32_e32 v78, v110, v74
	v_mul_f32_e32 v74, v71, v71
	v_add_f32_e32 v111, v111, v112
	v_fmac_f32_e32 v74, v70, v70
	v_fmac_f32_e32 v75, v72, v72
	v_add_f32_e32 v111, v115, v111
	v_add_f32_e32 v74, v74, v75
	v_add_f32_e32 v79, v111, v74
	v_sub_f32_e32 v75, v85, v107
	v_sub_f32_e32 v74, v84, v107
	v_sub_f32_e32 v77, v83, v107
	v_sub_f32_e32 v76, v82, v107
	v_pk_mul_f32 v[76:77], v[0:1], v[76:77] op_sel_hi:[0,1]
	v_pk_mul_f32 v[74:75], v[0:1], v[74:75] op_sel_hi:[0,1]
	v_pk_fma_f32 v[74:75], v[88:89], v[74:75], v[92:93]
	v_pk_fma_f32 v[76:77], v[86:87], v[76:77], v[90:91]
	v_pk_mul_f32 v[74:75], v[74:75], s[2:3] op_sel_hi:[1,0]
	v_pk_mul_f32 v[76:77], v[76:77], s[2:3] op_sel_hi:[1,0]
	v_pk_fma_f32 v[68:69], v[68:69], 0.5, v[74:75] op_sel_hi:[1,0,1]
	v_pk_fma_f32 v[66:67], v[66:67], 0.5, v[76:77] op_sel_hi:[1,0,1]
	v_add_f32_e32 v74, v68, v69
	v_add_f32_e32 v0, v66, v67
	v_add_f32_e32 v0, v0, v74
	v_mul_f32_e32 v74, v67, v67
	v_mul_f32_e32 v75, v69, v69
	v_add_f32_e32 v0, v78, v0
	v_fmac_f32_e32 v74, v66, v66
	v_fmac_f32_e32 v75, v68, v68
	s_nop 0
	s_nop 1
	v_bfe_u32 v77, v227, 4, 2
	v_sub_u32_e32 v76, 0, v77
	v_lshlrev_b32_e32 v76, 4, v76
	v_ashrrev_i32_e32 v77, 31, v76
	v_lshl_add_u64 v[76:77], v[108:109], 0, v[76:77]
	v_permlane16_swap_b32_e32 v70, v66
	v_permlane16_swap_b32_e32 v71, v67
	v_permlane16_swap_b32_e32 v72, v68
	v_permlane16_swap_b32_e32 v73, v69
	v_permlane32_swap_b32_e32 v70, v66
	v_permlane32_swap_b32_e32 v71, v67
	v_permlane32_swap_b32_e32 v72, v68
	v_permlane32_swap_b32_e32 v73, v69
	global_store_dwordx4 v[76:77], v[70:73], off offset:512
	global_store_dwordx4 v[76:77], v[66:69], off offset:576
	s_nop 1
	v_permlane32_swap_b32_e32 v70, v66
	v_permlane32_swap_b32_e32 v71, v67
	v_permlane32_swap_b32_e32 v72, v68
	v_permlane32_swap_b32_e32 v73, v69
	v_permlane16_swap_b32_e32 v70, v66
	v_permlane16_swap_b32_e32 v71, v67
	v_permlane16_swap_b32_e32 v72, v68
	v_permlane16_swap_b32_e32 v73, v69
	v_add_f32_e32 v74, v74, v75
	v_cvt_pk_bf16_f32 v70, v70, v71
	v_cvt_pk_bf16_f32 v71, v72, v73
	v_cvt_pk_bf16_f32 v72, v66, v67
	v_mov_b32_e32 v66, v0
	v_add_f32_e32 v74, v79, v74
	s_nop 0
	v_permlane16_swap_b32_e32 v0, v66
	v_add_f32_e32 v66, v0, v66
	v_mov_b32_e32 v0, v74
	s_nop 1
	v_permlane16_swap_b32_e32 v74, v0
	v_add_f32_e32 v67, v74, v0
	v_cvt_pk_bf16_f32 v73, v68, v69
	v_mov_b32_e32 v68, v66
	v_mov_b32_e32 v69, v67
	s_nop 0
	v_permlane32_swap_b32_e32 v66, v68
	v_permlane32_swap_b32_e32 v67, v69
	global_store_dwordx4 v106, v[70:73], s[46:47]
	s_and_saveexec_b64 s[26:27], s[40:41]
	s_cbranch_execz .LBB0_1711
	v_pk_add_f32 v[66:67], v[66:67], v[68:69]
	v_lshl_add_u64 v[68:69], s[8:9], 0, v[160:161]
	v_lshl_add_u64 v[68:69], s[38:39], 2, v[68:69]
	global_store_dwordx2 v[68:69], v[66:67], off
.LBB0_1711:
	s_or_b64 exec, exec, s[26:27]
	v_add_u32_e32 v68, 0x80, v158
	v_ashrrev_i32_e32 v69, 31, v68
	v_lshlrev_b64 v[66:67], 7, v[68:69]
	v_lshl_add_u64 v[74:75], v[146:147], 0, v[66:67]
	v_add_u32_e32 v96, 0x90, v158
	s_nop 1
	v_bfe_u32 v77, v227, 4, 2
	v_sub_u32_e32 v76, 0, v77
	v_lshlrev_b32_e32 v76, 4, v76
	v_ashrrev_i32_e32 v77, 31, v76
	v_lshl_add_u64 v[76:77], v[74:75], 0, v[76:77]
	global_load_dwordx4 v[70:73], v[76:77], off
	global_load_dwordx4 v[82:85], v[76:77], off offset:64
	v_ashrrev_i32_e32 v97, 31, v96
	v_lshlrev_b64 v[86:87], 7, v[96:97]
	v_add_u32_e32 v80, 0xa0, v158
	v_lshl_add_u64 v[74:75], v[146:147], 0, v[86:87]
	v_ashrrev_i32_e32 v81, 31, v80
	s_nop 1
	v_bfe_u32 v77, v227, 4, 2
	v_sub_u32_e32 v76, 0, v77
	v_lshlrev_b32_e32 v76, 4, v76
	v_ashrrev_i32_e32 v77, 31, v76
	v_lshl_add_u64 v[76:77], v[74:75], 0, v[76:77]
	global_load_dwordx4 v[88:91], v[76:77], off
	global_load_dwordx4 v[92:95], v[76:77], off offset:64
	v_lshlrev_b64 v[74:75], 7, v[80:81]
	v_lshl_add_u64 v[74:75], v[146:147], 0, v[74:75]
	s_nop 1
	v_bfe_u32 v77, v227, 4, 2
	v_sub_u32_e32 v76, 0, v77
	v_lshlrev_b32_e32 v76, 4, v76
	v_ashrrev_i32_e32 v77, 31, v76
	v_lshl_add_u64 v[76:77], v[74:75], 0, v[76:77]
	global_load_dwordx4 v[98:101], v[76:77], off
	global_load_dwordx4 v[102:105], v[76:77], off offset:64
	v_add_u32_e32 v74, 0xb0, v158
	v_ashrrev_i32_e32 v75, 31, v74
	v_lshlrev_b64 v[76:77], 7, v[74:75]
	v_lshl_add_u64 v[76:77], v[146:147], 0, v[76:77]
	s_nop 1
	v_bfe_u32 v79, v227, 4, 2
	v_sub_u32_e32 v78, 0, v79
	v_lshlrev_b32_e32 v78, 4, v78
	v_ashrrev_i32_e32 v79, 31, v78
	v_lshl_add_u64 v[78:79], v[76:77], 0, v[78:79]
	global_load_dwordx4 v[106:109], v[78:79], off
	global_load_dwordx4 v[110:113], v[78:79], off offset:64
	s_load_dwordx16 s[60:75], s[34:35], 0x38
	v_lshlrev_b64 v[78:79], 12, v[68:69]
	s_mov_b32 s2, 0x3a800000
	s_mov_b32 s1, 0x800000
	s_waitcnt lgkmcnt(0)
	v_lshl_add_u64 v[78:79], s[74:75], 0, v[78:79]
	v_lshl_add_u64 v[76:77], v[152:153], 2, v[78:79]
	s_nop 1
	v_bfe_u32 v123, v227, 4, 2
	v_sub_u32_e32 v122, 0, v123
	v_lshlrev_b32_e32 v122, 4, v122
	v_ashrrev_i32_e32 v123, 31, v122
	v_lshl_add_u64 v[122:123], v[76:77], 0, v[122:123]
	global_load_dwordx4 v[114:117], v[122:123], off offset:64
	global_load_dwordx4 v[118:121], v[122:123], off
	global_load_dwordx4 v[122:125], v[156:157], off offset:16
	global_load_dwordx4 v[126:129], v[156:157], off
	global_load_dwordx4 v[130:133], v[154:155], off offset:16
	global_load_dwordx4 v[134:137], v[154:155], off
	s_mov_b32 s16, 0x3fd744fd
	s_waitcnt vmcnt(12)
; __device__ __forceinline__ float xsum16(float v) { const auto r = __builtin_amdgcn_permlane16_swap(__float_as_uint(v), __float_as_uint(v), false, false); return __uint_as_float(r[0]) + __uint_as_float(r[1]); }
; __device__ __forceinline__ float xsum32(float v) { const auto r = __builtin_amdgcn_permlane32_swap(__float_as_uint(v), __float_as_uint(v), false, false); return __uint_as_float(r[0]) + __uint_as_float(r[1]); }
; __device__ __forceinline__ void row_stats4(const float* st, int rowb, int fq, float (&mu)[4], float (&rs)[4]) {
;     ...
;     for (int m = 0; m < 4; ++m) { const f32x4* p = (const f32x4*)(st + (size_t)(rowb + m * 16) * 32 + fq * 8); a[m] = p[0]; b[m] = p[1]; }
; #pragma unroll
;     for (int m = 0; m < 4; ++m) { float s1 = (a[m][0] + a[m][2]) + (b[m][0] + b[m][2]), s2 = (a[m][1] + a[m][3]) + (b[m][1] + b[m][3]);
;         s1 = xsum32(xsum16(s1)); s2 = xsum32(xsum16(s2));
;         const float mm = s1 * (1.0f / 1024.0f); mu[m] = mm; rs[m] = rsqrtf(fmaxf(s2 * (1.0f / 1024.0f) - mm * mm, 0.f) + LN_EPS_); }
;     __device__ __forceinline__ void operator()(const f32x4 (&acc)[2][2][4][2], const pg8::Unit& u, int wr, int wc, int fr, int fq) const {
;     ...
;                     for (int n = 0; n < 2; ++n) { yv[bj][n] = *(const f32x4*)(Yin + (size_t)row * D_ + col0 + bj * 128 + 4 * n); gq[bj][n] = *(const f32x4*)(g + col0 + bj * 128 + 4 * n); bq_[bj][n] = *(const f32x4*)(b + col0 + bj * 128 + 4 * n); }
;                 asm volatile("" ::: "memory");
;                 float s1 = 0.f, s2 = 0.f;
; #pragma unroll
;                 for (int bj = 0; bj < 2; ++bj) { float* yp = Y + (size_t)row * D_ + col0 + bj * 128; f32x4 v[2];
; #pragma unroll
;                     for (int n = 0; n < 2; ++n) { v[n] = (((yv[bj][n] - mu) * rs) * gq[bj][n] + bq_[bj][n]) * ALPHA_ + acc[ai][bj][m][n] * sc;
	v_permlane32_swap_b32_e32 v70, v82
	v_permlane32_swap_b32_e32 v71, v83
	v_permlane32_swap_b32_e32 v72, v84
	v_permlane32_swap_b32_e32 v73, v85
	v_permlane16_swap_b32_e32 v70, v82
	v_permlane16_swap_b32_e32 v71, v83
	v_permlane16_swap_b32_e32 v72, v84
	v_permlane16_swap_b32_e32 v73, v85
	v_mov_b32_e32 v78, v70
	v_mov_b32_e32 v79, v82
	v_mov_b32_e32 v158, v72
	v_mov_b32_e32 v159, v84
	v_mov_b32_e32 v82, v71
	v_mov_b32_e32 v84, v73
	v_pk_add_f32 v[78:79], v[78:79], v[158:159]
	v_pk_add_f32 v[82:83], v[82:83], v[84:85]
	v_pk_add_f32 v[78:79], v[78:79], v[78:79] op_sel:[0,1] op_sel_hi:[1,0]
	v_pk_add_f32 v[82:83], v[82:83], v[82:83] op_sel:[0,1] op_sel_hi:[1,0]
	v_mov_b32_e32 v0, v78
	v_mov_b32_e32 v69, v82
	s_nop 0
	v_permlane16_swap_b32_e32 v78, v0
	v_permlane16_swap_b32_e32 v82, v69
	v_add_f32_e32 v79, v78, v0
	v_add_f32_e32 v78, v82, v69
	v_mov_b32_e32 v83, v79
	v_mov_b32_e32 v82, v78
	s_waitcnt vmcnt(10)
	v_permlane32_swap_b32_e32 v88, v92
	v_permlane32_swap_b32_e32 v89, v93
	v_permlane32_swap_b32_e32 v90, v94
	v_permlane32_swap_b32_e32 v91, v95
	v_permlane16_swap_b32_e32 v88, v92
	v_permlane16_swap_b32_e32 v89, v93
	v_permlane16_swap_b32_e32 v90, v94
	v_permlane16_swap_b32_e32 v91, v95
	v_mov_b32_e32 v70, v88
	v_mov_b32_e32 v71, v92
	v_mov_b32_e32 v72, v90
	v_mov_b32_e32 v73, v94
	v_mov_b32_e32 v92, v89
	v_mov_b32_e32 v94, v91
	v_permlane32_swap_b32_e32 v79, v83
	v_permlane32_swap_b32_e32 v78, v82
	s_waitcnt vmcnt(8)
	v_permlane32_swap_b32_e32 v98, v102
	v_permlane32_swap_b32_e32 v99, v103
	v_permlane32_swap_b32_e32 v100, v104
	v_permlane32_swap_b32_e32 v101, v105
	v_permlane16_swap_b32_e32 v98, v102
	v_permlane16_swap_b32_e32 v99, v103
	v_permlane16_swap_b32_e32 v100, v104
	v_permlane16_swap_b32_e32 v101, v105
	v_mov_b32_e32 v88, v98
	v_mov_b32_e32 v89, v102
	v_mov_b32_e32 v90, v100
	v_mov_b32_e32 v91, v104
	v_mov_b32_e32 v102, v99
	v_mov_b32_e32 v104, v101
	v_pk_add_f32 v[70:71], v[70:71], v[72:73]
	v_pk_add_f32 v[72:73], v[92:93], v[94:95]
	v_pk_add_f32 v[78:79], v[78:79], v[82:83]
	s_nop 1
	v_bfe_u32 v85, v227, 4, 2
	v_sub_u32_e32 v84, 0, v85
	v_lshlrev_b32_e32 v84, 4, v84
	v_ashrrev_i32_e32 v85, 31, v84
	v_lshl_add_u64 v[84:85], v[76:77], 0, v[84:85]
	global_load_dwordx4 v[92:95], v[84:85], off offset:576
	global_load_dwordx4 v[98:101], v[84:85], off offset:512
	v_pk_mul_f32 v[162:163], v[78:79], s[2:3] op_sel_hi:[1,0]
	s_waitcnt vmcnt(8)
	v_permlane32_swap_b32_e32 v106, v110
	v_permlane32_swap_b32_e32 v107, v111
	v_permlane32_swap_b32_e32 v108, v112
	v_permlane32_swap_b32_e32 v109, v113
	v_permlane16_swap_b32_e32 v106, v110
	v_permlane16_swap_b32_e32 v107, v111
	v_permlane16_swap_b32_e32 v108, v112
	v_permlane16_swap_b32_e32 v109, v113
	v_mov_b32_e32 v78, v106
	v_mov_b32_e32 v79, v110
	v_mov_b32_e32 v82, v108
	v_mov_b32_e32 v83, v112
	v_mov_b32_e32 v110, v107
	v_mov_b32_e32 v112, v109
	v_pk_add_f32 v[84:85], v[88:89], v[90:91]
	v_pk_add_f32 v[88:89], v[102:103], v[104:105]
	v_pk_add_f32 v[78:79], v[78:79], v[82:83]
	v_pk_add_f32 v[82:83], v[110:111], v[112:113]
	global_load_dwordx4 v[102:105], v[156:157], off offset:528
	global_load_dwordx4 v[106:109], v[156:157], off offset:512
	global_load_dwordx4 v[110:113], v[154:155], off offset:528
	global_load_dwordx4 v[158:161], v[154:155], off offset:512
	v_fma_f32 v0, -v163, v163, v162
	v_max_f32_e32 v0, 0, v0
	v_add_f32_e32 v0, 0x3727c5ac, v0
	v_mul_f32_e32 v69, 0x4b800000, v0
	v_cmp_gt_f32_e32 vcc, s1, v0
	v_pk_add_f32 v[88:89], v[88:89], v[88:89] op_sel:[0,1] op_sel_hi:[1,0]
	v_pk_add_f32 v[78:79], v[78:79], v[78:79] op_sel:[0,1] op_sel_hi:[1,0]
	v_cndmask_b32_e32 v0, v0, v69, vcc
	v_rsq_f32_e32 v0, v0
	v_pk_add_f32 v[82:83], v[82:83], v[82:83] op_sel:[0,1] op_sel_hi:[1,0]
	s_waitcnt vmcnt(10)
	v_permlane32_swap_b32_e32 v118, v114
	v_permlane32_swap_b32_e32 v119, v115
	v_permlane32_swap_b32_e32 v120, v116
	v_permlane32_swap_b32_e32 v121, v117
	v_permlane16_swap_b32_e32 v118, v114
	v_permlane16_swap_b32_e32 v119, v115
	v_permlane16_swap_b32_e32 v120, v116
	v_permlane16_swap_b32_e32 v121, v117
	v_sub_f32_e32 v119, v119, v163
	v_sub_f32_e32 v118, v118, v163
	v_mul_f32_e32 v69, 0x45800000, v0
	v_cndmask_b32_e32 v162, v0, v69, vcc
	v_mov_b32_e32 v0, v88
	s_nop 1
	v_permlane16_swap_b32_e32 v88, v0
	v_add_f32_e32 v88, v88, v0
	v_mov_b32_e32 v0, v78
	s_nop 1
	v_permlane16_swap_b32_e32 v78, v0
	v_add_f32_e32 v83, v78, v0
	v_mov_b32_e32 v0, v82
	s_nop 1
	v_permlane16_swap_b32_e32 v82, v0
	v_add_f32_e32 v82, v82, v0
	v_ashrrev_i32_e32 v78, 8, v68
	v_lshlrev_b32_e32 v0, 6, v68
	v_sub_f32_e32 v69, v121, v163
	v_sub_f32_e32 v68, v120, v163
	v_pk_mul_f32 v[118:119], v[162:163], v[118:119] op_sel_hi:[0,1]
	v_pk_mul_f32 v[68:69], v[162:163], v[68:69] op_sel_hi:[0,1]
	s_waitcnt vmcnt(6)
; __device__ __forceinline__ float xsum16(float v) { const auto r = __builtin_amdgcn_permlane16_swap(__float_as_uint(v), __float_as_uint(v), false, false); return __uint_as_float(r[0]) + __uint_as_float(r[1]); }
; __device__ __forceinline__ float xsum32(float v) { const auto r = __builtin_amdgcn_permlane32_swap(__float_as_uint(v), __float_as_uint(v), false, false); return __uint_as_float(r[0]) + __uint_as_float(r[1]); }
; __device__ __forceinline__ size_t blk_off(int r, int c, int K) { return (size_t)(r >> 8) * 256 * K + (size_t)(c >> 6) * (256 * 64) + (size_t)((r & 255) * 64 + (c & 63)); }
; __device__ __forceinline__ u32x4 pack8(const f32x4 a, const f32x4 b) { u32x4 w; w.x = cvt_pk_bf16(a[0], a[1]); w.y = cvt_pk_bf16(a[2], a[3]); w.z = cvt_pk_bf16(b[0], b[1]); w.w = cvt_pk_bf16(b[2], b[3]); return w; }
;     __device__ __forceinline__ void operator()(const f32x4 (&acc)[2][2][4][2], const pg8::Unit& u, int wr, int wc, int fr, int fq) const {
;     ...
;                 for (int bj = 0; bj < 2; ++bj) { float* yp = Y + (size_t)row * D_ + col0 + bj * 128; f32x4 v[2];
; #pragma unroll
;                     for (int n = 0; n < 2; ++n) { v[n] = (((yv[bj][n] - mu) * rs) * gq[bj][n] + bq_[bj][n]) * ALPHA_ + acc[ai][bj][m][n] * sc;
;                         *(f32x4*)(yp + 4 * n) = v[n]; s1 += (v[n][0] + v[n][1]) + (v[n][2] + v[n][3]); s2 += (v[n][0] * v[n][0] + v[n][1] * v[n][1]) + (v[n][2] * v[n][2] + v[n][3] * v[n][3]); }
;                     *(u32x4*)(Yb + blk_off(row, col0 + bj * 128, D_)) = pack8(v[0], v[1]); }
;                 s1 = xsum32(xsum16(s1)); s2 = xsum32(xsum16(s2));
;                 if (fq == 0) *(f32x2*)(stn + (size_t)row * 32 + (u.pn * 4 + wc) * 2) = (f32x2){s1, s2}; asm volatile("" ::: "memory"); } }
	v_pk_fma_f32 v[68:69], v[128:129], v[68:69], v[136:137]
	v_pk_fma_f32 v[118:119], v[126:127], v[118:119], v[134:135]
	v_pk_mul_f32 v[68:69], v[68:69], s[16:17] op_sel_hi:[1,0]
	v_pk_mul_f32 v[118:119], v[118:119], s[16:17] op_sel_hi:[1,0]
	v_pk_fma_f32 v[64:65], v[64:65], 0.5, v[68:69] op_sel_hi:[1,0,1]
	v_pk_fma_f32 v[62:63], v[62:63], 0.5, v[118:119] op_sel_hi:[1,0,1]
	v_add_f32_e32 v69, v64, v65
	v_add_f32_e32 v68, v62, v63
	v_add_f32_e32 v68, v68, v69
	v_add_f32_e32 v118, 0, v68
	v_mul_f32_e32 v68, v63, v63
	v_mul_f32_e32 v69, v65, v65
	v_fmac_f32_e32 v68, v62, v62
	v_fmac_f32_e32 v69, v64, v64
	v_add_f32_e32 v119, v68, v69
	v_sub_f32_e32 v69, v117, v163
	v_sub_f32_e32 v68, v116, v163
	v_sub_f32_e32 v115, v115, v163
	v_sub_f32_e32 v114, v114, v163
	v_pk_mul_f32 v[114:115], v[162:163], v[114:115] op_sel_hi:[0,1]
	v_pk_mul_f32 v[68:69], v[162:163], v[68:69] op_sel_hi:[0,1]
	v_pk_fma_f32 v[68:69], v[124:125], v[68:69], v[132:133]
	v_pk_fma_f32 v[114:115], v[122:123], v[114:115], v[130:131]
	v_pk_mul_f32 v[68:69], v[68:69], s[16:17] op_sel_hi:[1,0]
	v_pk_mul_f32 v[114:115], v[114:115], s[16:17] op_sel_hi:[1,0]
	v_pk_fma_f32 v[60:61], v[60:61], 0.5, v[68:69] op_sel_hi:[1,0,1]
	v_pk_fma_f32 v[58:59], v[58:59], 0.5, v[114:115] op_sel_hi:[1,0,1]
	v_ashrrev_i32_e32 v79, 31, v78
	v_add_f32_e32 v68, v58, v59
	v_add_f32_e32 v69, v60, v61
	v_readlane_b32 s2, v253, 59
	v_lshlrev_b64 v[78:79], 19, v[78:79]
	s_movk_i32 s1, 0x33c0
	v_add_f32_e32 v68, v68, v69
	v_mul_f32_e32 v69, v59, v59
	v_readlane_b32 s3, v253, 60
	v_and_or_b32 v0, v0, s1, v196
	s_nop 0
	s_nop 1
	v_bfe_u32 v91, v227, 4, 2
	v_sub_u32_e32 v90, 0, v91
	v_lshlrev_b32_e32 v90, 4, v90
	v_ashrrev_i32_e32 v91, 31, v90
	v_lshl_add_u64 v[90:91], v[76:77], 0, v[90:91]
	v_permlane16_swap_b32_e32 v62, v58
	v_permlane16_swap_b32_e32 v63, v59
	v_permlane16_swap_b32_e32 v64, v60
	v_permlane16_swap_b32_e32 v65, v61
	v_permlane32_swap_b32_e32 v62, v58
	v_permlane32_swap_b32_e32 v63, v59
	v_permlane32_swap_b32_e32 v64, v60
	v_permlane32_swap_b32_e32 v65, v61
	global_store_dwordx4 v[90:91], v[62:65], off
	global_store_dwordx4 v[90:91], v[58:61], off offset:64
	s_nop 1
	v_permlane32_swap_b32_e32 v62, v58
	v_permlane32_swap_b32_e32 v63, v59
	v_permlane32_swap_b32_e32 v64, v60
	v_permlane32_swap_b32_e32 v65, v61
	v_permlane16_swap_b32_e32 v62, v58
	v_permlane16_swap_b32_e32 v63, v59
	v_permlane16_swap_b32_e32 v64, v60
	v_permlane16_swap_b32_e32 v65, v61
	v_fmac_f32_e32 v69, v58, v58
	v_cvt_pk_bf16_f32 v62, v62, v63
	v_cvt_pk_bf16_f32 v63, v64, v65
	v_cvt_pk_bf16_f32 v64, v58, v59
	v_lshl_add_u64 v[58:59], s[2:3], 0, v[78:79]
	v_mul_f32_e32 v114, v61, v61
	v_lshl_add_u64 v[78:79], v[58:59], 0, s[24:25]
	v_lshlrev_b32_e32 v0, 1, v0
	v_fmac_f32_e32 v114, v60, v60
	v_cvt_pk_bf16_f32 v65, v60, v61
	v_lshl_add_u64 v[60:61], v[78:79], 0, v[0:1]
	global_store_dwordx4 v[60:61], v[62:65], off
	s_waitcnt vmcnt(7)
	v_permlane32_swap_b32_e32 v98, v92
	v_permlane32_swap_b32_e32 v99, v93
	v_permlane32_swap_b32_e32 v100, v94
	v_permlane32_swap_b32_e32 v101, v95
	v_permlane16_swap_b32_e32 v98, v92
	v_permlane16_swap_b32_e32 v99, v93
	v_permlane16_swap_b32_e32 v100, v94
	v_permlane16_swap_b32_e32 v101, v95
	v_sub_f32_e32 v61, v101, v163
	v_sub_f32_e32 v60, v100, v163
	v_sub_f32_e32 v63, v99, v163
	v_sub_f32_e32 v62, v98, v163
	v_pk_mul_f32 v[62:63], v[162:163], v[62:63] op_sel_hi:[0,1]
	v_pk_mul_f32 v[60:61], v[162:163], v[60:61] op_sel_hi:[0,1]
	s_waitcnt vmcnt(3)
	v_pk_fma_f32 v[60:61], v[108:109], v[60:61], v[160:161]
	v_pk_fma_f32 v[62:63], v[106:107], v[62:63], v[158:159]
	v_pk_mul_f32 v[60:61], v[60:61], s[16:17] op_sel_hi:[1,0]
	v_pk_mul_f32 v[62:63], v[62:63], s[16:17] op_sel_hi:[1,0]
	v_pk_fma_f32 v[56:57], v[56:57], 0.5, v[60:61] op_sel_hi:[1,0,1]
	v_pk_fma_f32 v[54:55], v[54:55], 0.5, v[62:63] op_sel_hi:[1,0,1]
	v_add_f32_e32 v61, v56, v57
	v_add_f32_e32 v60, v54, v55
	v_add_f32_e32 v68, v118, v68
	v_add_f32_e32 v60, v60, v61
	v_add_f32_e32 v64, v68, v60
	v_mul_f32_e32 v60, v55, v55
	v_mul_f32_e32 v61, v57, v57
	v_add_f32_e32 v69, v69, v114
	v_fmac_f32_e32 v60, v54, v54
	v_fmac_f32_e32 v61, v56, v56
	v_add_f32_e32 v69, v119, v69
	v_add_f32_e32 v60, v60, v61
	v_add_f32_e32 v65, v69, v60
	v_sub_f32_e32 v61, v95, v163
	v_sub_f32_e32 v60, v94, v163
	v_sub_f32_e32 v63, v93, v163
	v_sub_f32_e32 v62, v92, v163
	v_pk_mul_f32 v[62:63], v[162:163], v[62:63] op_sel_hi:[0,1]
	v_pk_mul_f32 v[60:61], v[162:163], v[60:61] op_sel_hi:[0,1]
	v_pk_fma_f32 v[60:61], v[104:105], v[60:61], v[112:113]
	v_pk_fma_f32 v[62:63], v[102:103], v[62:63], v[110:111]
	v_pk_mul_f32 v[60:61], v[60:61], s[16:17] op_sel_hi:[1,0]
	v_pk_mul_f32 v[62:63], v[62:63], s[16:17] op_sel_hi:[1,0]
	v_pk_fma_f32 v[52:53], v[52:53], 0.5, v[60:61] op_sel_hi:[1,0,1]
	v_pk_fma_f32 v[50:51], v[50:51], 0.5, v[62:63] op_sel_hi:[1,0,1]
	v_add_f32_e32 v61, v52, v53
	v_add_f32_e32 v60, v50, v51
	v_add_f32_e32 v60, v60, v61
	v_mul_f32_e32 v61, v51, v51
	v_mul_f32_e32 v62, v53, v53
	s_nop 0
	s_nop 1
	v_bfe_u32 v69, v227, 4, 2
	v_sub_u32_e32 v68, 0, v69
	v_lshlrev_b32_e32 v68, 4, v68
	v_ashrrev_i32_e32 v69, 31, v68
	v_lshl_add_u64 v[68:69], v[76:77], 0, v[68:69]
	v_permlane16_swap_b32_e32 v54, v50
	v_permlane16_swap_b32_e32 v55, v51
	v_permlane16_swap_b32_e32 v56, v52
	v_permlane16_swap_b32_e32 v57, v53
	v_permlane32_swap_b32_e32 v54, v50
	v_permlane32_swap_b32_e32 v55, v51
	v_permlane32_swap_b32_e32 v56, v52
	v_permlane32_swap_b32_e32 v57, v53
	global_store_dwordx4 v[68:69], v[54:57], off offset:512
	global_store_dwordx4 v[68:69], v[50:53], off offset:576
	s_nop 1
	v_permlane32_swap_b32_e32 v54, v50
	v_permlane32_swap_b32_e32 v55, v51
	v_permlane32_swap_b32_e32 v56, v52
; __device__ __forceinline__ float xsum16(float v) { const auto r = __builtin_amdgcn_permlane16_swap(__float_as_uint(v), __float_as_uint(v), false, false); return __uint_as_float(r[0]) + __uint_as_float(r[1]); }
; __device__ __forceinline__ float xsum32(float v) { const auto r = __builtin_amdgcn_permlane32_swap(__float_as_uint(v), __float_as_uint(v), false, false); return __uint_as_float(r[0]) + __uint_as_float(r[1]); }
; __device__ __forceinline__ size_t blk_off(int r, int c, int K) { return (size_t)(r >> 8) * 256 * K + (size_t)(c >> 6) * (256 * 64) + (size_t)((r & 255) * 64 + (c & 63)); }
; __device__ __forceinline__ u32x4 pack8(const f32x4 a, const f32x4 b) { u32x4 w; w.x = cvt_pk_bf16(a[0], a[1]); w.y = cvt_pk_bf16(a[2], a[3]); w.z = cvt_pk_bf16(b[0], b[1]); w.w = cvt_pk_bf16(b[2], b[3]); return w; }
;     __device__ __forceinline__ void operator()(const f32x4 (&acc)[2][2][4][2], const pg8::Unit& u, int wr, int wc, int fr, int fq) const {
;     ...
;             for (int m = 0; m < 4; ++m) { const int row = row0 + ai * 128 + m * 16; const float mu = mu4[m], rs = rs4[m];
;                 f32x4 yv[2][2], gq[2][2], bq_[2][2];
; #pragma unroll
;                 for (int bj = 0; bj < 2; ++bj)
; #pragma unroll
;                     for (int n = 0; n < 2; ++n) { yv[bj][n] = *(const f32x4*)(Yin + (size_t)row * D_ + col0 + bj * 128 + 4 * n); gq[bj][n] = *(const f32x4*)(g + col0 + bj * 128 + 4 * n); bq_[bj][n] = *(const f32x4*)(b + col0 + bj * 128 + 4 * n); }
;     ...
;                         *(f32x4*)(yp + 4 * n) = v[n]; s1 += (v[n][0] + v[n][1]) + (v[n][2] + v[n][3]); s2 += (v[n][0] * v[n][0] + v[n][1] * v[n][1]) + (v[n][2] * v[n][2] + v[n][3] * v[n][3]); }
;                     *(u32x4*)(Yb + blk_off(row, col0 + bj * 128, D_)) = pack8(v[0], v[1]); }
;                 s1 = xsum32(xsum16(s1)); s2 = xsum32(xsum16(s2));
;                 if (fq == 0) *(f32x2*)(stn + (size_t)row * 32 + (u.pn * 4 + wc) * 2) = (f32x2){s1, s2}; asm volatile("" ::: "memory"); } }
	v_permlane32_swap_b32_e32 v57, v53
	v_permlane16_swap_b32_e32 v54, v50
	v_permlane16_swap_b32_e32 v55, v51
	v_permlane16_swap_b32_e32 v56, v52
	v_permlane16_swap_b32_e32 v57, v53
	v_add_f32_e32 v60, v64, v60
	v_fmac_f32_e32 v61, v50, v50
	v_fmac_f32_e32 v62, v52, v52
	v_lshl_add_u64 v[76:77], v[58:59], 0, s[44:45]
	v_add_f32_e32 v61, v61, v62
	v_cvt_pk_bf16_f32 v54, v54, v55
	v_cvt_pk_bf16_f32 v55, v56, v57
	v_cvt_pk_bf16_f32 v56, v50, v51
	v_lshl_add_u64 v[50:51], v[76:77], 0, v[0:1]
	v_mov_b32_e32 v0, v60
	v_pk_add_f32 v[70:71], v[70:71], v[70:71] op_sel:[0,1] op_sel_hi:[1,0]
	v_pk_add_f32 v[72:73], v[72:73], v[72:73] op_sel:[0,1] op_sel_hi:[1,0]
	v_pk_add_f32 v[84:85], v[84:85], v[84:85] op_sel:[0,1] op_sel_hi:[1,0]
	v_add_f32_e32 v61, v65, v61
	v_cvt_pk_bf16_f32 v57, v52, v53
	v_permlane16_swap_b32_e32 v60, v0
	v_mov_b32_e32 v71, v70
	v_mov_b32_e32 v73, v72
	v_mov_b32_e32 v85, v84
	global_store_dwordx4 v[50:51], v[54:57], off
	v_add_f32_e32 v50, v60, v0
	v_mov_b32_e32 v0, v61
	v_permlane16_swap_b32_e32 v70, v71
	v_permlane16_swap_b32_e32 v72, v73
	v_permlane16_swap_b32_e32 v84, v85
	v_permlane16_swap_b32_e32 v61, v0
	v_add_f32_e32 v71, v70, v71
	v_add_f32_e32 v70, v72, v73
	v_add_f32_e32 v89, v84, v85
	v_add_f32_e32 v51, v61, v0
	v_mov_b32_e32 v73, v71
	v_mov_b32_e32 v72, v70
	v_mov_b32_e32 v91, v89
	v_mov_b32_e32 v90, v88
	v_mov_b32_e32 v85, v83
	v_mov_b32_e32 v84, v82
	v_mov_b32_e32 v52, v50
	v_mov_b32_e32 v53, v51
	v_permlane32_swap_b32_e32 v71, v73
	v_permlane32_swap_b32_e32 v70, v72
	v_permlane32_swap_b32_e32 v89, v91
	v_permlane32_swap_b32_e32 v88, v90
	v_permlane32_swap_b32_e32 v83, v85
	v_permlane32_swap_b32_e32 v82, v84
	v_permlane32_swap_b32_e32 v50, v52
	v_permlane32_swap_b32_e32 v51, v53
	s_and_saveexec_b64 s[24:25], s[40:41]
	s_cbranch_execz .LBB0_1713
	v_pk_add_f32 v[50:51], v[50:51], v[52:53]
	v_lshl_add_u64 v[52:53], s[8:9], 0, v[66:67]
	v_lshl_add_u64 v[52:53], s[38:39], 2, v[52:53]
	global_store_dwordx2 v[52:53], v[50:51], off
.LBB0_1713:
	s_or_b64 exec, exec, s[24:25]
	v_pk_add_f32 v[50:51], v[70:71], v[72:73]
	s_mov_b32 s2, 0x3a800000
	v_pk_mul_f32 v[92:93], v[50:51], s[2:3] op_sel_hi:[1,0]
	s_mov_b32 s1, 0x800000
	v_fma_f32 v0, -v93, v93, v92
	v_max_f32_e32 v0, 0, v0
	v_add_f32_e32 v0, 0x3727c5ac, v0
	v_cmp_gt_f32_e32 vcc, s1, v0
	v_mul_f32_e32 v50, 0x4b800000, v0
	s_load_dwordx16 s[60:75], s[34:35], 0x38
	v_cndmask_b32_e32 v0, v0, v50, vcc
	v_rsq_f32_e32 v0, v0
	s_mov_b32 s2, 0x3fd744fd
	s_movk_i32 s1, 0x37c0
	v_mul_f32_e32 v50, 0x45800000, v0
	v_cndmask_b32_e32 v92, v0, v50, vcc
	v_lshlrev_b64 v[50:51], 12, v[96:97]
	s_waitcnt lgkmcnt(0)
	v_lshl_add_u64 v[50:51], s[74:75], 0, v[50:51]
	v_lshl_add_u64 v[94:95], v[152:153], 2, v[50:51]
	s_nop 1
	v_bfe_u32 v53, v227, 4, 2
	v_sub_u32_e32 v52, 0, v53
	v_lshlrev_b32_e32 v52, 4, v52
	v_ashrrev_i32_e32 v53, 31, v52
	v_lshl_add_u64 v[52:53], v[94:95], 0, v[52:53]
	global_load_dwordx4 v[98:101], v[52:53], off offset:64
	global_load_dwordx4 v[102:105], v[52:53], off
	global_load_dwordx4 v[106:109], v[156:157], off offset:16
	global_load_dwordx4 v[110:113], v[156:157], off
	global_load_dwordx4 v[114:117], v[154:155], off offset:16
	global_load_dwordx4 v[118:121], v[154:155], off
	s_nop 1
	v_bfe_u32 v55, v227, 4, 2
	v_sub_u32_e32 v54, 0, v55
	v_lshlrev_b32_e32 v54, 4, v54
	v_ashrrev_i32_e32 v55, 31, v54
	v_lshl_add_u64 v[54:55], v[94:95], 0, v[54:55]
	global_load_dwordx4 v[50:53], v[54:55], off offset:576
	global_load_dwordx4 v[70:73], v[54:55], off offset:512
	global_load_dwordx4 v[54:57], v[156:157], off offset:528
	global_load_dwordx4 v[62:65], v[156:157], off offset:512
	global_load_dwordx4 v[58:61], v[154:155], off offset:528
	global_load_dwordx4 v[66:69], v[154:155], off offset:512
	v_lshlrev_b32_e32 v0, 6, v96
	v_and_or_b32 v0, v0, s1, v196
	v_lshlrev_b32_e32 v0, 1, v0
	s_waitcnt vmcnt(10)
	v_permlane32_swap_b32_e32 v102, v98
	v_permlane32_swap_b32_e32 v103, v99
	v_permlane32_swap_b32_e32 v104, v100
	v_permlane32_swap_b32_e32 v105, v101
	v_permlane16_swap_b32_e32 v102, v98
	v_permlane16_swap_b32_e32 v103, v99
	v_permlane16_swap_b32_e32 v104, v100
	v_permlane16_swap_b32_e32 v105, v101
	v_sub_f32_e32 v97, v105, v93
	v_sub_f32_e32 v96, v104, v93
	v_sub_f32_e32 v103, v103, v93
	v_sub_f32_e32 v102, v102, v93
	v_pk_mul_f32 v[102:103], v[92:93], v[102:103] op_sel_hi:[0,1]
	v_pk_mul_f32 v[96:97], v[92:93], v[96:97] op_sel_hi:[0,1]
	s_waitcnt vmcnt(6)
; __device__ __forceinline__ float xsum16(float v) { const auto r = __builtin_amdgcn_permlane16_swap(__float_as_uint(v), __float_as_uint(v), false, false); return __uint_as_float(r[0]) + __uint_as_float(r[1]); }
; __device__ __forceinline__ float xsum32(float v) { const auto r = __builtin_amdgcn_permlane32_swap(__float_as_uint(v), __float_as_uint(v), false, false); return __uint_as_float(r[0]) + __uint_as_float(r[1]); }
; __device__ __forceinline__ size_t blk_off(int r, int c, int K) { return (size_t)(r >> 8) * 256 * K + (size_t)(c >> 6) * (256 * 64) + (size_t)((r & 255) * 64 + (c & 63)); }
; __device__ __forceinline__ u32x4 pack8(const f32x4 a, const f32x4 b) { u32x4 w; w.x = cvt_pk_bf16(a[0], a[1]); w.y = cvt_pk_bf16(a[2], a[3]); w.z = cvt_pk_bf16(b[0], b[1]); w.w = cvt_pk_bf16(b[2], b[3]); return w; }
;     __device__ __forceinline__ void operator()(const f32x4 (&acc)[2][2][4][2], const pg8::Unit& u, int wr, int wc, int fr, int fq) const {
;     ...
;                 for (int bj = 0; bj < 2; ++bj) { float* yp = Y + (size_t)row * D_ + col0 + bj * 128; f32x4 v[2];
; #pragma unroll
;                     for (int n = 0; n < 2; ++n) { v[n] = (((yv[bj][n] - mu) * rs) * gq[bj][n] + bq_[bj][n]) * ALPHA_ + acc[ai][bj][m][n] * sc;
;                         *(f32x4*)(yp + 4 * n) = v[n]; s1 += (v[n][0] + v[n][1]) + (v[n][2] + v[n][3]); s2 += (v[n][0] * v[n][0] + v[n][1] * v[n][1]) + (v[n][2] * v[n][2] + v[n][3] * v[n][3]); }
;                     *(u32x4*)(Yb + blk_off(row, col0 + bj * 128, D_)) = pack8(v[0], v[1]); }
;                 s1 = xsum32(xsum16(s1)); s2 = xsum32(xsum16(s2));
;                 if (fq == 0) *(f32x2*)(stn + (size_t)row * 32 + (u.pn * 4 + wc) * 2) = (f32x2){s1, s2}; asm volatile("" ::: "memory"); } }
	v_pk_fma_f32 v[96:97], v[112:113], v[96:97], v[120:121]
	v_pk_fma_f32 v[102:103], v[110:111], v[102:103], v[118:119]
	v_pk_mul_f32 v[96:97], v[96:97], s[2:3] op_sel_hi:[1,0]
	v_pk_mul_f32 v[102:103], v[102:103], s[2:3] op_sel_hi:[1,0]
	v_pk_fma_f32 v[104:105], v[48:49], 0.5, v[96:97] op_sel_hi:[1,0,1]
	v_pk_fma_f32 v[102:103], v[46:47], 0.5, v[102:103] op_sel_hi:[1,0,1]
	v_add_f32_e32 v47, v104, v105
	v_add_f32_e32 v46, v102, v103
	v_add_f32_e32 v46, v46, v47
	v_add_f32_e32 v110, 0, v46
	v_mul_f32_e32 v46, v103, v103
	v_mul_f32_e32 v47, v105, v105
	v_fmac_f32_e32 v46, v102, v102
	v_fmac_f32_e32 v47, v104, v104
	v_add_f32_e32 v111, v46, v47
	v_sub_f32_e32 v47, v101, v93
	v_sub_f32_e32 v46, v100, v93
	v_sub_f32_e32 v49, v99, v93
	v_sub_f32_e32 v48, v98, v93
	v_pk_mul_f32 v[48:49], v[92:93], v[48:49] op_sel_hi:[0,1]
	v_pk_mul_f32 v[46:47], v[92:93], v[46:47] op_sel_hi:[0,1]
	v_pk_fma_f32 v[46:47], v[108:109], v[46:47], v[116:117]
	v_pk_fma_f32 v[48:49], v[106:107], v[48:49], v[114:115]
	v_pk_mul_f32 v[46:47], v[46:47], s[2:3] op_sel_hi:[1,0]
	v_pk_mul_f32 v[48:49], v[48:49], s[2:3] op_sel_hi:[1,0]
	v_pk_fma_f32 v[98:99], v[44:45], 0.5, v[46:47] op_sel_hi:[1,0,1]
	v_pk_fma_f32 v[96:97], v[42:43], 0.5, v[48:49] op_sel_hi:[1,0,1]
	v_add_f32_e32 v43, v98, v99
	v_add_f32_e32 v42, v96, v97
	v_add_f32_e32 v42, v42, v43
	v_add_f32_e32 v47, v110, v42
	v_mul_f32_e32 v42, v97, v97
	v_mul_f32_e32 v43, v99, v99
	v_fmac_f32_e32 v42, v96, v96
	v_fmac_f32_e32 v43, v98, v98
	v_add_f32_e32 v42, v42, v43
	v_add_f32_e32 v46, v111, v42
	v_cvt_pk_bf16_f32 v42, v102, v103
	v_cvt_pk_bf16_f32 v43, v104, v105
	v_cvt_pk_bf16_f32 v44, v96, v97
	v_cvt_pk_bf16_f32 v45, v98, v99
	v_lshl_add_u64 v[48:49], v[78:79], 0, v[0:1]
	s_nop 0
	s_nop 1
	v_bfe_u32 v101, v227, 4, 2
	v_sub_u32_e32 v100, 0, v101
	v_lshlrev_b32_e32 v100, 4, v100
	v_ashrrev_i32_e32 v101, 31, v100
	v_lshl_add_u64 v[100:101], v[94:95], 0, v[100:101]
	v_permlane16_swap_b32_e32 v102, v96
	v_permlane16_swap_b32_e32 v103, v97
	v_permlane16_swap_b32_e32 v104, v98
	v_permlane16_swap_b32_e32 v105, v99
	v_permlane32_swap_b32_e32 v102, v96
	v_permlane32_swap_b32_e32 v103, v97
	v_permlane32_swap_b32_e32 v104, v98
	v_permlane32_swap_b32_e32 v105, v99
	global_store_dwordx4 v[100:101], v[102:105], off
	global_store_dwordx4 v[100:101], v[96:99], off offset:64
	s_nop 1
	v_permlane32_swap_b32_e32 v102, v96
	v_permlane32_swap_b32_e32 v103, v97
	v_permlane32_swap_b32_e32 v104, v98
	v_permlane32_swap_b32_e32 v105, v99
	v_permlane16_swap_b32_e32 v102, v96
	v_permlane16_swap_b32_e32 v103, v97
	v_permlane16_swap_b32_e32 v104, v98
	v_permlane16_swap_b32_e32 v105, v99
	global_store_dwordx4 v[48:49], v[42:45], off
	s_nop 0
	s_waitcnt vmcnt(7)
	v_permlane32_swap_b32_e32 v70, v50
	v_permlane32_swap_b32_e32 v71, v51
	v_permlane32_swap_b32_e32 v72, v52
	v_permlane32_swap_b32_e32 v73, v53
	v_permlane16_swap_b32_e32 v70, v50
	v_permlane16_swap_b32_e32 v71, v51
	v_permlane16_swap_b32_e32 v72, v52
	v_permlane16_swap_b32_e32 v73, v53
	v_sub_f32_e32 v43, v73, v93
	v_sub_f32_e32 v42, v72, v93
	v_sub_f32_e32 v45, v71, v93
	v_sub_f32_e32 v44, v70, v93
	v_pk_mul_f32 v[44:45], v[92:93], v[44:45] op_sel_hi:[0,1]
	v_pk_mul_f32 v[42:43], v[92:93], v[42:43] op_sel_hi:[0,1]
	s_waitcnt vmcnt(3)
	v_pk_fma_f32 v[42:43], v[64:65], v[42:43], v[68:69]
	v_pk_fma_f32 v[44:45], v[62:63], v[44:45], v[66:67]
	v_pk_mul_f32 v[42:43], v[42:43], s[2:3] op_sel_hi:[1,0]
	v_pk_mul_f32 v[44:45], v[44:45], s[2:3] op_sel_hi:[1,0]
	v_pk_fma_f32 v[40:41], v[40:41], 0.5, v[42:43] op_sel_hi:[1,0,1]
	v_pk_fma_f32 v[38:39], v[38:39], 0.5, v[44:45] op_sel_hi:[1,0,1]
	v_add_f32_e32 v43, v40, v41
	v_add_f32_e32 v42, v38, v39
	v_add_f32_e32 v42, v42, v43
	v_add_f32_e32 v47, v47, v42
	v_mul_f32_e32 v42, v39, v39
	v_mul_f32_e32 v43, v41, v41
	v_fmac_f32_e32 v42, v38, v38
	v_fmac_f32_e32 v43, v40, v40
	v_add_f32_e32 v42, v42, v43
	v_add_f32_e32 v46, v46, v42
	v_sub_f32_e32 v43, v53, v93
	v_sub_f32_e32 v42, v52, v93
	v_sub_f32_e32 v45, v51, v93
	v_sub_f32_e32 v44, v50, v93
	v_pk_mul_f32 v[44:45], v[92:93], v[44:45] op_sel_hi:[0,1]
	v_pk_mul_f32 v[42:43], v[92:93], v[42:43] op_sel_hi:[0,1]
	v_pk_fma_f32 v[42:43], v[56:57], v[42:43], v[60:61]
	v_pk_fma_f32 v[44:45], v[54:55], v[44:45], v[58:59]
	v_pk_mul_f32 v[42:43], v[42:43], s[2:3] op_sel_hi:[1,0]
	v_pk_mul_f32 v[44:45], v[44:45], s[2:3] op_sel_hi:[1,0]
	v_pk_fma_f32 v[36:37], v[36:37], 0.5, v[42:43] op_sel_hi:[1,0,1]
	v_pk_fma_f32 v[34:35], v[34:35], 0.5, v[44:45] op_sel_hi:[1,0,1]
	v_add_f32_e32 v43, v36, v37
	v_add_f32_e32 v42, v34, v35
	v_add_f32_e32 v42, v42, v43
	v_mul_f32_e32 v43, v35, v35
	v_mul_f32_e32 v44, v37, v37
	v_add_f32_e32 v42, v47, v42
	v_fmac_f32_e32 v43, v34, v34
	v_fmac_f32_e32 v44, v36, v36
	s_nop 0
	s_nop 1
	v_bfe_u32 v49, v227, 4, 2
	v_sub_u32_e32 v48, 0, v49
	v_lshlrev_b32_e32 v48, 4, v48
	v_ashrrev_i32_e32 v49, 31, v48
	v_lshl_add_u64 v[48:49], v[94:95], 0, v[48:49]
	v_permlane16_swap_b32_e32 v38, v34
	v_permlane16_swap_b32_e32 v39, v35
	v_permlane16_swap_b32_e32 v40, v36
	v_permlane16_swap_b32_e32 v41, v37
	v_permlane32_swap_b32_e32 v38, v34
	v_permlane32_swap_b32_e32 v39, v35
	v_permlane32_swap_b32_e32 v40, v36
	v_permlane32_swap_b32_e32 v41, v37
	global_store_dwordx4 v[48:49], v[38:41], off offset:512
	global_store_dwordx4 v[48:49], v[34:37], off offset:576
	s_nop 1
	v_permlane32_swap_b32_e32 v38, v34
	v_permlane32_swap_b32_e32 v39, v35
	v_permlane32_swap_b32_e32 v40, v36
	v_permlane32_swap_b32_e32 v41, v37
	v_permlane16_swap_b32_e32 v38, v34
	v_permlane16_swap_b32_e32 v39, v35
	v_permlane16_swap_b32_e32 v40, v36
	v_permlane16_swap_b32_e32 v41, v37
	v_add_f32_e32 v43, v43, v44
	v_cvt_pk_bf16_f32 v38, v38, v39
	v_cvt_pk_bf16_f32 v39, v40, v41
	v_cvt_pk_bf16_f32 v40, v34, v35
	v_lshl_add_u64 v[34:35], v[76:77], 0, v[0:1]
	v_mov_b32_e32 v0, v42
	v_add_f32_e32 v43, v46, v43
	v_cvt_pk_bf16_f32 v41, v36, v37
	v_permlane16_swap_b32_e32 v42, v0
	global_store_dwordx4 v[34:35], v[38:41], off
	v_add_f32_e32 v34, v42, v0
	v_mov_b32_e32 v0, v43
	s_nop 1
	v_permlane16_swap_b32_e32 v43, v0
	v_add_f32_e32 v35, v43, v0
	v_mov_b32_e32 v36, v34
	v_mov_b32_e32 v37, v35
	s_nop 0
	v_permlane32_swap_b32_e32 v34, v36
	v_permlane32_swap_b32_e32 v35, v37
	s_and_saveexec_b64 s[24:25], s[40:41]
	s_cbranch_execz .LBB0_1715
	v_pk_add_f32 v[34:35], v[34:35], v[36:37]
	v_lshl_add_u64 v[36:37], s[8:9], 0, v[86:87]
	v_lshl_add_u64 v[36:37], s[38:39], 2, v[36:37]
	global_store_dwordx2 v[36:37], v[34:35], off
; __device__ __forceinline__ size_t blk_off(int r, int c, int K) { return (size_t)(r >> 8) * 256 * K + (size_t)(c >> 6) * (256 * 64) + (size_t)((r & 255) * 64 + (c & 63)); }
; __device__ __forceinline__ u32x4 pack8(const f32x4 a, const f32x4 b) { u32x4 w; w.x = cvt_pk_bf16(a[0], a[1]); w.y = cvt_pk_bf16(a[2], a[3]); w.z = cvt_pk_bf16(b[0], b[1]); w.w = cvt_pk_bf16(b[2], b[3]); return w; }
; __device__ __forceinline__ void row_stats4(const float* st, int rowb, int fq, float (&mu)[4], float (&rs)[4]) {
;     ...
;         const float mm = s1 * (1.0f / 1024.0f); mu[m] = mm; rs[m] = rsqrtf(fmaxf(s2 * (1.0f / 1024.0f) - mm * mm, 0.f) + LN_EPS_); }
;     __device__ __forceinline__ void operator()(const f32x4 (&acc)[2][2][4][2], const pg8::Unit& u, int wr, int wc, int fr, int fq) const {
;     ...
;             for (int m = 0; m < 4; ++m) { const int row = row0 + ai * 128 + m * 16; const float mu = mu4[m], rs = rs4[m];
;                 f32x4 yv[2][2], gq[2][2], bq_[2][2];
; #pragma unroll
;                 for (int bj = 0; bj < 2; ++bj)
; #pragma unroll
;                     for (int n = 0; n < 2; ++n) { yv[bj][n] = *(const f32x4*)(Yin + (size_t)row * D_ + col0 + bj * 128 + 4 * n); gq[bj][n] = *(const f32x4*)(g + col0 + bj * 128 + 4 * n); bq_[bj][n] = *(const f32x4*)(b + col0 + bj * 128 + 4 * n); }
;                 asm volatile("" ::: "memory");
;                 float s1 = 0.f, s2 = 0.f;
; #pragma unroll
;                 for (int bj = 0; bj < 2; ++bj) { float* yp = Y + (size_t)row * D_ + col0 + bj * 128; f32x4 v[2];
; #pragma unroll
;                     for (int n = 0; n < 2; ++n) { v[n] = (((yv[bj][n] - mu) * rs) * gq[bj][n] + bq_[bj][n]) * ALPHA_ + acc[ai][bj][m][n] * sc;
;                         *(f32x4*)(yp + 4 * n) = v[n]; s1 += (v[n][0] + v[n][1]) + (v[n][2] + v[n][3]); s2 += (v[n][0] * v[n][0] + v[n][1] * v[n][1]) + (v[n][2] * v[n][2] + v[n][3] * v[n][3]); }
;                     *(u32x4*)(Yb + blk_off(row, col0 + bj * 128, D_)) = pack8(v[0], v[1]); }
.LBB0_1715:
	s_or_b64 exec, exec, s[24:25]
	v_pk_add_f32 v[34:35], v[88:89], v[90:91]
	s_mov_b32 s2, 0x3a800000
	v_pk_mul_f32 v[58:59], v[34:35], s[2:3] op_sel_hi:[1,0]
	s_mov_b32 s1, 0x800000
	v_fma_f32 v0, -v59, v59, v58
	v_max_f32_e32 v0, 0, v0
	v_add_f32_e32 v0, 0x3727c5ac, v0
	v_cmp_gt_f32_e32 vcc, s1, v0
	v_mul_f32_e32 v34, 0x4b800000, v0
	s_load_dwordx16 s[60:75], s[34:35], 0x38
	v_cndmask_b32_e32 v0, v0, v34, vcc
	v_rsq_f32_e32 v0, v0
	s_mov_b32 s2, 0x3fd744fd
	s_movk_i32 s1, 0x3bc0
	v_mul_f32_e32 v34, 0x45800000, v0
	v_cndmask_b32_e32 v58, v0, v34, vcc
	v_lshlrev_b64 v[34:35], 12, v[80:81]
	s_waitcnt lgkmcnt(0)
	v_lshl_add_u64 v[34:35], s[74:75], 0, v[34:35]
	v_lshl_add_u64 v[60:61], v[152:153], 2, v[34:35]
	s_nop 1
	v_bfe_u32 v37, v227, 4, 2
	v_sub_u32_e32 v36, 0, v37
	v_lshlrev_b32_e32 v36, 4, v36
	v_ashrrev_i32_e32 v37, 31, v36
	v_lshl_add_u64 v[36:37], v[60:61], 0, v[36:37]
	global_load_dwordx4 v[62:65], v[36:37], off offset:64
	global_load_dwordx4 v[66:69], v[36:37], off
	global_load_dwordx4 v[70:73], v[156:157], off offset:16
	global_load_dwordx4 v[86:89], v[156:157], off
	global_load_dwordx4 v[90:93], v[154:155], off offset:16
	global_load_dwordx4 v[94:97], v[154:155], off
	s_nop 1
	v_bfe_u32 v39, v227, 4, 2
	v_sub_u32_e32 v38, 0, v39
	v_lshlrev_b32_e32 v38, 4, v38
	v_ashrrev_i32_e32 v39, 31, v38
	v_lshl_add_u64 v[38:39], v[60:61], 0, v[38:39]
	global_load_dwordx4 v[34:37], v[38:39], off offset:576
	global_load_dwordx4 v[54:57], v[38:39], off offset:512
	global_load_dwordx4 v[38:41], v[156:157], off offset:528
	global_load_dwordx4 v[46:49], v[156:157], off offset:512
	global_load_dwordx4 v[42:45], v[154:155], off offset:528
	global_load_dwordx4 v[50:53], v[154:155], off offset:512
	v_lshlrev_b32_e32 v0, 6, v80
	v_and_or_b32 v0, v0, s1, v196
	v_lshlrev_b32_e32 v0, 1, v0
	s_waitcnt vmcnt(10)
	v_permlane32_swap_b32_e32 v66, v62
	v_permlane32_swap_b32_e32 v67, v63
	v_permlane32_swap_b32_e32 v68, v64
	v_permlane32_swap_b32_e32 v69, v65
	v_permlane16_swap_b32_e32 v66, v62
	v_permlane16_swap_b32_e32 v67, v63
	v_permlane16_swap_b32_e32 v68, v64
	v_permlane16_swap_b32_e32 v69, v65
	v_sub_f32_e32 v69, v69, v59
	v_sub_f32_e32 v68, v68, v59
	v_sub_f32_e32 v67, v67, v59
	v_sub_f32_e32 v66, v66, v59
	v_pk_mul_f32 v[66:67], v[58:59], v[66:67] op_sel_hi:[0,1]
	v_pk_mul_f32 v[68:69], v[58:59], v[68:69] op_sel_hi:[0,1]
	s_waitcnt vmcnt(6)
	v_pk_fma_f32 v[68:69], v[88:89], v[68:69], v[96:97]
	v_pk_fma_f32 v[66:67], v[86:87], v[66:67], v[94:95]
	v_pk_mul_f32 v[68:69], v[68:69], s[2:3] op_sel_hi:[1,0]
	v_pk_mul_f32 v[66:67], v[66:67], s[2:3] op_sel_hi:[1,0]
	v_pk_fma_f32 v[68:69], v[32:33], 0.5, v[68:69] op_sel_hi:[1,0,1]
	v_pk_fma_f32 v[66:67], v[30:31], 0.5, v[66:67] op_sel_hi:[1,0,1]
	v_add_f32_e32 v31, v68, v69
	v_add_f32_e32 v30, v66, v67
	v_add_f32_e32 v30, v30, v31
	v_add_f32_e32 v86, 0, v30
	v_mul_f32_e32 v30, v67, v67
	v_mul_f32_e32 v31, v69, v69
	v_fmac_f32_e32 v30, v66, v66
	v_fmac_f32_e32 v31, v68, v68
	v_add_f32_e32 v87, v30, v31
	v_sub_f32_e32 v31, v65, v59
	v_sub_f32_e32 v30, v64, v59
	v_sub_f32_e32 v33, v63, v59
	v_sub_f32_e32 v32, v62, v59
	v_pk_mul_f32 v[32:33], v[58:59], v[32:33] op_sel_hi:[0,1]
	v_pk_mul_f32 v[30:31], v[58:59], v[30:31] op_sel_hi:[0,1]
	v_pk_fma_f32 v[30:31], v[72:73], v[30:31], v[92:93]
	v_pk_fma_f32 v[32:33], v[70:71], v[32:33], v[90:91]
	v_pk_mul_f32 v[30:31], v[30:31], s[2:3] op_sel_hi:[1,0]
	v_pk_mul_f32 v[32:33], v[32:33], s[2:3] op_sel_hi:[1,0]
	v_pk_fma_f32 v[64:65], v[28:29], 0.5, v[30:31] op_sel_hi:[1,0,1]
	v_pk_fma_f32 v[62:63], v[26:27], 0.5, v[32:33] op_sel_hi:[1,0,1]
	v_add_f32_e32 v27, v64, v65
	v_add_f32_e32 v26, v62, v63
	v_add_f32_e32 v26, v26, v27
	v_add_f32_e32 v31, v86, v26
	v_mul_f32_e32 v26, v63, v63
	v_mul_f32_e32 v27, v65, v65
	v_fmac_f32_e32 v26, v62, v62
	v_fmac_f32_e32 v27, v64, v64
	v_add_f32_e32 v26, v26, v27
	v_add_f32_e32 v30, v87, v26
	v_cvt_pk_bf16_f32 v26, v66, v67
	v_cvt_pk_bf16_f32 v27, v68, v69
	v_cvt_pk_bf16_f32 v28, v62, v63
	v_cvt_pk_bf16_f32 v29, v64, v65
	v_lshl_add_u64 v[32:33], v[78:79], 0, v[0:1]
	s_nop 0
	s_nop 1
	v_bfe_u32 v71, v227, 4, 2
	v_sub_u32_e32 v70, 0, v71
	v_lshlrev_b32_e32 v70, 4, v70
	v_ashrrev_i32_e32 v71, 31, v70
	v_lshl_add_u64 v[70:71], v[60:61], 0, v[70:71]
	v_permlane16_swap_b32_e32 v66, v62
	v_permlane16_swap_b32_e32 v67, v63
	v_permlane16_swap_b32_e32 v68, v64
	v_permlane16_swap_b32_e32 v69, v65
	v_permlane32_swap_b32_e32 v66, v62
	v_permlane32_swap_b32_e32 v67, v63
	v_permlane32_swap_b32_e32 v68, v64
	v_permlane32_swap_b32_e32 v69, v65
	global_store_dwordx4 v[70:71], v[66:69], off
	global_store_dwordx4 v[70:71], v[62:65], off offset:64
	s_nop 1
	v_permlane32_swap_b32_e32 v66, v62
	v_permlane32_swap_b32_e32 v67, v63
	v_permlane32_swap_b32_e32 v68, v64
	v_permlane32_swap_b32_e32 v69, v65
	v_permlane16_swap_b32_e32 v66, v62
	v_permlane16_swap_b32_e32 v67, v63
	v_permlane16_swap_b32_e32 v68, v64
	v_permlane16_swap_b32_e32 v69, v65
	global_store_dwordx4 v[32:33], v[26:29], off
	s_nop 0
	s_waitcnt vmcnt(7)
	v_permlane32_swap_b32_e32 v54, v34
	v_permlane32_swap_b32_e32 v55, v35
	v_permlane32_swap_b32_e32 v56, v36
	v_permlane32_swap_b32_e32 v57, v37
	v_permlane16_swap_b32_e32 v54, v34
	v_permlane16_swap_b32_e32 v55, v35
	v_permlane16_swap_b32_e32 v56, v36
	v_permlane16_swap_b32_e32 v57, v37
	v_sub_f32_e32 v27, v57, v59
	v_sub_f32_e32 v26, v56, v59
	v_sub_f32_e32 v29, v55, v59
	v_sub_f32_e32 v28, v54, v59
	v_pk_mul_f32 v[28:29], v[58:59], v[28:29] op_sel_hi:[0,1]
	v_pk_mul_f32 v[26:27], v[58:59], v[26:27] op_sel_hi:[0,1]
	s_waitcnt vmcnt(3)
; __device__ __forceinline__ float xsum16(float v) { const auto r = __builtin_amdgcn_permlane16_swap(__float_as_uint(v), __float_as_uint(v), false, false); return __uint_as_float(r[0]) + __uint_as_float(r[1]); }
; __device__ __forceinline__ float xsum32(float v) { const auto r = __builtin_amdgcn_permlane32_swap(__float_as_uint(v), __float_as_uint(v), false, false); return __uint_as_float(r[0]) + __uint_as_float(r[1]); }
; __device__ __forceinline__ size_t blk_off(int r, int c, int K) { return (size_t)(r >> 8) * 256 * K + (size_t)(c >> 6) * (256 * 64) + (size_t)((r & 255) * 64 + (c & 63)); }
; __device__ __forceinline__ u32x4 pack8(const f32x4 a, const f32x4 b) { u32x4 w; w.x = cvt_pk_bf16(a[0], a[1]); w.y = cvt_pk_bf16(a[2], a[3]); w.z = cvt_pk_bf16(b[0], b[1]); w.w = cvt_pk_bf16(b[2], b[3]); return w; }
;     __device__ __forceinline__ void operator()(const f32x4 (&acc)[2][2][4][2], const pg8::Unit& u, int wr, int wc, int fr, int fq) const {
;     ...
;             for (int m = 0; m < 4; ++m) { const int row = row0 + ai * 128 + m * 16; const float mu = mu4[m], rs = rs4[m];
;                 f32x4 yv[2][2], gq[2][2], bq_[2][2];
; #pragma unroll
;                 for (int bj = 0; bj < 2; ++bj)
; #pragma unroll
;                     for (int n = 0; n < 2; ++n) { yv[bj][n] = *(const f32x4*)(Yin + (size_t)row * D_ + col0 + bj * 128 + 4 * n); gq[bj][n] = *(const f32x4*)(g + col0 + bj * 128 + 4 * n); bq_[bj][n] = *(const f32x4*)(b + col0 + bj * 128 + 4 * n); }
;     ...
;                 for (int bj = 0; bj < 2; ++bj) { float* yp = Y + (size_t)row * D_ + col0 + bj * 128; f32x4 v[2];
; #pragma unroll
;                     for (int n = 0; n < 2; ++n) { v[n] = (((yv[bj][n] - mu) * rs) * gq[bj][n] + bq_[bj][n]) * ALPHA_ + acc[ai][bj][m][n] * sc;
;                         *(f32x4*)(yp + 4 * n) = v[n]; s1 += (v[n][0] + v[n][1]) + (v[n][2] + v[n][3]); s2 += (v[n][0] * v[n][0] + v[n][1] * v[n][1]) + (v[n][2] * v[n][2] + v[n][3] * v[n][3]); }
;                     *(u32x4*)(Yb + blk_off(row, col0 + bj * 128, D_)) = pack8(v[0], v[1]); }
;                 s1 = xsum32(xsum16(s1)); s2 = xsum32(xsum16(s2));
;                 if (fq == 0) *(f32x2*)(stn + (size_t)row * 32 + (u.pn * 4 + wc) * 2) = (f32x2){s1, s2}; asm volatile("" ::: "memory"); } }
	v_pk_fma_f32 v[26:27], v[48:49], v[26:27], v[52:53]
	v_pk_fma_f32 v[28:29], v[46:47], v[28:29], v[50:51]
	v_pk_mul_f32 v[26:27], v[26:27], s[2:3] op_sel_hi:[1,0]
	v_pk_mul_f32 v[28:29], v[28:29], s[2:3] op_sel_hi:[1,0]
	v_pk_fma_f32 v[24:25], v[24:25], 0.5, v[26:27] op_sel_hi:[1,0,1]
	v_pk_fma_f32 v[22:23], v[22:23], 0.5, v[28:29] op_sel_hi:[1,0,1]
	v_add_f32_e32 v27, v24, v25
	v_add_f32_e32 v26, v22, v23
	v_add_f32_e32 v26, v26, v27
	v_add_f32_e32 v31, v31, v26
	v_mul_f32_e32 v26, v23, v23
	v_mul_f32_e32 v27, v25, v25
	v_fmac_f32_e32 v26, v22, v22
	v_fmac_f32_e32 v27, v24, v24
	v_add_f32_e32 v26, v26, v27
	v_add_f32_e32 v30, v30, v26
	v_sub_f32_e32 v27, v37, v59
	v_sub_f32_e32 v26, v36, v59
	v_sub_f32_e32 v29, v35, v59
	v_sub_f32_e32 v28, v34, v59
	v_pk_mul_f32 v[28:29], v[58:59], v[28:29] op_sel_hi:[0,1]
	v_pk_mul_f32 v[26:27], v[58:59], v[26:27] op_sel_hi:[0,1]
	v_pk_fma_f32 v[26:27], v[40:41], v[26:27], v[44:45]
	v_pk_fma_f32 v[28:29], v[38:39], v[28:29], v[42:43]
	v_pk_mul_f32 v[26:27], v[26:27], s[2:3] op_sel_hi:[1,0]
	v_pk_mul_f32 v[28:29], v[28:29], s[2:3] op_sel_hi:[1,0]
	v_pk_fma_f32 v[20:21], v[20:21], 0.5, v[26:27] op_sel_hi:[1,0,1]
	v_pk_fma_f32 v[18:19], v[18:19], 0.5, v[28:29] op_sel_hi:[1,0,1]
	v_add_f32_e32 v27, v20, v21
	v_add_f32_e32 v26, v18, v19
	v_add_f32_e32 v26, v26, v27
	v_mul_f32_e32 v27, v19, v19
	v_mul_f32_e32 v28, v21, v21
	v_add_f32_e32 v26, v31, v26
	v_fmac_f32_e32 v27, v18, v18
	v_fmac_f32_e32 v28, v20, v20
	s_nop 0
	s_nop 1
	v_bfe_u32 v33, v227, 4, 2
	v_sub_u32_e32 v32, 0, v33
	v_lshlrev_b32_e32 v32, 4, v32
	v_ashrrev_i32_e32 v33, 31, v32
	v_lshl_add_u64 v[32:33], v[60:61], 0, v[32:33]
	v_permlane16_swap_b32_e32 v22, v18
	v_permlane16_swap_b32_e32 v23, v19
	v_permlane16_swap_b32_e32 v24, v20
	v_permlane16_swap_b32_e32 v25, v21
	v_permlane32_swap_b32_e32 v22, v18
	v_permlane32_swap_b32_e32 v23, v19
	v_permlane32_swap_b32_e32 v24, v20
	v_permlane32_swap_b32_e32 v25, v21
	global_store_dwordx4 v[32:33], v[22:25], off offset:512
	global_store_dwordx4 v[32:33], v[18:21], off offset:576
	s_nop 1
	v_permlane32_swap_b32_e32 v22, v18
	v_permlane32_swap_b32_e32 v23, v19
	v_permlane32_swap_b32_e32 v24, v20
	v_permlane32_swap_b32_e32 v25, v21
	v_permlane16_swap_b32_e32 v22, v18
	v_permlane16_swap_b32_e32 v23, v19
	v_permlane16_swap_b32_e32 v24, v20
	v_permlane16_swap_b32_e32 v25, v21
	v_add_f32_e32 v27, v27, v28
	v_cvt_pk_bf16_f32 v22, v22, v23
	v_cvt_pk_bf16_f32 v23, v24, v25
	v_cvt_pk_bf16_f32 v24, v18, v19
	v_lshl_add_u64 v[18:19], v[76:77], 0, v[0:1]
	v_mov_b32_e32 v0, v26
	v_add_f32_e32 v27, v30, v27
	v_cvt_pk_bf16_f32 v25, v20, v21
	v_permlane16_swap_b32_e32 v26, v0
	global_store_dwordx4 v[18:19], v[22:25], off
	v_add_f32_e32 v18, v26, v0
	v_mov_b32_e32 v0, v27
	s_nop 1
	v_permlane16_swap_b32_e32 v27, v0
	v_add_f32_e32 v19, v27, v0
	v_mov_b32_e32 v20, v18
	v_mov_b32_e32 v21, v19
	s_nop 0
	v_permlane32_swap_b32_e32 v18, v20
	v_permlane32_swap_b32_e32 v19, v21
	s_and_saveexec_b64 s[24:25], s[40:41]
	s_cbranch_execz .LBB0_1717
	v_pk_add_f32 v[18:19], v[18:19], v[20:21]
	v_lshlrev_b64 v[20:21], 7, v[80:81]
	v_lshl_add_u64 v[20:21], s[8:9], 0, v[20:21]
	v_lshl_add_u64 v[20:21], s[38:39], 2, v[20:21]
	global_store_dwordx2 v[20:21], v[18:19], off
.LBB0_1717:
	s_or_b64 exec, exec, s[24:25]
	v_pk_add_f32 v[18:19], v[82:83], v[84:85]
	s_mov_b32 s2, 0x3a800000
	v_pk_mul_f32 v[42:43], v[18:19], s[2:3] op_sel_hi:[1,0]
	s_mov_b32 s1, 0x800000
	v_fma_f32 v0, -v43, v43, v42
	v_max_f32_e32 v0, 0, v0
	v_add_f32_e32 v0, 0x3727c5ac, v0
	v_cmp_gt_f32_e32 vcc, s1, v0
	v_mul_f32_e32 v18, 0x4b800000, v0
	s_load_dwordx16 s[60:75], s[34:35], 0x38
	v_cndmask_b32_e32 v0, v0, v18, vcc
	v_rsq_f32_e32 v0, v0
	s_mov_b32 s2, 0x3fd744fd
	s_movk_i32 s1, 0x3fc0
	v_mul_f32_e32 v18, 0x45800000, v0
	v_cndmask_b32_e32 v42, v0, v18, vcc
	v_lshlrev_b64 v[18:19], 12, v[74:75]
	s_waitcnt lgkmcnt(0)
	v_lshl_add_u64 v[18:19], s[74:75], 0, v[18:19]
	v_lshl_add_u64 v[44:45], v[152:153], 2, v[18:19]
	s_nop 1
	v_bfe_u32 v21, v227, 4, 2
	v_sub_u32_e32 v20, 0, v21
	v_lshlrev_b32_e32 v20, 4, v20
	v_ashrrev_i32_e32 v21, 31, v20
	v_lshl_add_u64 v[20:21], v[44:45], 0, v[20:21]
	global_load_dwordx4 v[46:49], v[20:21], off offset:64
	global_load_dwordx4 v[50:53], v[20:21], off
	global_load_dwordx4 v[54:57], v[156:157], off offset:16
	global_load_dwordx4 v[58:61], v[156:157], off
	global_load_dwordx4 v[62:65], v[154:155], off offset:16
	global_load_dwordx4 v[66:69], v[154:155], off
	s_nop 1
	v_bfe_u32 v23, v227, 4, 2
	v_sub_u32_e32 v22, 0, v23
	v_lshlrev_b32_e32 v22, 4, v22
	v_ashrrev_i32_e32 v23, 31, v22
	v_lshl_add_u64 v[22:23], v[44:45], 0, v[22:23]
	global_load_dwordx4 v[18:21], v[22:23], off offset:576
	global_load_dwordx4 v[38:41], v[22:23], off offset:512
	global_load_dwordx4 v[22:25], v[156:157], off offset:528
	global_load_dwordx4 v[30:33], v[156:157], off offset:512
	global_load_dwordx4 v[26:29], v[154:155], off offset:528
	global_load_dwordx4 v[34:37], v[154:155], off offset:512
	v_lshlrev_b32_e32 v0, 6, v74
	v_and_or_b32 v0, v0, s1, v196
	v_lshlrev_b32_e32 v0, 1, v0
	s_waitcnt vmcnt(10)
	v_permlane32_swap_b32_e32 v50, v46
	v_permlane32_swap_b32_e32 v51, v47
	v_permlane32_swap_b32_e32 v52, v48
	v_permlane32_swap_b32_e32 v53, v49
	v_permlane16_swap_b32_e32 v50, v46
	v_permlane16_swap_b32_e32 v51, v47
	v_permlane16_swap_b32_e32 v52, v48
	v_permlane16_swap_b32_e32 v53, v49
	v_sub_f32_e32 v53, v53, v43
	v_sub_f32_e32 v52, v52, v43
	v_sub_f32_e32 v51, v51, v43
	v_sub_f32_e32 v50, v50, v43
	v_pk_mul_f32 v[50:51], v[42:43], v[50:51] op_sel_hi:[0,1]
	v_pk_mul_f32 v[52:53], v[42:43], v[52:53] op_sel_hi:[0,1]
	s_waitcnt vmcnt(6)
; __device__ __forceinline__ float xsum16(float v) { const auto r = __builtin_amdgcn_permlane16_swap(__float_as_uint(v), __float_as_uint(v), false, false); return __uint_as_float(r[0]) + __uint_as_float(r[1]); }
; __device__ __forceinline__ float xsum32(float v) { const auto r = __builtin_amdgcn_permlane32_swap(__float_as_uint(v), __float_as_uint(v), false, false); return __uint_as_float(r[0]) + __uint_as_float(r[1]); }
; __device__ __forceinline__ size_t blk_off(int r, int c, int K) { return (size_t)(r >> 8) * 256 * K + (size_t)(c >> 6) * (256 * 64) + (size_t)((r & 255) * 64 + (c & 63)); }
; __device__ __forceinline__ u32x4 pack8(const f32x4 a, const f32x4 b) { u32x4 w; w.x = cvt_pk_bf16(a[0], a[1]); w.y = cvt_pk_bf16(a[2], a[3]); w.z = cvt_pk_bf16(b[0], b[1]); w.w = cvt_pk_bf16(b[2], b[3]); return w; }
;     __device__ __forceinline__ void operator()(const f32x4 (&acc)[2][2][4][2], const pg8::Unit& u, int wr, int wc, int fr, int fq) const {
;     ...
;                 for (int bj = 0; bj < 2; ++bj) { float* yp = Y + (size_t)row * D_ + col0 + bj * 128; f32x4 v[2];
; #pragma unroll
;                     for (int n = 0; n < 2; ++n) { v[n] = (((yv[bj][n] - mu) * rs) * gq[bj][n] + bq_[bj][n]) * ALPHA_ + acc[ai][bj][m][n] * sc;
;                         *(f32x4*)(yp + 4 * n) = v[n]; s1 += (v[n][0] + v[n][1]) + (v[n][2] + v[n][3]); s2 += (v[n][0] * v[n][0] + v[n][1] * v[n][1]) + (v[n][2] * v[n][2] + v[n][3] * v[n][3]); }
;                     *(u32x4*)(Yb + blk_off(row, col0 + bj * 128, D_)) = pack8(v[0], v[1]); }
;                 s1 = xsum32(xsum16(s1)); s2 = xsum32(xsum16(s2));
;                 if (fq == 0) *(f32x2*)(stn + (size_t)row * 32 + (u.pn * 4 + wc) * 2) = (f32x2){s1, s2}; asm volatile("" ::: "memory"); } }
	v_pk_fma_f32 v[52:53], v[60:61], v[52:53], v[68:69]
	v_pk_fma_f32 v[50:51], v[58:59], v[50:51], v[66:67]
	v_pk_mul_f32 v[52:53], v[52:53], s[2:3] op_sel_hi:[1,0]
	v_pk_mul_f32 v[50:51], v[50:51], s[2:3] op_sel_hi:[1,0]
	v_pk_fma_f32 v[52:53], v[16:17], 0.5, v[52:53] op_sel_hi:[1,0,1]
	v_pk_fma_f32 v[50:51], v[14:15], 0.5, v[50:51] op_sel_hi:[1,0,1]
	v_add_f32_e32 v15, v52, v53
	v_add_f32_e32 v14, v50, v51
	v_add_f32_e32 v14, v14, v15
	v_add_f32_e32 v58, 0, v14
	v_mul_f32_e32 v14, v51, v51
	v_mul_f32_e32 v15, v53, v53
	v_fmac_f32_e32 v14, v50, v50
	v_fmac_f32_e32 v15, v52, v52
	v_add_f32_e32 v59, v14, v15
	v_sub_f32_e32 v15, v49, v43
	v_sub_f32_e32 v14, v48, v43
	v_sub_f32_e32 v17, v47, v43
	v_sub_f32_e32 v16, v46, v43
	v_pk_mul_f32 v[16:17], v[42:43], v[16:17] op_sel_hi:[0,1]
	v_pk_mul_f32 v[14:15], v[42:43], v[14:15] op_sel_hi:[0,1]
	v_pk_fma_f32 v[14:15], v[56:57], v[14:15], v[64:65]
	v_pk_fma_f32 v[16:17], v[54:55], v[16:17], v[62:63]
	v_pk_mul_f32 v[14:15], v[14:15], s[2:3] op_sel_hi:[1,0]
	v_pk_mul_f32 v[16:17], v[16:17], s[2:3] op_sel_hi:[1,0]
	v_pk_fma_f32 v[48:49], v[12:13], 0.5, v[14:15] op_sel_hi:[1,0,1]
	v_pk_fma_f32 v[46:47], v[10:11], 0.5, v[16:17] op_sel_hi:[1,0,1]
	v_add_f32_e32 v11, v48, v49
	v_add_f32_e32 v10, v46, v47
	v_add_f32_e32 v10, v10, v11
	v_add_f32_e32 v15, v58, v10
	v_mul_f32_e32 v10, v47, v47
	v_mul_f32_e32 v11, v49, v49
	v_fmac_f32_e32 v10, v46, v46
	v_fmac_f32_e32 v11, v48, v48
	v_add_f32_e32 v10, v10, v11
	v_add_f32_e32 v14, v59, v10
	v_cvt_pk_bf16_f32 v10, v50, v51
	v_cvt_pk_bf16_f32 v11, v52, v53
	v_cvt_pk_bf16_f32 v12, v46, v47
	v_cvt_pk_bf16_f32 v13, v48, v49
	v_lshl_add_u64 v[16:17], v[78:79], 0, v[0:1]
	s_nop 0
	s_nop 1
	v_bfe_u32 v55, v227, 4, 2
	v_sub_u32_e32 v54, 0, v55
	v_lshlrev_b32_e32 v54, 4, v54
	v_ashrrev_i32_e32 v55, 31, v54
	v_lshl_add_u64 v[54:55], v[44:45], 0, v[54:55]
	v_permlane16_swap_b32_e32 v50, v46
	v_permlane16_swap_b32_e32 v51, v47
	v_permlane16_swap_b32_e32 v52, v48
	v_permlane16_swap_b32_e32 v53, v49
	v_permlane32_swap_b32_e32 v50, v46
	v_permlane32_swap_b32_e32 v51, v47
	v_permlane32_swap_b32_e32 v52, v48
	v_permlane32_swap_b32_e32 v53, v49
	global_store_dwordx4 v[54:55], v[50:53], off
	global_store_dwordx4 v[54:55], v[46:49], off offset:64
	s_nop 1
	v_permlane32_swap_b32_e32 v50, v46
	v_permlane32_swap_b32_e32 v51, v47
	v_permlane32_swap_b32_e32 v52, v48
	v_permlane32_swap_b32_e32 v53, v49
	v_permlane16_swap_b32_e32 v50, v46
	v_permlane16_swap_b32_e32 v51, v47
	v_permlane16_swap_b32_e32 v52, v48
	v_permlane16_swap_b32_e32 v53, v49
	global_store_dwordx4 v[16:17], v[10:13], off
	s_nop 0
	s_waitcnt vmcnt(7)
	v_permlane32_swap_b32_e32 v38, v18
	v_permlane32_swap_b32_e32 v39, v19
	v_permlane32_swap_b32_e32 v40, v20
	v_permlane32_swap_b32_e32 v41, v21
	v_permlane16_swap_b32_e32 v38, v18
	v_permlane16_swap_b32_e32 v39, v19
	v_permlane16_swap_b32_e32 v40, v20
	v_permlane16_swap_b32_e32 v41, v21
	v_sub_f32_e32 v11, v41, v43
	v_sub_f32_e32 v10, v40, v43
	v_sub_f32_e32 v13, v39, v43
	v_sub_f32_e32 v12, v38, v43
	v_pk_mul_f32 v[12:13], v[42:43], v[12:13] op_sel_hi:[0,1]
	v_pk_mul_f32 v[10:11], v[42:43], v[10:11] op_sel_hi:[0,1]
	s_waitcnt vmcnt(3)
	v_pk_fma_f32 v[10:11], v[32:33], v[10:11], v[36:37]
	v_pk_fma_f32 v[12:13], v[30:31], v[12:13], v[34:35]
	v_pk_mul_f32 v[10:11], v[10:11], s[2:3] op_sel_hi:[1,0]
	v_pk_mul_f32 v[12:13], v[12:13], s[2:3] op_sel_hi:[1,0]
	v_pk_fma_f32 v[8:9], v[8:9], 0.5, v[10:11] op_sel_hi:[1,0,1]
	v_pk_fma_f32 v[6:7], v[6:7], 0.5, v[12:13] op_sel_hi:[1,0,1]
	v_add_f32_e32 v11, v8, v9
	v_add_f32_e32 v10, v6, v7
	v_add_f32_e32 v10, v10, v11
	v_add_f32_e32 v15, v15, v10
	v_mul_f32_e32 v10, v7, v7
	v_mul_f32_e32 v11, v9, v9
	v_fmac_f32_e32 v10, v6, v6
	v_fmac_f32_e32 v11, v8, v8
	v_add_f32_e32 v10, v10, v11
	v_add_f32_e32 v14, v14, v10
	v_sub_f32_e32 v11, v21, v43
	v_sub_f32_e32 v10, v20, v43
	v_sub_f32_e32 v13, v19, v43
	v_sub_f32_e32 v12, v18, v43
	v_pk_mul_f32 v[12:13], v[42:43], v[12:13] op_sel_hi:[0,1]
	v_pk_mul_f32 v[10:11], v[42:43], v[10:11] op_sel_hi:[0,1]
	v_pk_fma_f32 v[10:11], v[24:25], v[10:11], v[28:29]
	v_pk_fma_f32 v[12:13], v[22:23], v[12:13], v[26:27]
	v_pk_mul_f32 v[10:11], v[10:11], s[2:3] op_sel_hi:[1,0]
	v_pk_mul_f32 v[12:13], v[12:13], s[2:3] op_sel_hi:[1,0]
	v_pk_fma_f32 v[4:5], v[4:5], 0.5, v[10:11] op_sel_hi:[1,0,1]
	v_pk_fma_f32 v[2:3], v[2:3], 0.5, v[12:13] op_sel_hi:[1,0,1]
	v_add_f32_e32 v11, v4, v5
	v_add_f32_e32 v10, v2, v3
	v_add_f32_e32 v10, v10, v11
	v_mul_f32_e32 v11, v3, v3
	v_mul_f32_e32 v12, v5, v5
	v_add_f32_e32 v10, v15, v10
	v_fmac_f32_e32 v11, v2, v2
	v_fmac_f32_e32 v12, v4, v4
	s_nop 0
	s_nop 1
	v_bfe_u32 v17, v227, 4, 2
	v_sub_u32_e32 v16, 0, v17
	v_lshlrev_b32_e32 v16, 4, v16
	v_ashrrev_i32_e32 v17, 31, v16
	v_lshl_add_u64 v[16:17], v[44:45], 0, v[16:17]
	v_permlane16_swap_b32_e32 v6, v2
	v_permlane16_swap_b32_e32 v7, v3
	v_permlane16_swap_b32_e32 v8, v4
	v_permlane16_swap_b32_e32 v9, v5
	v_permlane32_swap_b32_e32 v6, v2
	v_permlane32_swap_b32_e32 v7, v3
	v_permlane32_swap_b32_e32 v8, v4
	v_permlane32_swap_b32_e32 v9, v5
	global_store_dwordx4 v[16:17], v[6:9], off offset:512
	global_store_dwordx4 v[16:17], v[2:5], off offset:576
	s_nop 1
	v_permlane32_swap_b32_e32 v6, v2
	v_permlane32_swap_b32_e32 v7, v3
	v_permlane32_swap_b32_e32 v8, v4
	v_permlane32_swap_b32_e32 v9, v5
	v_permlane16_swap_b32_e32 v6, v2
	v_permlane16_swap_b32_e32 v7, v3
	v_permlane16_swap_b32_e32 v8, v4
	v_permlane16_swap_b32_e32 v9, v5
	v_add_f32_e32 v11, v11, v12
	v_cvt_pk_bf16_f32 v6, v6, v7
	v_cvt_pk_bf16_f32 v7, v8, v9
	v_cvt_pk_bf16_f32 v8, v2, v3
	v_lshl_add_u64 v[2:3], v[76:77], 0, v[0:1]
	v_mov_b32_e32 v0, v10
	v_add_f32_e32 v11, v14, v11
	v_cvt_pk_bf16_f32 v9, v4, v5
	v_permlane16_swap_b32_e32 v10, v0
	global_store_dwordx4 v[2:3], v[6:9], off
	v_add_f32_e32 v2, v10, v0
	v_mov_b32_e32 v0, v11
	s_nop 1
	v_permlane16_swap_b32_e32 v11, v0
	v_add_f32_e32 v3, v11, v0
	v_mov_b32_e32 v4, v2
	v_mov_b32_e32 v5, v3
	s_nop 0
	v_permlane32_swap_b32_e32 v2, v4
	v_permlane32_swap_b32_e32 v3, v5
	s_and_saveexec_b64 s[24:25], s[40:41]
	s_cbranch_execz .LBB0_1719
	v_pk_add_f32 v[2:3], v[2:3], v[4:5]
	v_lshlrev_b64 v[4:5], 7, v[74:75]
	v_lshl_add_u64 v[4:5], s[8:9], 0, v[4:5]
	v_lshl_add_u64 v[4:5], s[38:39], 2, v[4:5]
	global_store_dwordx2 v[4:5], v[2:3], off
